# GEMM unit loops: first K-iteration after an epilogue waits with vmcnt(24) at phase 4 and vmcnt(10) at phase 6 so the 16 epilogue stores drain under the K-loop
# baseline (speedup 1.0000x reference)
_Z11mega_kernel6Params:
	s_mov_b32 s94, 0
	s_load_dwordx16 s[36:51], s[0:1], 0x100
	s_load_dwordx2 s[24:25], s[0:1], 0x140
	v_and_b32_e32 v129, 0x3ff, v0
	v_cmp_gt_u32_e32 vcc, 4, v129
	s_and_saveexec_b64 s[4:5], vcc
	v_lshl_add_u32 v1, v129, 2, 0
	v_add_u32_e32 v1, 0x20000, v1
	v_mov_b32_e32 v2, 0
	ds_write_b32 v1, v2
	s_or_b64 exec, exec, s[4:5]
	s_waitcnt lgkmcnt(0)
	s_barrier
	s_getreg_b32 s3, hwreg(HW_REG_XCC_ID, 0, 4)
	s_and_b32 s33, s3, 15
	v_cmp_eq_u32_e64 s[92:93], 0, v129
	s_and_saveexec_b64 s[4:5], s[92:93]
	s_cbranch_execz .LBB0_5
	s_mov_b64 s[6:7], exec
	v_mbcnt_lo_u32_b32 v1, s6, 0
	v_mbcnt_hi_u32_b32 v1, s7, v1
	v_cmp_eq_u32_e32 vcc, 0, v1
	s_and_b64 s[8:9], exec, vcc
	s_mov_b64 exec, s[8:9]
	s_cbranch_execz .LBB0_5
	s_lshl_b32 s3, s33, 8
	s_bcnt1_i32_b64 s6, s[6:7]
	v_mov_b32_e32 v1, s3
	v_mov_b32_e32 v2, s6
	global_atomic_add v1, v2, s[48:49] offset:1024

.LBB0_155:
	ds_read_b128 v[154:157], v150
	ds_read_b128 v[158:161], v150 offset:1024
	ds_read_b128 v[162:165], v150 offset:2048
	ds_read_b128 v[166:169], v150 offset:3072
	s_add_u32 s26, s20, 0xfffc0080
	s_addc_u32 s27, s21, -1
	s_cmp_eq_u32 s86, 12
	s_cselect_b32 s29, s15, s27
	s_cselect_b32 s28, s82, s26
	s_cselect_b32 s27, s13, s85
	s_cselect_b32 s26, s83, s84
	v_lshl_add_u64 v[202:203], s[20:21], 0, v[138:139]
	s_add_i32 m0, s11, 0xc000
	ds_read_b128 v[170:173], v151
	ds_read_b128 v[174:177], v151 offset:1024
	ds_read_b128 v[178:181], v151 offset:2048
	ds_read_b128 v[182:185], v151 offset:3072
	ds_read_b128 v[186:189], v151 offset:4096
	ds_read_b128 v[190:193], v151 offset:5120
	ds_read_b128 v[194:197], v151 offset:6144
	ds_read_b128 v[198:201], v151 offset:7168
	global_load_lds_dwordx4 v[202:203], off
	v_lshl_add_u64 v[202:203], s[20:21], 0, v[140:141]
	s_add_i32 m0, s11, 0xe000
	s_nop 0
	global_load_lds_dwordx4 v[202:203], off
	s_waitcnt lgkmcnt(8)
	s_barrier
	s_waitcnt lgkmcnt(0)
	s_waitcnt lgkmcnt(0)
	v_mfma_f32_16x16x32_bf16 v[124:127], v[154:157], v[170:173], v[124:127]
	v_mfma_f32_16x16x32_bf16 v[120:123], v[162:165], v[170:173], v[120:123]
	v_mfma_f32_16x16x32_bf16 v[116:119], v[154:157], v[178:181], v[116:119]
	v_mfma_f32_16x16x32_bf16 v[112:115], v[162:165], v[178:181], v[112:115]
	v_mfma_f32_16x16x32_bf16 v[100:103], v[154:157], v[186:189], v[100:103]
	v_mfma_f32_16x16x32_bf16 v[96:99], v[162:165], v[186:189], v[96:99]
	v_mfma_f32_16x16x32_bf16 v[84:87], v[154:157], v[194:197], v[84:87]
	v_mfma_f32_16x16x32_bf16 v[80:83], v[162:165], v[194:197], v[80:83]
	v_mfma_f32_16x16x32_bf16 v[124:127], v[158:161], v[174:177], v[124:127]
	v_mfma_f32_16x16x32_bf16 v[120:123], v[166:169], v[174:177], v[120:123]
	v_mfma_f32_16x16x32_bf16 v[116:119], v[158:161], v[182:185], v[116:119]
	v_mfma_f32_16x16x32_bf16 v[112:115], v[166:169], v[182:185], v[112:115]
	v_mfma_f32_16x16x32_bf16 v[100:103], v[158:161], v[190:193], v[100:103]
	v_mfma_f32_16x16x32_bf16 v[96:99], v[166:169], v[190:193], v[96:99]
	v_mfma_f32_16x16x32_bf16 v[84:87], v[158:161], v[198:201], v[84:87]
	v_mfma_f32_16x16x32_bf16 v[80:83], v[166:169], v[198:201], v[80:83]
	s_barrier
	s_add_i32 s87, s72, s34
	v_lshl_add_u64 v[218:219], s[26:27], 0, v[134:135]
	s_mov_b32 m0, s87
	ds_read_b128 v[202:205], v152
	ds_read_b128 v[206:209], v152 offset:1024
	ds_read_b128 v[210:213], v152 offset:2048
	ds_read_b128 v[214:217], v152 offset:3072
	global_load_lds_dwordx4 v[218:219], off
	v_lshl_add_u64 v[220:221], s[26:27], 0, v[130:131]
	s_add_i32 m0, s87, 0x2000
	s_nop 0
	global_load_lds_dwordx4 v[220:221], off
	s_barrier
	s_waitcnt lgkmcnt(0)
	s_waitcnt lgkmcnt(0)
	v_mfma_f32_16x16x32_bf16 v[108:111], v[202:205], v[170:173], v[108:111]
	v_mfma_f32_16x16x32_bf16 v[104:107], v[210:213], v[170:173], v[104:107]
	v_mfma_f32_16x16x32_bf16 v[92:95], v[202:205], v[178:181], v[92:95]
	v_mfma_f32_16x16x32_bf16 v[88:91], v[210:213], v[178:181], v[88:91]
	v_mfma_f32_16x16x32_bf16 v[76:79], v[202:205], v[186:189], v[76:79]
	v_mfma_f32_16x16x32_bf16 v[72:75], v[210:213], v[186:189], v[72:75]
	v_mfma_f32_16x16x32_bf16 v[68:71], v[202:205], v[194:197], v[68:71]
	v_mfma_f32_16x16x32_bf16 v[64:67], v[210:213], v[194:197], v[64:67]
	v_mfma_f32_16x16x32_bf16 v[108:111], v[206:209], v[174:177], v[108:111]
	v_mfma_f32_16x16x32_bf16 v[104:107], v[214:217], v[174:177], v[104:107]
	v_mfma_f32_16x16x32_bf16 v[92:95], v[206:209], v[182:185], v[92:95]
	v_mfma_f32_16x16x32_bf16 v[88:91], v[214:217], v[182:185], v[88:91]
	v_mfma_f32_16x16x32_bf16 v[76:79], v[206:209], v[190:193], v[76:79]
	v_mfma_f32_16x16x32_bf16 v[72:75], v[214:217], v[190:193], v[72:75]
	v_mfma_f32_16x16x32_bf16 v[68:71], v[206:209], v[198:201], v[68:71]
	v_mfma_f32_16x16x32_bf16 v[64:67], v[214:217], v[198:201], v[64:67]
	s_mov_b32 m0, s11
	v_lshl_add_u64 v[222:223], s[28:29], 0, v[136:137]
	s_barrier
	ds_read_b128 v[170:173], v151 offset:16384
	ds_read_b128 v[174:177], v151 offset:17408
	ds_read_b128 v[178:181], v151 offset:18432
	ds_read_b128 v[182:185], v151 offset:19456
	ds_read_b128 v[186:189], v151 offset:20480
	ds_read_b128 v[190:193], v151 offset:21504
	ds_read_b128 v[194:197], v151 offset:22528
	ds_read_b128 v[198:201], v151 offset:23552
	global_load_lds_dwordx4 v[222:223], off
	v_lshl_add_u64 v[224:225], s[28:29], 0, v[132:133]
	s_mov_b32 m0, s35
	s_nop 0
	global_load_lds_dwordx4 v[224:225], off
	s_barrier
	s_waitcnt lgkmcnt(0)
	s_waitcnt lgkmcnt(0)
	v_mfma_f32_16x16x32_bf16 v[60:63], v[154:157], v[170:173], v[60:63]
	v_mfma_f32_16x16x32_bf16 v[56:59], v[162:165], v[170:173], v[56:59]
	v_mfma_f32_16x16x32_bf16 v[52:55], v[154:157], v[178:181], v[52:55]
	v_mfma_f32_16x16x32_bf16 v[48:51], v[162:165], v[178:181], v[48:51]
	v_mfma_f32_16x16x32_bf16 v[36:39], v[154:157], v[186:189], v[36:39]
	v_mfma_f32_16x16x32_bf16 v[32:35], v[162:165], v[186:189], v[32:35]
	v_mfma_f32_16x16x32_bf16 v[20:23], v[154:157], v[194:197], v[20:23]
	v_mfma_f32_16x16x32_bf16 v[16:19], v[162:165], v[194:197], v[16:19]
	v_mfma_f32_16x16x32_bf16 v[60:63], v[158:161], v[174:177], v[60:63]
	v_mfma_f32_16x16x32_bf16 v[56:59], v[166:169], v[174:177], v[56:59]
	v_mfma_f32_16x16x32_bf16 v[52:55], v[158:161], v[182:185], v[52:55]
	v_mfma_f32_16x16x32_bf16 v[48:51], v[166:169], v[182:185], v[48:51]
	v_mfma_f32_16x16x32_bf16 v[36:39], v[158:161], v[190:193], v[36:39]
	v_mfma_f32_16x16x32_bf16 v[32:35], v[166:169], v[190:193], v[32:35]
	v_mfma_f32_16x16x32_bf16 v[20:23], v[158:161], v[198:201], v[20:23]
	v_mfma_f32_16x16x32_bf16 v[16:19], v[166:169], v[198:201], v[16:19]
	s_barrier
	s_add_u32 s88, s26, 0x40000
	s_addc_u32 s89, s27, 0
	s_add_i32 s87, s73, s34
	v_lshl_add_u64 v[154:155], s[88:89], 0, v[134:135]
	s_mov_b32 m0, s87
	s_nop 0
	global_load_lds_dwordx4 v[154:155], off
	v_lshl_add_u64 v[154:155], s[88:89], 0, v[130:131]
	s_add_i32 m0, s87, 0x2000
	s_nop 0
	global_load_lds_dwordx4 v[154:155], off
	s_cmp_lg_u32 s94, 0
	s_cbranch_scc1 .Lrx1a
	s_waitcnt vmcnt(6)
.Lrx1a:
	s_waitcnt vmcnt(24)
	s_barrier
	v_mfma_f32_16x16x32_bf16 v[44:47], v[202:205], v[170:173], v[44:47]
	v_mfma_f32_16x16x32_bf16 v[40:43], v[210:213], v[170:173], v[40:43]
	v_mfma_f32_16x16x32_bf16 v[28:31], v[202:205], v[178:181], v[28:31]
	v_mfma_f32_16x16x32_bf16 v[24:27], v[210:213], v[178:181], v[24:27]
	v_mfma_f32_16x16x32_bf16 v[12:15], v[202:205], v[186:189], v[12:15]
	v_mfma_f32_16x16x32_bf16 v[8:11], v[210:213], v[186:189], v[8:11]
	v_mfma_f32_16x16x32_bf16 v[4:7], v[202:205], v[194:197], v[4:7]
	v_mfma_f32_16x16x32_bf16 v[0:3], v[210:213], v[194:197], v[0:3]
	v_mfma_f32_16x16x32_bf16 v[44:47], v[206:209], v[174:177], v[44:47]
	v_mfma_f32_16x16x32_bf16 v[40:43], v[214:217], v[174:177], v[40:43]
	v_mfma_f32_16x16x32_bf16 v[28:31], v[206:209], v[182:185], v[28:31]
	v_mfma_f32_16x16x32_bf16 v[24:27], v[214:217], v[182:185], v[24:27]
	v_mfma_f32_16x16x32_bf16 v[12:15], v[206:209], v[190:193], v[12:15]
	v_mfma_f32_16x16x32_bf16 v[8:11], v[214:217], v[190:193], v[8:11]
	v_mfma_f32_16x16x32_bf16 v[4:7], v[206:209], v[198:201], v[4:7]
	v_mfma_f32_16x16x32_bf16 v[0:3], v[214:217], v[198:201], v[0:3]
	s_add_i32 s87, 0, 0x18000
	v_add_u32_e32 v153, s87, v148
	s_barrier
	ds_read_b128 v[154:157], v153
	ds_read_b128 v[158:161], v153 offset:1024
	ds_read_b128 v[162:165], v153 offset:2048
	ds_read_b128 v[166:169], v153 offset:3072
	s_add_u32 s28, s28, 0x40000
	s_addc_u32 s29, s29, 0
	s_mov_b32 m0, s54
	v_lshl_add_u64 v[202:203], s[28:29], 0, v[136:137]
	ds_read_b128 v[170:173], v151 offset:32768
	ds_read_b128 v[174:177], v151 offset:33792
	ds_read_b128 v[178:181], v151 offset:34816
	ds_read_b128 v[182:185], v151 offset:35840
	ds_read_b128 v[186:189], v151 offset:36864
	ds_read_b128 v[190:193], v151 offset:37888
	ds_read_b128 v[194:197], v151 offset:38912
	ds_read_b128 v[198:201], v151 offset:39936
	global_load_lds_dwordx4 v[202:203], off
	v_lshl_add_u64 v[202:203], s[28:29], 0, v[132:133]
	s_mov_b32 m0, s55
	s_nop 0
	global_load_lds_dwordx4 v[202:203], off
	s_waitcnt lgkmcnt(8)
	s_barrier
	s_waitcnt lgkmcnt(0)
	s_waitcnt lgkmcnt(0)
	v_mfma_f32_16x16x32_bf16 v[124:127], v[154:157], v[170:173], v[124:127]
	v_mfma_f32_16x16x32_bf16 v[120:123], v[162:165], v[170:173], v[120:123]
	v_mfma_f32_16x16x32_bf16 v[116:119], v[154:157], v[178:181], v[116:119]
	v_mfma_f32_16x16x32_bf16 v[112:115], v[162:165], v[178:181], v[112:115]
	v_mfma_f32_16x16x32_bf16 v[100:103], v[154:157], v[186:189], v[100:103]
	v_mfma_f32_16x16x32_bf16 v[96:99], v[162:165], v[186:189], v[96:99]
	v_mfma_f32_16x16x32_bf16 v[84:87], v[154:157], v[194:197], v[84:87]
	v_mfma_f32_16x16x32_bf16 v[80:83], v[162:165], v[194:197], v[80:83]
	v_mfma_f32_16x16x32_bf16 v[124:127], v[158:161], v[174:177], v[124:127]
	v_mfma_f32_16x16x32_bf16 v[120:123], v[166:169], v[174:177], v[120:123]
	v_mfma_f32_16x16x32_bf16 v[116:119], v[158:161], v[182:185], v[116:119]
	v_mfma_f32_16x16x32_bf16 v[112:115], v[166:169], v[182:185], v[112:115]
	v_mfma_f32_16x16x32_bf16 v[100:103], v[158:161], v[190:193], v[100:103]
	v_mfma_f32_16x16x32_bf16 v[96:99], v[166:169], v[190:193], v[96:99]
	v_mfma_f32_16x16x32_bf16 v[84:87], v[158:161], v[198:201], v[84:87]
	v_mfma_f32_16x16x32_bf16 v[80:83], v[166:169], v[198:201], v[80:83]
	s_barrier
	s_add_i32 s28, 0, 0x1c000
	s_add_i32 s29, s87, s34
	v_add_u32_e32 v153, s28, v148
	v_lshl_add_u64 v[218:219], v[218:219], 0, s[8:9]
	s_mov_b32 m0, s29
	ds_read_b128 v[202:205], v153
	ds_read_b128 v[206:209], v153 offset:1024
	ds_read_b128 v[210:213], v153 offset:2048
	ds_read_b128 v[214:217], v153 offset:3072
	global_load_lds_dwordx4 v[218:219], off
	v_lshl_add_u64 v[218:219], v[220:221], 0, s[8:9]
	s_add_i32 m0, s29, 0x2000
	s_nop 0
	global_load_lds_dwordx4 v[218:219], off
	s_cmp_lg_u32 s94, 0
	s_cbranch_scc0 .Lrx1c
	s_waitcnt vmcnt(10)
	s_mov_b32 s94, 0
.Lrx1c:
	s_barrier
	s_waitcnt lgkmcnt(0)
	s_waitcnt lgkmcnt(0)
	v_mfma_f32_16x16x32_bf16 v[108:111], v[202:205], v[170:173], v[108:111]
	v_mfma_f32_16x16x32_bf16 v[104:107], v[210:213], v[170:173], v[104:107]
	v_mfma_f32_16x16x32_bf16 v[92:95], v[202:205], v[178:181], v[92:95]
	v_mfma_f32_16x16x32_bf16 v[88:91], v[210:213], v[178:181], v[88:91]
	v_mfma_f32_16x16x32_bf16 v[76:79], v[202:205], v[186:189], v[76:79]
	v_mfma_f32_16x16x32_bf16 v[72:75], v[210:213], v[186:189], v[72:75]
	v_mfma_f32_16x16x32_bf16 v[68:71], v[202:205], v[194:197], v[68:71]
	v_mfma_f32_16x16x32_bf16 v[64:67], v[210:213], v[194:197], v[64:67]
	v_mfma_f32_16x16x32_bf16 v[108:111], v[206:209], v[174:177], v[108:111]
	v_mfma_f32_16x16x32_bf16 v[104:107], v[214:217], v[174:177], v[104:107]
	v_mfma_f32_16x16x32_bf16 v[92:95], v[206:209], v[182:185], v[92:95]
	v_mfma_f32_16x16x32_bf16 v[88:91], v[214:217], v[182:185], v[88:91]
	v_mfma_f32_16x16x32_bf16 v[76:79], v[206:209], v[190:193], v[76:79]
	v_mfma_f32_16x16x32_bf16 v[72:75], v[214:217], v[190:193], v[72:75]
	v_mfma_f32_16x16x32_bf16 v[68:71], v[206:209], v[198:201], v[68:71]
	v_mfma_f32_16x16x32_bf16 v[64:67], v[214:217], v[198:201], v[64:67]
	s_mov_b32 m0, s57
	v_lshl_add_u64 v[218:219], v[222:223], 0, s[8:9]
	s_barrier
	ds_read_b128 v[170:173], v151 offset:49152
	ds_read_b128 v[174:177], v151 offset:50176
	ds_read_b128 v[178:181], v151 offset:51200
	ds_read_b128 v[182:185], v151 offset:52224
	ds_read_b128 v[186:189], v151 offset:53248
	ds_read_b128 v[190:193], v151 offset:54272
	ds_read_b128 v[194:197], v151 offset:55296
	ds_read_b128 v[198:201], v151 offset:56320
	global_load_lds_dwordx4 v[218:219], off
	v_lshl_add_u64 v[218:219], v[224:225], 0, s[8:9]
	s_mov_b32 m0, s70
	s_nop 0
	global_load_lds_dwordx4 v[218:219], off
	s_barrier
	s_waitcnt lgkmcnt(0)
	s_waitcnt lgkmcnt(0)
	v_mfma_f32_16x16x32_bf16 v[60:63], v[154:157], v[170:173], v[60:63]
	v_mfma_f32_16x16x32_bf16 v[56:59], v[162:165], v[170:173], v[56:59]
	v_mfma_f32_16x16x32_bf16 v[52:55], v[154:157], v[178:181], v[52:55]
	v_mfma_f32_16x16x32_bf16 v[48:51], v[162:165], v[178:181], v[48:51]
	v_mfma_f32_16x16x32_bf16 v[36:39], v[154:157], v[186:189], v[36:39]
	v_mfma_f32_16x16x32_bf16 v[32:35], v[162:165], v[186:189], v[32:35]
	v_mfma_f32_16x16x32_bf16 v[20:23], v[154:157], v[194:197], v[20:23]
	v_mfma_f32_16x16x32_bf16 v[16:19], v[162:165], v[194:197], v[16:19]
	v_mfma_f32_16x16x32_bf16 v[60:63], v[158:161], v[174:177], v[60:63]
	v_mfma_f32_16x16x32_bf16 v[56:59], v[166:169], v[174:177], v[56:59]
	v_mfma_f32_16x16x32_bf16 v[52:55], v[158:161], v[182:185], v[52:55]
	v_mfma_f32_16x16x32_bf16 v[48:51], v[166:169], v[182:185], v[48:51]
	v_mfma_f32_16x16x32_bf16 v[36:39], v[158:161], v[190:193], v[36:39]
	v_mfma_f32_16x16x32_bf16 v[32:35], v[166:169], v[190:193], v[32:35]
	v_mfma_f32_16x16x32_bf16 v[20:23], v[158:161], v[198:201], v[20:23]
	v_mfma_f32_16x16x32_bf16 v[16:19], v[166:169], v[198:201], v[16:19]
	s_barrier
	s_add_u32 s26, s26, 0x40080
	s_addc_u32 s27, s27, 0
	s_add_i32 s28, s28, s34
	v_lshl_add_u64 v[154:155], s[26:27], 0, v[134:135]
	s_mov_b32 m0, s28
	s_nop 0
	global_load_lds_dwordx4 v[154:155], off
	v_lshl_add_u64 v[154:155], s[26:27], 0, v[130:131]
	s_add_i32 m0, s28, 0x2000
	s_nop 0
	global_load_lds_dwordx4 v[154:155], off
	s_waitcnt vmcnt(6)
	s_barrier
	v_mfma_f32_16x16x32_bf16 v[44:47], v[202:205], v[170:173], v[44:47]
	v_mfma_f32_16x16x32_bf16 v[40:43], v[210:213], v[170:173], v[40:43]
	v_mfma_f32_16x16x32_bf16 v[28:31], v[202:205], v[178:181], v[28:31]
	v_mfma_f32_16x16x32_bf16 v[24:27], v[210:213], v[178:181], v[24:27]
	v_mfma_f32_16x16x32_bf16 v[12:15], v[202:205], v[186:189], v[12:15]
	v_mfma_f32_16x16x32_bf16 v[8:11], v[210:213], v[186:189], v[8:11]
	v_mfma_f32_16x16x32_bf16 v[4:7], v[202:205], v[194:197], v[4:7]
	v_mfma_f32_16x16x32_bf16 v[0:3], v[210:213], v[194:197], v[0:3]
	v_mfma_f32_16x16x32_bf16 v[44:47], v[206:209], v[174:177], v[44:47]
	v_mfma_f32_16x16x32_bf16 v[40:43], v[214:217], v[174:177], v[40:43]
	v_mfma_f32_16x16x32_bf16 v[28:31], v[206:209], v[182:185], v[28:31]
	v_mfma_f32_16x16x32_bf16 v[24:27], v[214:217], v[182:185], v[24:27]
	v_mfma_f32_16x16x32_bf16 v[12:15], v[206:209], v[190:193], v[12:15]
	v_mfma_f32_16x16x32_bf16 v[8:11], v[214:217], v[190:193], v[8:11]
	v_mfma_f32_16x16x32_bf16 v[4:7], v[206:209], v[198:201], v[4:7]
	v_mfma_f32_16x16x32_bf16 v[0:3], v[214:217], v[198:201], v[0:3]
	s_add_i32 s86, s86, 2
	s_add_u32 s20, s20, 0x100
	s_addc_u32 s21, s21, 0
	s_add_u32 s84, s84, 0x100
	s_addc_u32 s85, s85, 0
	s_cmp_gt_u32 s86, 13
	s_barrier
	s_cbranch_scc0 .LBB0_155
	v_lshl_add_u32 v153, s10, 8, v147
	v_lshl_or_b32 v154, s75, 8, v149
	v_mov_b64_e32 v[156:157], s[46:47]
	v_ashrrev_i32_e32 v155, 31, v154
	v_cvt_pk_bf16_f32 v68, v68, v69
	v_cvt_pk_bf16_f32 v69, v70, v71
	v_cvt_pk_bf16_f32 v70, v64, v65
	v_add_u32_e32 v64, 0x80, v153
	v_mad_i64_i32 v[158:159], s[20:21], v153, s74, v[156:157]
	v_cvt_pk_bf16_f32 v124, v124, v125
	v_cvt_pk_bf16_f32 v125, v126, v127
	v_cvt_pk_bf16_f32 v126, v120, v121
	v_lshlrev_b64 v[120:121], 1, v[154:155]
	v_mad_i64_i32 v[64:65], s[20:21], v64, s74, v[156:157]
	v_cvt_pk_bf16_f32 v127, v122, v123
	v_lshl_add_u64 v[122:123], v[158:159], 0, v[120:121]
	v_cvt_pk_bf16_f32 v108, v108, v109
	v_cvt_pk_bf16_f32 v109, v110, v111
	v_cvt_pk_bf16_f32 v110, v104, v105
	v_cvt_pk_bf16_f32 v111, v106, v107
	v_or_b32_e32 v104, 16, v153
	v_cvt_pk_bf16_f32 v60, v60, v61
	v_cvt_pk_bf16_f32 v61, v62, v63
	v_cvt_pk_bf16_f32 v62, v56, v57
	v_lshl_add_u64 v[56:57], v[64:65], 0, v[120:121]
	v_cvt_pk_bf16_f32 v44, v44, v45
	v_cvt_pk_bf16_f32 v45, v46, v47
	v_cvt_pk_bf16_f32 v46, v40, v41
	v_cvt_pk_bf16_f32 v47, v42, v43
	v_add_u32_e32 v40, 0x90, v153
	global_store_dwordx4 v[122:123], v[108:111], off offset:256
	global_store_dwordx4 v[56:57], v[44:47], off offset:256
	v_cvt_pk_bf16_f32 v92, v92, v93
	v_mad_i64_i32 v[108:109], s[20:21], v104, s74, v[156:157]
	v_mad_i64_i32 v[44:45], s[20:21], v40, s74, v[156:157]
	v_lshl_add_u64 v[108:109], v[108:109], 0, v[120:121]
	v_cvt_pk_bf16_f32 v93, v94, v95
	v_cvt_pk_bf16_f32 v94, v88, v89
	v_cvt_pk_bf16_f32 v95, v90, v91
	v_or_b32_e32 v88, 32, v153
	v_lshl_add_u64 v[44:45], v[44:45], 0, v[120:121]
	v_cvt_pk_bf16_f32 v28, v28, v29
	v_cvt_pk_bf16_f32 v29, v30, v31
	v_cvt_pk_bf16_f32 v30, v24, v25
	v_cvt_pk_bf16_f32 v31, v26, v27
	v_add_u32_e32 v24, 0xa0, v153
	global_store_dwordx4 v[108:109], v[92:95], off offset:256
	global_store_dwordx4 v[44:45], v[28:31], off offset:256
	v_cvt_pk_bf16_f32 v76, v76, v77
	v_mad_i64_i32 v[92:93], s[20:21], v88, s74, v[156:157]
	v_mad_i64_i32 v[28:29], s[20:21], v24, s74, v[156:157]
	v_lshl_add_u64 v[92:93], v[92:93], 0, v[120:121]
	v_cvt_pk_bf16_f32 v77, v78, v79
	v_cvt_pk_bf16_f32 v78, v72, v73
	v_cvt_pk_bf16_f32 v79, v74, v75
	v_or_b32_e32 v72, 48, v153
	v_lshl_add_u64 v[28:29], v[28:29], 0, v[120:121]
	v_cvt_pk_bf16_f32 v12, v12, v13
	v_cvt_pk_bf16_f32 v13, v14, v15
	v_cvt_pk_bf16_f32 v14, v8, v9
	v_cvt_pk_bf16_f32 v15, v10, v11
	v_add_u32_e32 v8, 0xb0, v153
	global_store_dwordx4 v[92:93], v[76:79], off offset:256
	global_store_dwordx4 v[28:29], v[12:15], off offset:256
	v_cvt_pk_bf16_f32 v104, v116, v117
	v_mad_i64_i32 v[76:77], s[20:21], v72, s74, v[156:157]
	v_mad_i64_i32 v[12:13], s[20:21], v8, s74, v[156:157]
	v_cvt_pk_bf16_f32 v105, v118, v119
	v_cvt_pk_bf16_f32 v106, v112, v113
	v_cvt_pk_bf16_f32 v107, v114, v115
	v_cvt_pk_bf16_f32 v88, v100, v101
	v_cvt_pk_bf16_f32 v89, v102, v103
	v_cvt_pk_bf16_f32 v90, v96, v97
	v_cvt_pk_bf16_f32 v91, v98, v99
	v_cvt_pk_bf16_f32 v72, v84, v85
	v_cvt_pk_bf16_f32 v73, v86, v87
	v_cvt_pk_bf16_f32 v74, v80, v81
	v_cvt_pk_bf16_f32 v75, v82, v83
	v_lshl_add_u64 v[76:77], v[76:77], 0, v[120:121]
	v_cvt_pk_bf16_f32 v71, v66, v67
	v_cvt_pk_bf16_f32 v63, v58, v59
	v_cvt_pk_bf16_f32 v40, v52, v53
	v_cvt_pk_bf16_f32 v41, v54, v55
	v_cvt_pk_bf16_f32 v42, v48, v49
	v_cvt_pk_bf16_f32 v43, v50, v51
	v_cvt_pk_bf16_f32 v24, v36, v37
	v_cvt_pk_bf16_f32 v25, v38, v39
	v_cvt_pk_bf16_f32 v26, v32, v33
	v_cvt_pk_bf16_f32 v27, v34, v35
	v_cvt_pk_bf16_f32 v8, v20, v21
	v_cvt_pk_bf16_f32 v9, v22, v23
	v_cvt_pk_bf16_f32 v10, v16, v17
	v_cvt_pk_bf16_f32 v11, v18, v19
	v_lshl_add_u64 v[12:13], v[12:13], 0, v[120:121]
	v_cvt_pk_bf16_f32 v4, v4, v5
	v_cvt_pk_bf16_f32 v5, v6, v7
	v_cvt_pk_bf16_f32 v6, v0, v1
	v_cvt_pk_bf16_f32 v7, v2, v3
	s_and_b64 vcc, exec, s[4:5]
	s_mov_b32 s75, s12
	s_mov_b32 s10, s14
	s_mov_b64 s[26:27], s[18:19]
	s_mov_b64 s[20:21], s[16:17]
	global_store_dwordx4 v[122:123], v[124:127], off
	global_store_dwordx4 v[108:109], v[104:107], off
	global_store_dwordx4 v[92:93], v[88:91], off
	global_store_dwordx4 v[76:77], v[72:75], off
	global_store_dwordx4 v[76:77], v[68:71], off offset:256
	global_store_dwordx4 v[56:57], v[60:63], off
	global_store_dwordx4 v[44:45], v[40:43], off
	global_store_dwordx4 v[28:29], v[24:27], off
	global_store_dwordx4 v[12:13], v[8:11], off
	global_store_dwordx4 v[12:13], v[4:7], off offset:256
	s_mov_b32 s94, 1
	s_cbranch_vccz .LBB0_152
	s_mov_b32 s94, 0
	s_waitcnt vmcnt(16)
	s_cmpk_gt_u32 s30, 0xff
	s_cbranch_scc1 .LBB0_159
	s_barrier

.LBB0_486:
	ds_read_b128 v[154:157], v151
	ds_read_b128 v[158:161], v151 offset:1024
	ds_read_b128 v[162:165], v151 offset:2048
	ds_read_b128 v[166:169], v151 offset:3072
	s_add_u32 s30, s28, 0xfffc0080
	s_addc_u32 s31, s29, -1
	s_cmp_eq_u32 s84, 12
	s_cselect_b32 s35, s19, s31
	s_cselect_b32 s34, s80, s30
	s_cselect_b32 s31, s17, s83
	s_cselect_b32 s30, s81, s82
	v_lshl_add_u64 v[202:203], s[28:29], 0, v[138:139]
	s_add_i32 m0, s15, 0xc000
	ds_read_b128 v[170:173], v152
	ds_read_b128 v[174:177], v152 offset:1024
	ds_read_b128 v[178:181], v152 offset:2048
	ds_read_b128 v[182:185], v152 offset:3072
	ds_read_b128 v[186:189], v152 offset:4096
	ds_read_b128 v[190:193], v152 offset:5120
	ds_read_b128 v[194:197], v152 offset:6144
	ds_read_b128 v[198:201], v152 offset:7168
	global_load_lds_dwordx4 v[202:203], off
	v_lshl_add_u64 v[202:203], s[28:29], 0, v[140:141]
	s_add_i32 m0, s15, 0xe000
	s_nop 0
	global_load_lds_dwordx4 v[202:203], off
	s_waitcnt lgkmcnt(8)
	s_barrier
	s_waitcnt lgkmcnt(0)
	s_waitcnt lgkmcnt(0)
	v_mfma_f32_16x16x32_bf16 v[124:127], v[154:157], v[170:173], v[124:127]
	v_mfma_f32_16x16x32_bf16 v[120:123], v[162:165], v[170:173], v[120:123]
	v_mfma_f32_16x16x32_bf16 v[116:119], v[154:157], v[178:181], v[116:119]
	v_mfma_f32_16x16x32_bf16 v[112:115], v[162:165], v[178:181], v[112:115]
	v_mfma_f32_16x16x32_bf16 v[100:103], v[154:157], v[186:189], v[100:103]
	v_mfma_f32_16x16x32_bf16 v[96:99], v[162:165], v[186:189], v[96:99]
	v_mfma_f32_16x16x32_bf16 v[84:87], v[154:157], v[194:197], v[84:87]
	v_mfma_f32_16x16x32_bf16 v[80:83], v[162:165], v[194:197], v[80:83]
	v_mfma_f32_16x16x32_bf16 v[124:127], v[158:161], v[174:177], v[124:127]
	v_mfma_f32_16x16x32_bf16 v[120:123], v[166:169], v[174:177], v[120:123]
	v_mfma_f32_16x16x32_bf16 v[116:119], v[158:161], v[182:185], v[116:119]
	v_mfma_f32_16x16x32_bf16 v[112:115], v[166:169], v[182:185], v[112:115]
	v_mfma_f32_16x16x32_bf16 v[100:103], v[158:161], v[190:193], v[100:103]
	v_mfma_f32_16x16x32_bf16 v[96:99], v[166:169], v[190:193], v[96:99]
	v_mfma_f32_16x16x32_bf16 v[84:87], v[158:161], v[198:201], v[84:87]
	v_mfma_f32_16x16x32_bf16 v[80:83], v[166:169], v[198:201], v[80:83]
	s_barrier
	s_add_i32 s85, s74, s55
	v_lshl_add_u64 v[218:219], s[30:31], 0, v[134:135]
	s_mov_b32 m0, s85
	ds_read_b128 v[202:205], v153
	ds_read_b128 v[206:209], v153 offset:1024
	ds_read_b128 v[210:213], v153 offset:2048
	ds_read_b128 v[214:217], v153 offset:3072
	global_load_lds_dwordx4 v[218:219], off
	v_lshl_add_u64 v[220:221], s[30:31], 0, v[130:131]
	s_add_i32 m0, s85, 0x2000
	s_nop 0
	global_load_lds_dwordx4 v[220:221], off
	s_barrier
	s_waitcnt lgkmcnt(0)
	s_waitcnt lgkmcnt(0)
	v_mfma_f32_16x16x32_bf16 v[108:111], v[202:205], v[170:173], v[108:111]
	v_mfma_f32_16x16x32_bf16 v[104:107], v[210:213], v[170:173], v[104:107]
	v_mfma_f32_16x16x32_bf16 v[92:95], v[202:205], v[178:181], v[92:95]
	v_mfma_f32_16x16x32_bf16 v[88:91], v[210:213], v[178:181], v[88:91]
	v_mfma_f32_16x16x32_bf16 v[76:79], v[202:205], v[186:189], v[76:79]
	v_mfma_f32_16x16x32_bf16 v[72:75], v[210:213], v[186:189], v[72:75]
	v_mfma_f32_16x16x32_bf16 v[68:71], v[202:205], v[194:197], v[68:71]
	v_mfma_f32_16x16x32_bf16 v[64:67], v[210:213], v[194:197], v[64:67]
	v_mfma_f32_16x16x32_bf16 v[108:111], v[206:209], v[174:177], v[108:111]
	v_mfma_f32_16x16x32_bf16 v[104:107], v[214:217], v[174:177], v[104:107]
	v_mfma_f32_16x16x32_bf16 v[92:95], v[206:209], v[182:185], v[92:95]
	v_mfma_f32_16x16x32_bf16 v[88:91], v[214:217], v[182:185], v[88:91]
	v_mfma_f32_16x16x32_bf16 v[76:79], v[206:209], v[190:193], v[76:79]
	v_mfma_f32_16x16x32_bf16 v[72:75], v[214:217], v[190:193], v[72:75]
	v_mfma_f32_16x16x32_bf16 v[68:71], v[206:209], v[198:201], v[68:71]
	v_mfma_f32_16x16x32_bf16 v[64:67], v[214:217], v[198:201], v[64:67]
	s_mov_b32 m0, s15
	v_lshl_add_u64 v[222:223], s[34:35], 0, v[136:137]
	s_barrier
	ds_read_b128 v[170:173], v152 offset:16384
	ds_read_b128 v[174:177], v152 offset:17408
	ds_read_b128 v[178:181], v152 offset:18432
	ds_read_b128 v[182:185], v152 offset:19456
	ds_read_b128 v[186:189], v152 offset:20480
	ds_read_b128 v[190:193], v152 offset:21504
	ds_read_b128 v[194:197], v152 offset:22528
	ds_read_b128 v[198:201], v152 offset:23552
	global_load_lds_dwordx4 v[222:223], off
	v_lshl_add_u64 v[224:225], s[34:35], 0, v[132:133]
	s_mov_b32 m0, s57
	s_nop 0
	global_load_lds_dwordx4 v[224:225], off
	s_barrier
	s_waitcnt lgkmcnt(0)
	s_waitcnt lgkmcnt(0)
	v_mfma_f32_16x16x32_bf16 v[60:63], v[154:157], v[170:173], v[60:63]
	v_mfma_f32_16x16x32_bf16 v[56:59], v[162:165], v[170:173], v[56:59]
	v_mfma_f32_16x16x32_bf16 v[52:55], v[154:157], v[178:181], v[52:55]
	v_mfma_f32_16x16x32_bf16 v[48:51], v[162:165], v[178:181], v[48:51]
	v_mfma_f32_16x16x32_bf16 v[36:39], v[154:157], v[186:189], v[36:39]
	v_mfma_f32_16x16x32_bf16 v[32:35], v[162:165], v[186:189], v[32:35]
	v_mfma_f32_16x16x32_bf16 v[20:23], v[154:157], v[194:197], v[20:23]
	v_mfma_f32_16x16x32_bf16 v[16:19], v[162:165], v[194:197], v[16:19]
	v_mfma_f32_16x16x32_bf16 v[60:63], v[158:161], v[174:177], v[60:63]
	v_mfma_f32_16x16x32_bf16 v[56:59], v[166:169], v[174:177], v[56:59]
	v_mfma_f32_16x16x32_bf16 v[52:55], v[158:161], v[182:185], v[52:55]
	v_mfma_f32_16x16x32_bf16 v[48:51], v[166:169], v[182:185], v[48:51]
	v_mfma_f32_16x16x32_bf16 v[36:39], v[158:161], v[190:193], v[36:39]
	v_mfma_f32_16x16x32_bf16 v[32:35], v[166:169], v[190:193], v[32:35]
	v_mfma_f32_16x16x32_bf16 v[20:23], v[158:161], v[198:201], v[20:23]
	v_mfma_f32_16x16x32_bf16 v[16:19], v[166:169], v[198:201], v[16:19]
	s_barrier
	s_add_u32 s86, s30, 0x40000
	s_addc_u32 s87, s31, 0
	s_add_i32 s85, s75, s55
	v_lshl_add_u64 v[154:155], s[86:87], 0, v[134:135]
	s_mov_b32 m0, s85
	s_nop 0
	global_load_lds_dwordx4 v[154:155], off
	v_lshl_add_u64 v[154:155], s[86:87], 0, v[130:131]
	s_add_i32 m0, s85, 0x2000
	s_nop 0
	global_load_lds_dwordx4 v[154:155], off
	s_cmp_lg_u32 s94, 0
	s_cbranch_scc1 .Lrx2a
	s_waitcnt vmcnt(6)
.Lrx2a:
	s_waitcnt vmcnt(24)
	s_barrier
	v_mfma_f32_16x16x32_bf16 v[44:47], v[202:205], v[170:173], v[44:47]
	v_mfma_f32_16x16x32_bf16 v[40:43], v[210:213], v[170:173], v[40:43]
	v_mfma_f32_16x16x32_bf16 v[28:31], v[202:205], v[178:181], v[28:31]
	v_mfma_f32_16x16x32_bf16 v[24:27], v[210:213], v[178:181], v[24:27]
	v_mfma_f32_16x16x32_bf16 v[12:15], v[202:205], v[186:189], v[12:15]
	v_mfma_f32_16x16x32_bf16 v[8:11], v[210:213], v[186:189], v[8:11]
	v_mfma_f32_16x16x32_bf16 v[4:7], v[202:205], v[194:197], v[4:7]
	v_mfma_f32_16x16x32_bf16 v[0:3], v[210:213], v[194:197], v[0:3]
	v_mfma_f32_16x16x32_bf16 v[44:47], v[206:209], v[174:177], v[44:47]
	v_mfma_f32_16x16x32_bf16 v[40:43], v[214:217], v[174:177], v[40:43]
	v_mfma_f32_16x16x32_bf16 v[28:31], v[206:209], v[182:185], v[28:31]
	v_mfma_f32_16x16x32_bf16 v[24:27], v[214:217], v[182:185], v[24:27]
	v_mfma_f32_16x16x32_bf16 v[12:15], v[206:209], v[190:193], v[12:15]
	v_mfma_f32_16x16x32_bf16 v[8:11], v[214:217], v[190:193], v[8:11]
	v_mfma_f32_16x16x32_bf16 v[4:7], v[206:209], v[198:201], v[4:7]
	v_mfma_f32_16x16x32_bf16 v[0:3], v[214:217], v[198:201], v[0:3]
	s_add_i32 s85, 0, 0x18000
	v_add_u32_e32 v166, s85, v149
	s_barrier
	ds_read_b128 v[154:157], v166
	ds_read_b128 v[158:161], v166 offset:1024
	ds_read_b128 v[162:165], v166 offset:2048
	ds_read_b128 v[166:169], v166 offset:3072
	s_add_u32 s34, s34, 0x40000
	s_addc_u32 s35, s35, 0
	s_mov_b32 m0, s60
	v_lshl_add_u64 v[202:203], s[34:35], 0, v[136:137]
	ds_read_b128 v[170:173], v152 offset:32768
	ds_read_b128 v[174:177], v152 offset:33792
	ds_read_b128 v[178:181], v152 offset:34816
	ds_read_b128 v[182:185], v152 offset:35840
	ds_read_b128 v[186:189], v152 offset:36864
	ds_read_b128 v[190:193], v152 offset:37888
	ds_read_b128 v[194:197], v152 offset:38912
	ds_read_b128 v[198:201], v152 offset:39936
	global_load_lds_dwordx4 v[202:203], off
	v_lshl_add_u64 v[202:203], s[34:35], 0, v[132:133]
	s_mov_b32 m0, s61
	s_nop 0
	global_load_lds_dwordx4 v[202:203], off
	s_waitcnt lgkmcnt(8)
	s_barrier
	s_waitcnt lgkmcnt(0)
	s_waitcnt lgkmcnt(0)
	v_mfma_f32_16x16x32_bf16 v[124:127], v[154:157], v[170:173], v[124:127]
	v_mfma_f32_16x16x32_bf16 v[120:123], v[162:165], v[170:173], v[120:123]
	v_mfma_f32_16x16x32_bf16 v[116:119], v[154:157], v[178:181], v[116:119]
	v_mfma_f32_16x16x32_bf16 v[112:115], v[162:165], v[178:181], v[112:115]
	v_mfma_f32_16x16x32_bf16 v[100:103], v[154:157], v[186:189], v[100:103]
	v_mfma_f32_16x16x32_bf16 v[96:99], v[162:165], v[186:189], v[96:99]
	v_mfma_f32_16x16x32_bf16 v[84:87], v[154:157], v[194:197], v[84:87]
	v_mfma_f32_16x16x32_bf16 v[80:83], v[162:165], v[194:197], v[80:83]
	v_mfma_f32_16x16x32_bf16 v[124:127], v[158:161], v[174:177], v[124:127]
	v_mfma_f32_16x16x32_bf16 v[120:123], v[166:169], v[174:177], v[120:123]
	v_mfma_f32_16x16x32_bf16 v[116:119], v[158:161], v[182:185], v[116:119]
	v_mfma_f32_16x16x32_bf16 v[112:115], v[166:169], v[182:185], v[112:115]
	v_mfma_f32_16x16x32_bf16 v[100:103], v[158:161], v[190:193], v[100:103]
	v_mfma_f32_16x16x32_bf16 v[96:99], v[166:169], v[190:193], v[96:99]
	v_mfma_f32_16x16x32_bf16 v[84:87], v[158:161], v[198:201], v[84:87]
	v_mfma_f32_16x16x32_bf16 v[80:83], v[166:169], v[198:201], v[80:83]
	s_barrier
	s_add_i32 s34, 0, 0x1c000
	s_add_i32 s35, s85, s55
	v_add_u32_e32 v214, s34, v149
	v_lshl_add_u64 v[218:219], v[218:219], 0, s[8:9]
	s_mov_b32 m0, s35
	ds_read_b128 v[202:205], v214
	ds_read_b128 v[206:209], v214 offset:1024
	ds_read_b128 v[210:213], v214 offset:2048
	ds_read_b128 v[214:217], v214 offset:3072
	global_load_lds_dwordx4 v[218:219], off
	v_lshl_add_u64 v[218:219], v[220:221], 0, s[8:9]
	s_add_i32 m0, s35, 0x2000
	s_nop 0
	global_load_lds_dwordx4 v[218:219], off
	s_cmp_lg_u32 s94, 0
	s_cbranch_scc0 .Lrx2c
	s_waitcnt vmcnt(10)
	s_mov_b32 s94, 0
.Lrx2c:
	s_barrier
	s_waitcnt lgkmcnt(0)
	s_waitcnt lgkmcnt(0)
	v_mfma_f32_16x16x32_bf16 v[108:111], v[202:205], v[170:173], v[108:111]
	v_mfma_f32_16x16x32_bf16 v[104:107], v[210:213], v[170:173], v[104:107]
	v_mfma_f32_16x16x32_bf16 v[92:95], v[202:205], v[178:181], v[92:95]
	v_mfma_f32_16x16x32_bf16 v[88:91], v[210:213], v[178:181], v[88:91]
	v_mfma_f32_16x16x32_bf16 v[76:79], v[202:205], v[186:189], v[76:79]
	v_mfma_f32_16x16x32_bf16 v[72:75], v[210:213], v[186:189], v[72:75]
	v_mfma_f32_16x16x32_bf16 v[68:71], v[202:205], v[194:197], v[68:71]
	v_mfma_f32_16x16x32_bf16 v[64:67], v[210:213], v[194:197], v[64:67]
	v_mfma_f32_16x16x32_bf16 v[108:111], v[206:209], v[174:177], v[108:111]
	v_mfma_f32_16x16x32_bf16 v[104:107], v[214:217], v[174:177], v[104:107]
	v_mfma_f32_16x16x32_bf16 v[92:95], v[206:209], v[182:185], v[92:95]
	v_mfma_f32_16x16x32_bf16 v[88:91], v[214:217], v[182:185], v[88:91]
	v_mfma_f32_16x16x32_bf16 v[76:79], v[206:209], v[190:193], v[76:79]
	v_mfma_f32_16x16x32_bf16 v[72:75], v[214:217], v[190:193], v[72:75]
	v_mfma_f32_16x16x32_bf16 v[68:71], v[206:209], v[198:201], v[68:71]
	v_mfma_f32_16x16x32_bf16 v[64:67], v[214:217], v[198:201], v[64:67]
	s_mov_b32 m0, s71
	v_lshl_add_u64 v[218:219], v[222:223], 0, s[8:9]
	s_barrier
	ds_read_b128 v[170:173], v152 offset:49152
	ds_read_b128 v[174:177], v152 offset:50176
	ds_read_b128 v[178:181], v152 offset:51200
	ds_read_b128 v[182:185], v152 offset:52224
	ds_read_b128 v[186:189], v152 offset:53248
	ds_read_b128 v[190:193], v152 offset:54272
	ds_read_b128 v[194:197], v152 offset:55296
	ds_read_b128 v[198:201], v152 offset:56320
	global_load_lds_dwordx4 v[218:219], off
	v_lshl_add_u64 v[218:219], v[224:225], 0, s[8:9]
	s_mov_b32 m0, s72
	s_nop 0
	global_load_lds_dwordx4 v[218:219], off
	s_barrier
	s_waitcnt lgkmcnt(0)
	s_waitcnt lgkmcnt(0)
	v_mfma_f32_16x16x32_bf16 v[60:63], v[154:157], v[170:173], v[60:63]
	v_mfma_f32_16x16x32_bf16 v[56:59], v[162:165], v[170:173], v[56:59]
	v_mfma_f32_16x16x32_bf16 v[52:55], v[154:157], v[178:181], v[52:55]
	v_mfma_f32_16x16x32_bf16 v[48:51], v[162:165], v[178:181], v[48:51]
	v_mfma_f32_16x16x32_bf16 v[36:39], v[154:157], v[186:189], v[36:39]
	v_mfma_f32_16x16x32_bf16 v[32:35], v[162:165], v[186:189], v[32:35]
	v_mfma_f32_16x16x32_bf16 v[20:23], v[154:157], v[194:197], v[20:23]
	v_mfma_f32_16x16x32_bf16 v[16:19], v[162:165], v[194:197], v[16:19]
	v_mfma_f32_16x16x32_bf16 v[60:63], v[158:161], v[174:177], v[60:63]
	v_mfma_f32_16x16x32_bf16 v[56:59], v[166:169], v[174:177], v[56:59]
	v_mfma_f32_16x16x32_bf16 v[52:55], v[158:161], v[182:185], v[52:55]
	v_mfma_f32_16x16x32_bf16 v[48:51], v[166:169], v[182:185], v[48:51]
	v_mfma_f32_16x16x32_bf16 v[36:39], v[158:161], v[190:193], v[36:39]
	v_mfma_f32_16x16x32_bf16 v[32:35], v[166:169], v[190:193], v[32:35]
	v_mfma_f32_16x16x32_bf16 v[20:23], v[158:161], v[198:201], v[20:23]
	v_mfma_f32_16x16x32_bf16 v[16:19], v[166:169], v[198:201], v[16:19]
	s_barrier
	s_add_u32 s30, s30, 0x40080
	s_addc_u32 s31, s31, 0
	s_add_i32 s34, s34, s55
	v_lshl_add_u64 v[154:155], s[30:31], 0, v[134:135]
	s_mov_b32 m0, s34
	s_nop 0
	global_load_lds_dwordx4 v[154:155], off
	v_lshl_add_u64 v[154:155], s[30:31], 0, v[130:131]
	s_add_i32 m0, s34, 0x2000
	s_nop 0
	global_load_lds_dwordx4 v[154:155], off
	s_waitcnt vmcnt(6)
	s_barrier
	v_mfma_f32_16x16x32_bf16 v[44:47], v[202:205], v[170:173], v[44:47]
	v_mfma_f32_16x16x32_bf16 v[40:43], v[210:213], v[170:173], v[40:43]
	v_mfma_f32_16x16x32_bf16 v[28:31], v[202:205], v[178:181], v[28:31]
	v_mfma_f32_16x16x32_bf16 v[24:27], v[210:213], v[178:181], v[24:27]
	v_mfma_f32_16x16x32_bf16 v[12:15], v[202:205], v[186:189], v[12:15]
	v_mfma_f32_16x16x32_bf16 v[8:11], v[210:213], v[186:189], v[8:11]
	v_mfma_f32_16x16x32_bf16 v[4:7], v[202:205], v[194:197], v[4:7]
	v_mfma_f32_16x16x32_bf16 v[0:3], v[210:213], v[194:197], v[0:3]
	v_mfma_f32_16x16x32_bf16 v[44:47], v[206:209], v[174:177], v[44:47]
	v_mfma_f32_16x16x32_bf16 v[40:43], v[214:217], v[174:177], v[40:43]
	v_mfma_f32_16x16x32_bf16 v[28:31], v[206:209], v[182:185], v[28:31]
	v_mfma_f32_16x16x32_bf16 v[24:27], v[214:217], v[182:185], v[24:27]
	v_mfma_f32_16x16x32_bf16 v[12:15], v[206:209], v[190:193], v[12:15]
	v_mfma_f32_16x16x32_bf16 v[8:11], v[214:217], v[190:193], v[8:11]
	v_mfma_f32_16x16x32_bf16 v[4:7], v[206:209], v[198:201], v[4:7]
	v_mfma_f32_16x16x32_bf16 v[0:3], v[214:217], v[198:201], v[0:3]
	s_add_i32 s84, s84, 2
	s_add_u32 s28, s28, 0x100
	s_addc_u32 s29, s29, 0
	s_add_u32 s82, s82, 0x100
	s_addc_u32 s83, s83, 0
	s_cmp_gt_u32 s84, 13
	s_barrier
	s_cbranch_scc0 .LBB0_486
	v_lshl_add_u32 v154, s14, 8, v148
	v_lshl_or_b32 v156, s79, 8, v150
	v_ashrrev_i32_e32 v155, 31, v154
	v_lshlrev_b64 v[158:159], 11, v[154:155]
	v_ashrrev_i32_e32 v157, 31, v156
	v_lshl_add_u64 v[158:159], s[46:47], 0, v[158:159]
	v_cvt_pk_bf16_f32 v124, v124, v125
	v_cvt_pk_bf16_f32 v125, v126, v127
	v_cvt_pk_bf16_f32 v126, v120, v121
	v_lshlrev_b64 v[120:121], 1, v[156:157]
	v_cvt_pk_bf16_f32 v127, v122, v123
	v_lshl_add_u64 v[122:123], v[158:159], 0, v[120:121]
	s_mov_b32 s14, 0x40000
	v_cvt_pk_bf16_f32 v108, v108, v109
	v_cvt_pk_bf16_f32 v109, v110, v111
	v_cvt_pk_bf16_f32 v110, v104, v105
	v_or_b32_e32 v104, 16, v154
	v_cvt_pk_bf16_f32 v60, v60, v61
	v_cvt_pk_bf16_f32 v61, v62, v63
	v_cvt_pk_bf16_f32 v63, v58, v59
	s_mov_b64 s[28:29], 0x40000
	v_add_co_u32_e32 v58, vcc, s14, v122
	v_ashrrev_i32_e32 v105, 31, v104
	v_cvt_pk_bf16_f32 v62, v56, v57
	v_lshl_add_u64 v[56:57], v[122:123], 0, s[28:29]
	v_addc_co_u32_e32 v59, vcc, 0, v123, vcc
	v_cvt_pk_bf16_f32 v44, v44, v45
	v_cvt_pk_bf16_f32 v45, v46, v47
	v_cvt_pk_bf16_f32 v46, v40, v41
	v_cvt_pk_bf16_f32 v47, v42, v43
	v_cvt_pk_bf16_f32 v111, v106, v107
	v_lshlrev_b64 v[104:105], 11, v[104:105]
	v_cvt_pk_bf16_f32 v92, v92, v93
	v_cvt_pk_bf16_f32 v93, v94, v95
	v_cvt_pk_bf16_f32 v94, v88, v89
	v_or_b32_e32 v88, 32, v154
	global_store_dwordx4 v[56:57], v[44:47], off offset:256
	s_mov_b64 s[28:29], 0x48000
	global_store_dwordx4 v[122:123], v[108:111], off offset:256
	v_add_co_u32_e32 v46, vcc, s76, v122
	s_nop 0
	v_lshl_add_u64 v[108:109], s[46:47], 0, v[104:105]
	v_ashrrev_i32_e32 v89, 31, v88
	v_lshl_add_u64 v[44:45], v[122:123], 0, s[28:29]
	v_addc_co_u32_e32 v47, vcc, 0, v123, vcc
	v_cvt_pk_bf16_f32 v28, v28, v29
	v_cvt_pk_bf16_f32 v29, v30, v31
	v_cvt_pk_bf16_f32 v30, v24, v25
	v_cvt_pk_bf16_f32 v31, v26, v27
	v_lshl_add_u64 v[108:109], v[108:109], 0, v[120:121]
	v_cvt_pk_bf16_f32 v95, v90, v91
	v_lshlrev_b64 v[88:89], 11, v[88:89]
	v_cvt_pk_bf16_f32 v76, v76, v77
	v_cvt_pk_bf16_f32 v77, v78, v79
	v_cvt_pk_bf16_f32 v78, v72, v73
	v_or_b32_e32 v72, 48, v154
	global_store_dwordx4 v[44:45], v[28:31], off offset:256
	global_store_dwordx4 v[108:109], v[92:95], off offset:256
	v_ashrrev_i32_e32 v73, 31, v72
	v_add_co_u32_e32 v30, vcc, s77, v122
	v_lshl_add_u64 v[92:93], s[46:47], 0, v[88:89]
	v_lshl_add_u64 v[28:29], v[122:123], 0, s[10:11]
	v_addc_co_u32_e32 v31, vcc, 0, v123, vcc
	v_cvt_pk_bf16_f32 v12, v12, v13
	v_cvt_pk_bf16_f32 v13, v14, v15
	v_cvt_pk_bf16_f32 v14, v8, v9
	v_cvt_pk_bf16_f32 v15, v10, v11
	v_lshl_add_u64 v[92:93], v[92:93], 0, v[120:121]
	v_cvt_pk_bf16_f32 v79, v74, v75
	v_lshlrev_b64 v[72:73], 11, v[72:73]
	global_store_dwordx4 v[28:29], v[12:15], off offset:256
	global_store_dwordx4 v[92:93], v[76:79], off offset:256
	v_cvt_pk_bf16_f32 v104, v116, v117
	v_add_co_u32_e32 v14, vcc, s78, v122
	v_lshl_add_u64 v[76:77], s[46:47], 0, v[72:73]
	s_nop 0
	v_addc_co_u32_e32 v15, vcc, 0, v123, vcc
	v_cvt_pk_bf16_f32 v105, v118, v119
	v_cvt_pk_bf16_f32 v106, v112, v113
	v_cvt_pk_bf16_f32 v107, v114, v115
	v_cvt_pk_bf16_f32 v88, v100, v101
	v_cvt_pk_bf16_f32 v89, v102, v103
	v_cvt_pk_bf16_f32 v90, v96, v97
	v_cvt_pk_bf16_f32 v91, v98, v99
	v_cvt_pk_bf16_f32 v72, v84, v85
	v_cvt_pk_bf16_f32 v73, v86, v87
	v_cvt_pk_bf16_f32 v74, v80, v81
	v_cvt_pk_bf16_f32 v75, v82, v83
	v_lshl_add_u64 v[76:77], v[76:77], 0, v[120:121]
	v_cvt_pk_bf16_f32 v68, v68, v69
	v_cvt_pk_bf16_f32 v69, v70, v71
	v_cvt_pk_bf16_f32 v70, v64, v65
	v_cvt_pk_bf16_f32 v71, v66, v67
	v_cvt_pk_bf16_f32 v40, v52, v53
	v_cvt_pk_bf16_f32 v41, v54, v55
	v_cvt_pk_bf16_f32 v42, v48, v49
	v_cvt_pk_bf16_f32 v43, v50, v51
	v_cvt_pk_bf16_f32 v24, v36, v37
	v_cvt_pk_bf16_f32 v25, v38, v39
	v_cvt_pk_bf16_f32 v26, v32, v33
	v_cvt_pk_bf16_f32 v27, v34, v35
	v_cvt_pk_bf16_f32 v8, v20, v21
	v_cvt_pk_bf16_f32 v9, v22, v23
	v_cvt_pk_bf16_f32 v10, v16, v17
	v_cvt_pk_bf16_f32 v11, v18, v19
	v_lshl_add_u64 v[12:13], v[122:123], 0, s[12:13]
	v_cvt_pk_bf16_f32 v4, v4, v5
	v_cvt_pk_bf16_f32 v5, v6, v7
	v_cvt_pk_bf16_f32 v6, v0, v1
	v_cvt_pk_bf16_f32 v7, v2, v3
	s_and_b64 vcc, exec, s[4:5]
	s_mov_b32 s79, s16
	s_mov_b32 s14, s18
	s_mov_b64 s[30:31], s[26:27]
	s_mov_b64 s[28:29], s[20:21]
	global_store_dwordx4 v[122:123], v[124:127], off
	global_store_dwordx4 v[108:109], v[104:107], off
	global_store_dwordx4 v[92:93], v[88:91], off
	global_store_dwordx4 v[76:77], v[72:75], off
	global_store_dwordx4 v[76:77], v[68:71], off offset:256
	global_store_dwordx4 v[58:59], v[60:63], off
	global_store_dwordx4 v[46:47], v[40:43], off
	global_store_dwordx4 v[30:31], v[24:27], off
	global_store_dwordx4 v[14:15], v[8:11], off
	global_store_dwordx4 v[12:13], v[4:7], off offset:256
	s_mov_b32 s94, 1
	s_cbranch_vccz .LBB0_483
	s_mov_b32 s94, 0
	s_waitcnt vmcnt(16)
	s_cmpk_gt_u32 s54, 0xff
	s_cbranch_scc1 .LBB0_490
	s_barrier

.LBB0_683:
	ds_read_b128 v[154:157], v151
	ds_read_b128 v[158:161], v151 offset:1024
	ds_read_b128 v[162:165], v151 offset:2048
	ds_read_b128 v[166:169], v151 offset:3072
	s_add_u32 s34, s30, 0xfffc0080
	s_addc_u32 s35, s31, -1
	s_cmp_eq_u32 s85, 12
	s_cselect_b32 s55, s19, s35
	s_cselect_b32 s54, s81, s34
	s_cselect_b32 s35, s17, s84
	s_cselect_b32 s34, s82, s83
	v_lshl_add_u64 v[202:203], s[30:31], 0, v[138:139]
	s_add_i32 m0, s29, 0xc000
	ds_read_b128 v[170:173], v152
	ds_read_b128 v[174:177], v152 offset:1024
	ds_read_b128 v[178:181], v152 offset:2048
	ds_read_b128 v[182:185], v152 offset:3072
	ds_read_b128 v[186:189], v152 offset:4096
	ds_read_b128 v[190:193], v152 offset:5120
	ds_read_b128 v[194:197], v152 offset:6144
	ds_read_b128 v[198:201], v152 offset:7168
	global_load_lds_dwordx4 v[202:203], off
	v_lshl_add_u64 v[202:203], s[30:31], 0, v[140:141]
	s_add_i32 m0, s29, 0xe000
	s_nop 0
	global_load_lds_dwordx4 v[202:203], off
	s_waitcnt lgkmcnt(8)
	s_barrier
	s_waitcnt lgkmcnt(0)
	s_waitcnt lgkmcnt(0)
	v_mfma_f32_16x16x32_bf16 v[124:127], v[154:157], v[170:173], v[124:127]
	v_mfma_f32_16x16x32_bf16 v[120:123], v[162:165], v[170:173], v[120:123]
	v_mfma_f32_16x16x32_bf16 v[108:111], v[154:157], v[178:181], v[108:111]
	v_mfma_f32_16x16x32_bf16 v[104:107], v[162:165], v[178:181], v[104:107]
	v_mfma_f32_16x16x32_bf16 v[92:95], v[154:157], v[186:189], v[92:95]
	v_mfma_f32_16x16x32_bf16 v[88:91], v[162:165], v[186:189], v[88:91]
	v_mfma_f32_16x16x32_bf16 v[76:79], v[154:157], v[194:197], v[76:79]
	v_mfma_f32_16x16x32_bf16 v[72:75], v[162:165], v[194:197], v[72:75]
	v_mfma_f32_16x16x32_bf16 v[124:127], v[158:161], v[174:177], v[124:127]
	v_mfma_f32_16x16x32_bf16 v[120:123], v[166:169], v[174:177], v[120:123]
	v_mfma_f32_16x16x32_bf16 v[108:111], v[158:161], v[182:185], v[108:111]
	v_mfma_f32_16x16x32_bf16 v[104:107], v[166:169], v[182:185], v[104:107]
	v_mfma_f32_16x16x32_bf16 v[92:95], v[158:161], v[190:193], v[92:95]
	v_mfma_f32_16x16x32_bf16 v[88:91], v[166:169], v[190:193], v[88:91]
	v_mfma_f32_16x16x32_bf16 v[76:79], v[158:161], v[198:201], v[76:79]
	v_mfma_f32_16x16x32_bf16 v[72:75], v[166:169], v[198:201], v[72:75]
	s_barrier
	s_add_i32 s86, s74, s60
	v_lshl_add_u64 v[218:219], s[34:35], 0, v[132:133]
	s_mov_b32 m0, s86
	ds_read_b128 v[202:205], v153
	ds_read_b128 v[206:209], v153 offset:1024
	ds_read_b128 v[210:213], v153 offset:2048
	ds_read_b128 v[214:217], v153 offset:3072
	global_load_lds_dwordx4 v[218:219], off
	v_lshl_add_u64 v[220:221], s[34:35], 0, v[136:137]
	s_add_i32 m0, s86, 0x2000
	s_nop 0
	global_load_lds_dwordx4 v[220:221], off
	s_barrier
	s_waitcnt lgkmcnt(0)
	s_waitcnt lgkmcnt(0)
	v_mfma_f32_16x16x32_bf16 v[116:119], v[202:205], v[170:173], v[116:119]
	v_mfma_f32_16x16x32_bf16 v[112:115], v[210:213], v[170:173], v[112:115]
	v_mfma_f32_16x16x32_bf16 v[100:103], v[202:205], v[178:181], v[100:103]
	v_mfma_f32_16x16x32_bf16 v[96:99], v[210:213], v[178:181], v[96:99]
	v_mfma_f32_16x16x32_bf16 v[84:87], v[202:205], v[186:189], v[84:87]
	v_mfma_f32_16x16x32_bf16 v[80:83], v[210:213], v[186:189], v[80:83]
	v_mfma_f32_16x16x32_bf16 v[68:71], v[202:205], v[194:197], v[68:71]
	v_mfma_f32_16x16x32_bf16 v[64:67], v[210:213], v[194:197], v[64:67]
	v_mfma_f32_16x16x32_bf16 v[116:119], v[206:209], v[174:177], v[116:119]
	v_mfma_f32_16x16x32_bf16 v[112:115], v[214:217], v[174:177], v[112:115]
	v_mfma_f32_16x16x32_bf16 v[100:103], v[206:209], v[182:185], v[100:103]
	v_mfma_f32_16x16x32_bf16 v[96:99], v[214:217], v[182:185], v[96:99]
	v_mfma_f32_16x16x32_bf16 v[84:87], v[206:209], v[190:193], v[84:87]
	v_mfma_f32_16x16x32_bf16 v[80:83], v[214:217], v[190:193], v[80:83]
	v_mfma_f32_16x16x32_bf16 v[68:71], v[206:209], v[198:201], v[68:71]
	v_mfma_f32_16x16x32_bf16 v[64:67], v[214:217], v[198:201], v[64:67]
	s_mov_b32 m0, s29
	v_lshl_add_u64 v[222:223], s[54:55], 0, v[130:131]
	s_barrier
	ds_read_b128 v[170:173], v152 offset:16384
	ds_read_b128 v[174:177], v152 offset:17408
	ds_read_b128 v[178:181], v152 offset:18432
	ds_read_b128 v[182:185], v152 offset:19456
	ds_read_b128 v[186:189], v152 offset:20480
	ds_read_b128 v[190:193], v152 offset:21504
	ds_read_b128 v[194:197], v152 offset:22528
	ds_read_b128 v[198:201], v152 offset:23552
	global_load_lds_dwordx4 v[222:223], off
	v_lshl_add_u64 v[224:225], s[54:55], 0, v[134:135]
	s_mov_b32 m0, s61
	s_nop 0
	global_load_lds_dwordx4 v[224:225], off
	s_barrier
	s_waitcnt lgkmcnt(0)
	s_waitcnt lgkmcnt(0)
	v_mfma_f32_16x16x32_bf16 v[60:63], v[154:157], v[170:173], v[60:63]
	v_mfma_f32_16x16x32_bf16 v[56:59], v[162:165], v[170:173], v[56:59]
	v_mfma_f32_16x16x32_bf16 v[44:47], v[154:157], v[178:181], v[44:47]
	v_mfma_f32_16x16x32_bf16 v[40:43], v[162:165], v[178:181], v[40:43]
	v_mfma_f32_16x16x32_bf16 v[28:31], v[154:157], v[186:189], v[28:31]
	v_mfma_f32_16x16x32_bf16 v[24:27], v[162:165], v[186:189], v[24:27]
	v_mfma_f32_16x16x32_bf16 v[12:15], v[154:157], v[194:197], v[12:15]
	v_mfma_f32_16x16x32_bf16 v[8:11], v[162:165], v[194:197], v[8:11]
	v_mfma_f32_16x16x32_bf16 v[60:63], v[158:161], v[174:177], v[60:63]
	v_mfma_f32_16x16x32_bf16 v[56:59], v[166:169], v[174:177], v[56:59]
	v_mfma_f32_16x16x32_bf16 v[44:47], v[158:161], v[182:185], v[44:47]
	v_mfma_f32_16x16x32_bf16 v[40:43], v[166:169], v[182:185], v[40:43]
	v_mfma_f32_16x16x32_bf16 v[28:31], v[158:161], v[190:193], v[28:31]
	v_mfma_f32_16x16x32_bf16 v[24:27], v[166:169], v[190:193], v[24:27]
	v_mfma_f32_16x16x32_bf16 v[12:15], v[158:161], v[198:201], v[12:15]
	v_mfma_f32_16x16x32_bf16 v[8:11], v[166:169], v[198:201], v[8:11]
	s_barrier
	s_add_u32 s86, s34, 0x40000
	s_addc_u32 s87, s35, 0
	s_add_i32 s88, s75, s60
	v_lshl_add_u64 v[154:155], s[86:87], 0, v[132:133]
	s_mov_b32 m0, s88
	s_nop 0
	global_load_lds_dwordx4 v[154:155], off
	v_lshl_add_u64 v[154:155], s[86:87], 0, v[136:137]
	s_add_i32 m0, s88, 0x2000
	s_nop 0
	global_load_lds_dwordx4 v[154:155], off
	s_cmp_lg_u32 s94, 0
	s_cbranch_scc1 .Lrx3a
	s_waitcnt vmcnt(6)
.Lrx3a:
	s_waitcnt vmcnt(24)
	s_barrier
	v_mfma_f32_16x16x32_bf16 v[52:55], v[202:205], v[170:173], v[52:55]
	v_mfma_f32_16x16x32_bf16 v[48:51], v[210:213], v[170:173], v[48:51]
	v_mfma_f32_16x16x32_bf16 v[36:39], v[202:205], v[178:181], v[36:39]
	v_mfma_f32_16x16x32_bf16 v[32:35], v[210:213], v[178:181], v[32:35]
	v_mfma_f32_16x16x32_bf16 v[20:23], v[202:205], v[186:189], v[20:23]
	v_mfma_f32_16x16x32_bf16 v[16:19], v[210:213], v[186:189], v[16:19]
	v_mfma_f32_16x16x32_bf16 v[4:7], v[202:205], v[194:197], v[4:7]
	v_mfma_f32_16x16x32_bf16 v[0:3], v[210:213], v[194:197], v[0:3]
	v_mfma_f32_16x16x32_bf16 v[52:55], v[206:209], v[174:177], v[52:55]
	v_mfma_f32_16x16x32_bf16 v[48:51], v[214:217], v[174:177], v[48:51]
	v_mfma_f32_16x16x32_bf16 v[36:39], v[206:209], v[182:185], v[36:39]
	v_mfma_f32_16x16x32_bf16 v[32:35], v[214:217], v[182:185], v[32:35]
	v_mfma_f32_16x16x32_bf16 v[20:23], v[206:209], v[190:193], v[20:23]
	v_mfma_f32_16x16x32_bf16 v[16:19], v[214:217], v[190:193], v[16:19]
	v_mfma_f32_16x16x32_bf16 v[4:7], v[206:209], v[198:201], v[4:7]
	v_mfma_f32_16x16x32_bf16 v[0:3], v[214:217], v[198:201], v[0:3]
	s_add_i32 s86, 0, 0x18000
	v_add_u32_e32 v166, s86, v149
	s_barrier
	ds_read_b128 v[154:157], v166
	ds_read_b128 v[158:161], v166 offset:1024
	ds_read_b128 v[162:165], v166 offset:2048
	ds_read_b128 v[166:169], v166 offset:3072
	s_add_u32 s54, s54, 0x40000
	s_addc_u32 s55, s55, 0
	s_mov_b32 m0, s62
	v_lshl_add_u64 v[202:203], s[54:55], 0, v[130:131]
	ds_read_b128 v[170:173], v152 offset:32768
	ds_read_b128 v[174:177], v152 offset:33792
	ds_read_b128 v[178:181], v152 offset:34816
	ds_read_b128 v[182:185], v152 offset:35840
	ds_read_b128 v[186:189], v152 offset:36864
	ds_read_b128 v[190:193], v152 offset:37888
	ds_read_b128 v[194:197], v152 offset:38912
	ds_read_b128 v[198:201], v152 offset:39936
	global_load_lds_dwordx4 v[202:203], off
	v_lshl_add_u64 v[202:203], s[54:55], 0, v[134:135]
	s_mov_b32 m0, s63
	s_nop 0
	global_load_lds_dwordx4 v[202:203], off
	s_waitcnt lgkmcnt(8)
	s_barrier
	s_waitcnt lgkmcnt(0)
	s_waitcnt lgkmcnt(0)
	v_mfma_f32_16x16x32_bf16 v[124:127], v[154:157], v[170:173], v[124:127]
	v_mfma_f32_16x16x32_bf16 v[120:123], v[162:165], v[170:173], v[120:123]
	v_mfma_f32_16x16x32_bf16 v[108:111], v[154:157], v[178:181], v[108:111]
	v_mfma_f32_16x16x32_bf16 v[104:107], v[162:165], v[178:181], v[104:107]
	v_mfma_f32_16x16x32_bf16 v[92:95], v[154:157], v[186:189], v[92:95]
	v_mfma_f32_16x16x32_bf16 v[88:91], v[162:165], v[186:189], v[88:91]
	v_mfma_f32_16x16x32_bf16 v[76:79], v[154:157], v[194:197], v[76:79]
	v_mfma_f32_16x16x32_bf16 v[72:75], v[162:165], v[194:197], v[72:75]
	v_mfma_f32_16x16x32_bf16 v[124:127], v[158:161], v[174:177], v[124:127]
	v_mfma_f32_16x16x32_bf16 v[120:123], v[166:169], v[174:177], v[120:123]
	v_mfma_f32_16x16x32_bf16 v[108:111], v[158:161], v[182:185], v[108:111]
	v_mfma_f32_16x16x32_bf16 v[104:107], v[166:169], v[182:185], v[104:107]
	v_mfma_f32_16x16x32_bf16 v[92:95], v[158:161], v[190:193], v[92:95]
	v_mfma_f32_16x16x32_bf16 v[88:91], v[166:169], v[190:193], v[88:91]
	v_mfma_f32_16x16x32_bf16 v[76:79], v[158:161], v[198:201], v[76:79]
	v_mfma_f32_16x16x32_bf16 v[72:75], v[166:169], v[198:201], v[72:75]
	s_barrier
	s_add_i32 s54, 0, 0x1c000
	s_add_i32 s55, s86, s60
	v_add_u32_e32 v214, s54, v149
	v_lshl_add_u64 v[218:219], v[218:219], 0, s[8:9]
	s_mov_b32 m0, s55
	ds_read_b128 v[202:205], v214
	ds_read_b128 v[206:209], v214 offset:1024
	ds_read_b128 v[210:213], v214 offset:2048
	ds_read_b128 v[214:217], v214 offset:3072
	global_load_lds_dwordx4 v[218:219], off
	v_lshl_add_u64 v[218:219], v[220:221], 0, s[8:9]
	s_add_i32 m0, s55, 0x2000
	s_nop 0
	global_load_lds_dwordx4 v[218:219], off
	s_cmp_lg_u32 s94, 0
	s_cbranch_scc0 .Lrx3c
	s_waitcnt vmcnt(10)
	s_mov_b32 s94, 0
.Lrx3c:
	s_barrier
	s_waitcnt lgkmcnt(0)
	s_waitcnt lgkmcnt(0)
	v_mfma_f32_16x16x32_bf16 v[116:119], v[202:205], v[170:173], v[116:119]
	v_mfma_f32_16x16x32_bf16 v[112:115], v[210:213], v[170:173], v[112:115]
	v_mfma_f32_16x16x32_bf16 v[100:103], v[202:205], v[178:181], v[100:103]
	v_mfma_f32_16x16x32_bf16 v[96:99], v[210:213], v[178:181], v[96:99]
	v_mfma_f32_16x16x32_bf16 v[84:87], v[202:205], v[186:189], v[84:87]
	v_mfma_f32_16x16x32_bf16 v[80:83], v[210:213], v[186:189], v[80:83]
	v_mfma_f32_16x16x32_bf16 v[68:71], v[202:205], v[194:197], v[68:71]
	v_mfma_f32_16x16x32_bf16 v[64:67], v[210:213], v[194:197], v[64:67]
	v_mfma_f32_16x16x32_bf16 v[116:119], v[206:209], v[174:177], v[116:119]
	v_mfma_f32_16x16x32_bf16 v[112:115], v[214:217], v[174:177], v[112:115]
	v_mfma_f32_16x16x32_bf16 v[100:103], v[206:209], v[182:185], v[100:103]
	v_mfma_f32_16x16x32_bf16 v[96:99], v[214:217], v[182:185], v[96:99]
	v_mfma_f32_16x16x32_bf16 v[84:87], v[206:209], v[190:193], v[84:87]
	v_mfma_f32_16x16x32_bf16 v[80:83], v[214:217], v[190:193], v[80:83]
	v_mfma_f32_16x16x32_bf16 v[68:71], v[206:209], v[198:201], v[68:71]
	v_mfma_f32_16x16x32_bf16 v[64:67], v[214:217], v[198:201], v[64:67]
	s_mov_b32 m0, s71
	v_lshl_add_u64 v[218:219], v[222:223], 0, s[8:9]
	s_barrier
	ds_read_b128 v[170:173], v152 offset:49152
	ds_read_b128 v[174:177], v152 offset:50176
	ds_read_b128 v[178:181], v152 offset:51200
	ds_read_b128 v[182:185], v152 offset:52224
	ds_read_b128 v[186:189], v152 offset:53248
	ds_read_b128 v[190:193], v152 offset:54272
	ds_read_b128 v[194:197], v152 offset:55296
	ds_read_b128 v[198:201], v152 offset:56320
	global_load_lds_dwordx4 v[218:219], off
	v_lshl_add_u64 v[218:219], v[224:225], 0, s[8:9]
	s_mov_b32 m0, s72
	s_nop 0
	global_load_lds_dwordx4 v[218:219], off
	s_barrier
	s_waitcnt lgkmcnt(0)
	s_waitcnt lgkmcnt(0)
	v_mfma_f32_16x16x32_bf16 v[60:63], v[154:157], v[170:173], v[60:63]
	v_mfma_f32_16x16x32_bf16 v[56:59], v[162:165], v[170:173], v[56:59]
	v_mfma_f32_16x16x32_bf16 v[44:47], v[154:157], v[178:181], v[44:47]
	v_mfma_f32_16x16x32_bf16 v[40:43], v[162:165], v[178:181], v[40:43]
	v_mfma_f32_16x16x32_bf16 v[28:31], v[154:157], v[186:189], v[28:31]
	v_mfma_f32_16x16x32_bf16 v[24:27], v[162:165], v[186:189], v[24:27]
	v_mfma_f32_16x16x32_bf16 v[12:15], v[154:157], v[194:197], v[12:15]
	v_mfma_f32_16x16x32_bf16 v[8:11], v[162:165], v[194:197], v[8:11]
	v_mfma_f32_16x16x32_bf16 v[60:63], v[158:161], v[174:177], v[60:63]
	v_mfma_f32_16x16x32_bf16 v[56:59], v[166:169], v[174:177], v[56:59]
	v_mfma_f32_16x16x32_bf16 v[44:47], v[158:161], v[182:185], v[44:47]
	v_mfma_f32_16x16x32_bf16 v[40:43], v[166:169], v[182:185], v[40:43]
	v_mfma_f32_16x16x32_bf16 v[28:31], v[158:161], v[190:193], v[28:31]
	v_mfma_f32_16x16x32_bf16 v[24:27], v[166:169], v[190:193], v[24:27]
	v_mfma_f32_16x16x32_bf16 v[12:15], v[158:161], v[198:201], v[12:15]
	v_mfma_f32_16x16x32_bf16 v[8:11], v[166:169], v[198:201], v[8:11]
	s_barrier
	s_add_u32 s34, s34, 0x40080
	s_addc_u32 s35, s35, 0
	s_add_i32 s54, s54, s60
	v_lshl_add_u64 v[154:155], s[34:35], 0, v[132:133]
	s_mov_b32 m0, s54
	s_nop 0
	global_load_lds_dwordx4 v[154:155], off
	v_lshl_add_u64 v[154:155], s[34:35], 0, v[136:137]
	s_add_i32 m0, s54, 0x2000
	s_nop 0
	global_load_lds_dwordx4 v[154:155], off
	s_waitcnt vmcnt(6)
	s_barrier
	v_mfma_f32_16x16x32_bf16 v[52:55], v[202:205], v[170:173], v[52:55]
	v_mfma_f32_16x16x32_bf16 v[48:51], v[210:213], v[170:173], v[48:51]
	v_mfma_f32_16x16x32_bf16 v[36:39], v[202:205], v[178:181], v[36:39]
	v_mfma_f32_16x16x32_bf16 v[32:35], v[210:213], v[178:181], v[32:35]
	v_mfma_f32_16x16x32_bf16 v[20:23], v[202:205], v[186:189], v[20:23]
	v_mfma_f32_16x16x32_bf16 v[16:19], v[210:213], v[186:189], v[16:19]
	v_mfma_f32_16x16x32_bf16 v[4:7], v[202:205], v[194:197], v[4:7]
	v_mfma_f32_16x16x32_bf16 v[0:3], v[210:213], v[194:197], v[0:3]
	v_mfma_f32_16x16x32_bf16 v[52:55], v[206:209], v[174:177], v[52:55]
	v_mfma_f32_16x16x32_bf16 v[48:51], v[214:217], v[174:177], v[48:51]
	v_mfma_f32_16x16x32_bf16 v[36:39], v[206:209], v[182:185], v[36:39]
	v_mfma_f32_16x16x32_bf16 v[32:35], v[214:217], v[182:185], v[32:35]
	v_mfma_f32_16x16x32_bf16 v[20:23], v[206:209], v[190:193], v[20:23]
	v_mfma_f32_16x16x32_bf16 v[16:19], v[214:217], v[190:193], v[16:19]
	v_mfma_f32_16x16x32_bf16 v[4:7], v[206:209], v[198:201], v[4:7]
	v_mfma_f32_16x16x32_bf16 v[0:3], v[214:217], v[198:201], v[0:3]
	s_add_i32 s85, s85, 2
	s_add_u32 s30, s30, 0x100
	s_addc_u32 s31, s31, 0
	s_add_u32 s83, s83, 0x100
	s_addc_u32 s84, s84, 0
	s_cmp_gt_u32 s85, 13
	s_barrier
	s_cbranch_scc0 .LBB0_683
	v_lshl_add_u32 v154, s28, 8, v148
	v_max_f32_e32 v126, v126, v126
	v_max_f32_e32 v127, v127, v127
	v_lshl_or_b32 v156, s80, 8, v150
	v_ashrrev_i32_e32 v155, 31, v154
	v_max_f32_e32 v124, v124, v124
	v_max_f32_e32 v120, v120, v120
	v_max_f32_e32 v125, v125, v125
	v_max_f32_e32 v121, v121, v121
	v_max_f32_e32 v126, 0, v126
	v_max_f32_e32 v122, v122, v122
	v_max_f32_e32 v127, 0, v127
	v_max_f32_e32 v123, v123, v123
	v_lshlrev_b64 v[158:159], 13, v[154:155]
	v_max_f32_e32 v124, 0, v124
	v_max_f32_e32 v120, 0, v120
	v_max_f32_e32 v125, 0, v125
	v_max_f32_e32 v121, 0, v121
	v_max_f32_e32 v122, 0, v122
	v_max_f32_e32 v123, 0, v123
	v_pk_mul_f32 v[126:127], v[126:127], v[126:127]
	v_ashrrev_i32_e32 v157, 31, v156
	v_lshl_add_u64 v[158:159], s[46:47], 0, v[158:159]
	v_pk_mul_f32 v[124:125], v[124:125], v[124:125]
	v_pk_mul_f32 v[120:121], v[120:121], v[120:121]
	v_pk_mul_f32 v[160:161], v[122:123], v[122:123]
	v_cvt_pk_bf16_f32 v123, v126, v127
	v_lshlrev_b64 v[126:127], 1, v[156:157]
	v_max_f32_e32 v112, v112, v112
	v_max_f32_e32 v113, v113, v113
	v_cvt_pk_bf16_f32 v122, v124, v125
	v_cvt_pk_bf16_f32 v124, v120, v121
	v_cvt_pk_bf16_f32 v125, v160, v161
	v_lshl_add_u64 v[120:121], v[158:159], 0, v[126:127]
	v_max_f32_e32 v112, 0, v112
	v_max_f32_e32 v113, 0, v113
	global_store_dwordx4 v[120:121], v[122:125], off
	v_max_f32_e32 v116, v116, v116
	v_max_f32_e32 v117, v117, v117
	v_pk_mul_f32 v[122:123], v[112:113], v[112:113]
	v_max_f32_e32 v113, v114, v114
	v_max_f32_e32 v112, v118, v118
	v_max_f32_e32 v114, 0, v113
	v_max_f32_e32 v113, v119, v119
	v_max_f32_e32 v115, v115, v115
	v_max_f32_e32 v116, 0, v116
	v_max_f32_e32 v117, 0, v117
	v_max_f32_e32 v112, 0, v112
	v_max_f32_e32 v113, 0, v113
	v_max_f32_e32 v115, 0, v115
	v_pk_mul_f32 v[116:117], v[116:117], v[116:117]
	v_pk_mul_f32 v[118:119], v[112:113], v[112:113]
	v_pk_mul_f32 v[124:125], v[114:115], v[114:115]
	v_max_f32_e32 v104, v104, v104
	v_max_f32_e32 v105, v105, v105
	v_cvt_pk_bf16_f32 v112, v116, v117
	v_cvt_pk_bf16_f32 v113, v118, v119
	v_cvt_pk_bf16_f32 v114, v122, v123
	v_cvt_pk_bf16_f32 v115, v124, v125
	v_max_f32_e32 v104, 0, v104
	v_max_f32_e32 v105, 0, v105
	global_store_dwordx4 v[120:121], v[112:115], off offset:256
	v_max_f32_e32 v108, v108, v108
	v_max_f32_e32 v109, v109, v109
	v_or_b32_e32 v112, 16, v154
	v_pk_mul_f32 v[114:115], v[104:105], v[104:105]
	v_max_f32_e32 v105, v106, v106
	v_ashrrev_i32_e32 v113, 31, v112
	v_max_f32_e32 v104, v110, v110
	v_max_f32_e32 v106, 0, v105
	v_max_f32_e32 v105, v111, v111
	v_max_f32_e32 v107, v107, v107
	v_lshlrev_b64 v[112:113], 13, v[112:113]
	v_max_f32_e32 v108, 0, v108
	v_max_f32_e32 v109, 0, v109
	v_max_f32_e32 v104, 0, v104
	v_max_f32_e32 v105, 0, v105
	v_max_f32_e32 v107, 0, v107
	v_lshl_add_u64 v[112:113], s[46:47], 0, v[112:113]
	v_pk_mul_f32 v[108:109], v[108:109], v[108:109]
	v_pk_mul_f32 v[110:111], v[104:105], v[104:105]
	v_pk_mul_f32 v[116:117], v[106:107], v[106:107]
	v_max_f32_e32 v96, v96, v96
	v_max_f32_e32 v97, v97, v97
	v_cvt_pk_bf16_f32 v104, v108, v109
	v_cvt_pk_bf16_f32 v105, v110, v111
	v_cvt_pk_bf16_f32 v106, v114, v115
	v_cvt_pk_bf16_f32 v107, v116, v117
	v_lshl_add_u64 v[108:109], v[112:113], 0, v[126:127]
	v_max_f32_e32 v96, 0, v96
	v_max_f32_e32 v97, 0, v97
	global_store_dwordx4 v[108:109], v[104:107], off
	v_max_f32_e32 v100, v100, v100
	v_max_f32_e32 v101, v101, v101
	v_pk_mul_f32 v[104:105], v[96:97], v[96:97]
	v_max_f32_e32 v97, v98, v98
	v_max_f32_e32 v96, v102, v102
	v_max_f32_e32 v98, 0, v97
	v_max_f32_e32 v97, v103, v103
	v_max_f32_e32 v99, v99, v99
	v_max_f32_e32 v100, 0, v100
	v_max_f32_e32 v101, 0, v101
	v_max_f32_e32 v96, 0, v96
	v_max_f32_e32 v97, 0, v97
	v_max_f32_e32 v99, 0, v99
	v_pk_mul_f32 v[100:101], v[100:101], v[100:101]
	v_pk_mul_f32 v[102:103], v[96:97], v[96:97]
	v_pk_mul_f32 v[106:107], v[98:99], v[98:99]
	v_max_f32_e32 v88, v88, v88
	v_max_f32_e32 v89, v89, v89
	v_cvt_pk_bf16_f32 v96, v100, v101
	v_cvt_pk_bf16_f32 v97, v102, v103
	v_cvt_pk_bf16_f32 v98, v104, v105
	v_cvt_pk_bf16_f32 v99, v106, v107
	v_max_f32_e32 v88, 0, v88
	v_max_f32_e32 v89, 0, v89
	global_store_dwordx4 v[108:109], v[96:99], off offset:256
	v_max_f32_e32 v92, v92, v92
	v_max_f32_e32 v93, v93, v93
	v_or_b32_e32 v96, 32, v154
	v_pk_mul_f32 v[98:99], v[88:89], v[88:89]
	v_max_f32_e32 v89, v90, v90
	v_ashrrev_i32_e32 v97, 31, v96
	v_max_f32_e32 v88, v94, v94
	v_max_f32_e32 v90, 0, v89
	v_max_f32_e32 v89, v95, v95
	v_max_f32_e32 v91, v91, v91
	v_lshlrev_b64 v[96:97], 13, v[96:97]
	v_max_f32_e32 v92, 0, v92
	v_max_f32_e32 v93, 0, v93
	v_max_f32_e32 v88, 0, v88
	v_max_f32_e32 v89, 0, v89
	v_max_f32_e32 v91, 0, v91
	v_lshl_add_u64 v[96:97], s[46:47], 0, v[96:97]
	v_pk_mul_f32 v[92:93], v[92:93], v[92:93]
	v_pk_mul_f32 v[94:95], v[88:89], v[88:89]
	v_pk_mul_f32 v[100:101], v[90:91], v[90:91]
	v_max_f32_e32 v80, v80, v80
	v_max_f32_e32 v81, v81, v81
	v_cvt_pk_bf16_f32 v88, v92, v93
	v_cvt_pk_bf16_f32 v89, v94, v95
	v_cvt_pk_bf16_f32 v90, v98, v99
	v_cvt_pk_bf16_f32 v91, v100, v101
	v_lshl_add_u64 v[92:93], v[96:97], 0, v[126:127]
	v_max_f32_e32 v80, 0, v80
	v_max_f32_e32 v81, 0, v81
	global_store_dwordx4 v[92:93], v[88:91], off
	v_max_f32_e32 v84, v84, v84
	v_max_f32_e32 v85, v85, v85
	v_pk_mul_f32 v[88:89], v[80:81], v[80:81]
	v_max_f32_e32 v81, v82, v82
	v_max_f32_e32 v80, v86, v86
	v_max_f32_e32 v82, 0, v81
	v_max_f32_e32 v81, v87, v87
	v_max_f32_e32 v83, v83, v83
	v_max_f32_e32 v84, 0, v84
	v_max_f32_e32 v85, 0, v85
	v_max_f32_e32 v80, 0, v80
	v_max_f32_e32 v81, 0, v81
	v_max_f32_e32 v83, 0, v83
	v_pk_mul_f32 v[84:85], v[84:85], v[84:85]
	v_pk_mul_f32 v[86:87], v[80:81], v[80:81]
	v_pk_mul_f32 v[90:91], v[82:83], v[82:83]
	v_max_f32_e32 v72, v72, v72
	v_max_f32_e32 v73, v73, v73
	v_cvt_pk_bf16_f32 v80, v84, v85
	v_cvt_pk_bf16_f32 v81, v86, v87
	v_cvt_pk_bf16_f32 v82, v88, v89
	v_cvt_pk_bf16_f32 v83, v90, v91
	v_max_f32_e32 v72, 0, v72
	v_max_f32_e32 v73, 0, v73
	global_store_dwordx4 v[92:93], v[80:83], off offset:256
	v_max_f32_e32 v76, v76, v76
	v_max_f32_e32 v77, v77, v77
	v_or_b32_e32 v80, 48, v154
	v_pk_mul_f32 v[82:83], v[72:73], v[72:73]
	v_max_f32_e32 v73, v74, v74
	v_ashrrev_i32_e32 v81, 31, v80
	v_max_f32_e32 v72, v78, v78
	v_max_f32_e32 v74, 0, v73
	v_max_f32_e32 v73, v79, v79
	v_max_f32_e32 v75, v75, v75
	v_lshlrev_b64 v[80:81], 13, v[80:81]
	v_max_f32_e32 v76, 0, v76
	v_max_f32_e32 v77, 0, v77
	v_max_f32_e32 v72, 0, v72
	v_max_f32_e32 v73, 0, v73
	v_max_f32_e32 v75, 0, v75
	v_lshl_add_u64 v[80:81], s[46:47], 0, v[80:81]
	v_pk_mul_f32 v[76:77], v[76:77], v[76:77]
	v_pk_mul_f32 v[78:79], v[72:73], v[72:73]
	v_pk_mul_f32 v[84:85], v[74:75], v[74:75]
	v_max_f32_e32 v64, v64, v64
	v_max_f32_e32 v65, v65, v65
	v_cvt_pk_bf16_f32 v72, v76, v77
	v_cvt_pk_bf16_f32 v73, v78, v79
	v_cvt_pk_bf16_f32 v74, v82, v83
	v_cvt_pk_bf16_f32 v75, v84, v85
	v_lshl_add_u64 v[76:77], v[80:81], 0, v[126:127]
	v_max_f32_e32 v64, 0, v64
	v_max_f32_e32 v65, 0, v65
	global_store_dwordx4 v[76:77], v[72:75], off
	v_max_f32_e32 v68, v68, v68
	v_max_f32_e32 v69, v69, v69
	v_pk_mul_f32 v[72:73], v[64:65], v[64:65]
	v_max_f32_e32 v65, v66, v66
	v_max_f32_e32 v64, v70, v70
	v_max_f32_e32 v66, 0, v65
	v_max_f32_e32 v65, v71, v71
	v_max_f32_e32 v67, v67, v67
	v_max_f32_e32 v68, 0, v68
	v_max_f32_e32 v69, 0, v69
	v_max_f32_e32 v64, 0, v64
	v_max_f32_e32 v65, 0, v65
	v_max_f32_e32 v67, 0, v67
	v_pk_mul_f32 v[68:69], v[68:69], v[68:69]
	v_pk_mul_f32 v[70:71], v[64:65], v[64:65]
	v_pk_mul_f32 v[74:75], v[66:67], v[66:67]
	v_max_f32_e32 v56, v56, v56
	v_max_f32_e32 v57, v57, v57
	v_cvt_pk_bf16_f32 v64, v68, v69
	v_cvt_pk_bf16_f32 v65, v70, v71
	v_cvt_pk_bf16_f32 v66, v72, v73
	v_cvt_pk_bf16_f32 v67, v74, v75
	v_max_f32_e32 v56, 0, v56
	v_max_f32_e32 v57, 0, v57
	global_store_dwordx4 v[76:77], v[64:67], off offset:256
	v_max_f32_e32 v60, v60, v60
	v_max_f32_e32 v61, v61, v61
	v_pk_mul_f32 v[64:65], v[56:57], v[56:57]
	v_max_f32_e32 v57, v58, v58
	v_max_f32_e32 v56, v62, v62
	v_max_f32_e32 v58, 0, v57
	v_max_f32_e32 v57, v63, v63
	v_max_f32_e32 v56, 0, v56
	v_max_f32_e32 v57, 0, v57
	v_max_f32_e32 v59, v59, v59
	v_max_f32_e32 v60, 0, v60
	v_max_f32_e32 v61, 0, v61
	v_max_f32_e32 v59, 0, v59
	v_pk_mul_f32 v[62:63], v[56:57], v[56:57]
	v_pk_mul_f32 v[60:61], v[60:61], v[60:61]
	v_pk_mul_f32 v[66:67], v[58:59], v[58:59]
	v_cvt_pk_bf16_f32 v57, v62, v63
	v_add_co_u32_e32 v62, vcc, s76, v120
	v_max_f32_e32 v48, v48, v48
	v_max_f32_e32 v49, v49, v49
	v_cvt_pk_bf16_f32 v56, v60, v61
	v_cvt_pk_bf16_f32 v58, v64, v65
	v_cvt_pk_bf16_f32 v59, v66, v67
	v_addc_co_u32_e32 v63, vcc, 0, v121, vcc
	v_max_f32_e32 v48, 0, v48
	v_max_f32_e32 v49, 0, v49
	global_store_dwordx4 v[62:63], v[56:59], off
	v_max_f32_e32 v52, v52, v52
	v_max_f32_e32 v53, v53, v53
	v_pk_mul_f32 v[56:57], v[48:49], v[48:49]
	v_max_f32_e32 v49, v50, v50
	v_max_f32_e32 v48, v54, v54
	v_max_f32_e32 v50, 0, v49
	v_max_f32_e32 v49, v55, v55
	v_max_f32_e32 v51, v51, v51
	v_max_f32_e32 v52, 0, v52
	v_max_f32_e32 v53, 0, v53
	v_max_f32_e32 v48, 0, v48
	v_max_f32_e32 v49, 0, v49
	v_max_f32_e32 v51, 0, v51
	s_mov_b64 s[30:31], 0x100000
	v_pk_mul_f32 v[52:53], v[52:53], v[52:53]
	v_pk_mul_f32 v[54:55], v[48:49], v[48:49]
	v_pk_mul_f32 v[58:59], v[50:51], v[50:51]
	v_max_f32_e32 v40, v40, v40
	v_max_f32_e32 v41, v41, v41
	v_lshl_add_u64 v[60:61], v[120:121], 0, s[30:31]
	v_cvt_pk_bf16_f32 v48, v52, v53
	v_cvt_pk_bf16_f32 v49, v54, v55
	v_cvt_pk_bf16_f32 v50, v56, v57
	v_cvt_pk_bf16_f32 v51, v58, v59
	v_max_f32_e32 v40, 0, v40
	v_max_f32_e32 v41, 0, v41
	global_store_dwordx4 v[60:61], v[48:51], off offset:256
	v_max_f32_e32 v44, v44, v44
	v_max_f32_e32 v45, v45, v45
	v_pk_mul_f32 v[48:49], v[40:41], v[40:41]
	v_max_f32_e32 v41, v42, v42
	v_max_f32_e32 v40, v46, v46
	v_max_f32_e32 v42, 0, v41
	v_max_f32_e32 v41, v47, v47
	v_max_f32_e32 v40, 0, v40
	v_max_f32_e32 v41, 0, v41
	v_max_f32_e32 v43, v43, v43
	v_max_f32_e32 v44, 0, v44
	v_max_f32_e32 v45, 0, v45
	v_max_f32_e32 v43, 0, v43
	v_pk_mul_f32 v[46:47], v[40:41], v[40:41]
	v_pk_mul_f32 v[44:45], v[44:45], v[44:45]
	v_pk_mul_f32 v[50:51], v[42:43], v[42:43]
	v_cvt_pk_bf16_f32 v41, v46, v47
	v_add_co_u32_e32 v46, vcc, s77, v120
	v_max_f32_e32 v32, v32, v32
	v_max_f32_e32 v33, v33, v33
	v_cvt_pk_bf16_f32 v40, v44, v45
	v_cvt_pk_bf16_f32 v42, v48, v49
	v_cvt_pk_bf16_f32 v43, v50, v51
	v_addc_co_u32_e32 v47, vcc, 0, v121, vcc
	v_max_f32_e32 v32, 0, v32
	v_max_f32_e32 v33, 0, v33
	global_store_dwordx4 v[46:47], v[40:43], off
	v_max_f32_e32 v36, v36, v36
	v_max_f32_e32 v37, v37, v37
	v_pk_mul_f32 v[40:41], v[32:33], v[32:33]
	v_max_f32_e32 v33, v34, v34
	v_max_f32_e32 v32, v38, v38
	v_max_f32_e32 v34, 0, v33
	v_max_f32_e32 v33, v39, v39
	v_max_f32_e32 v35, v35, v35
	v_max_f32_e32 v36, 0, v36
	v_max_f32_e32 v37, 0, v37
	v_max_f32_e32 v32, 0, v32
	v_max_f32_e32 v33, 0, v33
	v_max_f32_e32 v35, 0, v35
	v_pk_mul_f32 v[36:37], v[36:37], v[36:37]
	v_pk_mul_f32 v[38:39], v[32:33], v[32:33]
	v_pk_mul_f32 v[42:43], v[34:35], v[34:35]
	v_max_f32_e32 v24, v24, v24
	v_max_f32_e32 v25, v25, v25
	v_lshl_add_u64 v[44:45], v[120:121], 0, s[10:11]
	v_cvt_pk_bf16_f32 v32, v36, v37
	v_cvt_pk_bf16_f32 v33, v38, v39
	v_cvt_pk_bf16_f32 v34, v40, v41
	v_cvt_pk_bf16_f32 v35, v42, v43
	v_max_f32_e32 v24, 0, v24
	v_max_f32_e32 v25, 0, v25
	global_store_dwordx4 v[44:45], v[32:35], off offset:256
	v_max_f32_e32 v28, v28, v28
	v_max_f32_e32 v29, v29, v29
	v_pk_mul_f32 v[32:33], v[24:25], v[24:25]
	v_max_f32_e32 v25, v26, v26
	v_max_f32_e32 v24, v30, v30
	v_max_f32_e32 v26, 0, v25
	v_max_f32_e32 v25, v31, v31
	v_max_f32_e32 v24, 0, v24
	v_max_f32_e32 v25, 0, v25
	v_max_f32_e32 v27, v27, v27
	v_max_f32_e32 v28, 0, v28
	v_max_f32_e32 v29, 0, v29
	v_max_f32_e32 v27, 0, v27
	v_pk_mul_f32 v[30:31], v[24:25], v[24:25]
	v_pk_mul_f32 v[28:29], v[28:29], v[28:29]
	v_pk_mul_f32 v[34:35], v[26:27], v[26:27]
	v_cvt_pk_bf16_f32 v25, v30, v31
	v_add_co_u32_e32 v30, vcc, s78, v120
	v_max_f32_e32 v16, v16, v16
	v_max_f32_e32 v17, v17, v17
	v_cvt_pk_bf16_f32 v24, v28, v29
	v_cvt_pk_bf16_f32 v26, v32, v33
	v_cvt_pk_bf16_f32 v27, v34, v35
	v_addc_co_u32_e32 v31, vcc, 0, v121, vcc
	v_max_f32_e32 v16, 0, v16
	v_max_f32_e32 v17, 0, v17
	global_store_dwordx4 v[30:31], v[24:27], off
	v_max_f32_e32 v20, v20, v20
	v_max_f32_e32 v21, v21, v21
	v_pk_mul_f32 v[24:25], v[16:17], v[16:17]
	v_max_f32_e32 v17, v18, v18
	v_max_f32_e32 v16, v22, v22
	v_max_f32_e32 v18, 0, v17
	v_max_f32_e32 v17, v23, v23
	v_max_f32_e32 v19, v19, v19
	v_max_f32_e32 v20, 0, v20
	v_max_f32_e32 v21, 0, v21
	v_max_f32_e32 v16, 0, v16
	v_max_f32_e32 v17, 0, v17
	v_max_f32_e32 v19, 0, v19
	v_pk_mul_f32 v[20:21], v[20:21], v[20:21]
	v_pk_mul_f32 v[22:23], v[16:17], v[16:17]
	v_pk_mul_f32 v[26:27], v[18:19], v[18:19]
	v_max_f32_e32 v8, v8, v8
	v_max_f32_e32 v9, v9, v9
	v_lshl_add_u64 v[28:29], v[120:121], 0, s[12:13]
	v_cvt_pk_bf16_f32 v16, v20, v21
	v_cvt_pk_bf16_f32 v17, v22, v23
	v_cvt_pk_bf16_f32 v18, v24, v25
	v_cvt_pk_bf16_f32 v19, v26, v27
	v_max_f32_e32 v8, 0, v8
	v_max_f32_e32 v9, 0, v9
	global_store_dwordx4 v[28:29], v[16:19], off offset:256
	v_max_f32_e32 v12, v12, v12
	v_max_f32_e32 v13, v13, v13
	v_pk_mul_f32 v[16:17], v[8:9], v[8:9]
	v_max_f32_e32 v9, v10, v10
	v_max_f32_e32 v8, v14, v14
	v_max_f32_e32 v10, 0, v9
	v_max_f32_e32 v9, v15, v15
	v_max_f32_e32 v8, 0, v8
	v_max_f32_e32 v9, 0, v9
	v_max_f32_e32 v11, v11, v11
	v_max_f32_e32 v12, 0, v12
	v_max_f32_e32 v13, 0, v13
	v_max_f32_e32 v11, 0, v11
	v_pk_mul_f32 v[14:15], v[8:9], v[8:9]
	v_pk_mul_f32 v[12:13], v[12:13], v[12:13]
	v_pk_mul_f32 v[18:19], v[10:11], v[10:11]
	v_cvt_pk_bf16_f32 v9, v14, v15
	v_add_co_u32_e32 v14, vcc, s79, v120
	v_max_f32_e32 v0, v0, v0
	v_max_f32_e32 v1, v1, v1
	v_cvt_pk_bf16_f32 v8, v12, v13
	v_cvt_pk_bf16_f32 v10, v16, v17
	v_cvt_pk_bf16_f32 v11, v18, v19
	v_addc_co_u32_e32 v15, vcc, 0, v121, vcc
	v_max_f32_e32 v0, 0, v0
	v_max_f32_e32 v1, 0, v1
	global_store_dwordx4 v[14:15], v[8:11], off
	v_max_f32_e32 v4, v4, v4
	v_max_f32_e32 v5, v5, v5
	v_pk_mul_f32 v[8:9], v[0:1], v[0:1]
	v_max_f32_e32 v1, v2, v2
	v_max_f32_e32 v0, v6, v6
	v_max_f32_e32 v2, 0, v1
	v_max_f32_e32 v1, v7, v7
	v_max_f32_e32 v3, v3, v3
	v_max_f32_e32 v4, 0, v4
	v_max_f32_e32 v5, 0, v5
	v_max_f32_e32 v0, 0, v0
	v_max_f32_e32 v1, 0, v1
	v_max_f32_e32 v3, 0, v3
	v_pk_mul_f32 v[4:5], v[4:5], v[4:5]
	v_pk_mul_f32 v[6:7], v[0:1], v[0:1]
	v_pk_mul_f32 v[10:11], v[2:3], v[2:3]
	v_lshl_add_u64 v[12:13], v[120:121], 0, s[14:15]
	v_cvt_pk_bf16_f32 v0, v4, v5
	v_cvt_pk_bf16_f32 v1, v6, v7
	v_cvt_pk_bf16_f32 v2, v8, v9
	v_cvt_pk_bf16_f32 v3, v10, v11
	s_and_b64 vcc, exec, s[4:5]
	s_mov_b32 s80, s16
	s_mov_b32 s28, s18
	s_mov_b64 s[34:35], s[26:27]
	s_mov_b64 s[30:31], s[20:21]
	global_store_dwordx4 v[12:13], v[0:3], off offset:256
	s_mov_b32 s94, 1
	s_cbranch_vccz .LBB0_676
	s_mov_b32 s94, 0
	s_waitcnt vmcnt(16)
	s_cmpk_gt_u32 s56, 0xff
	s_cbranch_scc1 .LBB0_687
	s_barrier

.LBB0_776:
	ds_read_b128 v[156:159], v152
	ds_read_b128 v[160:163], v152 offset:1024
	ds_read_b128 v[164:167], v152 offset:2048
	ds_read_b128 v[168:171], v152 offset:3072
	s_add_u32 s34, s30, 0xfff00080
	s_addc_u32 s35, s31, -1
	s_cmp_eq_u32 s85, 60
	s_cselect_b32 s55, s21, s35
	s_cselect_b32 s54, s81, s34
	s_cselect_b32 s35, s19, s84
	s_cselect_b32 s34, s82, s83
	v_lshl_add_u64 v[204:205], s[30:31], 0, v[138:139]
	s_add_i32 m0, s17, 0xc000
	ds_read_b128 v[172:175], v153
	ds_read_b128 v[176:179], v153 offset:1024
	ds_read_b128 v[180:183], v153 offset:2048
	ds_read_b128 v[184:187], v153 offset:3072
	ds_read_b128 v[188:191], v153 offset:4096
	ds_read_b128 v[192:195], v153 offset:5120
	ds_read_b128 v[196:199], v153 offset:6144
	ds_read_b128 v[200:203], v153 offset:7168
	global_load_lds_dwordx4 v[204:205], off
	v_lshl_add_u64 v[204:205], s[30:31], 0, v[140:141]
	s_add_i32 m0, s17, 0xe000
	s_nop 0
	global_load_lds_dwordx4 v[204:205], off
	s_waitcnt lgkmcnt(8)
	s_barrier
	s_waitcnt lgkmcnt(0)
	s_waitcnt lgkmcnt(0)
	v_mfma_f32_16x16x32_bf16 v[124:127], v[156:159], v[172:175], v[124:127]
	v_mfma_f32_16x16x32_bf16 v[120:123], v[164:167], v[172:175], v[120:123]
	v_mfma_f32_16x16x32_bf16 v[116:119], v[156:159], v[180:183], v[116:119]
	v_mfma_f32_16x16x32_bf16 v[112:115], v[164:167], v[180:183], v[112:115]
	v_mfma_f32_16x16x32_bf16 v[100:103], v[156:159], v[188:191], v[100:103]
	v_mfma_f32_16x16x32_bf16 v[96:99], v[164:167], v[188:191], v[96:99]
	v_mfma_f32_16x16x32_bf16 v[84:87], v[156:159], v[196:199], v[84:87]
	v_mfma_f32_16x16x32_bf16 v[80:83], v[164:167], v[196:199], v[80:83]
	v_mfma_f32_16x16x32_bf16 v[124:127], v[160:163], v[176:179], v[124:127]
	v_mfma_f32_16x16x32_bf16 v[120:123], v[168:171], v[176:179], v[120:123]
	v_mfma_f32_16x16x32_bf16 v[116:119], v[160:163], v[184:187], v[116:119]
	v_mfma_f32_16x16x32_bf16 v[112:115], v[168:171], v[184:187], v[112:115]
	v_mfma_f32_16x16x32_bf16 v[100:103], v[160:163], v[192:195], v[100:103]
	v_mfma_f32_16x16x32_bf16 v[96:99], v[168:171], v[192:195], v[96:99]
	v_mfma_f32_16x16x32_bf16 v[84:87], v[160:163], v[200:203], v[84:87]
	v_mfma_f32_16x16x32_bf16 v[80:83], v[168:171], v[200:203], v[80:83]
	s_barrier
	s_add_i32 s86, s74, s57
	v_lshl_add_u64 v[220:221], s[34:35], 0, v[134:135]
	s_mov_b32 m0, s86
	ds_read_b128 v[204:207], v154
	ds_read_b128 v[208:211], v154 offset:1024
	ds_read_b128 v[212:215], v154 offset:2048
	ds_read_b128 v[216:219], v154 offset:3072
	global_load_lds_dwordx4 v[220:221], off
	v_lshl_add_u64 v[222:223], s[34:35], 0, v[130:131]
	s_add_i32 m0, s86, 0x2000
	s_nop 0
	global_load_lds_dwordx4 v[222:223], off
	s_barrier
	s_waitcnt lgkmcnt(0)
	s_waitcnt lgkmcnt(0)
	v_mfma_f32_16x16x32_bf16 v[108:111], v[204:207], v[172:175], v[108:111]
	v_mfma_f32_16x16x32_bf16 v[104:107], v[212:215], v[172:175], v[104:107]
	v_mfma_f32_16x16x32_bf16 v[92:95], v[204:207], v[180:183], v[92:95]
	v_mfma_f32_16x16x32_bf16 v[88:91], v[212:215], v[180:183], v[88:91]
	v_mfma_f32_16x16x32_bf16 v[76:79], v[204:207], v[188:191], v[76:79]
	v_mfma_f32_16x16x32_bf16 v[72:75], v[212:215], v[188:191], v[72:75]
	v_mfma_f32_16x16x32_bf16 v[68:71], v[204:207], v[196:199], v[68:71]
	v_mfma_f32_16x16x32_bf16 v[64:67], v[212:215], v[196:199], v[64:67]
	v_mfma_f32_16x16x32_bf16 v[108:111], v[208:211], v[176:179], v[108:111]
	v_mfma_f32_16x16x32_bf16 v[104:107], v[216:219], v[176:179], v[104:107]
	v_mfma_f32_16x16x32_bf16 v[92:95], v[208:211], v[184:187], v[92:95]
	v_mfma_f32_16x16x32_bf16 v[88:91], v[216:219], v[184:187], v[88:91]
	v_mfma_f32_16x16x32_bf16 v[76:79], v[208:211], v[192:195], v[76:79]
	v_mfma_f32_16x16x32_bf16 v[72:75], v[216:219], v[192:195], v[72:75]
	v_mfma_f32_16x16x32_bf16 v[68:71], v[208:211], v[200:203], v[68:71]
	v_mfma_f32_16x16x32_bf16 v[64:67], v[216:219], v[200:203], v[64:67]
	s_mov_b32 m0, s17
	v_lshl_add_u64 v[224:225], s[54:55], 0, v[136:137]
	s_barrier
	ds_read_b128 v[172:175], v153 offset:16384
	ds_read_b128 v[176:179], v153 offset:17408
	ds_read_b128 v[180:183], v153 offset:18432
	ds_read_b128 v[184:187], v153 offset:19456
	ds_read_b128 v[188:191], v153 offset:20480
	ds_read_b128 v[192:195], v153 offset:21504
	ds_read_b128 v[196:199], v153 offset:22528
	ds_read_b128 v[200:203], v153 offset:23552
	global_load_lds_dwordx4 v[224:225], off
	v_lshl_add_u64 v[226:227], s[54:55], 0, v[132:133]
	s_mov_b32 m0, s61
	s_nop 0
	global_load_lds_dwordx4 v[226:227], off
	s_barrier
	s_waitcnt lgkmcnt(0)
	s_waitcnt lgkmcnt(0)
	v_mfma_f32_16x16x32_bf16 v[60:63], v[156:159], v[172:175], v[60:63]
	v_mfma_f32_16x16x32_bf16 v[56:59], v[164:167], v[172:175], v[56:59]
	v_mfma_f32_16x16x32_bf16 v[52:55], v[156:159], v[180:183], v[52:55]
	v_mfma_f32_16x16x32_bf16 v[48:51], v[164:167], v[180:183], v[48:51]
	v_mfma_f32_16x16x32_bf16 v[36:39], v[156:159], v[188:191], v[36:39]
	v_mfma_f32_16x16x32_bf16 v[32:35], v[164:167], v[188:191], v[32:35]
	v_mfma_f32_16x16x32_bf16 v[20:23], v[156:159], v[196:199], v[20:23]
	v_mfma_f32_16x16x32_bf16 v[16:19], v[164:167], v[196:199], v[16:19]
	v_mfma_f32_16x16x32_bf16 v[60:63], v[160:163], v[176:179], v[60:63]
	v_mfma_f32_16x16x32_bf16 v[56:59], v[168:171], v[176:179], v[56:59]
	v_mfma_f32_16x16x32_bf16 v[52:55], v[160:163], v[184:187], v[52:55]
	v_mfma_f32_16x16x32_bf16 v[48:51], v[168:171], v[184:187], v[48:51]
	v_mfma_f32_16x16x32_bf16 v[36:39], v[160:163], v[192:195], v[36:39]
	v_mfma_f32_16x16x32_bf16 v[32:35], v[168:171], v[192:195], v[32:35]
	v_mfma_f32_16x16x32_bf16 v[20:23], v[160:163], v[200:203], v[20:23]
	v_mfma_f32_16x16x32_bf16 v[16:19], v[168:171], v[200:203], v[16:19]
	s_barrier
	s_add_u32 s86, s34, 0x100000
	s_addc_u32 s87, s35, 0
	s_add_i32 s88, s75, s57
	v_lshl_add_u64 v[156:157], s[86:87], 0, v[134:135]
	s_mov_b32 m0, s88
	s_nop 0
	global_load_lds_dwordx4 v[156:157], off
	v_lshl_add_u64 v[156:157], s[86:87], 0, v[130:131]
	s_add_i32 m0, s88, 0x2000
	s_nop 0
	global_load_lds_dwordx4 v[156:157], off
	s_cmp_lg_u32 s94, 0
	s_cbranch_scc1 .Lrx5a
	s_waitcnt vmcnt(6)
.Lrx5a:
	s_waitcnt vmcnt(24)
	s_barrier
	v_mfma_f32_16x16x32_bf16 v[44:47], v[204:207], v[172:175], v[44:47]
	v_mfma_f32_16x16x32_bf16 v[40:43], v[212:215], v[172:175], v[40:43]
	v_mfma_f32_16x16x32_bf16 v[28:31], v[204:207], v[180:183], v[28:31]
	v_mfma_f32_16x16x32_bf16 v[24:27], v[212:215], v[180:183], v[24:27]
	v_mfma_f32_16x16x32_bf16 v[12:15], v[204:207], v[188:191], v[12:15]
	v_mfma_f32_16x16x32_bf16 v[8:11], v[212:215], v[188:191], v[8:11]
	v_mfma_f32_16x16x32_bf16 v[4:7], v[204:207], v[196:199], v[4:7]
	v_mfma_f32_16x16x32_bf16 v[0:3], v[212:215], v[196:199], v[0:3]
	v_mfma_f32_16x16x32_bf16 v[44:47], v[208:211], v[176:179], v[44:47]
	v_mfma_f32_16x16x32_bf16 v[40:43], v[216:219], v[176:179], v[40:43]
	v_mfma_f32_16x16x32_bf16 v[28:31], v[208:211], v[184:187], v[28:31]
	v_mfma_f32_16x16x32_bf16 v[24:27], v[216:219], v[184:187], v[24:27]
	v_mfma_f32_16x16x32_bf16 v[12:15], v[208:211], v[192:195], v[12:15]
	v_mfma_f32_16x16x32_bf16 v[8:11], v[216:219], v[192:195], v[8:11]
	v_mfma_f32_16x16x32_bf16 v[4:7], v[208:211], v[200:203], v[4:7]
	v_mfma_f32_16x16x32_bf16 v[0:3], v[216:219], v[200:203], v[0:3]
	s_add_i32 s86, 0, 0x18000
	v_add_u32_e32 v155, s86, v150
	s_barrier
	ds_read_b128 v[156:159], v155
	ds_read_b128 v[160:163], v155 offset:1024
	ds_read_b128 v[164:167], v155 offset:2048
	ds_read_b128 v[168:171], v155 offset:3072
	s_add_u32 s54, s54, 0x100000
	s_addc_u32 s55, s55, 0
	s_mov_b32 m0, s62
	v_lshl_add_u64 v[204:205], s[54:55], 0, v[136:137]
	ds_read_b128 v[172:175], v153 offset:32768
	ds_read_b128 v[176:179], v153 offset:33792
	ds_read_b128 v[180:183], v153 offset:34816
	ds_read_b128 v[184:187], v153 offset:35840
	ds_read_b128 v[188:191], v153 offset:36864
	ds_read_b128 v[192:195], v153 offset:37888
	ds_read_b128 v[196:199], v153 offset:38912
	ds_read_b128 v[200:203], v153 offset:39936
	global_load_lds_dwordx4 v[204:205], off
	v_lshl_add_u64 v[204:205], s[54:55], 0, v[132:133]
	s_mov_b32 m0, s63
	s_nop 0
	global_load_lds_dwordx4 v[204:205], off
	s_waitcnt lgkmcnt(8)
	s_barrier
	s_waitcnt lgkmcnt(0)
	s_waitcnt lgkmcnt(0)
	v_mfma_f32_16x16x32_bf16 v[124:127], v[156:159], v[172:175], v[124:127]
	v_mfma_f32_16x16x32_bf16 v[120:123], v[164:167], v[172:175], v[120:123]
	v_mfma_f32_16x16x32_bf16 v[116:119], v[156:159], v[180:183], v[116:119]
	v_mfma_f32_16x16x32_bf16 v[112:115], v[164:167], v[180:183], v[112:115]
	v_mfma_f32_16x16x32_bf16 v[100:103], v[156:159], v[188:191], v[100:103]
	v_mfma_f32_16x16x32_bf16 v[96:99], v[164:167], v[188:191], v[96:99]
	v_mfma_f32_16x16x32_bf16 v[84:87], v[156:159], v[196:199], v[84:87]
	v_mfma_f32_16x16x32_bf16 v[80:83], v[164:167], v[196:199], v[80:83]
	v_mfma_f32_16x16x32_bf16 v[124:127], v[160:163], v[176:179], v[124:127]
	v_mfma_f32_16x16x32_bf16 v[120:123], v[168:171], v[176:179], v[120:123]
	v_mfma_f32_16x16x32_bf16 v[116:119], v[160:163], v[184:187], v[116:119]
	v_mfma_f32_16x16x32_bf16 v[112:115], v[168:171], v[184:187], v[112:115]
	v_mfma_f32_16x16x32_bf16 v[100:103], v[160:163], v[192:195], v[100:103]
	v_mfma_f32_16x16x32_bf16 v[96:99], v[168:171], v[192:195], v[96:99]
	v_mfma_f32_16x16x32_bf16 v[84:87], v[160:163], v[200:203], v[84:87]
	v_mfma_f32_16x16x32_bf16 v[80:83], v[168:171], v[200:203], v[80:83]
	s_barrier
	s_add_i32 s54, 0, 0x1c000
	s_add_i32 s55, s86, s57
	v_add_u32_e32 v155, s54, v150
	v_lshl_add_u64 v[220:221], v[220:221], 0, s[8:9]
	s_mov_b32 m0, s55
	ds_read_b128 v[204:207], v155
	ds_read_b128 v[208:211], v155 offset:1024
	ds_read_b128 v[212:215], v155 offset:2048
	ds_read_b128 v[216:219], v155 offset:3072
	global_load_lds_dwordx4 v[220:221], off
	v_lshl_add_u64 v[220:221], v[222:223], 0, s[8:9]
	s_add_i32 m0, s55, 0x2000
	s_nop 0
	global_load_lds_dwordx4 v[220:221], off
	s_cmp_lg_u32 s94, 0
	s_cbranch_scc0 .Lrx5c
	s_waitcnt vmcnt(10)
	s_mov_b32 s94, 0
.Lrx5c:
	s_barrier
	s_waitcnt lgkmcnt(0)
	s_waitcnt lgkmcnt(0)
	v_mfma_f32_16x16x32_bf16 v[108:111], v[204:207], v[172:175], v[108:111]
	v_mfma_f32_16x16x32_bf16 v[104:107], v[212:215], v[172:175], v[104:107]
	v_mfma_f32_16x16x32_bf16 v[92:95], v[204:207], v[180:183], v[92:95]
	v_mfma_f32_16x16x32_bf16 v[88:91], v[212:215], v[180:183], v[88:91]
	v_mfma_f32_16x16x32_bf16 v[76:79], v[204:207], v[188:191], v[76:79]
	v_mfma_f32_16x16x32_bf16 v[72:75], v[212:215], v[188:191], v[72:75]
	v_mfma_f32_16x16x32_bf16 v[68:71], v[204:207], v[196:199], v[68:71]
	v_mfma_f32_16x16x32_bf16 v[64:67], v[212:215], v[196:199], v[64:67]
	v_mfma_f32_16x16x32_bf16 v[108:111], v[208:211], v[176:179], v[108:111]
	v_mfma_f32_16x16x32_bf16 v[104:107], v[216:219], v[176:179], v[104:107]
	v_mfma_f32_16x16x32_bf16 v[92:95], v[208:211], v[184:187], v[92:95]
	v_mfma_f32_16x16x32_bf16 v[88:91], v[216:219], v[184:187], v[88:91]
	v_mfma_f32_16x16x32_bf16 v[76:79], v[208:211], v[192:195], v[76:79]
	v_mfma_f32_16x16x32_bf16 v[72:75], v[216:219], v[192:195], v[72:75]
	v_mfma_f32_16x16x32_bf16 v[68:71], v[208:211], v[200:203], v[68:71]
	v_mfma_f32_16x16x32_bf16 v[64:67], v[216:219], v[200:203], v[64:67]
	s_mov_b32 m0, s71
	v_lshl_add_u64 v[220:221], v[224:225], 0, s[8:9]
	s_barrier
	ds_read_b128 v[172:175], v153 offset:49152
	ds_read_b128 v[176:179], v153 offset:50176
	ds_read_b128 v[180:183], v153 offset:51200
	ds_read_b128 v[184:187], v153 offset:52224
	ds_read_b128 v[188:191], v153 offset:53248
	ds_read_b128 v[192:195], v153 offset:54272
	ds_read_b128 v[196:199], v153 offset:55296
	ds_read_b128 v[200:203], v153 offset:56320
	global_load_lds_dwordx4 v[220:221], off
	v_lshl_add_u64 v[220:221], v[226:227], 0, s[8:9]
	s_mov_b32 m0, s72
	s_nop 0
	global_load_lds_dwordx4 v[220:221], off
	s_barrier
	s_waitcnt lgkmcnt(0)
	s_waitcnt lgkmcnt(0)
	v_mfma_f32_16x16x32_bf16 v[60:63], v[156:159], v[172:175], v[60:63]
	v_mfma_f32_16x16x32_bf16 v[56:59], v[164:167], v[172:175], v[56:59]
	v_mfma_f32_16x16x32_bf16 v[52:55], v[156:159], v[180:183], v[52:55]
	v_mfma_f32_16x16x32_bf16 v[48:51], v[164:167], v[180:183], v[48:51]
	v_mfma_f32_16x16x32_bf16 v[36:39], v[156:159], v[188:191], v[36:39]
	v_mfma_f32_16x16x32_bf16 v[32:35], v[164:167], v[188:191], v[32:35]
	v_mfma_f32_16x16x32_bf16 v[20:23], v[156:159], v[196:199], v[20:23]
	v_mfma_f32_16x16x32_bf16 v[16:19], v[164:167], v[196:199], v[16:19]
	v_mfma_f32_16x16x32_bf16 v[60:63], v[160:163], v[176:179], v[60:63]
	v_mfma_f32_16x16x32_bf16 v[56:59], v[168:171], v[176:179], v[56:59]
	v_mfma_f32_16x16x32_bf16 v[52:55], v[160:163], v[184:187], v[52:55]
	v_mfma_f32_16x16x32_bf16 v[48:51], v[168:171], v[184:187], v[48:51]
	v_mfma_f32_16x16x32_bf16 v[36:39], v[160:163], v[192:195], v[36:39]
	v_mfma_f32_16x16x32_bf16 v[32:35], v[168:171], v[192:195], v[32:35]
	v_mfma_f32_16x16x32_bf16 v[20:23], v[160:163], v[200:203], v[20:23]
	v_mfma_f32_16x16x32_bf16 v[16:19], v[168:171], v[200:203], v[16:19]
	s_barrier
	s_add_u32 s34, s34, 0x100080
	s_addc_u32 s35, s35, 0
	s_add_i32 s54, s54, s57
	v_lshl_add_u64 v[156:157], s[34:35], 0, v[134:135]
	s_mov_b32 m0, s54
	s_nop 0
	global_load_lds_dwordx4 v[156:157], off
	v_lshl_add_u64 v[156:157], s[34:35], 0, v[130:131]
	s_add_i32 m0, s54, 0x2000
	s_nop 0
	global_load_lds_dwordx4 v[156:157], off
	s_waitcnt vmcnt(6)
	s_barrier
	v_mfma_f32_16x16x32_bf16 v[44:47], v[204:207], v[172:175], v[44:47]
	v_mfma_f32_16x16x32_bf16 v[40:43], v[212:215], v[172:175], v[40:43]
	v_mfma_f32_16x16x32_bf16 v[28:31], v[204:207], v[180:183], v[28:31]
	v_mfma_f32_16x16x32_bf16 v[24:27], v[212:215], v[180:183], v[24:27]
	v_mfma_f32_16x16x32_bf16 v[12:15], v[204:207], v[188:191], v[12:15]
	v_mfma_f32_16x16x32_bf16 v[8:11], v[212:215], v[188:191], v[8:11]
	v_mfma_f32_16x16x32_bf16 v[4:7], v[204:207], v[196:199], v[4:7]
	v_mfma_f32_16x16x32_bf16 v[0:3], v[212:215], v[196:199], v[0:3]
	v_mfma_f32_16x16x32_bf16 v[44:47], v[208:211], v[176:179], v[44:47]
	v_mfma_f32_16x16x32_bf16 v[40:43], v[216:219], v[176:179], v[40:43]
	v_mfma_f32_16x16x32_bf16 v[28:31], v[208:211], v[184:187], v[28:31]
	v_mfma_f32_16x16x32_bf16 v[24:27], v[216:219], v[184:187], v[24:27]
	v_mfma_f32_16x16x32_bf16 v[12:15], v[208:211], v[192:195], v[12:15]
	v_mfma_f32_16x16x32_bf16 v[8:11], v[216:219], v[192:195], v[8:11]
	v_mfma_f32_16x16x32_bf16 v[4:7], v[208:211], v[200:203], v[4:7]
	v_mfma_f32_16x16x32_bf16 v[0:3], v[216:219], v[200:203], v[0:3]
	s_add_i32 s85, s85, 2
	s_add_u32 s30, s30, 0x100
	s_addc_u32 s31, s31, 0
	s_add_u32 s83, s83, 0x100
	s_addc_u32 s84, s84, 0
	s_cmp_gt_u32 s85, 61
	s_barrier
	s_cbranch_scc0 .LBB0_776
	v_lshl_add_u32 v156, s16, 8, v149
	v_lshl_or_b32 v158, s80, 8, v151
	v_ashrrev_i32_e32 v157, 31, v156
	v_lshlrev_b64 v[160:161], 11, v[156:157]
	v_ashrrev_i32_e32 v159, 31, v158
	v_lshl_add_u64 v[160:161], s[44:45], 0, v[160:161]
	v_cvt_pk_bf16_f32 v124, v124, v125
	v_cvt_pk_bf16_f32 v125, v126, v127
	v_cvt_pk_bf16_f32 v126, v120, v121
	v_lshlrev_b64 v[120:121], 1, v[158:159]
	v_cvt_pk_bf16_f32 v127, v122, v123
	v_lshl_add_u64 v[122:123], v[160:161], 0, v[120:121]
	v_cvt_pk_bf16_f32 v108, v108, v109
	v_cvt_pk_bf16_f32 v109, v110, v111
	v_cvt_pk_bf16_f32 v110, v104, v105
	v_or_b32_e32 v104, 16, v156
	v_cvt_pk_bf16_f32 v60, v60, v61
	v_cvt_pk_bf16_f32 v61, v62, v63
	v_cvt_pk_bf16_f32 v63, v58, v59
	s_mov_b64 s[30:31], 0x40000
	v_add_co_u32_e32 v58, vcc, s76, v122
	v_ashrrev_i32_e32 v105, 31, v104
	v_cvt_pk_bf16_f32 v62, v56, v57
	v_lshl_add_u64 v[56:57], v[122:123], 0, s[30:31]
	v_addc_co_u32_e32 v59, vcc, 0, v123, vcc
	v_cvt_pk_bf16_f32 v44, v44, v45
	v_cvt_pk_bf16_f32 v45, v46, v47
	v_cvt_pk_bf16_f32 v46, v40, v41
	v_cvt_pk_bf16_f32 v47, v42, v43
	v_cvt_pk_bf16_f32 v111, v106, v107
	v_lshlrev_b64 v[104:105], 11, v[104:105]
	v_cvt_pk_bf16_f32 v92, v92, v93
	v_cvt_pk_bf16_f32 v93, v94, v95
	v_cvt_pk_bf16_f32 v94, v88, v89
	v_or_b32_e32 v88, 32, v156
	global_store_dwordx4 v[56:57], v[44:47], off offset:256
	global_store_dwordx4 v[122:123], v[108:111], off offset:256
	v_ashrrev_i32_e32 v89, 31, v88
	v_add_co_u32_e32 v46, vcc, s77, v122
	v_lshl_add_u64 v[108:109], s[44:45], 0, v[104:105]
	v_lshl_add_u64 v[44:45], v[122:123], 0, s[10:11]
	v_addc_co_u32_e32 v47, vcc, 0, v123, vcc
	v_cvt_pk_bf16_f32 v28, v28, v29
	v_cvt_pk_bf16_f32 v29, v30, v31
	v_cvt_pk_bf16_f32 v30, v24, v25
	v_cvt_pk_bf16_f32 v31, v26, v27
	v_lshl_add_u64 v[108:109], v[108:109], 0, v[120:121]
	v_cvt_pk_bf16_f32 v95, v90, v91
	v_lshlrev_b64 v[88:89], 11, v[88:89]
	v_cvt_pk_bf16_f32 v76, v76, v77
	v_cvt_pk_bf16_f32 v77, v78, v79
	v_cvt_pk_bf16_f32 v78, v72, v73
	v_or_b32_e32 v72, 48, v156
	global_store_dwordx4 v[44:45], v[28:31], off offset:256
	global_store_dwordx4 v[108:109], v[92:95], off offset:256
	v_ashrrev_i32_e32 v73, 31, v72
	v_add_co_u32_e32 v30, vcc, s78, v122
	v_lshl_add_u64 v[92:93], s[44:45], 0, v[88:89]
	v_lshl_add_u64 v[28:29], v[122:123], 0, s[12:13]
	v_addc_co_u32_e32 v31, vcc, 0, v123, vcc
	v_cvt_pk_bf16_f32 v12, v12, v13
	v_cvt_pk_bf16_f32 v13, v14, v15
	v_cvt_pk_bf16_f32 v14, v8, v9
	v_cvt_pk_bf16_f32 v15, v10, v11
	v_lshl_add_u64 v[92:93], v[92:93], 0, v[120:121]
	v_cvt_pk_bf16_f32 v79, v74, v75
	v_lshlrev_b64 v[72:73], 11, v[72:73]
	global_store_dwordx4 v[28:29], v[12:15], off offset:256
	global_store_dwordx4 v[92:93], v[76:79], off offset:256
	v_cvt_pk_bf16_f32 v104, v116, v117
	v_add_co_u32_e32 v14, vcc, s79, v122
	v_lshl_add_u64 v[76:77], s[44:45], 0, v[72:73]
	s_nop 0
	v_addc_co_u32_e32 v15, vcc, 0, v123, vcc
	v_cvt_pk_bf16_f32 v105, v118, v119
	v_cvt_pk_bf16_f32 v106, v112, v113
	v_cvt_pk_bf16_f32 v107, v114, v115
	v_cvt_pk_bf16_f32 v88, v100, v101
	v_cvt_pk_bf16_f32 v89, v102, v103
	v_cvt_pk_bf16_f32 v90, v96, v97
	v_cvt_pk_bf16_f32 v91, v98, v99
	v_cvt_pk_bf16_f32 v72, v84, v85
	v_cvt_pk_bf16_f32 v73, v86, v87
	v_cvt_pk_bf16_f32 v74, v80, v81
	v_cvt_pk_bf16_f32 v75, v82, v83
	v_lshl_add_u64 v[76:77], v[76:77], 0, v[120:121]
	v_cvt_pk_bf16_f32 v68, v68, v69
	v_cvt_pk_bf16_f32 v69, v70, v71
	v_cvt_pk_bf16_f32 v70, v64, v65
	v_cvt_pk_bf16_f32 v71, v66, v67
	v_cvt_pk_bf16_f32 v40, v52, v53
	v_cvt_pk_bf16_f32 v41, v54, v55
	v_cvt_pk_bf16_f32 v42, v48, v49
	v_cvt_pk_bf16_f32 v43, v50, v51
	v_cvt_pk_bf16_f32 v24, v36, v37
	v_cvt_pk_bf16_f32 v25, v38, v39
	v_cvt_pk_bf16_f32 v26, v32, v33
	v_cvt_pk_bf16_f32 v27, v34, v35
	v_cvt_pk_bf16_f32 v8, v20, v21
	v_cvt_pk_bf16_f32 v9, v22, v23
	v_cvt_pk_bf16_f32 v10, v16, v17
	v_cvt_pk_bf16_f32 v11, v18, v19
	v_lshl_add_u64 v[12:13], v[122:123], 0, s[14:15]
	v_cvt_pk_bf16_f32 v4, v4, v5
	v_cvt_pk_bf16_f32 v5, v6, v7
	v_cvt_pk_bf16_f32 v6, v0, v1
	v_cvt_pk_bf16_f32 v7, v2, v3
	s_and_b64 vcc, exec, s[4:5]
	s_mov_b32 s80, s18
	s_mov_b32 s16, s20
	s_mov_b64 s[34:35], s[28:29]
	s_mov_b64 s[30:31], s[26:27]
	global_store_dwordx4 v[122:123], v[124:127], off
	global_store_dwordx4 v[108:109], v[104:107], off
	global_store_dwordx4 v[92:93], v[88:91], off
	global_store_dwordx4 v[76:77], v[72:75], off
	global_store_dwordx4 v[76:77], v[68:71], off offset:256
	global_store_dwordx4 v[58:59], v[60:63], off
	global_store_dwordx4 v[46:47], v[40:43], off
	global_store_dwordx4 v[30:31], v[24:27], off
	global_store_dwordx4 v[14:15], v[8:11], off
	global_store_dwordx4 v[12:13], v[4:7], off offset:256
	s_mov_b32 s94, 1
	s_cbranch_vccz .LBB0_773
	s_mov_b32 s94, 0
	s_waitcnt vmcnt(16)
	s_cmpk_gt_u32 s56, 0xff
	s_cbranch_scc1 .LBB0_780
	s_barrier

.LBB0_912:
	ds_read_b128 v[156:159], v152
	ds_read_b128 v[160:163], v152 offset:1024
	ds_read_b128 v[164:167], v152 offset:2048
	ds_read_b128 v[168:171], v152 offset:3072
	s_add_u32 s54, s34, 0xfffc0080
	s_addc_u32 s55, s35, -1
	s_cmp_eq_u32 s87, 12
	s_cselect_b32 s57, s27, s55
	s_cselect_b32 s56, s83, s54
	s_cselect_b32 s55, s21, s86
	s_cselect_b32 s54, s84, s85
	v_lshl_add_u64 v[204:205], s[34:35], 0, v[138:139]
	s_add_i32 m0, s19, 0xc000
	ds_read_b128 v[172:175], v153
	ds_read_b128 v[176:179], v153 offset:1024
	ds_read_b128 v[180:183], v153 offset:2048
	ds_read_b128 v[184:187], v153 offset:3072
	ds_read_b128 v[188:191], v153 offset:4096
	ds_read_b128 v[192:195], v153 offset:5120
	ds_read_b128 v[196:199], v153 offset:6144
	ds_read_b128 v[200:203], v153 offset:7168
	global_load_lds_dwordx4 v[204:205], off
	v_lshl_add_u64 v[204:205], s[34:35], 0, v[140:141]
	s_add_i32 m0, s19, 0xe000
	s_nop 0
	global_load_lds_dwordx4 v[204:205], off
	s_waitcnt lgkmcnt(8)
	s_barrier
	s_waitcnt lgkmcnt(0)
	s_waitcnt lgkmcnt(0)
	v_mfma_f32_16x16x32_bf16 v[124:127], v[156:159], v[172:175], v[124:127]
	v_mfma_f32_16x16x32_bf16 v[120:123], v[164:167], v[172:175], v[120:123]
	v_mfma_f32_16x16x32_bf16 v[116:119], v[156:159], v[180:183], v[116:119]
	v_mfma_f32_16x16x32_bf16 v[112:115], v[164:167], v[180:183], v[112:115]
	v_mfma_f32_16x16x32_bf16 v[100:103], v[156:159], v[188:191], v[100:103]
	v_mfma_f32_16x16x32_bf16 v[96:99], v[164:167], v[188:191], v[96:99]
	v_mfma_f32_16x16x32_bf16 v[84:87], v[156:159], v[196:199], v[84:87]
	v_mfma_f32_16x16x32_bf16 v[80:83], v[164:167], v[196:199], v[80:83]
	v_mfma_f32_16x16x32_bf16 v[124:127], v[160:163], v[176:179], v[124:127]
	v_mfma_f32_16x16x32_bf16 v[120:123], v[168:171], v[176:179], v[120:123]
	v_mfma_f32_16x16x32_bf16 v[116:119], v[160:163], v[184:187], v[116:119]
	v_mfma_f32_16x16x32_bf16 v[112:115], v[168:171], v[184:187], v[112:115]
	v_mfma_f32_16x16x32_bf16 v[100:103], v[160:163], v[192:195], v[100:103]
	v_mfma_f32_16x16x32_bf16 v[96:99], v[168:171], v[192:195], v[96:99]
	v_mfma_f32_16x16x32_bf16 v[84:87], v[160:163], v[200:203], v[84:87]
	v_mfma_f32_16x16x32_bf16 v[80:83], v[168:171], v[200:203], v[80:83]
	s_barrier
	s_add_i32 s88, s76, s61
	v_lshl_add_u64 v[220:221], s[54:55], 0, v[134:135]
	s_mov_b32 m0, s88
	ds_read_b128 v[204:207], v154
	ds_read_b128 v[208:211], v154 offset:1024
	ds_read_b128 v[212:215], v154 offset:2048
	ds_read_b128 v[216:219], v154 offset:3072
	global_load_lds_dwordx4 v[220:221], off
	v_lshl_add_u64 v[222:223], s[54:55], 0, v[130:131]
	s_add_i32 m0, s88, 0x2000
	s_nop 0
	global_load_lds_dwordx4 v[222:223], off
	s_barrier
	s_waitcnt lgkmcnt(0)
	s_waitcnt lgkmcnt(0)
	v_mfma_f32_16x16x32_bf16 v[108:111], v[204:207], v[172:175], v[108:111]
	v_mfma_f32_16x16x32_bf16 v[104:107], v[212:215], v[172:175], v[104:107]
	v_mfma_f32_16x16x32_bf16 v[92:95], v[204:207], v[180:183], v[92:95]
	v_mfma_f32_16x16x32_bf16 v[88:91], v[212:215], v[180:183], v[88:91]
	v_mfma_f32_16x16x32_bf16 v[76:79], v[204:207], v[188:191], v[76:79]
	v_mfma_f32_16x16x32_bf16 v[72:75], v[212:215], v[188:191], v[72:75]
	v_mfma_f32_16x16x32_bf16 v[68:71], v[204:207], v[196:199], v[68:71]
	v_mfma_f32_16x16x32_bf16 v[64:67], v[212:215], v[196:199], v[64:67]
	v_mfma_f32_16x16x32_bf16 v[108:111], v[208:211], v[176:179], v[108:111]
	v_mfma_f32_16x16x32_bf16 v[104:107], v[216:219], v[176:179], v[104:107]
	v_mfma_f32_16x16x32_bf16 v[92:95], v[208:211], v[184:187], v[92:95]
	v_mfma_f32_16x16x32_bf16 v[88:91], v[216:219], v[184:187], v[88:91]
	v_mfma_f32_16x16x32_bf16 v[76:79], v[208:211], v[192:195], v[76:79]
	v_mfma_f32_16x16x32_bf16 v[72:75], v[216:219], v[192:195], v[72:75]
	v_mfma_f32_16x16x32_bf16 v[68:71], v[208:211], v[200:203], v[68:71]
	v_mfma_f32_16x16x32_bf16 v[64:67], v[216:219], v[200:203], v[64:67]
	s_mov_b32 m0, s19
	v_lshl_add_u64 v[224:225], s[56:57], 0, v[136:137]
	s_barrier
	ds_read_b128 v[172:175], v153 offset:16384
	ds_read_b128 v[176:179], v153 offset:17408
	ds_read_b128 v[180:183], v153 offset:18432
	ds_read_b128 v[184:187], v153 offset:19456
	ds_read_b128 v[188:191], v153 offset:20480
	ds_read_b128 v[192:195], v153 offset:21504
	ds_read_b128 v[196:199], v153 offset:22528
	ds_read_b128 v[200:203], v153 offset:23552
	global_load_lds_dwordx4 v[224:225], off
	v_lshl_add_u64 v[226:227], s[56:57], 0, v[132:133]
	s_mov_b32 m0, s63
	s_nop 0
	global_load_lds_dwordx4 v[226:227], off
	s_barrier
	s_waitcnt lgkmcnt(0)
	s_waitcnt lgkmcnt(0)
	v_mfma_f32_16x16x32_bf16 v[60:63], v[156:159], v[172:175], v[60:63]
	v_mfma_f32_16x16x32_bf16 v[56:59], v[164:167], v[172:175], v[56:59]
	v_mfma_f32_16x16x32_bf16 v[52:55], v[156:159], v[180:183], v[52:55]
	v_mfma_f32_16x16x32_bf16 v[48:51], v[164:167], v[180:183], v[48:51]
	v_mfma_f32_16x16x32_bf16 v[36:39], v[156:159], v[188:191], v[36:39]
	v_mfma_f32_16x16x32_bf16 v[32:35], v[164:167], v[188:191], v[32:35]
	v_mfma_f32_16x16x32_bf16 v[20:23], v[156:159], v[196:199], v[20:23]
	v_mfma_f32_16x16x32_bf16 v[16:19], v[164:167], v[196:199], v[16:19]
	v_mfma_f32_16x16x32_bf16 v[60:63], v[160:163], v[176:179], v[60:63]
	v_mfma_f32_16x16x32_bf16 v[56:59], v[168:171], v[176:179], v[56:59]
	v_mfma_f32_16x16x32_bf16 v[52:55], v[160:163], v[184:187], v[52:55]
	v_mfma_f32_16x16x32_bf16 v[48:51], v[168:171], v[184:187], v[48:51]
	v_mfma_f32_16x16x32_bf16 v[36:39], v[160:163], v[192:195], v[36:39]
	v_mfma_f32_16x16x32_bf16 v[32:35], v[168:171], v[192:195], v[32:35]
	v_mfma_f32_16x16x32_bf16 v[20:23], v[160:163], v[200:203], v[20:23]
	v_mfma_f32_16x16x32_bf16 v[16:19], v[168:171], v[200:203], v[16:19]
	s_barrier
	s_add_u32 s88, s54, 0x40000
	s_addc_u32 s89, s55, 0
	s_add_i32 s90, s77, s61
	v_lshl_add_u64 v[156:157], s[88:89], 0, v[134:135]
	s_mov_b32 m0, s90
	s_nop 0
	global_load_lds_dwordx4 v[156:157], off
	v_lshl_add_u64 v[156:157], s[88:89], 0, v[130:131]
	s_add_i32 m0, s90, 0x2000
	s_nop 0
	global_load_lds_dwordx4 v[156:157], off
	s_cmp_lg_u32 s94, 0
	s_cbranch_scc1 .Lrx6a
	s_waitcnt vmcnt(6)
.Lrx6a:
	s_waitcnt vmcnt(24)
	s_barrier
	v_mfma_f32_16x16x32_bf16 v[44:47], v[204:207], v[172:175], v[44:47]
	v_mfma_f32_16x16x32_bf16 v[40:43], v[212:215], v[172:175], v[40:43]
	v_mfma_f32_16x16x32_bf16 v[28:31], v[204:207], v[180:183], v[28:31]
	v_mfma_f32_16x16x32_bf16 v[24:27], v[212:215], v[180:183], v[24:27]
	v_mfma_f32_16x16x32_bf16 v[12:15], v[204:207], v[188:191], v[12:15]
	v_mfma_f32_16x16x32_bf16 v[8:11], v[212:215], v[188:191], v[8:11]
	v_mfma_f32_16x16x32_bf16 v[4:7], v[204:207], v[196:199], v[4:7]
	v_mfma_f32_16x16x32_bf16 v[0:3], v[212:215], v[196:199], v[0:3]
	v_mfma_f32_16x16x32_bf16 v[44:47], v[208:211], v[176:179], v[44:47]
	v_mfma_f32_16x16x32_bf16 v[40:43], v[216:219], v[176:179], v[40:43]
	v_mfma_f32_16x16x32_bf16 v[28:31], v[208:211], v[184:187], v[28:31]
	v_mfma_f32_16x16x32_bf16 v[24:27], v[216:219], v[184:187], v[24:27]
	v_mfma_f32_16x16x32_bf16 v[12:15], v[208:211], v[192:195], v[12:15]
	v_mfma_f32_16x16x32_bf16 v[8:11], v[216:219], v[192:195], v[8:11]
	v_mfma_f32_16x16x32_bf16 v[4:7], v[208:211], v[200:203], v[4:7]
	v_mfma_f32_16x16x32_bf16 v[0:3], v[216:219], v[200:203], v[0:3]
	s_add_i32 s88, 0, 0x18000
	v_add_u32_e32 v155, s88, v150
	s_barrier
	ds_read_b128 v[156:159], v155
	ds_read_b128 v[160:163], v155 offset:1024
	ds_read_b128 v[164:167], v155 offset:2048
	ds_read_b128 v[168:171], v155 offset:3072
	s_add_u32 s56, s56, 0x40000
	s_addc_u32 s57, s57, 0
	s_mov_b32 m0, s70
	v_lshl_add_u64 v[204:205], s[56:57], 0, v[136:137]
	ds_read_b128 v[172:175], v153 offset:32768
	ds_read_b128 v[176:179], v153 offset:33792
	ds_read_b128 v[180:183], v153 offset:34816
	ds_read_b128 v[184:187], v153 offset:35840
	ds_read_b128 v[188:191], v153 offset:36864
	ds_read_b128 v[192:195], v153 offset:37888
	ds_read_b128 v[196:199], v153 offset:38912
	ds_read_b128 v[200:203], v153 offset:39936
	global_load_lds_dwordx4 v[204:205], off
	v_lshl_add_u64 v[204:205], s[56:57], 0, v[132:133]
	s_mov_b32 m0, s71
	s_nop 0
	global_load_lds_dwordx4 v[204:205], off
	s_waitcnt lgkmcnt(8)
	s_barrier
	s_waitcnt lgkmcnt(0)
	s_waitcnt lgkmcnt(0)
	v_mfma_f32_16x16x32_bf16 v[124:127], v[156:159], v[172:175], v[124:127]
	v_mfma_f32_16x16x32_bf16 v[120:123], v[164:167], v[172:175], v[120:123]
	v_mfma_f32_16x16x32_bf16 v[116:119], v[156:159], v[180:183], v[116:119]
	v_mfma_f32_16x16x32_bf16 v[112:115], v[164:167], v[180:183], v[112:115]
	v_mfma_f32_16x16x32_bf16 v[100:103], v[156:159], v[188:191], v[100:103]
	v_mfma_f32_16x16x32_bf16 v[96:99], v[164:167], v[188:191], v[96:99]
	v_mfma_f32_16x16x32_bf16 v[84:87], v[156:159], v[196:199], v[84:87]
	v_mfma_f32_16x16x32_bf16 v[80:83], v[164:167], v[196:199], v[80:83]
	v_mfma_f32_16x16x32_bf16 v[124:127], v[160:163], v[176:179], v[124:127]
	v_mfma_f32_16x16x32_bf16 v[120:123], v[168:171], v[176:179], v[120:123]
	v_mfma_f32_16x16x32_bf16 v[116:119], v[160:163], v[184:187], v[116:119]
	v_mfma_f32_16x16x32_bf16 v[112:115], v[168:171], v[184:187], v[112:115]
	v_mfma_f32_16x16x32_bf16 v[100:103], v[160:163], v[192:195], v[100:103]
	v_mfma_f32_16x16x32_bf16 v[96:99], v[168:171], v[192:195], v[96:99]
	v_mfma_f32_16x16x32_bf16 v[84:87], v[160:163], v[200:203], v[84:87]
	v_mfma_f32_16x16x32_bf16 v[80:83], v[168:171], v[200:203], v[80:83]
	s_barrier
	s_add_i32 s56, 0, 0x1c000
	s_add_i32 s57, s88, s61
	v_add_u32_e32 v155, s56, v150
	v_lshl_add_u64 v[220:221], v[220:221], 0, s[10:11]
	s_mov_b32 m0, s57
	ds_read_b128 v[204:207], v155
	ds_read_b128 v[208:211], v155 offset:1024
	ds_read_b128 v[212:215], v155 offset:2048
	ds_read_b128 v[216:219], v155 offset:3072
	global_load_lds_dwordx4 v[220:221], off
	v_lshl_add_u64 v[220:221], v[222:223], 0, s[10:11]
	s_add_i32 m0, s57, 0x2000
	s_nop 0
	global_load_lds_dwordx4 v[220:221], off
	s_cmp_lg_u32 s94, 0
	s_cbranch_scc0 .Lrx6c
	s_waitcnt vmcnt(10)
	s_mov_b32 s94, 0
.Lrx6c:
	s_barrier
	s_waitcnt lgkmcnt(0)
	s_waitcnt lgkmcnt(0)
	v_mfma_f32_16x16x32_bf16 v[108:111], v[204:207], v[172:175], v[108:111]
	v_mfma_f32_16x16x32_bf16 v[104:107], v[212:215], v[172:175], v[104:107]
	v_mfma_f32_16x16x32_bf16 v[92:95], v[204:207], v[180:183], v[92:95]
	v_mfma_f32_16x16x32_bf16 v[88:91], v[212:215], v[180:183], v[88:91]
	v_mfma_f32_16x16x32_bf16 v[76:79], v[204:207], v[188:191], v[76:79]
	v_mfma_f32_16x16x32_bf16 v[72:75], v[212:215], v[188:191], v[72:75]
	v_mfma_f32_16x16x32_bf16 v[68:71], v[204:207], v[196:199], v[68:71]
	v_mfma_f32_16x16x32_bf16 v[64:67], v[212:215], v[196:199], v[64:67]
	v_mfma_f32_16x16x32_bf16 v[108:111], v[208:211], v[176:179], v[108:111]
	v_mfma_f32_16x16x32_bf16 v[104:107], v[216:219], v[176:179], v[104:107]
	v_mfma_f32_16x16x32_bf16 v[92:95], v[208:211], v[184:187], v[92:95]
	v_mfma_f32_16x16x32_bf16 v[88:91], v[216:219], v[184:187], v[88:91]
	v_mfma_f32_16x16x32_bf16 v[76:79], v[208:211], v[192:195], v[76:79]
	v_mfma_f32_16x16x32_bf16 v[72:75], v[216:219], v[192:195], v[72:75]
	v_mfma_f32_16x16x32_bf16 v[68:71], v[208:211], v[200:203], v[68:71]
	v_mfma_f32_16x16x32_bf16 v[64:67], v[216:219], v[200:203], v[64:67]
	s_mov_b32 m0, s73
	v_lshl_add_u64 v[220:221], v[224:225], 0, s[10:11]
	s_barrier
	ds_read_b128 v[172:175], v153 offset:49152
	ds_read_b128 v[176:179], v153 offset:50176
	ds_read_b128 v[180:183], v153 offset:51200
	ds_read_b128 v[184:187], v153 offset:52224
	ds_read_b128 v[188:191], v153 offset:53248
	ds_read_b128 v[192:195], v153 offset:54272
	ds_read_b128 v[196:199], v153 offset:55296
	ds_read_b128 v[200:203], v153 offset:56320
	global_load_lds_dwordx4 v[220:221], off
	v_lshl_add_u64 v[220:221], v[226:227], 0, s[10:11]
	s_mov_b32 m0, s74
	s_nop 0
	global_load_lds_dwordx4 v[220:221], off
	s_barrier
	s_waitcnt lgkmcnt(0)
	s_waitcnt lgkmcnt(0)
	v_mfma_f32_16x16x32_bf16 v[60:63], v[156:159], v[172:175], v[60:63]
	v_mfma_f32_16x16x32_bf16 v[56:59], v[164:167], v[172:175], v[56:59]
	v_mfma_f32_16x16x32_bf16 v[52:55], v[156:159], v[180:183], v[52:55]
	v_mfma_f32_16x16x32_bf16 v[48:51], v[164:167], v[180:183], v[48:51]
	v_mfma_f32_16x16x32_bf16 v[36:39], v[156:159], v[188:191], v[36:39]
	v_mfma_f32_16x16x32_bf16 v[32:35], v[164:167], v[188:191], v[32:35]
	v_mfma_f32_16x16x32_bf16 v[20:23], v[156:159], v[196:199], v[20:23]
	v_mfma_f32_16x16x32_bf16 v[16:19], v[164:167], v[196:199], v[16:19]
	v_mfma_f32_16x16x32_bf16 v[60:63], v[160:163], v[176:179], v[60:63]
	v_mfma_f32_16x16x32_bf16 v[56:59], v[168:171], v[176:179], v[56:59]
	v_mfma_f32_16x16x32_bf16 v[52:55], v[160:163], v[184:187], v[52:55]
	v_mfma_f32_16x16x32_bf16 v[48:51], v[168:171], v[184:187], v[48:51]
	v_mfma_f32_16x16x32_bf16 v[36:39], v[160:163], v[192:195], v[36:39]
	v_mfma_f32_16x16x32_bf16 v[32:35], v[168:171], v[192:195], v[32:35]
	v_mfma_f32_16x16x32_bf16 v[20:23], v[160:163], v[200:203], v[20:23]
	v_mfma_f32_16x16x32_bf16 v[16:19], v[168:171], v[200:203], v[16:19]
	s_barrier
	s_add_u32 s54, s54, 0x40080
	s_addc_u32 s55, s55, 0
	s_add_i32 s56, s56, s61
	v_lshl_add_u64 v[156:157], s[54:55], 0, v[134:135]
	s_mov_b32 m0, s56
	s_nop 0
	global_load_lds_dwordx4 v[156:157], off
	v_lshl_add_u64 v[156:157], s[54:55], 0, v[130:131]
	s_add_i32 m0, s56, 0x2000
	s_nop 0
	global_load_lds_dwordx4 v[156:157], off
	s_waitcnt vmcnt(6)
	s_barrier
	v_mfma_f32_16x16x32_bf16 v[44:47], v[204:207], v[172:175], v[44:47]
	v_mfma_f32_16x16x32_bf16 v[40:43], v[212:215], v[172:175], v[40:43]
	v_mfma_f32_16x16x32_bf16 v[28:31], v[204:207], v[180:183], v[28:31]
	v_mfma_f32_16x16x32_bf16 v[24:27], v[212:215], v[180:183], v[24:27]
	v_mfma_f32_16x16x32_bf16 v[12:15], v[204:207], v[188:191], v[12:15]
	v_mfma_f32_16x16x32_bf16 v[8:11], v[212:215], v[188:191], v[8:11]
	v_mfma_f32_16x16x32_bf16 v[4:7], v[204:207], v[196:199], v[4:7]
	v_mfma_f32_16x16x32_bf16 v[0:3], v[212:215], v[196:199], v[0:3]
	v_mfma_f32_16x16x32_bf16 v[44:47], v[208:211], v[176:179], v[44:47]
	v_mfma_f32_16x16x32_bf16 v[40:43], v[216:219], v[176:179], v[40:43]
	v_mfma_f32_16x16x32_bf16 v[28:31], v[208:211], v[184:187], v[28:31]
	v_mfma_f32_16x16x32_bf16 v[24:27], v[216:219], v[184:187], v[24:27]
	v_mfma_f32_16x16x32_bf16 v[12:15], v[208:211], v[192:195], v[12:15]
	v_mfma_f32_16x16x32_bf16 v[8:11], v[216:219], v[192:195], v[8:11]
	v_mfma_f32_16x16x32_bf16 v[4:7], v[208:211], v[200:203], v[4:7]
	v_mfma_f32_16x16x32_bf16 v[0:3], v[216:219], v[200:203], v[0:3]
	s_add_i32 s87, s87, 2
	s_add_u32 s34, s34, 0x100
	s_addc_u32 s35, s35, 0
	s_add_u32 s85, s85, 0x100
	s_addc_u32 s86, s86, 0
	s_cmp_gt_u32 s87, 13
	s_barrier
	s_cbranch_scc0 .LBB0_912
	v_lshl_add_u32 v156, s18, 8, v149
	v_lshl_or_b32 v158, s82, 8, v151
	v_ashrrev_i32_e32 v157, 31, v156
	v_lshlrev_b64 v[160:161], 11, v[156:157]
	v_ashrrev_i32_e32 v159, 31, v158
	v_lshl_add_u64 v[160:161], s[46:47], 0, v[160:161]
	v_cvt_pk_bf16_f32 v124, v124, v125
	v_cvt_pk_bf16_f32 v125, v126, v127
	v_cvt_pk_bf16_f32 v126, v120, v121
	v_lshlrev_b64 v[120:121], 1, v[158:159]
	v_cvt_pk_bf16_f32 v127, v122, v123
	v_lshl_add_u64 v[122:123], v[160:161], 0, v[120:121]
	v_cvt_pk_bf16_f32 v108, v108, v109
	v_cvt_pk_bf16_f32 v109, v110, v111
	v_cvt_pk_bf16_f32 v110, v104, v105
	v_or_b32_e32 v104, 16, v156
	v_cvt_pk_bf16_f32 v60, v60, v61
	v_cvt_pk_bf16_f32 v61, v62, v63
	v_cvt_pk_bf16_f32 v63, v58, v59
	v_add_co_u32_e32 v58, vcc, s78, v122
	v_ashrrev_i32_e32 v105, 31, v104
	v_cvt_pk_bf16_f32 v62, v56, v57
	v_lshl_add_u64 v[56:57], v[122:123], 0, s[8:9]
	v_addc_co_u32_e32 v59, vcc, 0, v123, vcc
	v_cvt_pk_bf16_f32 v44, v44, v45
	v_cvt_pk_bf16_f32 v45, v46, v47
	v_cvt_pk_bf16_f32 v46, v40, v41
	v_cvt_pk_bf16_f32 v47, v42, v43
	v_cvt_pk_bf16_f32 v111, v106, v107
	v_lshlrev_b64 v[104:105], 11, v[104:105]
	v_cvt_pk_bf16_f32 v92, v92, v93
	v_cvt_pk_bf16_f32 v93, v94, v95
	v_cvt_pk_bf16_f32 v94, v88, v89
	v_or_b32_e32 v88, 32, v156
	global_store_dwordx4 v[56:57], v[44:47], off offset:256
	global_store_dwordx4 v[122:123], v[108:111], off offset:256
	v_ashrrev_i32_e32 v89, 31, v88
	v_add_co_u32_e32 v46, vcc, s79, v122
	v_lshl_add_u64 v[108:109], s[46:47], 0, v[104:105]
	v_lshl_add_u64 v[44:45], v[122:123], 0, s[12:13]
	v_addc_co_u32_e32 v47, vcc, 0, v123, vcc
	v_cvt_pk_bf16_f32 v28, v28, v29
	v_cvt_pk_bf16_f32 v29, v30, v31
	v_cvt_pk_bf16_f32 v30, v24, v25
	v_cvt_pk_bf16_f32 v31, v26, v27
	v_lshl_add_u64 v[108:109], v[108:109], 0, v[120:121]
	v_cvt_pk_bf16_f32 v95, v90, v91
	v_lshlrev_b64 v[88:89], 11, v[88:89]
	v_cvt_pk_bf16_f32 v76, v76, v77
	v_cvt_pk_bf16_f32 v77, v78, v79
	v_cvt_pk_bf16_f32 v78, v72, v73
	v_or_b32_e32 v72, 48, v156
	global_store_dwordx4 v[44:45], v[28:31], off offset:256
	global_store_dwordx4 v[108:109], v[92:95], off offset:256
	v_ashrrev_i32_e32 v73, 31, v72
	v_add_co_u32_e32 v30, vcc, s80, v122
	v_lshl_add_u64 v[92:93], s[46:47], 0, v[88:89]
	v_lshl_add_u64 v[28:29], v[122:123], 0, s[14:15]
	v_addc_co_u32_e32 v31, vcc, 0, v123, vcc
	v_cvt_pk_bf16_f32 v12, v12, v13
	v_cvt_pk_bf16_f32 v13, v14, v15
	v_cvt_pk_bf16_f32 v14, v8, v9
	v_cvt_pk_bf16_f32 v15, v10, v11
	v_lshl_add_u64 v[92:93], v[92:93], 0, v[120:121]
	v_cvt_pk_bf16_f32 v79, v74, v75
	v_lshlrev_b64 v[72:73], 11, v[72:73]
	global_store_dwordx4 v[28:29], v[12:15], off offset:256
	global_store_dwordx4 v[92:93], v[76:79], off offset:256
	v_cvt_pk_bf16_f32 v104, v116, v117
	v_add_co_u32_e32 v14, vcc, s81, v122
	v_lshl_add_u64 v[76:77], s[46:47], 0, v[72:73]
	s_nop 0
	v_addc_co_u32_e32 v15, vcc, 0, v123, vcc
	v_cvt_pk_bf16_f32 v105, v118, v119
	v_cvt_pk_bf16_f32 v106, v112, v113
	v_cvt_pk_bf16_f32 v107, v114, v115
	v_cvt_pk_bf16_f32 v88, v100, v101
	v_cvt_pk_bf16_f32 v89, v102, v103
	v_cvt_pk_bf16_f32 v90, v96, v97
	v_cvt_pk_bf16_f32 v91, v98, v99
	v_cvt_pk_bf16_f32 v72, v84, v85
	v_cvt_pk_bf16_f32 v73, v86, v87
	v_cvt_pk_bf16_f32 v74, v80, v81
	v_cvt_pk_bf16_f32 v75, v82, v83
	v_lshl_add_u64 v[76:77], v[76:77], 0, v[120:121]
	v_cvt_pk_bf16_f32 v68, v68, v69
	v_cvt_pk_bf16_f32 v69, v70, v71
	v_cvt_pk_bf16_f32 v70, v64, v65
	v_cvt_pk_bf16_f32 v71, v66, v67
	v_cvt_pk_bf16_f32 v40, v52, v53
	v_cvt_pk_bf16_f32 v41, v54, v55
	v_cvt_pk_bf16_f32 v42, v48, v49
	v_cvt_pk_bf16_f32 v43, v50, v51
	v_cvt_pk_bf16_f32 v24, v36, v37
	v_cvt_pk_bf16_f32 v25, v38, v39
	v_cvt_pk_bf16_f32 v26, v32, v33
	v_cvt_pk_bf16_f32 v27, v34, v35
	v_cvt_pk_bf16_f32 v8, v20, v21
	v_cvt_pk_bf16_f32 v9, v22, v23
	v_cvt_pk_bf16_f32 v10, v16, v17
	v_cvt_pk_bf16_f32 v11, v18, v19
	v_lshl_add_u64 v[12:13], v[122:123], 0, s[16:17]
	v_cvt_pk_bf16_f32 v4, v4, v5
	v_cvt_pk_bf16_f32 v5, v6, v7
	v_cvt_pk_bf16_f32 v6, v0, v1
	v_cvt_pk_bf16_f32 v7, v2, v3
	s_and_b64 vcc, exec, s[4:5]
	s_mov_b32 s82, s20
	s_mov_b32 s18, s26
	s_mov_b64 s[54:55], s[30:31]
	s_mov_b64 s[34:35], s[28:29]
	global_store_dwordx4 v[122:123], v[124:127], off
	global_store_dwordx4 v[108:109], v[104:107], off
	global_store_dwordx4 v[92:93], v[88:91], off
	global_store_dwordx4 v[76:77], v[72:75], off
	global_store_dwordx4 v[76:77], v[68:71], off offset:256
	global_store_dwordx4 v[58:59], v[60:63], off
	global_store_dwordx4 v[46:47], v[40:43], off
	global_store_dwordx4 v[30:31], v[24:27], off
	global_store_dwordx4 v[14:15], v[8:11], off
	global_store_dwordx4 v[12:13], v[4:7], off offset:256
	s_mov_b32 s94, 1
	s_cbranch_vccz .LBB0_909
	s_mov_b32 s94, 0
	s_waitcnt vmcnt(16)
	s_cmpk_gt_u32 s60, 0xff
	s_cbranch_scc1 .LBB0_916
	s_barrier

.LBB0_1116:
	ds_read_b128 v[154:157], v150
	ds_read_b128 v[158:161], v150 offset:1024
	ds_read_b128 v[162:165], v150 offset:2048
	ds_read_b128 v[166:169], v150 offset:3072
	s_add_u32 s34, s30, 0xfffc0080
	s_addc_u32 s35, s31, -1
	s_cmp_eq_u32 s77, 12
	s_cselect_b32 s37, s19, s35
	s_cselect_b32 s36, s73, s34
	s_cselect_b32 s35, s17, s76
	s_cselect_b32 s34, s74, s75
	v_lshl_add_u64 v[202:203], s[30:31], 0, v[134:135]
	s_add_i32 m0, s29, 0xc000
	ds_read_b128 v[170:173], v151
	ds_read_b128 v[174:177], v151 offset:1024
	ds_read_b128 v[178:181], v151 offset:2048
	ds_read_b128 v[182:185], v151 offset:3072
	ds_read_b128 v[186:189], v151 offset:4096
	ds_read_b128 v[190:193], v151 offset:5120
	ds_read_b128 v[194:197], v151 offset:6144
	ds_read_b128 v[198:201], v151 offset:7168
	global_load_lds_dwordx4 v[202:203], off
	v_lshl_add_u64 v[202:203], s[30:31], 0, v[136:137]
	s_add_i32 m0, s29, 0xe000
	s_nop 0
	global_load_lds_dwordx4 v[202:203], off
	s_waitcnt lgkmcnt(8)
	s_barrier
	s_waitcnt lgkmcnt(0)
	s_waitcnt lgkmcnt(0)
	v_mfma_f32_16x16x32_bf16 v[120:123], v[154:157], v[170:173], v[120:123]
	v_mfma_f32_16x16x32_bf16 v[124:127], v[162:165], v[170:173], v[124:127]
	v_mfma_f32_16x16x32_bf16 v[104:107], v[154:157], v[178:181], v[104:107]
	v_mfma_f32_16x16x32_bf16 v[108:111], v[162:165], v[178:181], v[108:111]
	v_mfma_f32_16x16x32_bf16 v[88:91], v[154:157], v[186:189], v[88:91]
	v_mfma_f32_16x16x32_bf16 v[92:95], v[162:165], v[186:189], v[92:95]
	v_mfma_f32_16x16x32_bf16 v[72:75], v[154:157], v[194:197], v[72:75]
	v_mfma_f32_16x16x32_bf16 v[76:79], v[162:165], v[194:197], v[76:79]
	v_mfma_f32_16x16x32_bf16 v[120:123], v[158:161], v[174:177], v[120:123]
	v_mfma_f32_16x16x32_bf16 v[124:127], v[166:169], v[174:177], v[124:127]
	v_mfma_f32_16x16x32_bf16 v[104:107], v[158:161], v[182:185], v[104:107]
	v_mfma_f32_16x16x32_bf16 v[108:111], v[166:169], v[182:185], v[108:111]
	v_mfma_f32_16x16x32_bf16 v[88:91], v[158:161], v[190:193], v[88:91]
	v_mfma_f32_16x16x32_bf16 v[92:95], v[166:169], v[190:193], v[92:95]
	v_mfma_f32_16x16x32_bf16 v[72:75], v[158:161], v[198:201], v[72:75]
	v_mfma_f32_16x16x32_bf16 v[76:79], v[166:169], v[198:201], v[76:79]
	s_barrier
	s_add_i32 s78, s60, s42
	v_lshl_add_u64 v[218:219], s[34:35], 0, v[130:131]
	s_mov_b32 m0, s78
	ds_read_b128 v[202:205], v152
	ds_read_b128 v[206:209], v152 offset:1024
	ds_read_b128 v[210:213], v152 offset:2048
	ds_read_b128 v[214:217], v152 offset:3072
	global_load_lds_dwordx4 v[218:219], off
	v_lshl_add_u64 v[220:221], s[34:35], 0, v[132:133]
	s_add_i32 m0, s78, 0x2000
	s_nop 0
	global_load_lds_dwordx4 v[220:221], off
	s_barrier
	s_waitcnt lgkmcnt(0)
	s_waitcnt lgkmcnt(0)
	v_mfma_f32_16x16x32_bf16 v[112:115], v[202:205], v[170:173], v[112:115]
	v_mfma_f32_16x16x32_bf16 v[116:119], v[210:213], v[170:173], v[116:119]
	v_mfma_f32_16x16x32_bf16 v[96:99], v[202:205], v[178:181], v[96:99]
	v_mfma_f32_16x16x32_bf16 v[100:103], v[210:213], v[178:181], v[100:103]
	v_mfma_f32_16x16x32_bf16 v[80:83], v[202:205], v[186:189], v[80:83]
	v_mfma_f32_16x16x32_bf16 v[84:87], v[210:213], v[186:189], v[84:87]
	v_mfma_f32_16x16x32_bf16 v[64:67], v[202:205], v[194:197], v[64:67]
	v_mfma_f32_16x16x32_bf16 v[68:71], v[210:213], v[194:197], v[68:71]
	v_mfma_f32_16x16x32_bf16 v[112:115], v[206:209], v[174:177], v[112:115]
	v_mfma_f32_16x16x32_bf16 v[116:119], v[214:217], v[174:177], v[116:119]
	v_mfma_f32_16x16x32_bf16 v[96:99], v[206:209], v[182:185], v[96:99]
	v_mfma_f32_16x16x32_bf16 v[100:103], v[214:217], v[182:185], v[100:103]
	v_mfma_f32_16x16x32_bf16 v[80:83], v[206:209], v[190:193], v[80:83]
	v_mfma_f32_16x16x32_bf16 v[84:87], v[214:217], v[190:193], v[84:87]
	v_mfma_f32_16x16x32_bf16 v[64:67], v[206:209], v[198:201], v[64:67]
	v_mfma_f32_16x16x32_bf16 v[68:71], v[214:217], v[198:201], v[68:71]
	s_mov_b32 m0, s29
	v_lshl_add_u64 v[222:223], s[36:37], 0, v[130:131]
	s_barrier
	ds_read_b128 v[170:173], v151 offset:16384
	ds_read_b128 v[174:177], v151 offset:17408
	ds_read_b128 v[178:181], v151 offset:18432
	ds_read_b128 v[182:185], v151 offset:19456
	ds_read_b128 v[186:189], v151 offset:20480
	ds_read_b128 v[190:193], v151 offset:21504
	ds_read_b128 v[194:197], v151 offset:22528
	ds_read_b128 v[198:201], v151 offset:23552
	global_load_lds_dwordx4 v[222:223], off
	v_lshl_add_u64 v[224:225], s[36:37], 0, v[132:133]
	s_mov_b32 m0, s43
	s_nop 0
	global_load_lds_dwordx4 v[224:225], off
	s_barrier
	s_waitcnt lgkmcnt(0)
	s_waitcnt lgkmcnt(0)
	v_mfma_f32_16x16x32_bf16 v[56:59], v[154:157], v[170:173], v[56:59]
	v_mfma_f32_16x16x32_bf16 v[60:63], v[162:165], v[170:173], v[60:63]
	v_mfma_f32_16x16x32_bf16 v[40:43], v[154:157], v[178:181], v[40:43]
	v_mfma_f32_16x16x32_bf16 v[44:47], v[162:165], v[178:181], v[44:47]
	v_mfma_f32_16x16x32_bf16 v[24:27], v[154:157], v[186:189], v[24:27]
	v_mfma_f32_16x16x32_bf16 v[28:31], v[162:165], v[186:189], v[28:31]
	v_mfma_f32_16x16x32_bf16 v[8:11], v[154:157], v[194:197], v[8:11]
	v_mfma_f32_16x16x32_bf16 v[12:15], v[162:165], v[194:197], v[12:15]
	v_mfma_f32_16x16x32_bf16 v[56:59], v[158:161], v[174:177], v[56:59]
	v_mfma_f32_16x16x32_bf16 v[60:63], v[166:169], v[174:177], v[60:63]
	v_mfma_f32_16x16x32_bf16 v[40:43], v[158:161], v[182:185], v[40:43]
	v_mfma_f32_16x16x32_bf16 v[44:47], v[166:169], v[182:185], v[44:47]
	v_mfma_f32_16x16x32_bf16 v[24:27], v[158:161], v[190:193], v[24:27]
	v_mfma_f32_16x16x32_bf16 v[28:31], v[166:169], v[190:193], v[28:31]
	v_mfma_f32_16x16x32_bf16 v[8:11], v[158:161], v[198:201], v[8:11]
	v_mfma_f32_16x16x32_bf16 v[12:15], v[166:169], v[198:201], v[12:15]
	s_barrier
	s_add_u32 s78, s34, 0x40000
	s_addc_u32 s79, s35, 0
	s_add_i32 s80, s61, s42
	v_lshl_add_u64 v[154:155], s[78:79], 0, v[130:131]
	s_mov_b32 m0, s80
	s_nop 0
	global_load_lds_dwordx4 v[154:155], off
	v_lshl_add_u64 v[154:155], s[78:79], 0, v[132:133]
	s_add_i32 m0, s80, 0x2000
	s_nop 0
	global_load_lds_dwordx4 v[154:155], off
	s_cmp_lg_u32 s94, 0
	s_cbranch_scc1 .Lrx7a
	s_waitcnt vmcnt(6)
.Lrx7a:
	s_waitcnt vmcnt(24)
	s_barrier
	v_mfma_f32_16x16x32_bf16 v[48:51], v[202:205], v[170:173], v[48:51]
	v_mfma_f32_16x16x32_bf16 v[52:55], v[210:213], v[170:173], v[52:55]
	v_mfma_f32_16x16x32_bf16 v[32:35], v[202:205], v[178:181], v[32:35]
	v_mfma_f32_16x16x32_bf16 v[36:39], v[210:213], v[178:181], v[36:39]
	v_mfma_f32_16x16x32_bf16 v[16:19], v[202:205], v[186:189], v[16:19]
	v_mfma_f32_16x16x32_bf16 v[20:23], v[210:213], v[186:189], v[20:23]
	v_mfma_f32_16x16x32_bf16 v[0:3], v[202:205], v[194:197], v[0:3]
	v_mfma_f32_16x16x32_bf16 v[4:7], v[210:213], v[194:197], v[4:7]
	v_mfma_f32_16x16x32_bf16 v[48:51], v[206:209], v[174:177], v[48:51]
	v_mfma_f32_16x16x32_bf16 v[52:55], v[214:217], v[174:177], v[52:55]
	v_mfma_f32_16x16x32_bf16 v[32:35], v[206:209], v[182:185], v[32:35]
	v_mfma_f32_16x16x32_bf16 v[36:39], v[214:217], v[182:185], v[36:39]
	v_mfma_f32_16x16x32_bf16 v[16:19], v[206:209], v[190:193], v[16:19]
	v_mfma_f32_16x16x32_bf16 v[20:23], v[214:217], v[190:193], v[20:23]
	v_mfma_f32_16x16x32_bf16 v[0:3], v[206:209], v[198:201], v[0:3]
	v_mfma_f32_16x16x32_bf16 v[4:7], v[214:217], v[198:201], v[4:7]
	s_add_i32 s78, 0, 0x18000
	v_add_u32_e32 v153, s78, v148
	s_barrier
	ds_read_b128 v[154:157], v153
	ds_read_b128 v[158:161], v153 offset:1024
	ds_read_b128 v[162:165], v153 offset:2048
	ds_read_b128 v[166:169], v153 offset:3072
	s_add_u32 s36, s36, 0x40000
	s_addc_u32 s37, s37, 0
	s_mov_b32 m0, s52
	v_lshl_add_u64 v[202:203], s[36:37], 0, v[130:131]
	ds_read_b128 v[170:173], v151 offset:32768
	ds_read_b128 v[174:177], v151 offset:33792
	ds_read_b128 v[178:181], v151 offset:34816
	ds_read_b128 v[182:185], v151 offset:35840
	ds_read_b128 v[186:189], v151 offset:36864
	ds_read_b128 v[190:193], v151 offset:37888
	ds_read_b128 v[194:197], v151 offset:38912
	ds_read_b128 v[198:201], v151 offset:39936
	global_load_lds_dwordx4 v[202:203], off
	v_lshl_add_u64 v[202:203], s[36:37], 0, v[132:133]
	s_mov_b32 m0, s53
	s_nop 0
	global_load_lds_dwordx4 v[202:203], off
	s_waitcnt lgkmcnt(8)
	s_barrier
	s_waitcnt lgkmcnt(0)
	s_waitcnt lgkmcnt(0)
	v_mfma_f32_16x16x32_bf16 v[120:123], v[154:157], v[170:173], v[120:123]
	v_mfma_f32_16x16x32_bf16 v[124:127], v[162:165], v[170:173], v[124:127]
	v_mfma_f32_16x16x32_bf16 v[104:107], v[154:157], v[178:181], v[104:107]
	v_mfma_f32_16x16x32_bf16 v[108:111], v[162:165], v[178:181], v[108:111]
	v_mfma_f32_16x16x32_bf16 v[88:91], v[154:157], v[186:189], v[88:91]
	v_mfma_f32_16x16x32_bf16 v[92:95], v[162:165], v[186:189], v[92:95]
	v_mfma_f32_16x16x32_bf16 v[72:75], v[154:157], v[194:197], v[72:75]
	v_mfma_f32_16x16x32_bf16 v[76:79], v[162:165], v[194:197], v[76:79]
	v_mfma_f32_16x16x32_bf16 v[120:123], v[158:161], v[174:177], v[120:123]
	v_mfma_f32_16x16x32_bf16 v[124:127], v[166:169], v[174:177], v[124:127]
	v_mfma_f32_16x16x32_bf16 v[104:107], v[158:161], v[182:185], v[104:107]
	v_mfma_f32_16x16x32_bf16 v[108:111], v[166:169], v[182:185], v[108:111]
	v_mfma_f32_16x16x32_bf16 v[88:91], v[158:161], v[190:193], v[88:91]
	v_mfma_f32_16x16x32_bf16 v[92:95], v[166:169], v[190:193], v[92:95]
	v_mfma_f32_16x16x32_bf16 v[72:75], v[158:161], v[198:201], v[72:75]
	v_mfma_f32_16x16x32_bf16 v[76:79], v[166:169], v[198:201], v[76:79]
	s_barrier
	s_add_i32 s36, 0, 0x1c000
	s_add_i32 s37, s78, s42
	v_add_u32_e32 v153, s36, v148
	v_lshl_add_u64 v[218:219], v[218:219], 0, s[8:9]
	s_mov_b32 m0, s37
	ds_read_b128 v[202:205], v153
	ds_read_b128 v[206:209], v153 offset:1024
	ds_read_b128 v[210:213], v153 offset:2048
	ds_read_b128 v[214:217], v153 offset:3072
	global_load_lds_dwordx4 v[218:219], off
	v_lshl_add_u64 v[218:219], v[220:221], 0, s[8:9]
	s_add_i32 m0, s37, 0x2000
	s_nop 0
	global_load_lds_dwordx4 v[218:219], off
	s_cmp_lg_u32 s94, 0
	s_cbranch_scc0 .Lrx7c
	s_waitcnt vmcnt(10)
	s_mov_b32 s94, 0
.Lrx7c:
	s_barrier
	s_waitcnt lgkmcnt(0)
	s_waitcnt lgkmcnt(0)
	v_mfma_f32_16x16x32_bf16 v[112:115], v[202:205], v[170:173], v[112:115]
	v_mfma_f32_16x16x32_bf16 v[116:119], v[210:213], v[170:173], v[116:119]
	v_mfma_f32_16x16x32_bf16 v[96:99], v[202:205], v[178:181], v[96:99]
	v_mfma_f32_16x16x32_bf16 v[100:103], v[210:213], v[178:181], v[100:103]
	v_mfma_f32_16x16x32_bf16 v[80:83], v[202:205], v[186:189], v[80:83]
	v_mfma_f32_16x16x32_bf16 v[84:87], v[210:213], v[186:189], v[84:87]
	v_mfma_f32_16x16x32_bf16 v[64:67], v[202:205], v[194:197], v[64:67]
	v_mfma_f32_16x16x32_bf16 v[68:71], v[210:213], v[194:197], v[68:71]
	v_mfma_f32_16x16x32_bf16 v[112:115], v[206:209], v[174:177], v[112:115]
	v_mfma_f32_16x16x32_bf16 v[116:119], v[214:217], v[174:177], v[116:119]
	v_mfma_f32_16x16x32_bf16 v[96:99], v[206:209], v[182:185], v[96:99]
	v_mfma_f32_16x16x32_bf16 v[100:103], v[214:217], v[182:185], v[100:103]
	v_mfma_f32_16x16x32_bf16 v[80:83], v[206:209], v[190:193], v[80:83]
	v_mfma_f32_16x16x32_bf16 v[84:87], v[214:217], v[190:193], v[84:87]
	v_mfma_f32_16x16x32_bf16 v[64:67], v[206:209], v[198:201], v[64:67]
	v_mfma_f32_16x16x32_bf16 v[68:71], v[214:217], v[198:201], v[68:71]
	s_mov_b32 m0, s55
	v_lshl_add_u64 v[218:219], v[222:223], 0, s[8:9]
	s_barrier
	ds_read_b128 v[170:173], v151 offset:49152
	ds_read_b128 v[174:177], v151 offset:50176
	ds_read_b128 v[178:181], v151 offset:51200
	ds_read_b128 v[182:185], v151 offset:52224
	ds_read_b128 v[186:189], v151 offset:53248
	ds_read_b128 v[190:193], v151 offset:54272
	ds_read_b128 v[194:197], v151 offset:55296
	ds_read_b128 v[198:201], v151 offset:56320
	global_load_lds_dwordx4 v[218:219], off
	v_lshl_add_u64 v[218:219], v[224:225], 0, s[8:9]
	s_mov_b32 m0, s56
	s_nop 0
	global_load_lds_dwordx4 v[218:219], off
	s_barrier
	s_waitcnt lgkmcnt(0)
	s_waitcnt lgkmcnt(0)
	v_mfma_f32_16x16x32_bf16 v[56:59], v[154:157], v[170:173], v[56:59]
	v_mfma_f32_16x16x32_bf16 v[60:63], v[162:165], v[170:173], v[60:63]
	v_mfma_f32_16x16x32_bf16 v[40:43], v[154:157], v[178:181], v[40:43]
	v_mfma_f32_16x16x32_bf16 v[44:47], v[162:165], v[178:181], v[44:47]
	v_mfma_f32_16x16x32_bf16 v[24:27], v[154:157], v[186:189], v[24:27]
	v_mfma_f32_16x16x32_bf16 v[28:31], v[162:165], v[186:189], v[28:31]
	v_mfma_f32_16x16x32_bf16 v[8:11], v[154:157], v[194:197], v[8:11]
	v_mfma_f32_16x16x32_bf16 v[12:15], v[162:165], v[194:197], v[12:15]
	v_mfma_f32_16x16x32_bf16 v[56:59], v[158:161], v[174:177], v[56:59]
	v_mfma_f32_16x16x32_bf16 v[60:63], v[166:169], v[174:177], v[60:63]
	v_mfma_f32_16x16x32_bf16 v[40:43], v[158:161], v[182:185], v[40:43]
	v_mfma_f32_16x16x32_bf16 v[44:47], v[166:169], v[182:185], v[44:47]
	v_mfma_f32_16x16x32_bf16 v[24:27], v[158:161], v[190:193], v[24:27]
	v_mfma_f32_16x16x32_bf16 v[28:31], v[166:169], v[190:193], v[28:31]
	v_mfma_f32_16x16x32_bf16 v[8:11], v[158:161], v[198:201], v[8:11]
	v_mfma_f32_16x16x32_bf16 v[12:15], v[166:169], v[198:201], v[12:15]
	s_barrier
	s_add_u32 s34, s34, 0x40080
	s_addc_u32 s35, s35, 0
	s_add_i32 s36, s36, s42
	v_lshl_add_u64 v[154:155], s[34:35], 0, v[130:131]
	s_mov_b32 m0, s36
	s_nop 0
	global_load_lds_dwordx4 v[154:155], off
	v_lshl_add_u64 v[154:155], s[34:35], 0, v[132:133]
	s_add_i32 m0, s36, 0x2000
	s_nop 0
	global_load_lds_dwordx4 v[154:155], off
	s_waitcnt vmcnt(6)
	s_barrier
	v_mfma_f32_16x16x32_bf16 v[48:51], v[202:205], v[170:173], v[48:51]
	v_mfma_f32_16x16x32_bf16 v[52:55], v[210:213], v[170:173], v[52:55]
	v_mfma_f32_16x16x32_bf16 v[32:35], v[202:205], v[178:181], v[32:35]
	v_mfma_f32_16x16x32_bf16 v[36:39], v[210:213], v[178:181], v[36:39]
	v_mfma_f32_16x16x32_bf16 v[16:19], v[202:205], v[186:189], v[16:19]
	v_mfma_f32_16x16x32_bf16 v[20:23], v[210:213], v[186:189], v[20:23]
	v_mfma_f32_16x16x32_bf16 v[0:3], v[202:205], v[194:197], v[0:3]
	v_mfma_f32_16x16x32_bf16 v[4:7], v[210:213], v[194:197], v[4:7]
	v_mfma_f32_16x16x32_bf16 v[48:51], v[206:209], v[174:177], v[48:51]
	v_mfma_f32_16x16x32_bf16 v[52:55], v[214:217], v[174:177], v[52:55]
	v_mfma_f32_16x16x32_bf16 v[32:35], v[206:209], v[182:185], v[32:35]
	v_mfma_f32_16x16x32_bf16 v[36:39], v[214:217], v[182:185], v[36:39]
	v_mfma_f32_16x16x32_bf16 v[16:19], v[206:209], v[190:193], v[16:19]
	v_mfma_f32_16x16x32_bf16 v[20:23], v[214:217], v[190:193], v[20:23]
	v_mfma_f32_16x16x32_bf16 v[0:3], v[206:209], v[198:201], v[0:3]
	v_mfma_f32_16x16x32_bf16 v[4:7], v[214:217], v[198:201], v[4:7]
	s_add_i32 s77, s77, 2
	s_add_u32 s30, s30, 0x100
	s_addc_u32 s31, s31, 0
	s_add_u32 s75, s75, 0x100
	s_addc_u32 s76, s76, 0
	s_cmp_gt_u32 s77, 13
	s_barrier
	s_cbranch_scc0 .LBB0_1116
	v_mul_f32_e32 v124, 0xbfb8aa3b, v124
	v_exp_f32_e32 v154, v124
	v_mul_f32_e32 v124, 0xbfb8aa3b, v125
	v_exp_f32_e32 v155, v124
	v_lshl_add_u32 v124, s28, 8, v145
	v_ashrrev_i32_e32 v125, 31, v124
	v_lshlrev_b64 v[158:159], 11, v[124:125]
	v_pk_add_f32 v[154:155], v[154:155], 1.0 op_sel_hi:[1,0]
	v_mul_f32_e32 v126, 0xbfb8aa3b, v126
	v_div_scale_f32 v153, s[30:31], v155, v155, v121
	v_rcp_f32_e32 v157, v153
	v_mul_f32_e32 v127, 0xbfb8aa3b, v127
	v_exp_f32_e32 v126, v126
	v_exp_f32_e32 v127, v127
	v_fma_f32 v125, -v153, v157, 1.0
	v_fmac_f32_e32 v157, v125, v157
	v_div_scale_f32 v125, vcc, v121, v155, v121
	v_mul_f32_e32 v160, v125, v157
	v_fma_f32 v161, -v153, v160, v125
	v_fmac_f32_e32 v160, v161, v157
	v_fma_f32 v125, -v153, v160, v125
	v_div_scale_f32 v153, s[30:31], v154, v154, v120
	v_rcp_f32_e32 v161, v153
	v_div_fmas_f32 v125, v125, v157, v160
	v_div_fixup_f32 v121, v125, v155, v121
	v_pk_add_f32 v[126:127], v[126:127], 1.0 op_sel_hi:[1,0]
	v_fma_f32 v125, -v153, v161, 1.0
	v_fmac_f32_e32 v161, v125, v161
	v_div_scale_f32 v125, vcc, v120, v154, v120
	v_mul_f32_e32 v155, v125, v161
	v_fma_f32 v157, -v153, v155, v125
	v_fmac_f32_e32 v155, v157, v161
	v_fma_f32 v125, -v153, v155, v125
	v_div_scale_f32 v153, s[30:31], v127, v127, v123
	v_rcp_f32_e32 v157, v153
	v_div_fmas_f32 v125, v125, v161, v155
	v_div_fixup_f32 v120, v125, v154, v120
	v_mul_f32_e32 v116, 0xbfb8aa3b, v116
	v_fma_f32 v125, -v153, v157, 1.0
	v_fmac_f32_e32 v157, v125, v157
	v_div_scale_f32 v125, vcc, v123, v127, v123
	v_mul_f32_e32 v154, v125, v157
	v_fma_f32 v155, -v153, v154, v125
	v_fmac_f32_e32 v154, v155, v157
	v_fma_f32 v125, -v153, v154, v125
	v_div_scale_f32 v153, s[30:31], v126, v126, v122
	v_rcp_f32_e32 v155, v153
	v_div_fmas_f32 v125, v125, v157, v154
	v_div_fixup_f32 v123, v125, v127, v123
	v_mul_f32_e32 v117, 0xbfb8aa3b, v117
	v_fma_f32 v125, -v153, v155, 1.0
	v_fmac_f32_e32 v155, v125, v155
	v_div_scale_f32 v125, vcc, v122, v126, v122
	v_mul_f32_e32 v127, v125, v155
	v_fma_f32 v154, -v153, v127, v125
	v_exp_f32_e32 v116, v116
	v_exp_f32_e32 v117, v117
	v_fmac_f32_e32 v127, v154, v155
	v_fma_f32 v125, -v153, v127, v125
	v_div_fmas_f32 v125, v125, v155, v127
	v_div_fixup_f32 v125, v125, v126, v122
	v_pk_add_f32 v[126:127], v[116:117], 1.0 op_sel_hi:[1,0]
	v_cvt_pk_bf16_f32 v123, v125, v123
	v_div_scale_f32 v125, s[30:31], v127, v127, v113
	v_lshl_or_b32 v156, s72, 7, v149
	v_rcp_f32_e32 v153, v125
	v_ashrrev_i32_e32 v157, 31, v156
	v_lshl_add_u64 v[158:159], s[46:47], 0, v[158:159]
	v_cvt_pk_bf16_f32 v122, v120, v121
	v_lshlrev_b64 v[120:121], 1, v[156:157]
	v_lshl_add_u64 v[116:117], v[158:159], 0, v[120:121]
	global_store_dwordx2 v[116:117], v[122:123], off
	v_fma_f32 v122, -v125, v153, 1.0
	v_fmac_f32_e32 v153, v122, v153
	v_div_scale_f32 v122, vcc, v113, v127, v113
	v_mul_f32_e32 v123, v122, v153
	v_fma_f32 v154, -v125, v123, v122
	v_fmac_f32_e32 v123, v154, v153
	v_fma_f32 v122, -v125, v123, v122
	v_div_scale_f32 v125, s[30:31], v126, v126, v112
	v_rcp_f32_e32 v154, v125
	v_div_fmas_f32 v122, v122, v153, v123
	v_mul_f32_e32 v118, 0xbfb8aa3b, v118
	v_mul_f32_e32 v119, 0xbfb8aa3b, v119
	v_div_fixup_f32 v113, v122, v127, v113
	v_fma_f32 v122, -v125, v154, 1.0
	v_exp_f32_e32 v118, v118
	v_exp_f32_e32 v119, v119
	v_fmac_f32_e32 v154, v122, v154
	v_div_scale_f32 v122, vcc, v112, v126, v112
	v_mul_f32_e32 v123, v122, v154
	v_fma_f32 v127, -v125, v123, v122
	v_fmac_f32_e32 v123, v127, v154
	v_pk_add_f32 v[118:119], v[118:119], 1.0 op_sel_hi:[1,0]
	v_fma_f32 v122, -v125, v123, v122
	v_div_scale_f32 v125, s[30:31], v119, v119, v115
	v_rcp_f32_e32 v127, v125
	v_div_fmas_f32 v122, v122, v154, v123
	v_div_fixup_f32 v112, v122, v126, v112
	v_mul_f32_e32 v108, 0xbfb8aa3b, v108
	v_fma_f32 v122, -v125, v127, 1.0
	v_fmac_f32_e32 v127, v122, v127
	v_div_scale_f32 v122, vcc, v115, v119, v115
	v_mul_f32_e32 v123, v122, v127
	v_fma_f32 v126, -v125, v123, v122
	v_fmac_f32_e32 v123, v126, v127
	v_fma_f32 v122, -v125, v123, v122
	v_div_scale_f32 v125, s[30:31], v118, v118, v114
	v_rcp_f32_e32 v126, v125
	v_div_fmas_f32 v122, v122, v127, v123
	v_div_fixup_f32 v115, v122, v119, v115
	v_mul_f32_e32 v109, 0xbfb8aa3b, v109
	v_fma_f32 v119, -v125, v126, 1.0
	v_fmac_f32_e32 v126, v119, v126
	v_div_scale_f32 v119, vcc, v114, v118, v114
	v_mul_f32_e32 v122, v119, v126
	v_fma_f32 v123, -v125, v122, v119
	v_exp_f32_e32 v108, v108
	v_exp_f32_e32 v109, v109
	v_fmac_f32_e32 v122, v123, v126
	v_fma_f32 v119, -v125, v122, v119
	v_div_fmas_f32 v119, v119, v126, v122
	v_div_fixup_f32 v114, v119, v118, v114
	v_pk_add_f32 v[108:109], v[108:109], 1.0 op_sel_hi:[1,0]
	v_cvt_pk_bf16_f32 v112, v112, v113
	v_cvt_pk_bf16_f32 v113, v114, v115
	v_div_scale_f32 v114, s[30:31], v109, v109, v105
	v_rcp_f32_e32 v115, v114
	v_mul_f32_e32 v110, 0xbfb8aa3b, v110
	v_mul_f32_e32 v111, 0xbfb8aa3b, v111
	v_exp_f32_e32 v110, v110
	v_fma_f32 v118, -v114, v115, 1.0
	v_fmac_f32_e32 v115, v118, v115
	v_div_scale_f32 v118, vcc, v105, v109, v105
	v_mul_f32_e32 v119, v118, v115
	v_fma_f32 v122, -v114, v119, v118
	v_fmac_f32_e32 v119, v122, v115
	v_fma_f32 v114, -v114, v119, v118
	v_div_scale_f32 v118, s[30:31], v108, v108, v104
	v_rcp_f32_e32 v122, v118
	v_div_fmas_f32 v114, v114, v115, v119
	v_exp_f32_e32 v111, v111
	v_div_fixup_f32 v105, v114, v109, v105
	v_fma_f32 v109, -v118, v122, 1.0
	v_fmac_f32_e32 v122, v109, v122
	v_div_scale_f32 v109, vcc, v104, v108, v104
	v_mul_f32_e32 v114, v109, v122
	v_fma_f32 v115, -v118, v114, v109
	v_pk_add_f32 v[110:111], v[110:111], 1.0 op_sel_hi:[1,0]
	v_fmac_f32_e32 v114, v115, v122
	v_div_scale_f32 v115, s[30:31], v111, v111, v107
	v_fma_f32 v109, -v118, v114, v109
	v_rcp_f32_e32 v118, v115
	v_div_fmas_f32 v109, v109, v122, v114
	v_div_fixup_f32 v104, v109, v108, v104
	v_mul_f32_e32 v100, 0xbfb8aa3b, v100
	v_fma_f32 v108, -v115, v118, 1.0
	v_fmac_f32_e32 v118, v108, v118
	v_div_scale_f32 v108, vcc, v107, v111, v107
	v_mul_f32_e32 v109, v108, v118
	v_fma_f32 v114, -v115, v109, v108
	v_fmac_f32_e32 v109, v114, v118
	v_div_scale_f32 v114, s[30:31], v110, v110, v106
	v_fma_f32 v108, -v115, v109, v108
	v_rcp_f32_e32 v115, v114
	v_div_fmas_f32 v108, v108, v118, v109
	v_div_fixup_f32 v107, v108, v111, v107
	v_mul_f32_e32 v101, 0xbfb8aa3b, v101
	v_fma_f32 v108, -v114, v115, 1.0
	v_fmac_f32_e32 v115, v108, v115
	v_div_scale_f32 v108, vcc, v106, v110, v106
	v_mul_f32_e32 v109, v108, v115
	v_exp_f32_e32 v100, v100
	v_exp_f32_e32 v101, v101
	v_fma_f32 v111, -v114, v109, v108
	v_fmac_f32_e32 v109, v111, v115
	v_fma_f32 v108, -v114, v109, v108
	v_div_fmas_f32 v108, v108, v115, v109
	v_pk_add_f32 v[100:101], v[100:101], 1.0 op_sel_hi:[1,0]
	global_store_dwordx2 v[116:117], v[112:113], off offset:128
	v_or_b32_e32 v112, 16, v124
	v_div_fixup_f32 v106, v108, v110, v106
	v_div_scale_f32 v108, s[30:31], v101, v101, v97
	v_ashrrev_i32_e32 v113, 31, v112
	v_rcp_f32_e32 v109, v108
	v_lshlrev_b64 v[112:113], 11, v[112:113]
	v_lshl_add_u64 v[112:113], s[46:47], 0, v[112:113]
	v_cvt_pk_bf16_f32 v104, v104, v105
	v_cvt_pk_bf16_f32 v105, v106, v107
	v_lshl_add_u64 v[106:107], v[112:113], 0, v[120:121]
	global_store_dwordx2 v[106:107], v[104:105], off
	v_fma_f32 v104, -v108, v109, 1.0
	v_fmac_f32_e32 v109, v104, v109
	v_div_scale_f32 v104, vcc, v97, v101, v97
	v_mul_f32_e32 v105, v104, v109
	v_fma_f32 v110, -v108, v105, v104
	v_fmac_f32_e32 v105, v110, v109
	v_fma_f32 v104, -v108, v105, v104
	v_div_scale_f32 v108, s[30:31], v100, v100, v96
	v_rcp_f32_e32 v110, v108
	v_mul_f32_e32 v102, 0xbfb8aa3b, v102
	v_mul_f32_e32 v103, 0xbfb8aa3b, v103
	v_div_fmas_f32 v104, v104, v109, v105
	v_exp_f32_e32 v102, v102
	v_exp_f32_e32 v103, v103
	v_div_fixup_f32 v97, v104, v101, v97
	v_fma_f32 v101, -v108, v110, 1.0
	v_fmac_f32_e32 v110, v101, v110
	v_div_scale_f32 v101, vcc, v96, v100, v96
	v_mul_f32_e32 v104, v101, v110
	v_fma_f32 v105, -v108, v104, v101
	v_pk_add_f32 v[102:103], v[102:103], 1.0 op_sel_hi:[1,0]
	v_fmac_f32_e32 v104, v105, v110
	v_div_scale_f32 v105, s[30:31], v103, v103, v99
	v_fma_f32 v101, -v108, v104, v101
	v_rcp_f32_e32 v108, v105
	v_div_fmas_f32 v101, v101, v110, v104
	v_div_fixup_f32 v96, v101, v100, v96
	v_mul_f32_e32 v92, 0xbfb8aa3b, v92
	v_fma_f32 v100, -v105, v108, 1.0
	v_fmac_f32_e32 v108, v100, v108
	v_div_scale_f32 v100, vcc, v99, v103, v99
	v_mul_f32_e32 v101, v100, v108
	v_fma_f32 v104, -v105, v101, v100
	v_fmac_f32_e32 v101, v104, v108
	v_div_scale_f32 v104, s[30:31], v102, v102, v98
	v_fma_f32 v100, -v105, v101, v100
	v_rcp_f32_e32 v105, v104
	v_div_fmas_f32 v100, v100, v108, v101
	v_div_fixup_f32 v99, v100, v103, v99
	v_mul_f32_e32 v93, 0xbfb8aa3b, v93
	v_fma_f32 v100, -v104, v105, 1.0
	v_fmac_f32_e32 v105, v100, v105
	v_div_scale_f32 v100, vcc, v98, v102, v98
	v_mul_f32_e32 v101, v100, v105
	v_fma_f32 v103, -v104, v101, v100
	v_exp_f32_e32 v92, v92
	v_exp_f32_e32 v93, v93
	v_fmac_f32_e32 v101, v103, v105
	v_fma_f32 v100, -v104, v101, v100
	v_div_fmas_f32 v100, v100, v105, v101
	v_div_fixup_f32 v98, v100, v102, v98
	v_pk_add_f32 v[92:93], v[92:93], 1.0 op_sel_hi:[1,0]
	v_cvt_pk_bf16_f32 v96, v96, v97
	v_cvt_pk_bf16_f32 v97, v98, v99
	v_div_scale_f32 v98, s[30:31], v93, v93, v89
	v_rcp_f32_e32 v99, v98
	v_mul_f32_e32 v94, 0xbfb8aa3b, v94
	v_mul_f32_e32 v95, 0xbfb8aa3b, v95
	v_exp_f32_e32 v94, v94
	v_fma_f32 v100, -v98, v99, 1.0
	v_fmac_f32_e32 v99, v100, v99
	v_div_scale_f32 v100, vcc, v89, v93, v89
	v_mul_f32_e32 v101, v100, v99
	v_fma_f32 v102, -v98, v101, v100
	v_fmac_f32_e32 v101, v102, v99
	v_fma_f32 v98, -v98, v101, v100
	v_div_scale_f32 v100, s[30:31], v92, v92, v88
	v_rcp_f32_e32 v102, v100
	v_div_fmas_f32 v98, v98, v99, v101
	v_exp_f32_e32 v95, v95
	v_div_fixup_f32 v89, v98, v93, v89
	v_fma_f32 v93, -v100, v102, 1.0
	v_fmac_f32_e32 v102, v93, v102
	v_div_scale_f32 v93, vcc, v88, v92, v88
	v_mul_f32_e32 v98, v93, v102
	v_fma_f32 v99, -v100, v98, v93
	v_pk_add_f32 v[94:95], v[94:95], 1.0 op_sel_hi:[1,0]
	v_fmac_f32_e32 v98, v99, v102
	v_div_scale_f32 v99, s[30:31], v95, v95, v91
	v_fma_f32 v93, -v100, v98, v93
	v_rcp_f32_e32 v100, v99
	v_div_fmas_f32 v93, v93, v102, v98
	v_div_fixup_f32 v88, v93, v92, v88
	v_mul_f32_e32 v84, 0xbfb8aa3b, v84
	v_fma_f32 v92, -v99, v100, 1.0
	v_fmac_f32_e32 v100, v92, v100
	v_div_scale_f32 v92, vcc, v91, v95, v91
	v_mul_f32_e32 v93, v92, v100
	v_fma_f32 v98, -v99, v93, v92
	v_fmac_f32_e32 v93, v98, v100
	v_div_scale_f32 v98, s[30:31], v94, v94, v90
	v_fma_f32 v92, -v99, v93, v92
	v_rcp_f32_e32 v99, v98
	v_div_fmas_f32 v92, v92, v100, v93
	v_div_fixup_f32 v91, v92, v95, v91
	v_mul_f32_e32 v85, 0xbfb8aa3b, v85
	v_fma_f32 v92, -v98, v99, 1.0
	v_fmac_f32_e32 v99, v92, v99
	v_div_scale_f32 v92, vcc, v90, v94, v90
	v_mul_f32_e32 v93, v92, v99
	v_exp_f32_e32 v84, v84
	v_exp_f32_e32 v85, v85
	v_fma_f32 v95, -v98, v93, v92
	v_fmac_f32_e32 v93, v95, v99
	v_fma_f32 v92, -v98, v93, v92
	v_div_fmas_f32 v92, v92, v99, v93
	v_pk_add_f32 v[84:85], v[84:85], 1.0 op_sel_hi:[1,0]
	global_store_dwordx2 v[106:107], v[96:97], off offset:128
	v_or_b32_e32 v96, 32, v124
	v_div_fixup_f32 v90, v92, v94, v90
	v_div_scale_f32 v92, s[30:31], v85, v85, v81
	v_ashrrev_i32_e32 v97, 31, v96
	v_rcp_f32_e32 v93, v92
	v_lshlrev_b64 v[96:97], 11, v[96:97]
	v_lshl_add_u64 v[96:97], s[46:47], 0, v[96:97]
	v_cvt_pk_bf16_f32 v88, v88, v89
	v_cvt_pk_bf16_f32 v89, v90, v91
	v_lshl_add_u64 v[90:91], v[96:97], 0, v[120:121]
	global_store_dwordx2 v[90:91], v[88:89], off
	v_fma_f32 v88, -v92, v93, 1.0
	v_fmac_f32_e32 v93, v88, v93
	v_div_scale_f32 v88, vcc, v81, v85, v81
	v_mul_f32_e32 v89, v88, v93
	v_fma_f32 v94, -v92, v89, v88
	v_fmac_f32_e32 v89, v94, v93
	v_fma_f32 v88, -v92, v89, v88
	v_div_scale_f32 v92, s[30:31], v84, v84, v80
	v_rcp_f32_e32 v94, v92
	v_mul_f32_e32 v86, 0xbfb8aa3b, v86
	v_mul_f32_e32 v87, 0xbfb8aa3b, v87
	v_div_fmas_f32 v88, v88, v93, v89
	v_exp_f32_e32 v86, v86
	v_exp_f32_e32 v87, v87
	v_div_fixup_f32 v81, v88, v85, v81
	v_fma_f32 v85, -v92, v94, 1.0
	v_fmac_f32_e32 v94, v85, v94
	v_div_scale_f32 v85, vcc, v80, v84, v80
	v_mul_f32_e32 v88, v85, v94
	v_fma_f32 v89, -v92, v88, v85
	v_pk_add_f32 v[86:87], v[86:87], 1.0 op_sel_hi:[1,0]
	v_fmac_f32_e32 v88, v89, v94
	v_div_scale_f32 v89, s[30:31], v87, v87, v83
	v_fma_f32 v85, -v92, v88, v85
	v_rcp_f32_e32 v92, v89
	v_div_fmas_f32 v85, v85, v94, v88
	v_div_fixup_f32 v80, v85, v84, v80
	v_mul_f32_e32 v76, 0xbfb8aa3b, v76
	v_fma_f32 v84, -v89, v92, 1.0
	v_fmac_f32_e32 v92, v84, v92
	v_div_scale_f32 v84, vcc, v83, v87, v83
	v_mul_f32_e32 v85, v84, v92
	v_fma_f32 v88, -v89, v85, v84
	v_fmac_f32_e32 v85, v88, v92
	v_div_scale_f32 v88, s[30:31], v86, v86, v82
	v_fma_f32 v84, -v89, v85, v84
	v_rcp_f32_e32 v89, v88
	v_div_fmas_f32 v84, v84, v92, v85
	v_div_fixup_f32 v83, v84, v87, v83
	v_mul_f32_e32 v77, 0xbfb8aa3b, v77
	v_fma_f32 v84, -v88, v89, 1.0
	v_fmac_f32_e32 v89, v84, v89
	v_div_scale_f32 v84, vcc, v82, v86, v82
	v_mul_f32_e32 v85, v84, v89
	v_fma_f32 v87, -v88, v85, v84
	v_exp_f32_e32 v76, v76
	v_exp_f32_e32 v77, v77
	v_fmac_f32_e32 v85, v87, v89
	v_fma_f32 v84, -v88, v85, v84
	v_div_fmas_f32 v84, v84, v89, v85
	v_div_fixup_f32 v82, v84, v86, v82
	v_pk_add_f32 v[76:77], v[76:77], 1.0 op_sel_hi:[1,0]
	v_cvt_pk_bf16_f32 v80, v80, v81
	v_cvt_pk_bf16_f32 v81, v82, v83
	v_div_scale_f32 v82, s[30:31], v77, v77, v73
	v_rcp_f32_e32 v83, v82
	v_mul_f32_e32 v78, 0xbfb8aa3b, v78
	v_mul_f32_e32 v79, 0xbfb8aa3b, v79
	v_exp_f32_e32 v78, v78
	v_fma_f32 v84, -v82, v83, 1.0
	v_fmac_f32_e32 v83, v84, v83
	v_div_scale_f32 v84, vcc, v73, v77, v73
	v_mul_f32_e32 v85, v84, v83
	v_fma_f32 v86, -v82, v85, v84
	v_fmac_f32_e32 v85, v86, v83
	v_fma_f32 v82, -v82, v85, v84
	v_div_scale_f32 v84, s[30:31], v76, v76, v72
	v_rcp_f32_e32 v86, v84
	v_div_fmas_f32 v82, v82, v83, v85
	v_exp_f32_e32 v79, v79
	v_div_fixup_f32 v73, v82, v77, v73
	v_fma_f32 v77, -v84, v86, 1.0
	v_fmac_f32_e32 v86, v77, v86
	v_div_scale_f32 v77, vcc, v72, v76, v72
	v_mul_f32_e32 v82, v77, v86
	v_fma_f32 v83, -v84, v82, v77
	v_pk_add_f32 v[78:79], v[78:79], 1.0 op_sel_hi:[1,0]
	v_fmac_f32_e32 v82, v83, v86
	v_div_scale_f32 v83, s[30:31], v79, v79, v75
	v_fma_f32 v77, -v84, v82, v77
	v_rcp_f32_e32 v84, v83
	v_div_fmas_f32 v77, v77, v86, v82
	v_div_fixup_f32 v72, v77, v76, v72
	v_mul_f32_e32 v68, 0xbfb8aa3b, v68
	v_fma_f32 v76, -v83, v84, 1.0
	v_fmac_f32_e32 v84, v76, v84
	v_div_scale_f32 v76, vcc, v75, v79, v75
	v_mul_f32_e32 v77, v76, v84
	v_fma_f32 v82, -v83, v77, v76
	v_fmac_f32_e32 v77, v82, v84
	v_div_scale_f32 v82, s[30:31], v78, v78, v74
	v_fma_f32 v76, -v83, v77, v76
	v_rcp_f32_e32 v83, v82
	v_div_fmas_f32 v76, v76, v84, v77
	v_div_fixup_f32 v75, v76, v79, v75
	v_mul_f32_e32 v69, 0xbfb8aa3b, v69
	v_fma_f32 v76, -v82, v83, 1.0
	v_fmac_f32_e32 v83, v76, v83
	v_div_scale_f32 v76, vcc, v74, v78, v74
	v_mul_f32_e32 v77, v76, v83
	v_exp_f32_e32 v68, v68
	v_exp_f32_e32 v69, v69
	v_fma_f32 v79, -v82, v77, v76
	v_fmac_f32_e32 v77, v79, v83
	v_fma_f32 v76, -v82, v77, v76
	v_div_fmas_f32 v76, v76, v83, v77
	v_pk_add_f32 v[68:69], v[68:69], 1.0 op_sel_hi:[1,0]
	global_store_dwordx2 v[90:91], v[80:81], off offset:128
	v_or_b32_e32 v80, 48, v124
	v_div_fixup_f32 v74, v76, v78, v74
	v_div_scale_f32 v76, s[30:31], v69, v69, v65
	v_ashrrev_i32_e32 v81, 31, v80
	v_rcp_f32_e32 v77, v76
	v_lshlrev_b64 v[80:81], 11, v[80:81]
	v_lshl_add_u64 v[80:81], s[46:47], 0, v[80:81]
	v_cvt_pk_bf16_f32 v72, v72, v73
	v_cvt_pk_bf16_f32 v73, v74, v75
	v_lshl_add_u64 v[74:75], v[80:81], 0, v[120:121]
	global_store_dwordx2 v[74:75], v[72:73], off
	v_fma_f32 v72, -v76, v77, 1.0
	v_fmac_f32_e32 v77, v72, v77
	v_div_scale_f32 v72, vcc, v65, v69, v65
	v_mul_f32_e32 v73, v72, v77
	v_fma_f32 v78, -v76, v73, v72
	v_fmac_f32_e32 v73, v78, v77
	v_fma_f32 v72, -v76, v73, v72
	v_div_scale_f32 v76, s[30:31], v68, v68, v64
	v_rcp_f32_e32 v78, v76
	v_mul_f32_e32 v70, 0xbfb8aa3b, v70
	v_mul_f32_e32 v71, 0xbfb8aa3b, v71
	v_div_fmas_f32 v72, v72, v77, v73
	v_exp_f32_e32 v70, v70
	v_exp_f32_e32 v71, v71
	v_div_fixup_f32 v65, v72, v69, v65
	v_fma_f32 v69, -v76, v78, 1.0
	v_fmac_f32_e32 v78, v69, v78
	v_div_scale_f32 v69, vcc, v64, v68, v64
	v_mul_f32_e32 v72, v69, v78
	v_fma_f32 v73, -v76, v72, v69
	v_pk_add_f32 v[70:71], v[70:71], 1.0 op_sel_hi:[1,0]
	v_fmac_f32_e32 v72, v73, v78
	v_div_scale_f32 v73, s[30:31], v71, v71, v67
	v_fma_f32 v69, -v76, v72, v69
	v_rcp_f32_e32 v76, v73
	v_div_fmas_f32 v69, v69, v78, v72
	v_div_fixup_f32 v64, v69, v68, v64
	v_mul_f32_e32 v60, 0xbfb8aa3b, v60
	v_fma_f32 v68, -v73, v76, 1.0
	v_fmac_f32_e32 v76, v68, v76
	v_div_scale_f32 v68, vcc, v67, v71, v67
	v_mul_f32_e32 v69, v68, v76
	v_fma_f32 v72, -v73, v69, v68
	v_fmac_f32_e32 v69, v72, v76
	v_div_scale_f32 v72, s[30:31], v70, v70, v66
	v_fma_f32 v68, -v73, v69, v68
	v_rcp_f32_e32 v73, v72
	v_div_fmas_f32 v68, v68, v76, v69
	v_div_fixup_f32 v67, v68, v71, v67
	v_mul_f32_e32 v61, 0xbfb8aa3b, v61
	v_fma_f32 v68, -v72, v73, 1.0
	v_fmac_f32_e32 v73, v68, v73
	v_div_scale_f32 v68, vcc, v66, v70, v66
	v_mul_f32_e32 v69, v68, v73
	v_exp_f32_e32 v60, v60
	v_exp_f32_e32 v61, v61
	v_fma_f32 v71, -v72, v69, v68
	v_fmac_f32_e32 v69, v71, v73
	v_fma_f32 v68, -v72, v69, v68
	v_div_fmas_f32 v68, v68, v73, v69
	v_pk_add_f32 v[60:61], v[60:61], 1.0 op_sel_hi:[1,0]
	v_div_fixup_f32 v66, v68, v70, v66
	v_div_scale_f32 v68, s[30:31], v61, v61, v57
	v_rcp_f32_e32 v69, v68
	v_cvt_pk_bf16_f32 v64, v64, v65
	v_cvt_pk_bf16_f32 v65, v66, v67
	global_store_dwordx2 v[74:75], v[64:65], off offset:128
	v_fma_f32 v64, -v68, v69, 1.0
	v_fmac_f32_e32 v69, v64, v69
	v_div_scale_f32 v64, vcc, v57, v61, v57
	v_mul_f32_e32 v65, v64, v69
	v_fma_f32 v66, -v68, v65, v64
	v_fmac_f32_e32 v65, v66, v69
	v_div_scale_f32 v66, s[30:31], v60, v60, v56
	v_rcp_f32_e32 v67, v66
	v_fma_f32 v64, -v68, v65, v64
	v_mul_f32_e32 v62, 0xbfb8aa3b, v62
	v_mul_f32_e32 v63, 0xbfb8aa3b, v63
	v_div_fmas_f32 v64, v64, v69, v65
	v_exp_f32_e32 v62, v62
	v_exp_f32_e32 v63, v63
	v_div_fixup_f32 v57, v64, v61, v57
	v_fma_f32 v61, -v66, v67, 1.0
	v_fmac_f32_e32 v67, v61, v67
	v_div_scale_f32 v61, vcc, v56, v60, v56
	v_mul_f32_e32 v64, v61, v67
	v_fma_f32 v65, -v66, v64, v61
	v_pk_add_f32 v[62:63], v[62:63], 1.0 op_sel_hi:[1,0]
	v_fmac_f32_e32 v64, v65, v67
	v_div_scale_f32 v65, s[30:31], v63, v63, v59
	v_fma_f32 v61, -v66, v64, v61
	v_rcp_f32_e32 v66, v65
	v_div_fmas_f32 v61, v61, v67, v64
	v_div_fixup_f32 v56, v61, v60, v56
	v_mul_f32_e32 v52, 0xbfb8aa3b, v52
	v_fma_f32 v60, -v65, v66, 1.0
	v_fmac_f32_e32 v66, v60, v66
	v_div_scale_f32 v60, vcc, v59, v63, v59
	v_mul_f32_e32 v61, v60, v66
	v_fma_f32 v64, -v65, v61, v60
	v_fmac_f32_e32 v61, v64, v66
	v_div_scale_f32 v64, s[30:31], v62, v62, v58
	v_fma_f32 v60, -v65, v61, v60
	v_rcp_f32_e32 v65, v64
	v_div_fmas_f32 v60, v60, v66, v61
	v_div_fixup_f32 v59, v60, v63, v59
	v_mul_f32_e32 v53, 0xbfb8aa3b, v53
	v_fma_f32 v60, -v64, v65, 1.0
	v_fmac_f32_e32 v65, v60, v65
	v_div_scale_f32 v60, vcc, v58, v62, v58
	v_mul_f32_e32 v61, v60, v65
	v_exp_f32_e32 v52, v52
	v_exp_f32_e32 v53, v53
	v_fma_f32 v63, -v64, v61, v60
	v_fmac_f32_e32 v61, v63, v65
	v_fma_f32 v60, -v64, v61, v60
	v_div_fmas_f32 v60, v60, v65, v61
	v_pk_add_f32 v[52:53], v[52:53], 1.0 op_sel_hi:[1,0]
	v_div_fixup_f32 v58, v60, v62, v58
	v_div_scale_f32 v62, s[30:31], v53, v53, v49
	v_rcp_f32_e32 v63, v62
	v_add_co_u32_e32 v60, vcc, s62, v116
	v_cvt_pk_bf16_f32 v56, v56, v57
	v_cvt_pk_bf16_f32 v57, v58, v59
	v_addc_co_u32_e32 v61, vcc, 0, v117, vcc
	global_store_dwordx2 v[60:61], v[56:57], off
	v_fma_f32 v56, -v62, v63, 1.0
	v_fmac_f32_e32 v63, v56, v63
	v_div_scale_f32 v56, vcc, v49, v53, v49
	v_mul_f32_e32 v57, v56, v63
	v_fma_f32 v60, -v62, v57, v56
	v_fmac_f32_e32 v57, v60, v63
	v_div_scale_f32 v60, s[30:31], v52, v52, v48
	v_rcp_f32_e32 v61, v60
	v_fma_f32 v56, -v62, v57, v56
	v_mul_f32_e32 v54, 0xbfb8aa3b, v54
	v_mul_f32_e32 v55, 0xbfb8aa3b, v55
	v_div_fmas_f32 v56, v56, v63, v57
	v_exp_f32_e32 v54, v54
	v_exp_f32_e32 v55, v55
	v_div_fixup_f32 v49, v56, v53, v49
	v_fma_f32 v53, -v60, v61, 1.0
	v_fmac_f32_e32 v61, v53, v61
	v_div_scale_f32 v53, vcc, v48, v52, v48
	v_mul_f32_e32 v56, v53, v61
	v_fma_f32 v57, -v60, v56, v53
	v_pk_add_f32 v[54:55], v[54:55], 1.0 op_sel_hi:[1,0]
	v_fmac_f32_e32 v56, v57, v61
	v_div_scale_f32 v57, s[30:31], v55, v55, v51
	v_fma_f32 v53, -v60, v56, v53
	v_rcp_f32_e32 v60, v57
	v_div_fmas_f32 v53, v53, v61, v56
	v_div_fixup_f32 v48, v53, v52, v48
	v_mul_f32_e32 v44, 0xbfb8aa3b, v44
	v_fma_f32 v52, -v57, v60, 1.0
	v_fmac_f32_e32 v60, v52, v60
	v_div_scale_f32 v52, vcc, v51, v55, v51
	v_mul_f32_e32 v53, v52, v60
	v_fma_f32 v56, -v57, v53, v52
	v_fmac_f32_e32 v53, v56, v60
	v_div_scale_f32 v56, s[30:31], v54, v54, v50
	v_fma_f32 v52, -v57, v53, v52
	v_rcp_f32_e32 v57, v56
	v_div_fmas_f32 v52, v52, v60, v53
	v_div_fixup_f32 v51, v52, v55, v51
	v_mul_f32_e32 v45, 0xbfb8aa3b, v45
	v_fma_f32 v52, -v56, v57, 1.0
	v_fmac_f32_e32 v57, v52, v57
	v_div_scale_f32 v52, vcc, v50, v54, v50
	v_mul_f32_e32 v53, v52, v57
	v_exp_f32_e32 v44, v44
	v_exp_f32_e32 v45, v45
	v_fma_f32 v55, -v56, v53, v52
	v_fmac_f32_e32 v53, v55, v57
	v_fma_f32 v52, -v56, v53, v52
	v_div_fmas_f32 v52, v52, v57, v53
	v_pk_add_f32 v[44:45], v[44:45], 1.0 op_sel_hi:[1,0]
	v_div_fixup_f32 v50, v52, v54, v50
	v_div_scale_f32 v52, s[30:31], v45, v45, v41
	v_rcp_f32_e32 v53, v52
	v_lshl_add_u64 v[58:59], v[116:117], 0, s[6:7]
	v_cvt_pk_bf16_f32 v48, v48, v49
	v_cvt_pk_bf16_f32 v49, v50, v51
	global_store_dwordx2 v[58:59], v[48:49], off offset:128
	v_fma_f32 v48, -v52, v53, 1.0
	v_fmac_f32_e32 v53, v48, v53
	v_div_scale_f32 v48, vcc, v41, v45, v41
	v_mul_f32_e32 v49, v48, v53
	v_fma_f32 v50, -v52, v49, v48
	v_fmac_f32_e32 v49, v50, v53
	v_div_scale_f32 v50, s[30:31], v44, v44, v40
	v_rcp_f32_e32 v51, v50
	v_fma_f32 v48, -v52, v49, v48
	v_mul_f32_e32 v46, 0xbfb8aa3b, v46
	v_mul_f32_e32 v47, 0xbfb8aa3b, v47
	v_div_fmas_f32 v48, v48, v53, v49
	v_exp_f32_e32 v46, v46
	v_exp_f32_e32 v47, v47
	v_div_fixup_f32 v41, v48, v45, v41
	v_fma_f32 v45, -v50, v51, 1.0
	v_fmac_f32_e32 v51, v45, v51
	v_div_scale_f32 v45, vcc, v40, v44, v40
	v_mul_f32_e32 v48, v45, v51
	v_fma_f32 v49, -v50, v48, v45
	v_pk_add_f32 v[46:47], v[46:47], 1.0 op_sel_hi:[1,0]
	v_fmac_f32_e32 v48, v49, v51
	v_div_scale_f32 v49, s[30:31], v47, v47, v43
	v_fma_f32 v45, -v50, v48, v45
	v_rcp_f32_e32 v50, v49
	v_div_fmas_f32 v45, v45, v51, v48
	v_div_fixup_f32 v40, v45, v44, v40
	v_mul_f32_e32 v36, 0xbfb8aa3b, v36
	v_fma_f32 v44, -v49, v50, 1.0
	v_fmac_f32_e32 v50, v44, v50
	v_div_scale_f32 v44, vcc, v43, v47, v43
	v_mul_f32_e32 v45, v44, v50
	v_fma_f32 v48, -v49, v45, v44
	v_fmac_f32_e32 v45, v48, v50
	v_div_scale_f32 v48, s[30:31], v46, v46, v42
	v_fma_f32 v44, -v49, v45, v44
	v_rcp_f32_e32 v49, v48
	v_div_fmas_f32 v44, v44, v50, v45
	v_div_fixup_f32 v43, v44, v47, v43
	v_mul_f32_e32 v37, 0xbfb8aa3b, v37
	v_fma_f32 v44, -v48, v49, 1.0
	v_fmac_f32_e32 v49, v44, v49
	v_div_scale_f32 v44, vcc, v42, v46, v42
	v_mul_f32_e32 v45, v44, v49
	v_exp_f32_e32 v36, v36
	v_exp_f32_e32 v37, v37
	v_fma_f32 v47, -v48, v45, v44
	v_fmac_f32_e32 v45, v47, v49
	v_fma_f32 v44, -v48, v45, v44
	v_div_fmas_f32 v44, v44, v49, v45
	v_pk_add_f32 v[36:37], v[36:37], 1.0 op_sel_hi:[1,0]
	v_div_fixup_f32 v42, v44, v46, v42
	v_div_scale_f32 v46, s[30:31], v37, v37, v33
	v_rcp_f32_e32 v47, v46
	v_add_co_u32_e32 v44, vcc, s63, v116
	v_cvt_pk_bf16_f32 v40, v40, v41
	v_cvt_pk_bf16_f32 v41, v42, v43
	v_addc_co_u32_e32 v45, vcc, 0, v117, vcc
	global_store_dwordx2 v[44:45], v[40:41], off
	v_fma_f32 v40, -v46, v47, 1.0
	v_fmac_f32_e32 v47, v40, v47
	v_div_scale_f32 v40, vcc, v33, v37, v33
	v_mul_f32_e32 v41, v40, v47
	v_fma_f32 v44, -v46, v41, v40
	v_fmac_f32_e32 v41, v44, v47
	v_div_scale_f32 v44, s[30:31], v36, v36, v32
	v_rcp_f32_e32 v45, v44
	v_fma_f32 v40, -v46, v41, v40
	v_mul_f32_e32 v38, 0xbfb8aa3b, v38
	v_mul_f32_e32 v39, 0xbfb8aa3b, v39
	v_div_fmas_f32 v40, v40, v47, v41
	v_exp_f32_e32 v38, v38
	v_exp_f32_e32 v39, v39
	v_div_fixup_f32 v33, v40, v37, v33
	v_fma_f32 v37, -v44, v45, 1.0
	v_fmac_f32_e32 v45, v37, v45
	v_div_scale_f32 v37, vcc, v32, v36, v32
	v_mul_f32_e32 v40, v37, v45
	v_fma_f32 v41, -v44, v40, v37
	v_pk_add_f32 v[38:39], v[38:39], 1.0 op_sel_hi:[1,0]
	v_fmac_f32_e32 v40, v41, v45
	v_div_scale_f32 v41, s[30:31], v39, v39, v35
	v_fma_f32 v37, -v44, v40, v37
	v_rcp_f32_e32 v44, v41
	v_div_fmas_f32 v37, v37, v45, v40
	v_div_fixup_f32 v32, v37, v36, v32
	v_mul_f32_e32 v28, 0xbfb8aa3b, v28
	v_fma_f32 v36, -v41, v44, 1.0
	v_fmac_f32_e32 v44, v36, v44
	v_div_scale_f32 v36, vcc, v35, v39, v35
	v_mul_f32_e32 v37, v36, v44
	v_fma_f32 v40, -v41, v37, v36
	v_fmac_f32_e32 v37, v40, v44
	v_div_scale_f32 v40, s[30:31], v38, v38, v34
	v_fma_f32 v36, -v41, v37, v36
	v_rcp_f32_e32 v41, v40
	v_div_fmas_f32 v36, v36, v44, v37
	v_div_fixup_f32 v35, v36, v39, v35
	v_mul_f32_e32 v29, 0xbfb8aa3b, v29
	v_fma_f32 v36, -v40, v41, 1.0
	v_fmac_f32_e32 v41, v36, v41
	v_div_scale_f32 v36, vcc, v34, v38, v34
	v_mul_f32_e32 v37, v36, v41
	v_exp_f32_e32 v28, v28
	v_exp_f32_e32 v29, v29
	v_fma_f32 v39, -v40, v37, v36
	v_fmac_f32_e32 v37, v39, v41
	v_fma_f32 v36, -v40, v37, v36
	v_div_fmas_f32 v36, v36, v41, v37
	v_pk_add_f32 v[28:29], v[28:29], 1.0 op_sel_hi:[1,0]
	v_div_fixup_f32 v34, v36, v38, v34
	v_div_scale_f32 v36, s[30:31], v29, v29, v25
	v_rcp_f32_e32 v37, v36
	v_lshl_add_u64 v[42:43], v[116:117], 0, s[10:11]
	v_cvt_pk_bf16_f32 v32, v32, v33
	v_cvt_pk_bf16_f32 v33, v34, v35
	global_store_dwordx2 v[42:43], v[32:33], off offset:128
	v_fma_f32 v32, -v36, v37, 1.0
	v_fmac_f32_e32 v37, v32, v37
	v_div_scale_f32 v32, vcc, v25, v29, v25
	v_mul_f32_e32 v33, v32, v37
	v_fma_f32 v34, -v36, v33, v32
	v_fmac_f32_e32 v33, v34, v37
	v_div_scale_f32 v34, s[30:31], v28, v28, v24
	v_rcp_f32_e32 v35, v34
	v_fma_f32 v32, -v36, v33, v32
	v_mul_f32_e32 v30, 0xbfb8aa3b, v30
	v_mul_f32_e32 v31, 0xbfb8aa3b, v31
	v_div_fmas_f32 v32, v32, v37, v33
	v_exp_f32_e32 v30, v30
	v_exp_f32_e32 v31, v31
	v_div_fixup_f32 v25, v32, v29, v25
	v_fma_f32 v29, -v34, v35, 1.0
	v_fmac_f32_e32 v35, v29, v35
	v_div_scale_f32 v29, vcc, v24, v28, v24
	v_mul_f32_e32 v32, v29, v35
	v_fma_f32 v33, -v34, v32, v29
	v_pk_add_f32 v[30:31], v[30:31], 1.0 op_sel_hi:[1,0]
	v_fmac_f32_e32 v32, v33, v35
	v_div_scale_f32 v33, s[30:31], v31, v31, v27
	v_fma_f32 v29, -v34, v32, v29
	v_rcp_f32_e32 v34, v33
	v_div_fmas_f32 v29, v29, v35, v32
	v_div_fixup_f32 v24, v29, v28, v24
	v_mul_f32_e32 v20, 0xbfb8aa3b, v20
	v_fma_f32 v28, -v33, v34, 1.0
	v_fmac_f32_e32 v34, v28, v34
	v_div_scale_f32 v28, vcc, v27, v31, v27
	v_mul_f32_e32 v29, v28, v34
	v_fma_f32 v32, -v33, v29, v28
	v_fmac_f32_e32 v29, v32, v34
	v_div_scale_f32 v32, s[30:31], v30, v30, v26
	v_fma_f32 v28, -v33, v29, v28
	v_rcp_f32_e32 v33, v32
	v_div_fmas_f32 v28, v28, v34, v29
	v_div_fixup_f32 v27, v28, v31, v27
	v_mul_f32_e32 v21, 0xbfb8aa3b, v21
	v_fma_f32 v28, -v32, v33, 1.0
	v_fmac_f32_e32 v33, v28, v33
	v_div_scale_f32 v28, vcc, v26, v30, v26
	v_mul_f32_e32 v29, v28, v33
	v_exp_f32_e32 v20, v20
	v_exp_f32_e32 v21, v21
	v_fma_f32 v31, -v32, v29, v28
	v_fmac_f32_e32 v29, v31, v33
	v_fma_f32 v28, -v32, v29, v28
	v_div_fmas_f32 v28, v28, v33, v29
	v_pk_add_f32 v[20:21], v[20:21], 1.0 op_sel_hi:[1,0]
	v_div_fixup_f32 v26, v28, v30, v26
	v_div_scale_f32 v30, s[30:31], v21, v21, v17
	v_rcp_f32_e32 v31, v30
	v_add_co_u32_e32 v28, vcc, s70, v116
	v_cvt_pk_bf16_f32 v24, v24, v25
	v_cvt_pk_bf16_f32 v25, v26, v27
	v_addc_co_u32_e32 v29, vcc, 0, v117, vcc
	global_store_dwordx2 v[28:29], v[24:25], off
	v_fma_f32 v24, -v30, v31, 1.0
	v_fmac_f32_e32 v31, v24, v31
	v_div_scale_f32 v24, vcc, v17, v21, v17
	v_mul_f32_e32 v25, v24, v31
	v_fma_f32 v28, -v30, v25, v24
	v_fmac_f32_e32 v25, v28, v31
	v_div_scale_f32 v28, s[30:31], v20, v20, v16
	v_rcp_f32_e32 v29, v28
	v_fma_f32 v24, -v30, v25, v24
	v_mul_f32_e32 v22, 0xbfb8aa3b, v22
	v_mul_f32_e32 v23, 0xbfb8aa3b, v23
	v_div_fmas_f32 v24, v24, v31, v25
	v_exp_f32_e32 v22, v22
	v_exp_f32_e32 v23, v23
	v_div_fixup_f32 v17, v24, v21, v17
	v_fma_f32 v21, -v28, v29, 1.0
	v_fmac_f32_e32 v29, v21, v29
	v_div_scale_f32 v21, vcc, v16, v20, v16
	v_mul_f32_e32 v24, v21, v29
	v_fma_f32 v25, -v28, v24, v21
	v_pk_add_f32 v[22:23], v[22:23], 1.0 op_sel_hi:[1,0]
	v_fmac_f32_e32 v24, v25, v29
	v_div_scale_f32 v25, s[30:31], v23, v23, v19
	v_fma_f32 v21, -v28, v24, v21
	v_rcp_f32_e32 v28, v25
	v_div_fmas_f32 v21, v21, v29, v24
	v_div_fixup_f32 v16, v21, v20, v16
	v_mul_f32_e32 v12, 0xbfb8aa3b, v12
	v_fma_f32 v20, -v25, v28, 1.0
	v_fmac_f32_e32 v28, v20, v28
	v_div_scale_f32 v20, vcc, v19, v23, v19
	v_mul_f32_e32 v21, v20, v28
	v_fma_f32 v24, -v25, v21, v20
	v_fmac_f32_e32 v21, v24, v28
	v_div_scale_f32 v24, s[30:31], v22, v22, v18
	v_fma_f32 v20, -v25, v21, v20
	v_rcp_f32_e32 v25, v24
	v_div_fmas_f32 v20, v20, v28, v21
	v_div_fixup_f32 v19, v20, v23, v19
	v_mul_f32_e32 v13, 0xbfb8aa3b, v13
	v_fma_f32 v20, -v24, v25, 1.0
	v_fmac_f32_e32 v25, v20, v25
	v_div_scale_f32 v20, vcc, v18, v22, v18
	v_mul_f32_e32 v21, v20, v25
	v_exp_f32_e32 v12, v12
	v_exp_f32_e32 v13, v13
	v_fma_f32 v23, -v24, v21, v20
	v_fmac_f32_e32 v21, v23, v25
	v_fma_f32 v20, -v24, v21, v20
	v_div_fmas_f32 v20, v20, v25, v21
	v_pk_add_f32 v[12:13], v[12:13], 1.0 op_sel_hi:[1,0]
	v_div_fixup_f32 v18, v20, v22, v18
	v_div_scale_f32 v20, s[30:31], v13, v13, v9
	v_rcp_f32_e32 v21, v20
	v_lshl_add_u64 v[26:27], v[116:117], 0, s[12:13]
	v_cvt_pk_bf16_f32 v16, v16, v17
	v_cvt_pk_bf16_f32 v17, v18, v19
	global_store_dwordx2 v[26:27], v[16:17], off offset:128
	v_fma_f32 v16, -v20, v21, 1.0
	v_fmac_f32_e32 v21, v16, v21
	v_div_scale_f32 v16, vcc, v9, v13, v9
	v_mul_f32_e32 v17, v16, v21
	v_fma_f32 v18, -v20, v17, v16
	v_fmac_f32_e32 v17, v18, v21
	v_div_scale_f32 v18, s[30:31], v12, v12, v8
	v_rcp_f32_e32 v19, v18
	v_fma_f32 v16, -v20, v17, v16
	v_mul_f32_e32 v14, 0xbfb8aa3b, v14
	v_mul_f32_e32 v15, 0xbfb8aa3b, v15
	v_div_fmas_f32 v16, v16, v21, v17
	v_exp_f32_e32 v14, v14
	v_exp_f32_e32 v15, v15
	v_div_fixup_f32 v9, v16, v13, v9
	v_fma_f32 v13, -v18, v19, 1.0
	v_fmac_f32_e32 v19, v13, v19
	v_div_scale_f32 v13, vcc, v8, v12, v8
	v_mul_f32_e32 v16, v13, v19
	v_fma_f32 v17, -v18, v16, v13
	v_pk_add_f32 v[14:15], v[14:15], 1.0 op_sel_hi:[1,0]
	v_fmac_f32_e32 v16, v17, v19
	v_div_scale_f32 v17, s[30:31], v15, v15, v11
	v_fma_f32 v13, -v18, v16, v13
	v_rcp_f32_e32 v18, v17
	v_div_fmas_f32 v13, v13, v19, v16
	v_div_fixup_f32 v8, v13, v12, v8
	v_mul_f32_e32 v4, 0xbfb8aa3b, v4
	v_fma_f32 v12, -v17, v18, 1.0
	v_fmac_f32_e32 v18, v12, v18
	v_div_scale_f32 v12, vcc, v11, v15, v11
	v_mul_f32_e32 v13, v12, v18
	v_fma_f32 v16, -v17, v13, v12
	v_fmac_f32_e32 v13, v16, v18
	v_div_scale_f32 v16, s[30:31], v14, v14, v10
	v_fma_f32 v12, -v17, v13, v12
	v_rcp_f32_e32 v17, v16
	v_div_fmas_f32 v12, v12, v18, v13
	v_div_fixup_f32 v11, v12, v15, v11
	v_mul_f32_e32 v5, 0xbfb8aa3b, v5
	v_fma_f32 v12, -v16, v17, 1.0
	v_fmac_f32_e32 v17, v12, v17
	v_div_scale_f32 v12, vcc, v10, v14, v10
	v_mul_f32_e32 v13, v12, v17
	v_exp_f32_e32 v4, v4
	v_exp_f32_e32 v5, v5
	v_fma_f32 v15, -v16, v13, v12
	v_fmac_f32_e32 v13, v15, v17
	v_fma_f32 v12, -v16, v13, v12
	v_div_fmas_f32 v12, v12, v17, v13
	v_pk_add_f32 v[4:5], v[4:5], 1.0 op_sel_hi:[1,0]
	v_div_fixup_f32 v10, v12, v14, v10
	v_div_scale_f32 v14, s[30:31], v5, v5, v1
	v_rcp_f32_e32 v15, v14
	v_add_co_u32_e32 v12, vcc, s71, v116
	v_cvt_pk_bf16_f32 v8, v8, v9
	v_cvt_pk_bf16_f32 v9, v10, v11
	v_addc_co_u32_e32 v13, vcc, 0, v117, vcc
	global_store_dwordx2 v[12:13], v[8:9], off
	v_fma_f32 v8, -v14, v15, 1.0
	v_fmac_f32_e32 v15, v8, v15
	v_div_scale_f32 v8, vcc, v1, v5, v1
	v_mul_f32_e32 v9, v8, v15
	v_fma_f32 v12, -v14, v9, v8
	v_fmac_f32_e32 v9, v12, v15
	v_div_scale_f32 v12, s[30:31], v4, v4, v0
	v_rcp_f32_e32 v13, v12
	v_fma_f32 v8, -v14, v9, v8
	v_mul_f32_e32 v6, 0xbfb8aa3b, v6
	v_mul_f32_e32 v7, 0xbfb8aa3b, v7
	v_div_fmas_f32 v8, v8, v15, v9
	v_exp_f32_e32 v6, v6
	v_exp_f32_e32 v7, v7
	v_div_fixup_f32 v1, v8, v5, v1
	v_fma_f32 v5, -v12, v13, 1.0
	v_fmac_f32_e32 v13, v5, v13
	v_div_scale_f32 v5, vcc, v0, v4, v0
	v_mul_f32_e32 v8, v5, v13
	v_fma_f32 v9, -v12, v8, v5
	v_pk_add_f32 v[6:7], v[6:7], 1.0 op_sel_hi:[1,0]
	v_fmac_f32_e32 v8, v9, v13
	v_div_scale_f32 v9, s[30:31], v7, v7, v3
	v_fma_f32 v5, -v12, v8, v5
	v_rcp_f32_e32 v12, v9
	v_div_fmas_f32 v5, v5, v13, v8
	v_div_fixup_f32 v0, v5, v4, v0
	v_lshl_add_u64 v[10:11], v[116:117], 0, s[14:15]
	v_fma_f32 v4, -v9, v12, 1.0
	v_fmac_f32_e32 v12, v4, v12
	v_div_scale_f32 v4, vcc, v3, v7, v3
	v_mul_f32_e32 v5, v4, v12
	v_fma_f32 v8, -v9, v5, v4
	v_fmac_f32_e32 v5, v8, v12
	v_div_scale_f32 v8, s[30:31], v6, v6, v2
	v_fma_f32 v4, -v9, v5, v4
	v_rcp_f32_e32 v9, v8
	v_div_fmas_f32 v4, v4, v12, v5
	v_div_fixup_f32 v3, v4, v7, v3
	v_cvt_pk_bf16_f32 v0, v0, v1
	v_fma_f32 v4, -v8, v9, 1.0
	v_fmac_f32_e32 v9, v4, v9
	v_div_scale_f32 v4, vcc, v2, v6, v2
	v_mul_f32_e32 v5, v4, v9
	v_fma_f32 v7, -v8, v5, v4
	v_fmac_f32_e32 v5, v7, v9
	v_fma_f32 v4, -v8, v5, v4
	v_div_fmas_f32 v4, v4, v9, v5
	v_div_fixup_f32 v2, v4, v6, v2
	v_cvt_pk_bf16_f32 v1, v2, v3
	s_and_b64 vcc, exec, s[4:5]
	s_mov_b32 s72, s16
	s_mov_b32 s28, s18
	s_mov_b64 s[34:35], s[26:27]
	s_mov_b64 s[30:31], s[20:21]
	global_store_dwordx2 v[10:11], v[0:1], off offset:128
	s_mov_b32 s94, 1
	s_cbranch_vccz .LBB0_1109
	s_mov_b32 s94, 0
	s_waitcnt vmcnt(16)
	s_cmpk_gt_u32 s40, 0xff
	s_cbranch_scc1 .LBB0_1120
	s_barrier

.LBB0_1141:
	ds_read_b128 v[150:153], v145
	ds_read_b128 v[154:157], v145 offset:1024
	ds_read_b128 v[158:161], v145 offset:2048
	ds_read_b128 v[162:165], v145 offset:3072
	s_add_u32 s34, s30, 0xfffc0080
	s_addc_u32 s35, s31, -1
	s_cmp_eq_u32 s77, 12
	s_cselect_b32 s37, s19, s35
	s_cselect_b32 s36, s73, s34
	s_cselect_b32 s35, s17, s76
	s_cselect_b32 s34, s74, s75
	v_lshl_add_u64 v[198:199], s[30:31], 0, v[134:135]
	s_add_i32 m0, s29, 0xc000
	ds_read_b128 v[166:169], v148
	ds_read_b128 v[170:173], v148 offset:1024
	ds_read_b128 v[174:177], v148 offset:2048
	ds_read_b128 v[178:181], v148 offset:3072
	ds_read_b128 v[182:185], v148 offset:4096
	ds_read_b128 v[186:189], v148 offset:5120
	ds_read_b128 v[190:193], v148 offset:6144
	ds_read_b128 v[194:197], v148 offset:7168
	global_load_lds_dwordx4 v[198:199], off
	v_lshl_add_u64 v[198:199], s[30:31], 0, v[136:137]
	s_add_i32 m0, s29, 0xe000
	s_nop 0
	global_load_lds_dwordx4 v[198:199], off
	s_waitcnt lgkmcnt(8)
	s_barrier
	s_waitcnt lgkmcnt(0)
	s_waitcnt lgkmcnt(0)
	v_mfma_f32_16x16x32_bf16 v[120:123], v[150:153], v[166:169], v[120:123]
	v_mfma_f32_16x16x32_bf16 v[124:127], v[158:161], v[166:169], v[124:127]
	v_mfma_f32_16x16x32_bf16 v[104:107], v[150:153], v[174:177], v[104:107]
	v_mfma_f32_16x16x32_bf16 v[108:111], v[158:161], v[174:177], v[108:111]
	v_mfma_f32_16x16x32_bf16 v[88:91], v[150:153], v[182:185], v[88:91]
	v_mfma_f32_16x16x32_bf16 v[92:95], v[158:161], v[182:185], v[92:95]
	v_mfma_f32_16x16x32_bf16 v[72:75], v[150:153], v[190:193], v[72:75]
	v_mfma_f32_16x16x32_bf16 v[76:79], v[158:161], v[190:193], v[76:79]
	v_mfma_f32_16x16x32_bf16 v[120:123], v[154:157], v[170:173], v[120:123]
	v_mfma_f32_16x16x32_bf16 v[124:127], v[162:165], v[170:173], v[124:127]
	v_mfma_f32_16x16x32_bf16 v[104:107], v[154:157], v[178:181], v[104:107]
	v_mfma_f32_16x16x32_bf16 v[108:111], v[162:165], v[178:181], v[108:111]
	v_mfma_f32_16x16x32_bf16 v[88:91], v[154:157], v[186:189], v[88:91]
	v_mfma_f32_16x16x32_bf16 v[92:95], v[162:165], v[186:189], v[92:95]
	v_mfma_f32_16x16x32_bf16 v[72:75], v[154:157], v[194:197], v[72:75]
	v_mfma_f32_16x16x32_bf16 v[76:79], v[162:165], v[194:197], v[76:79]
	s_barrier
	s_add_i32 s78, s60, s42
	v_lshl_add_u64 v[214:215], s[34:35], 0, v[130:131]
	s_mov_b32 m0, s78
	ds_read_b128 v[198:201], v149
	ds_read_b128 v[202:205], v149 offset:1024
	ds_read_b128 v[206:209], v149 offset:2048
	ds_read_b128 v[210:213], v149 offset:3072
	global_load_lds_dwordx4 v[214:215], off
	v_lshl_add_u64 v[216:217], s[34:35], 0, v[132:133]
	s_add_i32 m0, s78, 0x2000
	s_nop 0
	global_load_lds_dwordx4 v[216:217], off
	s_barrier
	s_waitcnt lgkmcnt(0)
	s_waitcnt lgkmcnt(0)
	v_mfma_f32_16x16x32_bf16 v[112:115], v[198:201], v[166:169], v[112:115]
	v_mfma_f32_16x16x32_bf16 v[116:119], v[206:209], v[166:169], v[116:119]
	v_mfma_f32_16x16x32_bf16 v[96:99], v[198:201], v[174:177], v[96:99]
	v_mfma_f32_16x16x32_bf16 v[100:103], v[206:209], v[174:177], v[100:103]
	v_mfma_f32_16x16x32_bf16 v[80:83], v[198:201], v[182:185], v[80:83]
	v_mfma_f32_16x16x32_bf16 v[84:87], v[206:209], v[182:185], v[84:87]
	v_mfma_f32_16x16x32_bf16 v[64:67], v[198:201], v[190:193], v[64:67]
	v_mfma_f32_16x16x32_bf16 v[68:71], v[206:209], v[190:193], v[68:71]
	v_mfma_f32_16x16x32_bf16 v[112:115], v[202:205], v[170:173], v[112:115]
	v_mfma_f32_16x16x32_bf16 v[116:119], v[210:213], v[170:173], v[116:119]
	v_mfma_f32_16x16x32_bf16 v[96:99], v[202:205], v[178:181], v[96:99]
	v_mfma_f32_16x16x32_bf16 v[100:103], v[210:213], v[178:181], v[100:103]
	v_mfma_f32_16x16x32_bf16 v[80:83], v[202:205], v[186:189], v[80:83]
	v_mfma_f32_16x16x32_bf16 v[84:87], v[210:213], v[186:189], v[84:87]
	v_mfma_f32_16x16x32_bf16 v[64:67], v[202:205], v[194:197], v[64:67]
	v_mfma_f32_16x16x32_bf16 v[68:71], v[210:213], v[194:197], v[68:71]
	s_mov_b32 m0, s29
	v_lshl_add_u64 v[218:219], s[36:37], 0, v[130:131]
	s_barrier
	ds_read_b128 v[166:169], v148 offset:16384
	ds_read_b128 v[170:173], v148 offset:17408
	ds_read_b128 v[174:177], v148 offset:18432
	ds_read_b128 v[178:181], v148 offset:19456
	ds_read_b128 v[182:185], v148 offset:20480
	ds_read_b128 v[186:189], v148 offset:21504
	ds_read_b128 v[190:193], v148 offset:22528
	ds_read_b128 v[194:197], v148 offset:23552
	global_load_lds_dwordx4 v[218:219], off
	v_lshl_add_u64 v[220:221], s[36:37], 0, v[132:133]
	s_mov_b32 m0, s43
	s_nop 0
	global_load_lds_dwordx4 v[220:221], off
	s_barrier
	s_waitcnt lgkmcnt(0)
	s_waitcnt lgkmcnt(0)
	v_mfma_f32_16x16x32_bf16 v[56:59], v[150:153], v[166:169], v[56:59]
	v_mfma_f32_16x16x32_bf16 v[60:63], v[158:161], v[166:169], v[60:63]
	v_mfma_f32_16x16x32_bf16 v[40:43], v[150:153], v[174:177], v[40:43]
	v_mfma_f32_16x16x32_bf16 v[44:47], v[158:161], v[174:177], v[44:47]
	v_mfma_f32_16x16x32_bf16 v[24:27], v[150:153], v[182:185], v[24:27]
	v_mfma_f32_16x16x32_bf16 v[28:31], v[158:161], v[182:185], v[28:31]
	v_mfma_f32_16x16x32_bf16 v[8:11], v[150:153], v[190:193], v[8:11]
	v_mfma_f32_16x16x32_bf16 v[12:15], v[158:161], v[190:193], v[12:15]
	v_mfma_f32_16x16x32_bf16 v[56:59], v[154:157], v[170:173], v[56:59]
	v_mfma_f32_16x16x32_bf16 v[60:63], v[162:165], v[170:173], v[60:63]
	v_mfma_f32_16x16x32_bf16 v[40:43], v[154:157], v[178:181], v[40:43]
	v_mfma_f32_16x16x32_bf16 v[44:47], v[162:165], v[178:181], v[44:47]
	v_mfma_f32_16x16x32_bf16 v[24:27], v[154:157], v[186:189], v[24:27]
	v_mfma_f32_16x16x32_bf16 v[28:31], v[162:165], v[186:189], v[28:31]
	v_mfma_f32_16x16x32_bf16 v[8:11], v[154:157], v[194:197], v[8:11]
	v_mfma_f32_16x16x32_bf16 v[12:15], v[162:165], v[194:197], v[12:15]
	s_barrier
	s_add_u32 s78, s34, 0x40000
	s_addc_u32 s79, s35, 0
	s_add_i32 s80, s61, s42
	v_lshl_add_u64 v[150:151], s[78:79], 0, v[130:131]
	s_mov_b32 m0, s80
	s_nop 0
	global_load_lds_dwordx4 v[150:151], off
	v_lshl_add_u64 v[150:151], s[78:79], 0, v[132:133]
	s_add_i32 m0, s80, 0x2000
	s_nop 0
	global_load_lds_dwordx4 v[150:151], off
	s_cmp_lg_u32 s94, 0
	s_cbranch_scc1 .Lrx8a
	s_waitcnt vmcnt(6)
.Lrx8a:
	s_waitcnt vmcnt(24)
	s_barrier
	v_mfma_f32_16x16x32_bf16 v[48:51], v[198:201], v[166:169], v[48:51]
	v_mfma_f32_16x16x32_bf16 v[52:55], v[206:209], v[166:169], v[52:55]
	v_mfma_f32_16x16x32_bf16 v[32:35], v[198:201], v[174:177], v[32:35]
	v_mfma_f32_16x16x32_bf16 v[36:39], v[206:209], v[174:177], v[36:39]
	v_mfma_f32_16x16x32_bf16 v[16:19], v[198:201], v[182:185], v[16:19]
	v_mfma_f32_16x16x32_bf16 v[20:23], v[206:209], v[182:185], v[20:23]
	v_mfma_f32_16x16x32_bf16 v[0:3], v[198:201], v[190:193], v[0:3]
	v_mfma_f32_16x16x32_bf16 v[4:7], v[206:209], v[190:193], v[4:7]
	v_mfma_f32_16x16x32_bf16 v[48:51], v[202:205], v[170:173], v[48:51]
	v_mfma_f32_16x16x32_bf16 v[52:55], v[210:213], v[170:173], v[52:55]
	v_mfma_f32_16x16x32_bf16 v[32:35], v[202:205], v[178:181], v[32:35]
	v_mfma_f32_16x16x32_bf16 v[36:39], v[210:213], v[178:181], v[36:39]
	v_mfma_f32_16x16x32_bf16 v[16:19], v[202:205], v[186:189], v[16:19]
	v_mfma_f32_16x16x32_bf16 v[20:23], v[210:213], v[186:189], v[20:23]
	v_mfma_f32_16x16x32_bf16 v[0:3], v[202:205], v[194:197], v[0:3]
	v_mfma_f32_16x16x32_bf16 v[4:7], v[210:213], v[194:197], v[4:7]
	s_add_i32 s78, 0, 0x18000
	v_add_u32_e32 v162, s78, v143
	s_barrier
	ds_read_b128 v[150:153], v162
	ds_read_b128 v[154:157], v162 offset:1024
	ds_read_b128 v[158:161], v162 offset:2048
	ds_read_b128 v[162:165], v162 offset:3072
	s_add_u32 s36, s36, 0x40000
	s_addc_u32 s37, s37, 0
	s_mov_b32 m0, s52
	v_lshl_add_u64 v[198:199], s[36:37], 0, v[130:131]
	ds_read_b128 v[166:169], v148 offset:32768
	ds_read_b128 v[170:173], v148 offset:33792
	ds_read_b128 v[174:177], v148 offset:34816
	ds_read_b128 v[178:181], v148 offset:35840
	ds_read_b128 v[182:185], v148 offset:36864
	ds_read_b128 v[186:189], v148 offset:37888
	ds_read_b128 v[190:193], v148 offset:38912
	ds_read_b128 v[194:197], v148 offset:39936
	global_load_lds_dwordx4 v[198:199], off
	v_lshl_add_u64 v[198:199], s[36:37], 0, v[132:133]
	s_mov_b32 m0, s53
	s_nop 0
	global_load_lds_dwordx4 v[198:199], off
	s_waitcnt lgkmcnt(8)
	s_barrier
	s_waitcnt lgkmcnt(0)
	s_waitcnt lgkmcnt(0)
	v_mfma_f32_16x16x32_bf16 v[120:123], v[150:153], v[166:169], v[120:123]
	v_mfma_f32_16x16x32_bf16 v[124:127], v[158:161], v[166:169], v[124:127]
	v_mfma_f32_16x16x32_bf16 v[104:107], v[150:153], v[174:177], v[104:107]
	v_mfma_f32_16x16x32_bf16 v[108:111], v[158:161], v[174:177], v[108:111]
	v_mfma_f32_16x16x32_bf16 v[88:91], v[150:153], v[182:185], v[88:91]
	v_mfma_f32_16x16x32_bf16 v[92:95], v[158:161], v[182:185], v[92:95]
	v_mfma_f32_16x16x32_bf16 v[72:75], v[150:153], v[190:193], v[72:75]
	v_mfma_f32_16x16x32_bf16 v[76:79], v[158:161], v[190:193], v[76:79]
	v_mfma_f32_16x16x32_bf16 v[120:123], v[154:157], v[170:173], v[120:123]
	v_mfma_f32_16x16x32_bf16 v[124:127], v[162:165], v[170:173], v[124:127]
	v_mfma_f32_16x16x32_bf16 v[104:107], v[154:157], v[178:181], v[104:107]
	v_mfma_f32_16x16x32_bf16 v[108:111], v[162:165], v[178:181], v[108:111]
	v_mfma_f32_16x16x32_bf16 v[88:91], v[154:157], v[186:189], v[88:91]
	v_mfma_f32_16x16x32_bf16 v[92:95], v[162:165], v[186:189], v[92:95]
	v_mfma_f32_16x16x32_bf16 v[72:75], v[154:157], v[194:197], v[72:75]
	v_mfma_f32_16x16x32_bf16 v[76:79], v[162:165], v[194:197], v[76:79]
	s_barrier
	s_add_i32 s36, 0, 0x1c000
	s_add_i32 s37, s78, s42
	v_add_u32_e32 v210, s36, v143
	v_lshl_add_u64 v[214:215], v[214:215], 0, s[8:9]
	s_mov_b32 m0, s37
	ds_read_b128 v[198:201], v210
	ds_read_b128 v[202:205], v210 offset:1024
	ds_read_b128 v[206:209], v210 offset:2048
	ds_read_b128 v[210:213], v210 offset:3072
	global_load_lds_dwordx4 v[214:215], off
	v_lshl_add_u64 v[214:215], v[216:217], 0, s[8:9]
	s_add_i32 m0, s37, 0x2000
	s_nop 0
	global_load_lds_dwordx4 v[214:215], off
	s_cmp_lg_u32 s94, 0
	s_cbranch_scc0 .Lrx8c
	s_waitcnt vmcnt(10)
	s_mov_b32 s94, 0
.Lrx8c:
	s_barrier
	s_waitcnt lgkmcnt(0)
	s_waitcnt lgkmcnt(0)
	v_mfma_f32_16x16x32_bf16 v[112:115], v[198:201], v[166:169], v[112:115]
	v_mfma_f32_16x16x32_bf16 v[116:119], v[206:209], v[166:169], v[116:119]
	v_mfma_f32_16x16x32_bf16 v[96:99], v[198:201], v[174:177], v[96:99]
	v_mfma_f32_16x16x32_bf16 v[100:103], v[206:209], v[174:177], v[100:103]
	v_mfma_f32_16x16x32_bf16 v[80:83], v[198:201], v[182:185], v[80:83]
	v_mfma_f32_16x16x32_bf16 v[84:87], v[206:209], v[182:185], v[84:87]
	v_mfma_f32_16x16x32_bf16 v[64:67], v[198:201], v[190:193], v[64:67]
	v_mfma_f32_16x16x32_bf16 v[68:71], v[206:209], v[190:193], v[68:71]
	v_mfma_f32_16x16x32_bf16 v[112:115], v[202:205], v[170:173], v[112:115]
	v_mfma_f32_16x16x32_bf16 v[116:119], v[210:213], v[170:173], v[116:119]
	v_mfma_f32_16x16x32_bf16 v[96:99], v[202:205], v[178:181], v[96:99]
	v_mfma_f32_16x16x32_bf16 v[100:103], v[210:213], v[178:181], v[100:103]
	v_mfma_f32_16x16x32_bf16 v[80:83], v[202:205], v[186:189], v[80:83]
	v_mfma_f32_16x16x32_bf16 v[84:87], v[210:213], v[186:189], v[84:87]
	v_mfma_f32_16x16x32_bf16 v[64:67], v[202:205], v[194:197], v[64:67]
	v_mfma_f32_16x16x32_bf16 v[68:71], v[210:213], v[194:197], v[68:71]
	s_mov_b32 m0, s55
	v_lshl_add_u64 v[214:215], v[218:219], 0, s[8:9]
	s_barrier
	ds_read_b128 v[166:169], v148 offset:49152
	ds_read_b128 v[170:173], v148 offset:50176
	ds_read_b128 v[174:177], v148 offset:51200
	ds_read_b128 v[178:181], v148 offset:52224
	ds_read_b128 v[182:185], v148 offset:53248
	ds_read_b128 v[186:189], v148 offset:54272
	ds_read_b128 v[190:193], v148 offset:55296
	ds_read_b128 v[194:197], v148 offset:56320
	global_load_lds_dwordx4 v[214:215], off
	v_lshl_add_u64 v[214:215], v[220:221], 0, s[8:9]
	s_mov_b32 m0, s56
	s_nop 0
	global_load_lds_dwordx4 v[214:215], off
	s_barrier
	s_waitcnt lgkmcnt(0)
	s_waitcnt lgkmcnt(0)
	v_mfma_f32_16x16x32_bf16 v[56:59], v[150:153], v[166:169], v[56:59]
	v_mfma_f32_16x16x32_bf16 v[60:63], v[158:161], v[166:169], v[60:63]
	v_mfma_f32_16x16x32_bf16 v[40:43], v[150:153], v[174:177], v[40:43]
	v_mfma_f32_16x16x32_bf16 v[44:47], v[158:161], v[174:177], v[44:47]
	v_mfma_f32_16x16x32_bf16 v[24:27], v[150:153], v[182:185], v[24:27]
	v_mfma_f32_16x16x32_bf16 v[28:31], v[158:161], v[182:185], v[28:31]
	v_mfma_f32_16x16x32_bf16 v[8:11], v[150:153], v[190:193], v[8:11]
	v_mfma_f32_16x16x32_bf16 v[12:15], v[158:161], v[190:193], v[12:15]
	v_mfma_f32_16x16x32_bf16 v[56:59], v[154:157], v[170:173], v[56:59]
	v_mfma_f32_16x16x32_bf16 v[60:63], v[162:165], v[170:173], v[60:63]
	v_mfma_f32_16x16x32_bf16 v[40:43], v[154:157], v[178:181], v[40:43]
	v_mfma_f32_16x16x32_bf16 v[44:47], v[162:165], v[178:181], v[44:47]
	v_mfma_f32_16x16x32_bf16 v[24:27], v[154:157], v[186:189], v[24:27]
	v_mfma_f32_16x16x32_bf16 v[28:31], v[162:165], v[186:189], v[28:31]
	v_mfma_f32_16x16x32_bf16 v[8:11], v[154:157], v[194:197], v[8:11]
	v_mfma_f32_16x16x32_bf16 v[12:15], v[162:165], v[194:197], v[12:15]
	s_barrier
	s_add_u32 s34, s34, 0x40080
	s_addc_u32 s35, s35, 0
	s_add_i32 s36, s36, s42
	v_lshl_add_u64 v[150:151], s[34:35], 0, v[130:131]
	s_mov_b32 m0, s36
	s_nop 0
	global_load_lds_dwordx4 v[150:151], off
	v_lshl_add_u64 v[150:151], s[34:35], 0, v[132:133]
	s_add_i32 m0, s36, 0x2000
	s_nop 0
	global_load_lds_dwordx4 v[150:151], off
	s_waitcnt vmcnt(6)
	s_barrier
	v_mfma_f32_16x16x32_bf16 v[48:51], v[198:201], v[166:169], v[48:51]
	v_mfma_f32_16x16x32_bf16 v[52:55], v[206:209], v[166:169], v[52:55]
	v_mfma_f32_16x16x32_bf16 v[32:35], v[198:201], v[174:177], v[32:35]
	v_mfma_f32_16x16x32_bf16 v[36:39], v[206:209], v[174:177], v[36:39]
	v_mfma_f32_16x16x32_bf16 v[16:19], v[198:201], v[182:185], v[16:19]
	v_mfma_f32_16x16x32_bf16 v[20:23], v[206:209], v[182:185], v[20:23]
	v_mfma_f32_16x16x32_bf16 v[0:3], v[198:201], v[190:193], v[0:3]
	v_mfma_f32_16x16x32_bf16 v[4:7], v[206:209], v[190:193], v[4:7]
	v_mfma_f32_16x16x32_bf16 v[48:51], v[202:205], v[170:173], v[48:51]
	v_mfma_f32_16x16x32_bf16 v[52:55], v[210:213], v[170:173], v[52:55]
	v_mfma_f32_16x16x32_bf16 v[32:35], v[202:205], v[178:181], v[32:35]
	v_mfma_f32_16x16x32_bf16 v[36:39], v[210:213], v[178:181], v[36:39]
	v_mfma_f32_16x16x32_bf16 v[16:19], v[202:205], v[186:189], v[16:19]
	v_mfma_f32_16x16x32_bf16 v[20:23], v[210:213], v[186:189], v[20:23]
	v_mfma_f32_16x16x32_bf16 v[0:3], v[202:205], v[194:197], v[0:3]
	v_mfma_f32_16x16x32_bf16 v[4:7], v[210:213], v[194:197], v[4:7]
	s_add_i32 s77, s77, 2
	s_add_u32 s30, s30, 0x100
	s_addc_u32 s31, s31, 0
	s_add_u32 s75, s75, 0x100
	s_addc_u32 s76, s76, 0
	s_cmp_gt_u32 s77, 13
	s_barrier
	s_cbranch_scc0 .LBB0_1141
	v_mul_f32_e32 v124, 0xbfb8aa3b, v124
	v_exp_f32_e32 v150, v124
	v_mul_f32_e32 v124, 0xbfb8aa3b, v125
	v_exp_f32_e32 v151, v124
	v_lshl_add_u32 v124, s28, 8, v142
	v_ashrrev_i32_e32 v125, 31, v124
	v_lshlrev_b64 v[154:155], 11, v[124:125]
	v_pk_add_f32 v[150:151], v[150:151], 1.0 op_sel_hi:[1,0]
	v_mul_f32_e32 v126, 0xbfb8aa3b, v126
	v_div_scale_f32 v153, s[30:31], v151, v151, v121
	v_rcp_f32_e32 v156, v153
	v_mul_f32_e32 v127, 0xbfb8aa3b, v127
	v_exp_f32_e32 v126, v126
	v_exp_f32_e32 v127, v127
	v_fma_f32 v125, -v153, v156, 1.0
	v_fmac_f32_e32 v156, v125, v156
	v_div_scale_f32 v125, vcc, v121, v151, v121
	v_mul_f32_e32 v157, v125, v156
	v_fma_f32 v158, -v153, v157, v125
	v_fmac_f32_e32 v157, v158, v156
	v_fma_f32 v125, -v153, v157, v125
	v_div_scale_f32 v153, s[30:31], v150, v150, v120
	v_rcp_f32_e32 v158, v153
	v_div_fmas_f32 v125, v125, v156, v157
	v_div_fixup_f32 v121, v125, v151, v121
	v_pk_add_f32 v[126:127], v[126:127], 1.0 op_sel_hi:[1,0]
	v_fma_f32 v125, -v153, v158, 1.0
	v_fmac_f32_e32 v158, v125, v158
	v_div_scale_f32 v125, vcc, v120, v150, v120
	v_mul_f32_e32 v151, v125, v158
	v_fma_f32 v156, -v153, v151, v125
	v_fmac_f32_e32 v151, v156, v158
	v_fma_f32 v125, -v153, v151, v125
	v_div_scale_f32 v153, s[30:31], v127, v127, v123
	v_rcp_f32_e32 v156, v153
	v_div_fmas_f32 v125, v125, v158, v151
	v_div_fixup_f32 v120, v125, v150, v120
	v_mul_f32_e32 v116, 0xbfb8aa3b, v116
	v_fma_f32 v125, -v153, v156, 1.0
	v_fmac_f32_e32 v156, v125, v156
	v_div_scale_f32 v125, vcc, v123, v127, v123
	v_mul_f32_e32 v150, v125, v156
	v_fma_f32 v151, -v153, v150, v125
	v_fmac_f32_e32 v150, v151, v156
	v_div_scale_f32 v151, s[30:31], v126, v126, v122
	v_fma_f32 v125, -v153, v150, v125
	v_rcp_f32_e32 v153, v151
	v_div_fmas_f32 v125, v125, v156, v150
	v_div_fixup_f32 v123, v125, v127, v123
	v_mul_f32_e32 v117, 0xbfb8aa3b, v117
	v_fma_f32 v125, -v151, v153, 1.0
	v_fmac_f32_e32 v153, v125, v153
	v_div_scale_f32 v125, vcc, v122, v126, v122
	v_mul_f32_e32 v127, v125, v153
	v_fma_f32 v150, -v151, v127, v125
	v_exp_f32_e32 v116, v116
	v_exp_f32_e32 v117, v117
	v_fmac_f32_e32 v127, v150, v153
	v_fma_f32 v125, -v151, v127, v125
	v_div_fmas_f32 v125, v125, v153, v127
	v_div_fixup_f32 v125, v125, v126, v122
	v_pk_add_f32 v[126:127], v[116:117], 1.0 op_sel_hi:[1,0]
	v_cvt_pk_bf16_f32 v123, v125, v123
	v_div_scale_f32 v125, s[30:31], v127, v127, v113
	v_lshl_or_b32 v152, s72, 7, v144
	v_rcp_f32_e32 v150, v125
	v_ashrrev_i32_e32 v153, 31, v152
	v_lshl_add_u64 v[154:155], s[46:47], 0, v[154:155]
	v_cvt_pk_bf16_f32 v122, v120, v121
	v_lshlrev_b64 v[120:121], 1, v[152:153]
	v_lshl_add_u64 v[116:117], v[154:155], 0, v[120:121]
	global_store_dwordx2 v[116:117], v[122:123], off
	v_fma_f32 v122, -v125, v150, 1.0
	v_fmac_f32_e32 v150, v122, v150
	v_div_scale_f32 v122, vcc, v113, v127, v113
	v_mul_f32_e32 v123, v122, v150
	v_fma_f32 v151, -v125, v123, v122
	v_fmac_f32_e32 v123, v151, v150
	v_fma_f32 v122, -v125, v123, v122
	v_div_scale_f32 v125, s[30:31], v126, v126, v112
	v_rcp_f32_e32 v151, v125
	v_div_fmas_f32 v122, v122, v150, v123
	v_mul_f32_e32 v118, 0xbfb8aa3b, v118
	v_mul_f32_e32 v119, 0xbfb8aa3b, v119
	v_div_fixup_f32 v113, v122, v127, v113
	v_fma_f32 v122, -v125, v151, 1.0
	v_exp_f32_e32 v118, v118
	v_exp_f32_e32 v119, v119
	v_fmac_f32_e32 v151, v122, v151
	v_div_scale_f32 v122, vcc, v112, v126, v112
	v_mul_f32_e32 v123, v122, v151
	v_fma_f32 v127, -v125, v123, v122
	v_fmac_f32_e32 v123, v127, v151
	v_pk_add_f32 v[118:119], v[118:119], 1.0 op_sel_hi:[1,0]
	v_fma_f32 v122, -v125, v123, v122
	v_div_scale_f32 v125, s[30:31], v119, v119, v115
	v_rcp_f32_e32 v127, v125
	v_div_fmas_f32 v122, v122, v151, v123
	v_div_fixup_f32 v112, v122, v126, v112
	v_mul_f32_e32 v108, 0xbfb8aa3b, v108
	v_fma_f32 v122, -v125, v127, 1.0
	v_fmac_f32_e32 v127, v122, v127
	v_div_scale_f32 v122, vcc, v115, v119, v115
	v_mul_f32_e32 v123, v122, v127
	v_fma_f32 v126, -v125, v123, v122
	v_fmac_f32_e32 v123, v126, v127
	v_fma_f32 v122, -v125, v123, v122
	v_div_scale_f32 v125, s[30:31], v118, v118, v114
	v_rcp_f32_e32 v126, v125
	v_div_fmas_f32 v122, v122, v127, v123
	v_div_fixup_f32 v115, v122, v119, v115
	v_mul_f32_e32 v109, 0xbfb8aa3b, v109
	v_fma_f32 v119, -v125, v126, 1.0
	v_fmac_f32_e32 v126, v119, v126
	v_div_scale_f32 v119, vcc, v114, v118, v114
	v_mul_f32_e32 v122, v119, v126
	v_fma_f32 v123, -v125, v122, v119
	v_exp_f32_e32 v108, v108
	v_exp_f32_e32 v109, v109
	v_fmac_f32_e32 v122, v123, v126
	v_fma_f32 v119, -v125, v122, v119
	v_div_fmas_f32 v119, v119, v126, v122
	v_div_fixup_f32 v114, v119, v118, v114
	v_pk_add_f32 v[108:109], v[108:109], 1.0 op_sel_hi:[1,0]
	v_cvt_pk_bf16_f32 v112, v112, v113
	v_cvt_pk_bf16_f32 v113, v114, v115
	v_div_scale_f32 v114, s[30:31], v109, v109, v105
	v_rcp_f32_e32 v115, v114
	v_mul_f32_e32 v110, 0xbfb8aa3b, v110
	v_mul_f32_e32 v111, 0xbfb8aa3b, v111
	v_exp_f32_e32 v110, v110
	v_fma_f32 v118, -v114, v115, 1.0
	v_fmac_f32_e32 v115, v118, v115
	v_div_scale_f32 v118, vcc, v105, v109, v105
	v_mul_f32_e32 v119, v118, v115
	v_fma_f32 v122, -v114, v119, v118
	v_fmac_f32_e32 v119, v122, v115
	v_fma_f32 v114, -v114, v119, v118
	v_div_scale_f32 v118, s[30:31], v108, v108, v104
	v_rcp_f32_e32 v122, v118
	v_div_fmas_f32 v114, v114, v115, v119
	v_exp_f32_e32 v111, v111
	v_div_fixup_f32 v105, v114, v109, v105
	v_fma_f32 v109, -v118, v122, 1.0
	v_fmac_f32_e32 v122, v109, v122
	v_div_scale_f32 v109, vcc, v104, v108, v104
	v_mul_f32_e32 v114, v109, v122
	v_fma_f32 v115, -v118, v114, v109
	v_pk_add_f32 v[110:111], v[110:111], 1.0 op_sel_hi:[1,0]
	v_fmac_f32_e32 v114, v115, v122
	v_div_scale_f32 v115, s[30:31], v111, v111, v107
	v_fma_f32 v109, -v118, v114, v109
	v_rcp_f32_e32 v118, v115
	v_div_fmas_f32 v109, v109, v122, v114
	v_div_fixup_f32 v104, v109, v108, v104
	v_mul_f32_e32 v100, 0xbfb8aa3b, v100
	v_fma_f32 v108, -v115, v118, 1.0
	v_fmac_f32_e32 v118, v108, v118
	v_div_scale_f32 v108, vcc, v107, v111, v107
	v_mul_f32_e32 v109, v108, v118
	v_fma_f32 v114, -v115, v109, v108
	v_fmac_f32_e32 v109, v114, v118
	v_div_scale_f32 v114, s[30:31], v110, v110, v106
	v_fma_f32 v108, -v115, v109, v108
	v_rcp_f32_e32 v115, v114
	v_div_fmas_f32 v108, v108, v118, v109
	v_div_fixup_f32 v107, v108, v111, v107
	v_mul_f32_e32 v101, 0xbfb8aa3b, v101
	v_fma_f32 v108, -v114, v115, 1.0
	v_fmac_f32_e32 v115, v108, v115
	v_div_scale_f32 v108, vcc, v106, v110, v106
	v_mul_f32_e32 v109, v108, v115
	v_exp_f32_e32 v100, v100
	v_exp_f32_e32 v101, v101
	v_fma_f32 v111, -v114, v109, v108
	v_fmac_f32_e32 v109, v111, v115
	v_fma_f32 v108, -v114, v109, v108
	v_div_fmas_f32 v108, v108, v115, v109
	v_pk_add_f32 v[100:101], v[100:101], 1.0 op_sel_hi:[1,0]
	global_store_dwordx2 v[116:117], v[112:113], off offset:128
	v_or_b32_e32 v112, 16, v124
	v_div_fixup_f32 v106, v108, v110, v106
	v_div_scale_f32 v108, s[30:31], v101, v101, v97
	v_ashrrev_i32_e32 v113, 31, v112
	v_rcp_f32_e32 v109, v108
	v_lshlrev_b64 v[112:113], 11, v[112:113]
	v_lshl_add_u64 v[112:113], s[46:47], 0, v[112:113]
	v_cvt_pk_bf16_f32 v104, v104, v105
	v_cvt_pk_bf16_f32 v105, v106, v107
	v_lshl_add_u64 v[106:107], v[112:113], 0, v[120:121]
	global_store_dwordx2 v[106:107], v[104:105], off
	v_fma_f32 v104, -v108, v109, 1.0
	v_fmac_f32_e32 v109, v104, v109
	v_div_scale_f32 v104, vcc, v97, v101, v97
	v_mul_f32_e32 v105, v104, v109
	v_fma_f32 v110, -v108, v105, v104
	v_fmac_f32_e32 v105, v110, v109
	v_fma_f32 v104, -v108, v105, v104
	v_div_scale_f32 v108, s[30:31], v100, v100, v96
	v_rcp_f32_e32 v110, v108
	v_mul_f32_e32 v102, 0xbfb8aa3b, v102
	v_mul_f32_e32 v103, 0xbfb8aa3b, v103
	v_div_fmas_f32 v104, v104, v109, v105
	v_exp_f32_e32 v102, v102
	v_exp_f32_e32 v103, v103
	v_div_fixup_f32 v97, v104, v101, v97
	v_fma_f32 v101, -v108, v110, 1.0
	v_fmac_f32_e32 v110, v101, v110
	v_div_scale_f32 v101, vcc, v96, v100, v96
	v_mul_f32_e32 v104, v101, v110
	v_fma_f32 v105, -v108, v104, v101
	v_pk_add_f32 v[102:103], v[102:103], 1.0 op_sel_hi:[1,0]
	v_fmac_f32_e32 v104, v105, v110
	v_div_scale_f32 v105, s[30:31], v103, v103, v99
	v_fma_f32 v101, -v108, v104, v101
	v_rcp_f32_e32 v108, v105
	v_div_fmas_f32 v101, v101, v110, v104
	v_div_fixup_f32 v96, v101, v100, v96
	v_mul_f32_e32 v92, 0xbfb8aa3b, v92
	v_fma_f32 v100, -v105, v108, 1.0
	v_fmac_f32_e32 v108, v100, v108
	v_div_scale_f32 v100, vcc, v99, v103, v99
	v_mul_f32_e32 v101, v100, v108
	v_fma_f32 v104, -v105, v101, v100
	v_fmac_f32_e32 v101, v104, v108
	v_div_scale_f32 v104, s[30:31], v102, v102, v98
	v_fma_f32 v100, -v105, v101, v100
	v_rcp_f32_e32 v105, v104
	v_div_fmas_f32 v100, v100, v108, v101
	v_div_fixup_f32 v99, v100, v103, v99
	v_mul_f32_e32 v93, 0xbfb8aa3b, v93
	v_fma_f32 v100, -v104, v105, 1.0
	v_fmac_f32_e32 v105, v100, v105
	v_div_scale_f32 v100, vcc, v98, v102, v98
	v_mul_f32_e32 v101, v100, v105
	v_fma_f32 v103, -v104, v101, v100
	v_exp_f32_e32 v92, v92
	v_exp_f32_e32 v93, v93
	v_fmac_f32_e32 v101, v103, v105
	v_fma_f32 v100, -v104, v101, v100
	v_div_fmas_f32 v100, v100, v105, v101
	v_div_fixup_f32 v98, v100, v102, v98
	v_pk_add_f32 v[92:93], v[92:93], 1.0 op_sel_hi:[1,0]
	v_cvt_pk_bf16_f32 v96, v96, v97
	v_cvt_pk_bf16_f32 v97, v98, v99
	v_div_scale_f32 v98, s[30:31], v93, v93, v89
	v_rcp_f32_e32 v99, v98
	v_mul_f32_e32 v94, 0xbfb8aa3b, v94
	v_mul_f32_e32 v95, 0xbfb8aa3b, v95
	v_exp_f32_e32 v94, v94
	v_fma_f32 v100, -v98, v99, 1.0
	v_fmac_f32_e32 v99, v100, v99
	v_div_scale_f32 v100, vcc, v89, v93, v89
	v_mul_f32_e32 v101, v100, v99
	v_fma_f32 v102, -v98, v101, v100
	v_fmac_f32_e32 v101, v102, v99
	v_fma_f32 v98, -v98, v101, v100
	v_div_scale_f32 v100, s[30:31], v92, v92, v88
	v_rcp_f32_e32 v102, v100
	v_div_fmas_f32 v98, v98, v99, v101
	v_exp_f32_e32 v95, v95
	v_div_fixup_f32 v89, v98, v93, v89
	v_fma_f32 v93, -v100, v102, 1.0
	v_fmac_f32_e32 v102, v93, v102
	v_div_scale_f32 v93, vcc, v88, v92, v88
	v_mul_f32_e32 v98, v93, v102
	v_fma_f32 v99, -v100, v98, v93
	v_pk_add_f32 v[94:95], v[94:95], 1.0 op_sel_hi:[1,0]
	v_fmac_f32_e32 v98, v99, v102
	v_div_scale_f32 v99, s[30:31], v95, v95, v91
	v_fma_f32 v93, -v100, v98, v93
	v_rcp_f32_e32 v100, v99
	v_div_fmas_f32 v93, v93, v102, v98
	v_div_fixup_f32 v88, v93, v92, v88
	v_mul_f32_e32 v84, 0xbfb8aa3b, v84
	v_fma_f32 v92, -v99, v100, 1.0
	v_fmac_f32_e32 v100, v92, v100
	v_div_scale_f32 v92, vcc, v91, v95, v91
	v_mul_f32_e32 v93, v92, v100
	v_fma_f32 v98, -v99, v93, v92
	v_fmac_f32_e32 v93, v98, v100
	v_div_scale_f32 v98, s[30:31], v94, v94, v90
	v_fma_f32 v92, -v99, v93, v92
	v_rcp_f32_e32 v99, v98
	v_div_fmas_f32 v92, v92, v100, v93
	v_div_fixup_f32 v91, v92, v95, v91
	v_mul_f32_e32 v85, 0xbfb8aa3b, v85
	v_fma_f32 v92, -v98, v99, 1.0
	v_fmac_f32_e32 v99, v92, v99
	v_div_scale_f32 v92, vcc, v90, v94, v90
	v_mul_f32_e32 v93, v92, v99
	v_exp_f32_e32 v84, v84
	v_exp_f32_e32 v85, v85
	v_fma_f32 v95, -v98, v93, v92
	v_fmac_f32_e32 v93, v95, v99
	v_fma_f32 v92, -v98, v93, v92
	v_div_fmas_f32 v92, v92, v99, v93
	v_pk_add_f32 v[84:85], v[84:85], 1.0 op_sel_hi:[1,0]
	global_store_dwordx2 v[106:107], v[96:97], off offset:128
	v_or_b32_e32 v96, 32, v124
	v_div_fixup_f32 v90, v92, v94, v90
	v_div_scale_f32 v92, s[30:31], v85, v85, v81
	v_ashrrev_i32_e32 v97, 31, v96
	v_rcp_f32_e32 v93, v92
	v_lshlrev_b64 v[96:97], 11, v[96:97]
	v_lshl_add_u64 v[96:97], s[46:47], 0, v[96:97]
	v_cvt_pk_bf16_f32 v88, v88, v89
	v_cvt_pk_bf16_f32 v89, v90, v91
	v_lshl_add_u64 v[90:91], v[96:97], 0, v[120:121]
	global_store_dwordx2 v[90:91], v[88:89], off
	v_fma_f32 v88, -v92, v93, 1.0
	v_fmac_f32_e32 v93, v88, v93
	v_div_scale_f32 v88, vcc, v81, v85, v81
	v_mul_f32_e32 v89, v88, v93
	v_fma_f32 v94, -v92, v89, v88
	v_fmac_f32_e32 v89, v94, v93
	v_fma_f32 v88, -v92, v89, v88
	v_div_scale_f32 v92, s[30:31], v84, v84, v80
	v_rcp_f32_e32 v94, v92
	v_mul_f32_e32 v86, 0xbfb8aa3b, v86
	v_mul_f32_e32 v87, 0xbfb8aa3b, v87
	v_div_fmas_f32 v88, v88, v93, v89
	v_exp_f32_e32 v86, v86
	v_exp_f32_e32 v87, v87
	v_div_fixup_f32 v81, v88, v85, v81
	v_fma_f32 v85, -v92, v94, 1.0
	v_fmac_f32_e32 v94, v85, v94
	v_div_scale_f32 v85, vcc, v80, v84, v80
	v_mul_f32_e32 v88, v85, v94
	v_fma_f32 v89, -v92, v88, v85
	v_pk_add_f32 v[86:87], v[86:87], 1.0 op_sel_hi:[1,0]
	v_fmac_f32_e32 v88, v89, v94
	v_div_scale_f32 v89, s[30:31], v87, v87, v83
	v_fma_f32 v85, -v92, v88, v85
	v_rcp_f32_e32 v92, v89
	v_div_fmas_f32 v85, v85, v94, v88
	v_div_fixup_f32 v80, v85, v84, v80
	v_mul_f32_e32 v76, 0xbfb8aa3b, v76
	v_fma_f32 v84, -v89, v92, 1.0
	v_fmac_f32_e32 v92, v84, v92
	v_div_scale_f32 v84, vcc, v83, v87, v83
	v_mul_f32_e32 v85, v84, v92
	v_fma_f32 v88, -v89, v85, v84
	v_fmac_f32_e32 v85, v88, v92
	v_div_scale_f32 v88, s[30:31], v86, v86, v82
	v_fma_f32 v84, -v89, v85, v84
	v_rcp_f32_e32 v89, v88
	v_div_fmas_f32 v84, v84, v92, v85
	v_div_fixup_f32 v83, v84, v87, v83
	v_mul_f32_e32 v77, 0xbfb8aa3b, v77
	v_fma_f32 v84, -v88, v89, 1.0
	v_fmac_f32_e32 v89, v84, v89
	v_div_scale_f32 v84, vcc, v82, v86, v82
	v_mul_f32_e32 v85, v84, v89
	v_fma_f32 v87, -v88, v85, v84
	v_exp_f32_e32 v76, v76
	v_exp_f32_e32 v77, v77
	v_fmac_f32_e32 v85, v87, v89
	v_fma_f32 v84, -v88, v85, v84
	v_div_fmas_f32 v84, v84, v89, v85
	v_div_fixup_f32 v82, v84, v86, v82
	v_pk_add_f32 v[76:77], v[76:77], 1.0 op_sel_hi:[1,0]
	v_cvt_pk_bf16_f32 v80, v80, v81
	v_cvt_pk_bf16_f32 v81, v82, v83
	v_div_scale_f32 v82, s[30:31], v77, v77, v73
	v_rcp_f32_e32 v83, v82
	v_mul_f32_e32 v78, 0xbfb8aa3b, v78
	v_mul_f32_e32 v79, 0xbfb8aa3b, v79
	v_exp_f32_e32 v78, v78
	v_fma_f32 v84, -v82, v83, 1.0
	v_fmac_f32_e32 v83, v84, v83
	v_div_scale_f32 v84, vcc, v73, v77, v73
	v_mul_f32_e32 v85, v84, v83
	v_fma_f32 v86, -v82, v85, v84
	v_fmac_f32_e32 v85, v86, v83
	v_fma_f32 v82, -v82, v85, v84
	v_div_scale_f32 v84, s[30:31], v76, v76, v72
	v_rcp_f32_e32 v86, v84
	v_div_fmas_f32 v82, v82, v83, v85
	v_exp_f32_e32 v79, v79
	v_div_fixup_f32 v73, v82, v77, v73
	v_fma_f32 v77, -v84, v86, 1.0
	v_fmac_f32_e32 v86, v77, v86
	v_div_scale_f32 v77, vcc, v72, v76, v72
	v_mul_f32_e32 v82, v77, v86
	v_fma_f32 v83, -v84, v82, v77
	v_pk_add_f32 v[78:79], v[78:79], 1.0 op_sel_hi:[1,0]
	v_fmac_f32_e32 v82, v83, v86
	v_div_scale_f32 v83, s[30:31], v79, v79, v75
	v_fma_f32 v77, -v84, v82, v77
	v_rcp_f32_e32 v84, v83
	v_div_fmas_f32 v77, v77, v86, v82
	v_div_fixup_f32 v72, v77, v76, v72
	v_mul_f32_e32 v68, 0xbfb8aa3b, v68
	v_fma_f32 v76, -v83, v84, 1.0
	v_fmac_f32_e32 v84, v76, v84
	v_div_scale_f32 v76, vcc, v75, v79, v75
	v_mul_f32_e32 v77, v76, v84
	v_fma_f32 v82, -v83, v77, v76
	v_fmac_f32_e32 v77, v82, v84
	v_div_scale_f32 v82, s[30:31], v78, v78, v74
	v_fma_f32 v76, -v83, v77, v76
	v_rcp_f32_e32 v83, v82
	v_div_fmas_f32 v76, v76, v84, v77
	v_div_fixup_f32 v75, v76, v79, v75
	v_mul_f32_e32 v69, 0xbfb8aa3b, v69
	v_fma_f32 v76, -v82, v83, 1.0
	v_fmac_f32_e32 v83, v76, v83
	v_div_scale_f32 v76, vcc, v74, v78, v74
	v_mul_f32_e32 v77, v76, v83
	v_exp_f32_e32 v68, v68
	v_exp_f32_e32 v69, v69
	v_fma_f32 v79, -v82, v77, v76
	v_fmac_f32_e32 v77, v79, v83
	v_fma_f32 v76, -v82, v77, v76
	v_div_fmas_f32 v76, v76, v83, v77
	v_pk_add_f32 v[68:69], v[68:69], 1.0 op_sel_hi:[1,0]
	global_store_dwordx2 v[90:91], v[80:81], off offset:128
	v_or_b32_e32 v80, 48, v124
	v_div_fixup_f32 v74, v76, v78, v74
	v_div_scale_f32 v76, s[30:31], v69, v69, v65
	v_ashrrev_i32_e32 v81, 31, v80
	v_rcp_f32_e32 v77, v76
	v_lshlrev_b64 v[80:81], 11, v[80:81]
	v_lshl_add_u64 v[80:81], s[46:47], 0, v[80:81]
	v_cvt_pk_bf16_f32 v72, v72, v73
	v_cvt_pk_bf16_f32 v73, v74, v75
	v_lshl_add_u64 v[74:75], v[80:81], 0, v[120:121]
	global_store_dwordx2 v[74:75], v[72:73], off
	v_fma_f32 v72, -v76, v77, 1.0
	v_fmac_f32_e32 v77, v72, v77
	v_div_scale_f32 v72, vcc, v65, v69, v65
	v_mul_f32_e32 v73, v72, v77
	v_fma_f32 v78, -v76, v73, v72
	v_fmac_f32_e32 v73, v78, v77
	v_fma_f32 v72, -v76, v73, v72
	v_div_scale_f32 v76, s[30:31], v68, v68, v64
	v_rcp_f32_e32 v78, v76
	v_mul_f32_e32 v70, 0xbfb8aa3b, v70
	v_mul_f32_e32 v71, 0xbfb8aa3b, v71
	v_div_fmas_f32 v72, v72, v77, v73
	v_exp_f32_e32 v70, v70
	v_exp_f32_e32 v71, v71
	v_div_fixup_f32 v65, v72, v69, v65
	v_fma_f32 v69, -v76, v78, 1.0
	v_fmac_f32_e32 v78, v69, v78
	v_div_scale_f32 v69, vcc, v64, v68, v64
	v_mul_f32_e32 v72, v69, v78
	v_fma_f32 v73, -v76, v72, v69
	v_pk_add_f32 v[70:71], v[70:71], 1.0 op_sel_hi:[1,0]
	v_fmac_f32_e32 v72, v73, v78
	v_div_scale_f32 v73, s[30:31], v71, v71, v67
	v_fma_f32 v69, -v76, v72, v69
	v_rcp_f32_e32 v76, v73
	v_div_fmas_f32 v69, v69, v78, v72
	v_div_fixup_f32 v64, v69, v68, v64
	v_mul_f32_e32 v60, 0xbfb8aa3b, v60
	v_fma_f32 v68, -v73, v76, 1.0
	v_fmac_f32_e32 v76, v68, v76
	v_div_scale_f32 v68, vcc, v67, v71, v67
	v_mul_f32_e32 v69, v68, v76
	v_fma_f32 v72, -v73, v69, v68
	v_fmac_f32_e32 v69, v72, v76
	v_div_scale_f32 v72, s[30:31], v70, v70, v66
	v_fma_f32 v68, -v73, v69, v68
	v_rcp_f32_e32 v73, v72
	v_div_fmas_f32 v68, v68, v76, v69
	v_div_fixup_f32 v67, v68, v71, v67
	v_mul_f32_e32 v61, 0xbfb8aa3b, v61
	v_fma_f32 v68, -v72, v73, 1.0
	v_fmac_f32_e32 v73, v68, v73
	v_div_scale_f32 v68, vcc, v66, v70, v66
	v_mul_f32_e32 v69, v68, v73
	v_exp_f32_e32 v60, v60
	v_exp_f32_e32 v61, v61
	v_fma_f32 v71, -v72, v69, v68
	v_fmac_f32_e32 v69, v71, v73
	v_fma_f32 v68, -v72, v69, v68
	v_div_fmas_f32 v68, v68, v73, v69
	v_pk_add_f32 v[60:61], v[60:61], 1.0 op_sel_hi:[1,0]
	v_div_fixup_f32 v66, v68, v70, v66
	v_div_scale_f32 v68, s[30:31], v61, v61, v57
	v_rcp_f32_e32 v69, v68
	v_cvt_pk_bf16_f32 v64, v64, v65
	v_cvt_pk_bf16_f32 v65, v66, v67
	global_store_dwordx2 v[74:75], v[64:65], off offset:128
	v_fma_f32 v64, -v68, v69, 1.0
	v_fmac_f32_e32 v69, v64, v69
	v_div_scale_f32 v64, vcc, v57, v61, v57
	v_mul_f32_e32 v65, v64, v69
	v_fma_f32 v66, -v68, v65, v64
	v_fmac_f32_e32 v65, v66, v69
	v_div_scale_f32 v66, s[30:31], v60, v60, v56
	v_rcp_f32_e32 v67, v66
	v_fma_f32 v64, -v68, v65, v64
	v_mul_f32_e32 v62, 0xbfb8aa3b, v62
	v_mul_f32_e32 v63, 0xbfb8aa3b, v63
	v_div_fmas_f32 v64, v64, v69, v65
	v_exp_f32_e32 v62, v62
	v_exp_f32_e32 v63, v63
	v_div_fixup_f32 v57, v64, v61, v57
	v_fma_f32 v61, -v66, v67, 1.0
	v_fmac_f32_e32 v67, v61, v67
	v_div_scale_f32 v61, vcc, v56, v60, v56
	v_mul_f32_e32 v64, v61, v67
	v_fma_f32 v65, -v66, v64, v61
	v_pk_add_f32 v[62:63], v[62:63], 1.0 op_sel_hi:[1,0]
	v_fmac_f32_e32 v64, v65, v67
	v_div_scale_f32 v65, s[30:31], v63, v63, v59
	v_fma_f32 v61, -v66, v64, v61
	v_rcp_f32_e32 v66, v65
	v_div_fmas_f32 v61, v61, v67, v64
	v_div_fixup_f32 v56, v61, v60, v56
	v_mul_f32_e32 v52, 0xbfb8aa3b, v52
	v_fma_f32 v60, -v65, v66, 1.0
	v_fmac_f32_e32 v66, v60, v66
	v_div_scale_f32 v60, vcc, v59, v63, v59
	v_mul_f32_e32 v61, v60, v66
	v_fma_f32 v64, -v65, v61, v60
	v_fmac_f32_e32 v61, v64, v66
	v_div_scale_f32 v64, s[30:31], v62, v62, v58
	v_fma_f32 v60, -v65, v61, v60
	v_rcp_f32_e32 v65, v64
	v_div_fmas_f32 v60, v60, v66, v61
	v_div_fixup_f32 v59, v60, v63, v59
	v_mul_f32_e32 v53, 0xbfb8aa3b, v53
	v_fma_f32 v60, -v64, v65, 1.0
	v_fmac_f32_e32 v65, v60, v65
	v_div_scale_f32 v60, vcc, v58, v62, v58
	v_mul_f32_e32 v61, v60, v65
	v_exp_f32_e32 v52, v52
	v_exp_f32_e32 v53, v53
	v_fma_f32 v63, -v64, v61, v60
	v_fmac_f32_e32 v61, v63, v65
	v_fma_f32 v60, -v64, v61, v60
	v_div_fmas_f32 v60, v60, v65, v61
	v_pk_add_f32 v[52:53], v[52:53], 1.0 op_sel_hi:[1,0]
	v_div_fixup_f32 v58, v60, v62, v58
	v_div_scale_f32 v62, s[30:31], v53, v53, v49
	v_rcp_f32_e32 v63, v62
	v_add_co_u32_e32 v60, vcc, s62, v116
	v_cvt_pk_bf16_f32 v56, v56, v57
	v_cvt_pk_bf16_f32 v57, v58, v59
	v_addc_co_u32_e32 v61, vcc, 0, v117, vcc
	global_store_dwordx2 v[60:61], v[56:57], off
	v_fma_f32 v56, -v62, v63, 1.0
	v_fmac_f32_e32 v63, v56, v63
	v_div_scale_f32 v56, vcc, v49, v53, v49
	v_mul_f32_e32 v57, v56, v63
	v_fma_f32 v60, -v62, v57, v56
	v_fmac_f32_e32 v57, v60, v63
	v_div_scale_f32 v60, s[30:31], v52, v52, v48
	v_rcp_f32_e32 v61, v60
	v_fma_f32 v56, -v62, v57, v56
	v_mul_f32_e32 v54, 0xbfb8aa3b, v54
	v_mul_f32_e32 v55, 0xbfb8aa3b, v55
	v_div_fmas_f32 v56, v56, v63, v57
	v_exp_f32_e32 v54, v54
	v_exp_f32_e32 v55, v55
	v_div_fixup_f32 v49, v56, v53, v49
	v_fma_f32 v53, -v60, v61, 1.0
	v_fmac_f32_e32 v61, v53, v61
	v_div_scale_f32 v53, vcc, v48, v52, v48
	v_mul_f32_e32 v56, v53, v61
	v_fma_f32 v57, -v60, v56, v53
	v_pk_add_f32 v[54:55], v[54:55], 1.0 op_sel_hi:[1,0]
	v_fmac_f32_e32 v56, v57, v61
	v_div_scale_f32 v57, s[30:31], v55, v55, v51
	v_fma_f32 v53, -v60, v56, v53
	v_rcp_f32_e32 v60, v57
	v_div_fmas_f32 v53, v53, v61, v56
	v_div_fixup_f32 v48, v53, v52, v48
	v_mul_f32_e32 v44, 0xbfb8aa3b, v44
	v_fma_f32 v52, -v57, v60, 1.0
	v_fmac_f32_e32 v60, v52, v60
	v_div_scale_f32 v52, vcc, v51, v55, v51
	v_mul_f32_e32 v53, v52, v60
	v_fma_f32 v56, -v57, v53, v52
	v_fmac_f32_e32 v53, v56, v60
	v_div_scale_f32 v56, s[30:31], v54, v54, v50
	v_fma_f32 v52, -v57, v53, v52
	v_rcp_f32_e32 v57, v56
	v_div_fmas_f32 v52, v52, v60, v53
	v_div_fixup_f32 v51, v52, v55, v51
	v_mul_f32_e32 v45, 0xbfb8aa3b, v45
	v_fma_f32 v52, -v56, v57, 1.0
	v_fmac_f32_e32 v57, v52, v57
	v_div_scale_f32 v52, vcc, v50, v54, v50
	v_mul_f32_e32 v53, v52, v57
	v_exp_f32_e32 v44, v44
	v_exp_f32_e32 v45, v45
	v_fma_f32 v55, -v56, v53, v52
	v_fmac_f32_e32 v53, v55, v57
	v_fma_f32 v52, -v56, v53, v52
	v_div_fmas_f32 v52, v52, v57, v53
	v_pk_add_f32 v[44:45], v[44:45], 1.0 op_sel_hi:[1,0]
	v_div_fixup_f32 v50, v52, v54, v50
	v_div_scale_f32 v52, s[30:31], v45, v45, v41
	v_rcp_f32_e32 v53, v52
	v_lshl_add_u64 v[58:59], v[116:117], 0, s[6:7]
	v_cvt_pk_bf16_f32 v48, v48, v49
	v_cvt_pk_bf16_f32 v49, v50, v51
	global_store_dwordx2 v[58:59], v[48:49], off offset:128
	v_fma_f32 v48, -v52, v53, 1.0
	v_fmac_f32_e32 v53, v48, v53
	v_div_scale_f32 v48, vcc, v41, v45, v41
	v_mul_f32_e32 v49, v48, v53
	v_fma_f32 v50, -v52, v49, v48
	v_fmac_f32_e32 v49, v50, v53
	v_div_scale_f32 v50, s[30:31], v44, v44, v40
	v_rcp_f32_e32 v51, v50
	v_fma_f32 v48, -v52, v49, v48
	v_mul_f32_e32 v46, 0xbfb8aa3b, v46
	v_mul_f32_e32 v47, 0xbfb8aa3b, v47
	v_div_fmas_f32 v48, v48, v53, v49
	v_exp_f32_e32 v46, v46
	v_exp_f32_e32 v47, v47
	v_div_fixup_f32 v41, v48, v45, v41
	v_fma_f32 v45, -v50, v51, 1.0
	v_fmac_f32_e32 v51, v45, v51
	v_div_scale_f32 v45, vcc, v40, v44, v40
	v_mul_f32_e32 v48, v45, v51
	v_fma_f32 v49, -v50, v48, v45
	v_pk_add_f32 v[46:47], v[46:47], 1.0 op_sel_hi:[1,0]
	v_fmac_f32_e32 v48, v49, v51
	v_div_scale_f32 v49, s[30:31], v47, v47, v43
	v_fma_f32 v45, -v50, v48, v45
	v_rcp_f32_e32 v50, v49
	v_div_fmas_f32 v45, v45, v51, v48
	v_div_fixup_f32 v40, v45, v44, v40
	v_mul_f32_e32 v36, 0xbfb8aa3b, v36
	v_fma_f32 v44, -v49, v50, 1.0
	v_fmac_f32_e32 v50, v44, v50
	v_div_scale_f32 v44, vcc, v43, v47, v43
	v_mul_f32_e32 v45, v44, v50
	v_fma_f32 v48, -v49, v45, v44
	v_fmac_f32_e32 v45, v48, v50
	v_div_scale_f32 v48, s[30:31], v46, v46, v42
	v_fma_f32 v44, -v49, v45, v44
	v_rcp_f32_e32 v49, v48
	v_div_fmas_f32 v44, v44, v50, v45
	v_div_fixup_f32 v43, v44, v47, v43
	v_mul_f32_e32 v37, 0xbfb8aa3b, v37
	v_fma_f32 v44, -v48, v49, 1.0
	v_fmac_f32_e32 v49, v44, v49
	v_div_scale_f32 v44, vcc, v42, v46, v42
	v_mul_f32_e32 v45, v44, v49
	v_exp_f32_e32 v36, v36
	v_exp_f32_e32 v37, v37
	v_fma_f32 v47, -v48, v45, v44
	v_fmac_f32_e32 v45, v47, v49
	v_fma_f32 v44, -v48, v45, v44
	v_div_fmas_f32 v44, v44, v49, v45
	v_pk_add_f32 v[36:37], v[36:37], 1.0 op_sel_hi:[1,0]
	v_div_fixup_f32 v42, v44, v46, v42
	v_div_scale_f32 v46, s[30:31], v37, v37, v33
	v_rcp_f32_e32 v47, v46
	v_add_co_u32_e32 v44, vcc, s63, v116
	v_cvt_pk_bf16_f32 v40, v40, v41
	v_cvt_pk_bf16_f32 v41, v42, v43
	v_addc_co_u32_e32 v45, vcc, 0, v117, vcc
	global_store_dwordx2 v[44:45], v[40:41], off
	v_fma_f32 v40, -v46, v47, 1.0
	v_fmac_f32_e32 v47, v40, v47
	v_div_scale_f32 v40, vcc, v33, v37, v33
	v_mul_f32_e32 v41, v40, v47
	v_fma_f32 v44, -v46, v41, v40
	v_fmac_f32_e32 v41, v44, v47
	v_div_scale_f32 v44, s[30:31], v36, v36, v32
	v_rcp_f32_e32 v45, v44
	v_fma_f32 v40, -v46, v41, v40
	v_mul_f32_e32 v38, 0xbfb8aa3b, v38
	v_mul_f32_e32 v39, 0xbfb8aa3b, v39
	v_div_fmas_f32 v40, v40, v47, v41
	v_exp_f32_e32 v38, v38
	v_exp_f32_e32 v39, v39
	v_div_fixup_f32 v33, v40, v37, v33
	v_fma_f32 v37, -v44, v45, 1.0
	v_fmac_f32_e32 v45, v37, v45
	v_div_scale_f32 v37, vcc, v32, v36, v32
	v_mul_f32_e32 v40, v37, v45
	v_fma_f32 v41, -v44, v40, v37
	v_pk_add_f32 v[38:39], v[38:39], 1.0 op_sel_hi:[1,0]
	v_fmac_f32_e32 v40, v41, v45
	v_div_scale_f32 v41, s[30:31], v39, v39, v35
	v_fma_f32 v37, -v44, v40, v37
	v_rcp_f32_e32 v44, v41
	v_div_fmas_f32 v37, v37, v45, v40
	v_div_fixup_f32 v32, v37, v36, v32
	v_mul_f32_e32 v28, 0xbfb8aa3b, v28
	v_fma_f32 v36, -v41, v44, 1.0
	v_fmac_f32_e32 v44, v36, v44
	v_div_scale_f32 v36, vcc, v35, v39, v35
	v_mul_f32_e32 v37, v36, v44
	v_fma_f32 v40, -v41, v37, v36
	v_fmac_f32_e32 v37, v40, v44
	v_div_scale_f32 v40, s[30:31], v38, v38, v34
	v_fma_f32 v36, -v41, v37, v36
	v_rcp_f32_e32 v41, v40
	v_div_fmas_f32 v36, v36, v44, v37
	v_div_fixup_f32 v35, v36, v39, v35
	v_mul_f32_e32 v29, 0xbfb8aa3b, v29
	v_fma_f32 v36, -v40, v41, 1.0
	v_fmac_f32_e32 v41, v36, v41
	v_div_scale_f32 v36, vcc, v34, v38, v34
	v_mul_f32_e32 v37, v36, v41
	v_exp_f32_e32 v28, v28
	v_exp_f32_e32 v29, v29
	v_fma_f32 v39, -v40, v37, v36
	v_fmac_f32_e32 v37, v39, v41
	v_fma_f32 v36, -v40, v37, v36
	v_div_fmas_f32 v36, v36, v41, v37
	v_pk_add_f32 v[28:29], v[28:29], 1.0 op_sel_hi:[1,0]
	v_div_fixup_f32 v34, v36, v38, v34
	v_div_scale_f32 v36, s[30:31], v29, v29, v25
	v_rcp_f32_e32 v37, v36
	v_lshl_add_u64 v[42:43], v[116:117], 0, s[10:11]
	v_cvt_pk_bf16_f32 v32, v32, v33
	v_cvt_pk_bf16_f32 v33, v34, v35
	global_store_dwordx2 v[42:43], v[32:33], off offset:128
	v_fma_f32 v32, -v36, v37, 1.0
	v_fmac_f32_e32 v37, v32, v37
	v_div_scale_f32 v32, vcc, v25, v29, v25
	v_mul_f32_e32 v33, v32, v37
	v_fma_f32 v34, -v36, v33, v32
	v_fmac_f32_e32 v33, v34, v37
	v_div_scale_f32 v34, s[30:31], v28, v28, v24
	v_rcp_f32_e32 v35, v34
	v_fma_f32 v32, -v36, v33, v32
	v_mul_f32_e32 v30, 0xbfb8aa3b, v30
	v_mul_f32_e32 v31, 0xbfb8aa3b, v31
	v_div_fmas_f32 v32, v32, v37, v33
	v_exp_f32_e32 v30, v30
	v_exp_f32_e32 v31, v31
	v_div_fixup_f32 v25, v32, v29, v25
	v_fma_f32 v29, -v34, v35, 1.0
	v_fmac_f32_e32 v35, v29, v35
	v_div_scale_f32 v29, vcc, v24, v28, v24
	v_mul_f32_e32 v32, v29, v35
	v_fma_f32 v33, -v34, v32, v29
	v_pk_add_f32 v[30:31], v[30:31], 1.0 op_sel_hi:[1,0]
	v_fmac_f32_e32 v32, v33, v35
	v_div_scale_f32 v33, s[30:31], v31, v31, v27
	v_fma_f32 v29, -v34, v32, v29
	v_rcp_f32_e32 v34, v33
	v_div_fmas_f32 v29, v29, v35, v32
	v_div_fixup_f32 v24, v29, v28, v24
	v_mul_f32_e32 v20, 0xbfb8aa3b, v20
	v_fma_f32 v28, -v33, v34, 1.0
	v_fmac_f32_e32 v34, v28, v34
	v_div_scale_f32 v28, vcc, v27, v31, v27
	v_mul_f32_e32 v29, v28, v34
	v_fma_f32 v32, -v33, v29, v28
	v_fmac_f32_e32 v29, v32, v34
	v_div_scale_f32 v32, s[30:31], v30, v30, v26
	v_fma_f32 v28, -v33, v29, v28
	v_rcp_f32_e32 v33, v32
	v_div_fmas_f32 v28, v28, v34, v29
	v_div_fixup_f32 v27, v28, v31, v27
	v_mul_f32_e32 v21, 0xbfb8aa3b, v21
	v_fma_f32 v28, -v32, v33, 1.0
	v_fmac_f32_e32 v33, v28, v33
	v_div_scale_f32 v28, vcc, v26, v30, v26
	v_mul_f32_e32 v29, v28, v33
	v_exp_f32_e32 v20, v20
	v_exp_f32_e32 v21, v21
	v_fma_f32 v31, -v32, v29, v28
	v_fmac_f32_e32 v29, v31, v33
	v_fma_f32 v28, -v32, v29, v28
	v_div_fmas_f32 v28, v28, v33, v29
	v_pk_add_f32 v[20:21], v[20:21], 1.0 op_sel_hi:[1,0]
	v_div_fixup_f32 v26, v28, v30, v26
	v_div_scale_f32 v30, s[30:31], v21, v21, v17
	v_rcp_f32_e32 v31, v30
	v_add_co_u32_e32 v28, vcc, s70, v116
	v_cvt_pk_bf16_f32 v24, v24, v25
	v_cvt_pk_bf16_f32 v25, v26, v27
	v_addc_co_u32_e32 v29, vcc, 0, v117, vcc
	global_store_dwordx2 v[28:29], v[24:25], off
	v_fma_f32 v24, -v30, v31, 1.0
	v_fmac_f32_e32 v31, v24, v31
	v_div_scale_f32 v24, vcc, v17, v21, v17
	v_mul_f32_e32 v25, v24, v31
	v_fma_f32 v28, -v30, v25, v24
	v_fmac_f32_e32 v25, v28, v31
	v_div_scale_f32 v28, s[30:31], v20, v20, v16
	v_rcp_f32_e32 v29, v28
	v_fma_f32 v24, -v30, v25, v24
	v_mul_f32_e32 v22, 0xbfb8aa3b, v22
	v_mul_f32_e32 v23, 0xbfb8aa3b, v23
	v_div_fmas_f32 v24, v24, v31, v25
	v_exp_f32_e32 v22, v22
	v_exp_f32_e32 v23, v23
	v_div_fixup_f32 v17, v24, v21, v17
	v_fma_f32 v21, -v28, v29, 1.0
	v_fmac_f32_e32 v29, v21, v29
	v_div_scale_f32 v21, vcc, v16, v20, v16
	v_mul_f32_e32 v24, v21, v29
	v_fma_f32 v25, -v28, v24, v21
	v_pk_add_f32 v[22:23], v[22:23], 1.0 op_sel_hi:[1,0]
	v_fmac_f32_e32 v24, v25, v29
	v_div_scale_f32 v25, s[30:31], v23, v23, v19
	v_fma_f32 v21, -v28, v24, v21
	v_rcp_f32_e32 v28, v25
	v_div_fmas_f32 v21, v21, v29, v24
	v_div_fixup_f32 v16, v21, v20, v16
	v_mul_f32_e32 v12, 0xbfb8aa3b, v12
	v_fma_f32 v20, -v25, v28, 1.0
	v_fmac_f32_e32 v28, v20, v28
	v_div_scale_f32 v20, vcc, v19, v23, v19
	v_mul_f32_e32 v21, v20, v28
	v_fma_f32 v24, -v25, v21, v20
	v_fmac_f32_e32 v21, v24, v28
	v_div_scale_f32 v24, s[30:31], v22, v22, v18
	v_fma_f32 v20, -v25, v21, v20
	v_rcp_f32_e32 v25, v24
	v_div_fmas_f32 v20, v20, v28, v21
	v_div_fixup_f32 v19, v20, v23, v19
	v_mul_f32_e32 v13, 0xbfb8aa3b, v13
	v_fma_f32 v20, -v24, v25, 1.0
	v_fmac_f32_e32 v25, v20, v25
	v_div_scale_f32 v20, vcc, v18, v22, v18
	v_mul_f32_e32 v21, v20, v25
	v_exp_f32_e32 v12, v12
	v_exp_f32_e32 v13, v13
	v_fma_f32 v23, -v24, v21, v20
	v_fmac_f32_e32 v21, v23, v25
	v_fma_f32 v20, -v24, v21, v20
	v_div_fmas_f32 v20, v20, v25, v21
	v_pk_add_f32 v[12:13], v[12:13], 1.0 op_sel_hi:[1,0]
	v_div_fixup_f32 v18, v20, v22, v18
	v_div_scale_f32 v20, s[30:31], v13, v13, v9
	v_rcp_f32_e32 v21, v20
	v_lshl_add_u64 v[26:27], v[116:117], 0, s[12:13]
	v_cvt_pk_bf16_f32 v16, v16, v17
	v_cvt_pk_bf16_f32 v17, v18, v19
	global_store_dwordx2 v[26:27], v[16:17], off offset:128
	v_fma_f32 v16, -v20, v21, 1.0
	v_fmac_f32_e32 v21, v16, v21
	v_div_scale_f32 v16, vcc, v9, v13, v9
	v_mul_f32_e32 v17, v16, v21
	v_fma_f32 v18, -v20, v17, v16
	v_fmac_f32_e32 v17, v18, v21
	v_div_scale_f32 v18, s[30:31], v12, v12, v8
	v_rcp_f32_e32 v19, v18
	v_fma_f32 v16, -v20, v17, v16
	v_mul_f32_e32 v14, 0xbfb8aa3b, v14
	v_mul_f32_e32 v15, 0xbfb8aa3b, v15
	v_div_fmas_f32 v16, v16, v21, v17
	v_exp_f32_e32 v14, v14
	v_exp_f32_e32 v15, v15
	v_div_fixup_f32 v9, v16, v13, v9
	v_fma_f32 v13, -v18, v19, 1.0
	v_fmac_f32_e32 v19, v13, v19
	v_div_scale_f32 v13, vcc, v8, v12, v8
	v_mul_f32_e32 v16, v13, v19
	v_fma_f32 v17, -v18, v16, v13
	v_pk_add_f32 v[14:15], v[14:15], 1.0 op_sel_hi:[1,0]
	v_fmac_f32_e32 v16, v17, v19
	v_div_scale_f32 v17, s[30:31], v15, v15, v11
	v_fma_f32 v13, -v18, v16, v13
	v_rcp_f32_e32 v18, v17
	v_div_fmas_f32 v13, v13, v19, v16
	v_div_fixup_f32 v8, v13, v12, v8
	v_mul_f32_e32 v4, 0xbfb8aa3b, v4
	v_fma_f32 v12, -v17, v18, 1.0
	v_fmac_f32_e32 v18, v12, v18
	v_div_scale_f32 v12, vcc, v11, v15, v11
	v_mul_f32_e32 v13, v12, v18
	v_fma_f32 v16, -v17, v13, v12
	v_fmac_f32_e32 v13, v16, v18
	v_div_scale_f32 v16, s[30:31], v14, v14, v10
	v_fma_f32 v12, -v17, v13, v12
	v_rcp_f32_e32 v17, v16
	v_div_fmas_f32 v12, v12, v18, v13
	v_div_fixup_f32 v11, v12, v15, v11
	v_mul_f32_e32 v5, 0xbfb8aa3b, v5
	v_fma_f32 v12, -v16, v17, 1.0
	v_fmac_f32_e32 v17, v12, v17
	v_div_scale_f32 v12, vcc, v10, v14, v10
	v_mul_f32_e32 v13, v12, v17
	v_exp_f32_e32 v4, v4
	v_exp_f32_e32 v5, v5
	v_fma_f32 v15, -v16, v13, v12
	v_fmac_f32_e32 v13, v15, v17
	v_fma_f32 v12, -v16, v13, v12
	v_div_fmas_f32 v12, v12, v17, v13
	v_pk_add_f32 v[4:5], v[4:5], 1.0 op_sel_hi:[1,0]
	v_div_fixup_f32 v10, v12, v14, v10
	v_div_scale_f32 v14, s[30:31], v5, v5, v1
	v_rcp_f32_e32 v15, v14
	v_add_co_u32_e32 v12, vcc, s71, v116
	v_cvt_pk_bf16_f32 v8, v8, v9
	v_cvt_pk_bf16_f32 v9, v10, v11
	v_addc_co_u32_e32 v13, vcc, 0, v117, vcc
	global_store_dwordx2 v[12:13], v[8:9], off
	v_fma_f32 v8, -v14, v15, 1.0
	v_fmac_f32_e32 v15, v8, v15
	v_div_scale_f32 v8, vcc, v1, v5, v1
	v_mul_f32_e32 v9, v8, v15
	v_fma_f32 v12, -v14, v9, v8
	v_fmac_f32_e32 v9, v12, v15
	v_div_scale_f32 v12, s[30:31], v4, v4, v0
	v_rcp_f32_e32 v13, v12
	v_fma_f32 v8, -v14, v9, v8
	v_mul_f32_e32 v6, 0xbfb8aa3b, v6
	v_mul_f32_e32 v7, 0xbfb8aa3b, v7
	v_div_fmas_f32 v8, v8, v15, v9
	v_exp_f32_e32 v6, v6
	v_exp_f32_e32 v7, v7
	v_div_fixup_f32 v1, v8, v5, v1
	v_fma_f32 v5, -v12, v13, 1.0
	v_fmac_f32_e32 v13, v5, v13
	v_div_scale_f32 v5, vcc, v0, v4, v0
	v_mul_f32_e32 v8, v5, v13
	v_fma_f32 v9, -v12, v8, v5
	v_pk_add_f32 v[6:7], v[6:7], 1.0 op_sel_hi:[1,0]
	v_fmac_f32_e32 v8, v9, v13
	v_div_scale_f32 v9, s[30:31], v7, v7, v3
	v_fma_f32 v5, -v12, v8, v5
	v_rcp_f32_e32 v12, v9
	v_div_fmas_f32 v5, v5, v13, v8
	v_div_fixup_f32 v0, v5, v4, v0
	v_lshl_add_u64 v[10:11], v[116:117], 0, s[14:15]
	v_fma_f32 v4, -v9, v12, 1.0
	v_fmac_f32_e32 v12, v4, v12
	v_div_scale_f32 v4, vcc, v3, v7, v3
	v_mul_f32_e32 v5, v4, v12
	v_fma_f32 v8, -v9, v5, v4
	v_fmac_f32_e32 v5, v8, v12
	v_div_scale_f32 v8, s[30:31], v6, v6, v2
	v_fma_f32 v4, -v9, v5, v4
	v_rcp_f32_e32 v9, v8
	v_div_fmas_f32 v4, v4, v12, v5
	v_div_fixup_f32 v3, v4, v7, v3
	v_cvt_pk_bf16_f32 v0, v0, v1
	v_fma_f32 v4, -v8, v9, 1.0
	v_fmac_f32_e32 v9, v4, v9
	v_div_scale_f32 v4, vcc, v2, v6, v2
	v_mul_f32_e32 v5, v4, v9
	v_fma_f32 v7, -v8, v5, v4
	v_fmac_f32_e32 v5, v7, v9
	v_fma_f32 v4, -v8, v5, v4
	v_div_fmas_f32 v4, v4, v9, v5
	v_div_fixup_f32 v2, v4, v6, v2
	v_cvt_pk_bf16_f32 v1, v2, v3
	s_and_b64 vcc, exec, s[4:5]
	s_mov_b32 s72, s16
	s_mov_b32 s28, s18
	s_mov_b64 s[34:35], s[26:27]
	s_mov_b64 s[30:31], s[20:21]
	global_store_dwordx2 v[10:11], v[0:1], off offset:128
	s_mov_b32 s94, 1
	s_cbranch_vccz .LBB0_1134
	s_mov_b32 s94, 0
	s_waitcnt vmcnt(16)
	s_cmpk_gt_u32 s40, 0xff
	s_cbranch_scc1 .LBB0_1145
	s_barrier

.LBB0_1291:
	ds_read_b128 v[154:157], v151
	ds_read_b128 v[158:161], v151 offset:1024
	ds_read_b128 v[162:165], v151 offset:2048
	ds_read_b128 v[166:169], v151 offset:3072
	s_add_u32 s36, s34, 0xfffc0080
	s_addc_u32 s37, s35, -1
	s_cmp_eq_u32 s79, 12
	s_cselect_b32 s39, s21, s37
	s_cselect_b32 s38, s75, s36
	s_cselect_b32 s37, s19, s78
	s_cselect_b32 s36, s76, s77
	v_lshl_add_u64 v[202:203], s[34:35], 0, v[138:139]
	s_add_i32 m0, s31, 0xc000
	ds_read_b128 v[170:173], v152
	ds_read_b128 v[174:177], v152 offset:1024
	ds_read_b128 v[178:181], v152 offset:2048
	ds_read_b128 v[182:185], v152 offset:3072
	ds_read_b128 v[186:189], v152 offset:4096
	ds_read_b128 v[190:193], v152 offset:5120
	ds_read_b128 v[194:197], v152 offset:6144
	ds_read_b128 v[198:201], v152 offset:7168
	global_load_lds_dwordx4 v[202:203], off
	v_lshl_add_u64 v[202:203], s[34:35], 0, v[140:141]
	s_add_i32 m0, s31, 0xe000
	s_nop 0
	global_load_lds_dwordx4 v[202:203], off
	s_waitcnt lgkmcnt(8)
	s_barrier
	s_waitcnt lgkmcnt(0)
	s_waitcnt lgkmcnt(0)
	v_mfma_f32_16x16x32_bf16 v[124:127], v[154:157], v[170:173], v[124:127]
	v_mfma_f32_16x16x32_bf16 v[120:123], v[162:165], v[170:173], v[120:123]
	v_mfma_f32_16x16x32_bf16 v[108:111], v[154:157], v[178:181], v[108:111]
	v_mfma_f32_16x16x32_bf16 v[104:107], v[162:165], v[178:181], v[104:107]
	v_mfma_f32_16x16x32_bf16 v[92:95], v[154:157], v[186:189], v[92:95]
	v_mfma_f32_16x16x32_bf16 v[88:91], v[162:165], v[186:189], v[88:91]
	v_mfma_f32_16x16x32_bf16 v[76:79], v[154:157], v[194:197], v[76:79]
	v_mfma_f32_16x16x32_bf16 v[72:75], v[162:165], v[194:197], v[72:75]
	v_mfma_f32_16x16x32_bf16 v[124:127], v[158:161], v[174:177], v[124:127]
	v_mfma_f32_16x16x32_bf16 v[120:123], v[166:169], v[174:177], v[120:123]
	v_mfma_f32_16x16x32_bf16 v[108:111], v[158:161], v[182:185], v[108:111]
	v_mfma_f32_16x16x32_bf16 v[104:107], v[166:169], v[182:185], v[104:107]
	v_mfma_f32_16x16x32_bf16 v[92:95], v[158:161], v[190:193], v[92:95]
	v_mfma_f32_16x16x32_bf16 v[88:91], v[166:169], v[190:193], v[88:91]
	v_mfma_f32_16x16x32_bf16 v[76:79], v[158:161], v[198:201], v[76:79]
	v_mfma_f32_16x16x32_bf16 v[72:75], v[166:169], v[198:201], v[72:75]
	s_barrier
	s_add_i32 s80, s62, s52
	v_lshl_add_u64 v[218:219], s[36:37], 0, v[132:133]
	s_mov_b32 m0, s80
	ds_read_b128 v[202:205], v153
	ds_read_b128 v[206:209], v153 offset:1024
	ds_read_b128 v[210:213], v153 offset:2048
	ds_read_b128 v[214:217], v153 offset:3072
	global_load_lds_dwordx4 v[218:219], off
	v_lshl_add_u64 v[220:221], s[36:37], 0, v[136:137]
	s_add_i32 m0, s80, 0x2000
	s_nop 0
	global_load_lds_dwordx4 v[220:221], off
	s_barrier
	s_waitcnt lgkmcnt(0)
	s_waitcnt lgkmcnt(0)
	v_mfma_f32_16x16x32_bf16 v[116:119], v[202:205], v[170:173], v[116:119]
	v_mfma_f32_16x16x32_bf16 v[112:115], v[210:213], v[170:173], v[112:115]
	v_mfma_f32_16x16x32_bf16 v[100:103], v[202:205], v[178:181], v[100:103]
	v_mfma_f32_16x16x32_bf16 v[96:99], v[210:213], v[178:181], v[96:99]
	v_mfma_f32_16x16x32_bf16 v[84:87], v[202:205], v[186:189], v[84:87]
	v_mfma_f32_16x16x32_bf16 v[80:83], v[210:213], v[186:189], v[80:83]
	v_mfma_f32_16x16x32_bf16 v[68:71], v[202:205], v[194:197], v[68:71]
	v_mfma_f32_16x16x32_bf16 v[64:67], v[210:213], v[194:197], v[64:67]
	v_mfma_f32_16x16x32_bf16 v[116:119], v[206:209], v[174:177], v[116:119]
	v_mfma_f32_16x16x32_bf16 v[112:115], v[214:217], v[174:177], v[112:115]
	v_mfma_f32_16x16x32_bf16 v[100:103], v[206:209], v[182:185], v[100:103]
	v_mfma_f32_16x16x32_bf16 v[96:99], v[214:217], v[182:185], v[96:99]
	v_mfma_f32_16x16x32_bf16 v[84:87], v[206:209], v[190:193], v[84:87]
	v_mfma_f32_16x16x32_bf16 v[80:83], v[214:217], v[190:193], v[80:83]
	v_mfma_f32_16x16x32_bf16 v[68:71], v[206:209], v[198:201], v[68:71]
	v_mfma_f32_16x16x32_bf16 v[64:67], v[214:217], v[198:201], v[64:67]
	s_mov_b32 m0, s31
	v_lshl_add_u64 v[222:223], s[38:39], 0, v[130:131]
	s_barrier
	ds_read_b128 v[170:173], v152 offset:16384
	ds_read_b128 v[174:177], v152 offset:17408
	ds_read_b128 v[178:181], v152 offset:18432
	ds_read_b128 v[182:185], v152 offset:19456
	ds_read_b128 v[186:189], v152 offset:20480
	ds_read_b128 v[190:193], v152 offset:21504
	ds_read_b128 v[194:197], v152 offset:22528
	ds_read_b128 v[198:201], v152 offset:23552
	global_load_lds_dwordx4 v[222:223], off
	v_lshl_add_u64 v[224:225], s[38:39], 0, v[134:135]
	s_mov_b32 m0, s53
	s_nop 0
	global_load_lds_dwordx4 v[224:225], off
	s_barrier
	s_waitcnt lgkmcnt(0)
	s_waitcnt lgkmcnt(0)
	v_mfma_f32_16x16x32_bf16 v[60:63], v[154:157], v[170:173], v[60:63]
	v_mfma_f32_16x16x32_bf16 v[56:59], v[162:165], v[170:173], v[56:59]
	v_mfma_f32_16x16x32_bf16 v[44:47], v[154:157], v[178:181], v[44:47]
	v_mfma_f32_16x16x32_bf16 v[40:43], v[162:165], v[178:181], v[40:43]
	v_mfma_f32_16x16x32_bf16 v[28:31], v[154:157], v[186:189], v[28:31]
	v_mfma_f32_16x16x32_bf16 v[24:27], v[162:165], v[186:189], v[24:27]
	v_mfma_f32_16x16x32_bf16 v[12:15], v[154:157], v[194:197], v[12:15]
	v_mfma_f32_16x16x32_bf16 v[8:11], v[162:165], v[194:197], v[8:11]
	v_mfma_f32_16x16x32_bf16 v[60:63], v[158:161], v[174:177], v[60:63]
	v_mfma_f32_16x16x32_bf16 v[56:59], v[166:169], v[174:177], v[56:59]
	v_mfma_f32_16x16x32_bf16 v[44:47], v[158:161], v[182:185], v[44:47]
	v_mfma_f32_16x16x32_bf16 v[40:43], v[166:169], v[182:185], v[40:43]
	v_mfma_f32_16x16x32_bf16 v[28:31], v[158:161], v[190:193], v[28:31]
	v_mfma_f32_16x16x32_bf16 v[24:27], v[166:169], v[190:193], v[24:27]
	v_mfma_f32_16x16x32_bf16 v[12:15], v[158:161], v[198:201], v[12:15]
	v_mfma_f32_16x16x32_bf16 v[8:11], v[166:169], v[198:201], v[8:11]
	s_barrier
	s_add_u32 s80, s36, 0x40000
	s_addc_u32 s81, s37, 0
	s_add_i32 s82, s63, s52
	v_lshl_add_u64 v[154:155], s[80:81], 0, v[132:133]
	s_mov_b32 m0, s82
	s_nop 0
	global_load_lds_dwordx4 v[154:155], off
	v_lshl_add_u64 v[154:155], s[80:81], 0, v[136:137]
	s_add_i32 m0, s82, 0x2000
	s_nop 0
	global_load_lds_dwordx4 v[154:155], off
	s_cmp_lg_u32 s94, 0
	s_cbranch_scc1 .Lrx9a
	s_waitcnt vmcnt(6)
.Lrx9a:
	s_waitcnt vmcnt(24)
	s_barrier
	v_mfma_f32_16x16x32_bf16 v[52:55], v[202:205], v[170:173], v[52:55]
	v_mfma_f32_16x16x32_bf16 v[48:51], v[210:213], v[170:173], v[48:51]
	v_mfma_f32_16x16x32_bf16 v[36:39], v[202:205], v[178:181], v[36:39]
	v_mfma_f32_16x16x32_bf16 v[32:35], v[210:213], v[178:181], v[32:35]
	v_mfma_f32_16x16x32_bf16 v[20:23], v[202:205], v[186:189], v[20:23]
	v_mfma_f32_16x16x32_bf16 v[16:19], v[210:213], v[186:189], v[16:19]
	v_mfma_f32_16x16x32_bf16 v[4:7], v[202:205], v[194:197], v[4:7]
	v_mfma_f32_16x16x32_bf16 v[0:3], v[210:213], v[194:197], v[0:3]
	v_mfma_f32_16x16x32_bf16 v[52:55], v[206:209], v[174:177], v[52:55]
	v_mfma_f32_16x16x32_bf16 v[48:51], v[214:217], v[174:177], v[48:51]
	v_mfma_f32_16x16x32_bf16 v[36:39], v[206:209], v[182:185], v[36:39]
	v_mfma_f32_16x16x32_bf16 v[32:35], v[214:217], v[182:185], v[32:35]
	v_mfma_f32_16x16x32_bf16 v[20:23], v[206:209], v[190:193], v[20:23]
	v_mfma_f32_16x16x32_bf16 v[16:19], v[214:217], v[190:193], v[16:19]
	v_mfma_f32_16x16x32_bf16 v[4:7], v[206:209], v[198:201], v[4:7]
	v_mfma_f32_16x16x32_bf16 v[0:3], v[214:217], v[198:201], v[0:3]
	s_add_i32 s80, 0, 0x18000
	v_add_u32_e32 v166, s80, v149
	s_barrier
	ds_read_b128 v[154:157], v166
	ds_read_b128 v[158:161], v166 offset:1024
	ds_read_b128 v[162:165], v166 offset:2048
	ds_read_b128 v[166:169], v166 offset:3072
	s_add_u32 s38, s38, 0x40000
	s_addc_u32 s39, s39, 0
	s_mov_b32 m0, s54
	v_lshl_add_u64 v[202:203], s[38:39], 0, v[130:131]
	ds_read_b128 v[170:173], v152 offset:32768
	ds_read_b128 v[174:177], v152 offset:33792
	ds_read_b128 v[178:181], v152 offset:34816
	ds_read_b128 v[182:185], v152 offset:35840
	ds_read_b128 v[186:189], v152 offset:36864
	ds_read_b128 v[190:193], v152 offset:37888
	ds_read_b128 v[194:197], v152 offset:38912
	ds_read_b128 v[198:201], v152 offset:39936
	global_load_lds_dwordx4 v[202:203], off
	v_lshl_add_u64 v[202:203], s[38:39], 0, v[134:135]
	s_mov_b32 m0, s55
	s_nop 0
	global_load_lds_dwordx4 v[202:203], off
	s_waitcnt lgkmcnt(8)
	s_barrier
	s_waitcnt lgkmcnt(0)
	s_waitcnt lgkmcnt(0)
	v_mfma_f32_16x16x32_bf16 v[124:127], v[154:157], v[170:173], v[124:127]
	v_mfma_f32_16x16x32_bf16 v[120:123], v[162:165], v[170:173], v[120:123]
	v_mfma_f32_16x16x32_bf16 v[108:111], v[154:157], v[178:181], v[108:111]
	v_mfma_f32_16x16x32_bf16 v[104:107], v[162:165], v[178:181], v[104:107]
	v_mfma_f32_16x16x32_bf16 v[92:95], v[154:157], v[186:189], v[92:95]
	v_mfma_f32_16x16x32_bf16 v[88:91], v[162:165], v[186:189], v[88:91]
	v_mfma_f32_16x16x32_bf16 v[76:79], v[154:157], v[194:197], v[76:79]
	v_mfma_f32_16x16x32_bf16 v[72:75], v[162:165], v[194:197], v[72:75]
	v_mfma_f32_16x16x32_bf16 v[124:127], v[158:161], v[174:177], v[124:127]
	v_mfma_f32_16x16x32_bf16 v[120:123], v[166:169], v[174:177], v[120:123]
	v_mfma_f32_16x16x32_bf16 v[108:111], v[158:161], v[182:185], v[108:111]
	v_mfma_f32_16x16x32_bf16 v[104:107], v[166:169], v[182:185], v[104:107]
	v_mfma_f32_16x16x32_bf16 v[92:95], v[158:161], v[190:193], v[92:95]
	v_mfma_f32_16x16x32_bf16 v[88:91], v[166:169], v[190:193], v[88:91]
	v_mfma_f32_16x16x32_bf16 v[76:79], v[158:161], v[198:201], v[76:79]
	v_mfma_f32_16x16x32_bf16 v[72:75], v[166:169], v[198:201], v[72:75]
	s_barrier
	s_add_i32 s38, 0, 0x1c000
	s_add_i32 s39, s80, s52
	v_add_u32_e32 v214, s38, v149
	v_lshl_add_u64 v[218:219], v[218:219], 0, s[8:9]
	s_mov_b32 m0, s39
	ds_read_b128 v[202:205], v214
	ds_read_b128 v[206:209], v214 offset:1024
	ds_read_b128 v[210:213], v214 offset:2048
	ds_read_b128 v[214:217], v214 offset:3072
	global_load_lds_dwordx4 v[218:219], off
	v_lshl_add_u64 v[218:219], v[220:221], 0, s[8:9]
	s_add_i32 m0, s39, 0x2000
	s_nop 0
	global_load_lds_dwordx4 v[218:219], off
	s_cmp_lg_u32 s94, 0
	s_cbranch_scc0 .Lrx9c
	s_waitcnt vmcnt(10)
	s_mov_b32 s94, 0
.Lrx9c:
	s_barrier
	s_waitcnt lgkmcnt(0)
	s_waitcnt lgkmcnt(0)
	v_mfma_f32_16x16x32_bf16 v[116:119], v[202:205], v[170:173], v[116:119]
	v_mfma_f32_16x16x32_bf16 v[112:115], v[210:213], v[170:173], v[112:115]
	v_mfma_f32_16x16x32_bf16 v[100:103], v[202:205], v[178:181], v[100:103]
	v_mfma_f32_16x16x32_bf16 v[96:99], v[210:213], v[178:181], v[96:99]
	v_mfma_f32_16x16x32_bf16 v[84:87], v[202:205], v[186:189], v[84:87]
	v_mfma_f32_16x16x32_bf16 v[80:83], v[210:213], v[186:189], v[80:83]
	v_mfma_f32_16x16x32_bf16 v[68:71], v[202:205], v[194:197], v[68:71]
	v_mfma_f32_16x16x32_bf16 v[64:67], v[210:213], v[194:197], v[64:67]
	v_mfma_f32_16x16x32_bf16 v[116:119], v[206:209], v[174:177], v[116:119]
	v_mfma_f32_16x16x32_bf16 v[112:115], v[214:217], v[174:177], v[112:115]
	v_mfma_f32_16x16x32_bf16 v[100:103], v[206:209], v[182:185], v[100:103]
	v_mfma_f32_16x16x32_bf16 v[96:99], v[214:217], v[182:185], v[96:99]
	v_mfma_f32_16x16x32_bf16 v[84:87], v[206:209], v[190:193], v[84:87]
	v_mfma_f32_16x16x32_bf16 v[80:83], v[214:217], v[190:193], v[80:83]
	v_mfma_f32_16x16x32_bf16 v[68:71], v[206:209], v[198:201], v[68:71]
	v_mfma_f32_16x16x32_bf16 v[64:67], v[214:217], v[198:201], v[64:67]
	s_mov_b32 m0, s57
	v_lshl_add_u64 v[218:219], v[222:223], 0, s[8:9]
	s_barrier
	ds_read_b128 v[170:173], v152 offset:49152
	ds_read_b128 v[174:177], v152 offset:50176
	ds_read_b128 v[178:181], v152 offset:51200
	ds_read_b128 v[182:185], v152 offset:52224
	ds_read_b128 v[186:189], v152 offset:53248
	ds_read_b128 v[190:193], v152 offset:54272
	ds_read_b128 v[194:197], v152 offset:55296
	ds_read_b128 v[198:201], v152 offset:56320
	global_load_lds_dwordx4 v[218:219], off
	v_lshl_add_u64 v[218:219], v[224:225], 0, s[8:9]
	s_mov_b32 m0, s60
	s_nop 0
	global_load_lds_dwordx4 v[218:219], off
	s_barrier
	s_waitcnt lgkmcnt(0)
	s_waitcnt lgkmcnt(0)
	v_mfma_f32_16x16x32_bf16 v[60:63], v[154:157], v[170:173], v[60:63]
	v_mfma_f32_16x16x32_bf16 v[56:59], v[162:165], v[170:173], v[56:59]
	v_mfma_f32_16x16x32_bf16 v[44:47], v[154:157], v[178:181], v[44:47]
	v_mfma_f32_16x16x32_bf16 v[40:43], v[162:165], v[178:181], v[40:43]
	v_mfma_f32_16x16x32_bf16 v[28:31], v[154:157], v[186:189], v[28:31]
	v_mfma_f32_16x16x32_bf16 v[24:27], v[162:165], v[186:189], v[24:27]
	v_mfma_f32_16x16x32_bf16 v[12:15], v[154:157], v[194:197], v[12:15]
	v_mfma_f32_16x16x32_bf16 v[8:11], v[162:165], v[194:197], v[8:11]
	v_mfma_f32_16x16x32_bf16 v[60:63], v[158:161], v[174:177], v[60:63]
	v_mfma_f32_16x16x32_bf16 v[56:59], v[166:169], v[174:177], v[56:59]
	v_mfma_f32_16x16x32_bf16 v[44:47], v[158:161], v[182:185], v[44:47]
	v_mfma_f32_16x16x32_bf16 v[40:43], v[166:169], v[182:185], v[40:43]
	v_mfma_f32_16x16x32_bf16 v[28:31], v[158:161], v[190:193], v[28:31]
	v_mfma_f32_16x16x32_bf16 v[24:27], v[166:169], v[190:193], v[24:27]
	v_mfma_f32_16x16x32_bf16 v[12:15], v[158:161], v[198:201], v[12:15]
	v_mfma_f32_16x16x32_bf16 v[8:11], v[166:169], v[198:201], v[8:11]
	s_barrier
	s_add_u32 s36, s36, 0x40080
	s_addc_u32 s37, s37, 0
	s_add_i32 s38, s38, s52
	v_lshl_add_u64 v[154:155], s[36:37], 0, v[132:133]
	s_mov_b32 m0, s38
	s_nop 0
	global_load_lds_dwordx4 v[154:155], off
	v_lshl_add_u64 v[154:155], s[36:37], 0, v[136:137]
	s_add_i32 m0, s38, 0x2000
	s_nop 0
	global_load_lds_dwordx4 v[154:155], off
	s_waitcnt vmcnt(6)
	s_barrier
	v_mfma_f32_16x16x32_bf16 v[52:55], v[202:205], v[170:173], v[52:55]
	v_mfma_f32_16x16x32_bf16 v[48:51], v[210:213], v[170:173], v[48:51]
	v_mfma_f32_16x16x32_bf16 v[36:39], v[202:205], v[178:181], v[36:39]
	v_mfma_f32_16x16x32_bf16 v[32:35], v[210:213], v[178:181], v[32:35]
	v_mfma_f32_16x16x32_bf16 v[20:23], v[202:205], v[186:189], v[20:23]
	v_mfma_f32_16x16x32_bf16 v[16:19], v[210:213], v[186:189], v[16:19]
	v_mfma_f32_16x16x32_bf16 v[4:7], v[202:205], v[194:197], v[4:7]
	v_mfma_f32_16x16x32_bf16 v[0:3], v[210:213], v[194:197], v[0:3]
	v_mfma_f32_16x16x32_bf16 v[52:55], v[206:209], v[174:177], v[52:55]
	v_mfma_f32_16x16x32_bf16 v[48:51], v[214:217], v[174:177], v[48:51]
	v_mfma_f32_16x16x32_bf16 v[36:39], v[206:209], v[182:185], v[36:39]
	v_mfma_f32_16x16x32_bf16 v[32:35], v[214:217], v[182:185], v[32:35]
	v_mfma_f32_16x16x32_bf16 v[20:23], v[206:209], v[190:193], v[20:23]
	v_mfma_f32_16x16x32_bf16 v[16:19], v[214:217], v[190:193], v[16:19]
	v_mfma_f32_16x16x32_bf16 v[4:7], v[206:209], v[198:201], v[4:7]
	v_mfma_f32_16x16x32_bf16 v[0:3], v[214:217], v[198:201], v[0:3]
	s_add_i32 s79, s79, 2
	s_add_u32 s34, s34, 0x100
	s_addc_u32 s35, s35, 0
	s_add_u32 s77, s77, 0x100
	s_addc_u32 s78, s78, 0
	s_cmp_gt_u32 s79, 13
	s_barrier
	s_cbranch_scc0 .LBB0_1291
	v_lshl_add_u32 v154, s30, 8, v148
	v_max_f32_e32 v126, v126, v126
	v_max_f32_e32 v127, v127, v127
	v_lshl_or_b32 v156, s74, 8, v150
	v_ashrrev_i32_e32 v155, 31, v154
	v_max_f32_e32 v124, v124, v124
	v_max_f32_e32 v120, v120, v120
	v_max_f32_e32 v125, v125, v125
	v_max_f32_e32 v121, v121, v121
	v_max_f32_e32 v126, 0, v126
	v_max_f32_e32 v122, v122, v122
	v_max_f32_e32 v127, 0, v127
	v_max_f32_e32 v123, v123, v123
	v_lshlrev_b64 v[158:159], 13, v[154:155]
	v_max_f32_e32 v124, 0, v124
	v_max_f32_e32 v120, 0, v120
	v_max_f32_e32 v125, 0, v125
	v_max_f32_e32 v121, 0, v121
	v_max_f32_e32 v122, 0, v122
	v_max_f32_e32 v123, 0, v123
	v_pk_mul_f32 v[126:127], v[126:127], v[126:127]
	v_ashrrev_i32_e32 v157, 31, v156
	v_lshl_add_u64 v[158:159], s[46:47], 0, v[158:159]
	v_pk_mul_f32 v[124:125], v[124:125], v[124:125]
	v_pk_mul_f32 v[120:121], v[120:121], v[120:121]
	v_pk_mul_f32 v[160:161], v[122:123], v[122:123]
	v_cvt_pk_bf16_f32 v123, v126, v127
	v_lshlrev_b64 v[126:127], 1, v[156:157]
	v_max_f32_e32 v112, v112, v112
	v_max_f32_e32 v113, v113, v113
	v_cvt_pk_bf16_f32 v122, v124, v125
	v_cvt_pk_bf16_f32 v124, v120, v121
	v_cvt_pk_bf16_f32 v125, v160, v161
	v_lshl_add_u64 v[120:121], v[158:159], 0, v[126:127]
	v_max_f32_e32 v112, 0, v112
	v_max_f32_e32 v113, 0, v113
	global_store_dwordx4 v[120:121], v[122:125], off
	v_max_f32_e32 v116, v116, v116
	v_max_f32_e32 v117, v117, v117
	v_pk_mul_f32 v[122:123], v[112:113], v[112:113]
	v_max_f32_e32 v113, v114, v114
	v_max_f32_e32 v112, v118, v118
	v_max_f32_e32 v114, 0, v113
	v_max_f32_e32 v113, v119, v119
	v_max_f32_e32 v115, v115, v115
	v_max_f32_e32 v116, 0, v116
	v_max_f32_e32 v117, 0, v117
	v_max_f32_e32 v112, 0, v112
	v_max_f32_e32 v113, 0, v113
	v_max_f32_e32 v115, 0, v115
	v_pk_mul_f32 v[116:117], v[116:117], v[116:117]
	v_pk_mul_f32 v[118:119], v[112:113], v[112:113]
	v_pk_mul_f32 v[124:125], v[114:115], v[114:115]
	v_max_f32_e32 v104, v104, v104
	v_max_f32_e32 v105, v105, v105
	v_cvt_pk_bf16_f32 v112, v116, v117
	v_cvt_pk_bf16_f32 v113, v118, v119
	v_cvt_pk_bf16_f32 v114, v122, v123
	v_cvt_pk_bf16_f32 v115, v124, v125
	v_max_f32_e32 v104, 0, v104
	v_max_f32_e32 v105, 0, v105
	global_store_dwordx4 v[120:121], v[112:115], off offset:256
	v_max_f32_e32 v108, v108, v108
	v_max_f32_e32 v109, v109, v109
	v_or_b32_e32 v112, 16, v154
	v_pk_mul_f32 v[114:115], v[104:105], v[104:105]
	v_max_f32_e32 v105, v106, v106
	v_ashrrev_i32_e32 v113, 31, v112
	v_max_f32_e32 v104, v110, v110
	v_max_f32_e32 v106, 0, v105
	v_max_f32_e32 v105, v111, v111
	v_max_f32_e32 v107, v107, v107
	v_lshlrev_b64 v[112:113], 13, v[112:113]
	v_max_f32_e32 v108, 0, v108
	v_max_f32_e32 v109, 0, v109
	v_max_f32_e32 v104, 0, v104
	v_max_f32_e32 v105, 0, v105
	v_max_f32_e32 v107, 0, v107
	v_lshl_add_u64 v[112:113], s[46:47], 0, v[112:113]
	v_pk_mul_f32 v[108:109], v[108:109], v[108:109]
	v_pk_mul_f32 v[110:111], v[104:105], v[104:105]
	v_pk_mul_f32 v[116:117], v[106:107], v[106:107]
	v_max_f32_e32 v96, v96, v96
	v_max_f32_e32 v97, v97, v97
	v_cvt_pk_bf16_f32 v104, v108, v109
	v_cvt_pk_bf16_f32 v105, v110, v111
	v_cvt_pk_bf16_f32 v106, v114, v115
	v_cvt_pk_bf16_f32 v107, v116, v117
	v_lshl_add_u64 v[108:109], v[112:113], 0, v[126:127]
	v_max_f32_e32 v96, 0, v96
	v_max_f32_e32 v97, 0, v97
	global_store_dwordx4 v[108:109], v[104:107], off
	v_max_f32_e32 v100, v100, v100
	v_max_f32_e32 v101, v101, v101
	v_pk_mul_f32 v[104:105], v[96:97], v[96:97]
	v_max_f32_e32 v97, v98, v98
	v_max_f32_e32 v96, v102, v102
	v_max_f32_e32 v98, 0, v97
	v_max_f32_e32 v97, v103, v103
	v_max_f32_e32 v99, v99, v99
	v_max_f32_e32 v100, 0, v100
	v_max_f32_e32 v101, 0, v101
	v_max_f32_e32 v96, 0, v96
	v_max_f32_e32 v97, 0, v97
	v_max_f32_e32 v99, 0, v99
	v_pk_mul_f32 v[100:101], v[100:101], v[100:101]
	v_pk_mul_f32 v[102:103], v[96:97], v[96:97]
	v_pk_mul_f32 v[106:107], v[98:99], v[98:99]
	v_max_f32_e32 v88, v88, v88
	v_max_f32_e32 v89, v89, v89
	v_cvt_pk_bf16_f32 v96, v100, v101
	v_cvt_pk_bf16_f32 v97, v102, v103
	v_cvt_pk_bf16_f32 v98, v104, v105
	v_cvt_pk_bf16_f32 v99, v106, v107
	v_max_f32_e32 v88, 0, v88
	v_max_f32_e32 v89, 0, v89
	global_store_dwordx4 v[108:109], v[96:99], off offset:256
	v_max_f32_e32 v92, v92, v92
	v_max_f32_e32 v93, v93, v93
	v_or_b32_e32 v96, 32, v154
	v_pk_mul_f32 v[98:99], v[88:89], v[88:89]
	v_max_f32_e32 v89, v90, v90
	v_ashrrev_i32_e32 v97, 31, v96
	v_max_f32_e32 v88, v94, v94
	v_max_f32_e32 v90, 0, v89
	v_max_f32_e32 v89, v95, v95
	v_max_f32_e32 v91, v91, v91
	v_lshlrev_b64 v[96:97], 13, v[96:97]
	v_max_f32_e32 v92, 0, v92
	v_max_f32_e32 v93, 0, v93
	v_max_f32_e32 v88, 0, v88
	v_max_f32_e32 v89, 0, v89
	v_max_f32_e32 v91, 0, v91
	v_lshl_add_u64 v[96:97], s[46:47], 0, v[96:97]
	v_pk_mul_f32 v[92:93], v[92:93], v[92:93]
	v_pk_mul_f32 v[94:95], v[88:89], v[88:89]
	v_pk_mul_f32 v[100:101], v[90:91], v[90:91]
	v_max_f32_e32 v80, v80, v80
	v_max_f32_e32 v81, v81, v81
	v_cvt_pk_bf16_f32 v88, v92, v93
	v_cvt_pk_bf16_f32 v89, v94, v95
	v_cvt_pk_bf16_f32 v90, v98, v99
	v_cvt_pk_bf16_f32 v91, v100, v101
	v_lshl_add_u64 v[92:93], v[96:97], 0, v[126:127]
	v_max_f32_e32 v80, 0, v80
	v_max_f32_e32 v81, 0, v81
	global_store_dwordx4 v[92:93], v[88:91], off
	v_max_f32_e32 v84, v84, v84
	v_max_f32_e32 v85, v85, v85
	v_pk_mul_f32 v[88:89], v[80:81], v[80:81]
	v_max_f32_e32 v81, v82, v82
	v_max_f32_e32 v80, v86, v86
	v_max_f32_e32 v82, 0, v81
	v_max_f32_e32 v81, v87, v87
	v_max_f32_e32 v83, v83, v83
	v_max_f32_e32 v84, 0, v84
	v_max_f32_e32 v85, 0, v85
	v_max_f32_e32 v80, 0, v80
	v_max_f32_e32 v81, 0, v81
	v_max_f32_e32 v83, 0, v83
	v_pk_mul_f32 v[84:85], v[84:85], v[84:85]
	v_pk_mul_f32 v[86:87], v[80:81], v[80:81]
	v_pk_mul_f32 v[90:91], v[82:83], v[82:83]
	v_max_f32_e32 v72, v72, v72
	v_max_f32_e32 v73, v73, v73
	v_cvt_pk_bf16_f32 v80, v84, v85
	v_cvt_pk_bf16_f32 v81, v86, v87
	v_cvt_pk_bf16_f32 v82, v88, v89
	v_cvt_pk_bf16_f32 v83, v90, v91
	v_max_f32_e32 v72, 0, v72
	v_max_f32_e32 v73, 0, v73
	global_store_dwordx4 v[92:93], v[80:83], off offset:256
	v_max_f32_e32 v76, v76, v76
	v_max_f32_e32 v77, v77, v77
	v_or_b32_e32 v80, 48, v154
	v_pk_mul_f32 v[82:83], v[72:73], v[72:73]
	v_max_f32_e32 v73, v74, v74
	v_ashrrev_i32_e32 v81, 31, v80
	v_max_f32_e32 v72, v78, v78
	v_max_f32_e32 v74, 0, v73
	v_max_f32_e32 v73, v79, v79
	v_max_f32_e32 v75, v75, v75
	v_lshlrev_b64 v[80:81], 13, v[80:81]
	v_max_f32_e32 v76, 0, v76
	v_max_f32_e32 v77, 0, v77
	v_max_f32_e32 v72, 0, v72
	v_max_f32_e32 v73, 0, v73
	v_max_f32_e32 v75, 0, v75
	v_lshl_add_u64 v[80:81], s[46:47], 0, v[80:81]
	v_pk_mul_f32 v[76:77], v[76:77], v[76:77]
	v_pk_mul_f32 v[78:79], v[72:73], v[72:73]
	v_pk_mul_f32 v[84:85], v[74:75], v[74:75]
	v_max_f32_e32 v64, v64, v64
	v_max_f32_e32 v65, v65, v65
	v_cvt_pk_bf16_f32 v72, v76, v77
	v_cvt_pk_bf16_f32 v73, v78, v79
	v_cvt_pk_bf16_f32 v74, v82, v83
	v_cvt_pk_bf16_f32 v75, v84, v85
	v_lshl_add_u64 v[76:77], v[80:81], 0, v[126:127]
	v_max_f32_e32 v64, 0, v64
	v_max_f32_e32 v65, 0, v65
	global_store_dwordx4 v[76:77], v[72:75], off
	v_max_f32_e32 v68, v68, v68
	v_max_f32_e32 v69, v69, v69
	v_pk_mul_f32 v[72:73], v[64:65], v[64:65]
	v_max_f32_e32 v65, v66, v66
	v_max_f32_e32 v64, v70, v70
	v_max_f32_e32 v66, 0, v65
	v_max_f32_e32 v65, v71, v71
	v_max_f32_e32 v67, v67, v67
	v_max_f32_e32 v68, 0, v68
	v_max_f32_e32 v69, 0, v69
	v_max_f32_e32 v64, 0, v64
	v_max_f32_e32 v65, 0, v65
	v_max_f32_e32 v67, 0, v67
	v_pk_mul_f32 v[68:69], v[68:69], v[68:69]
	v_pk_mul_f32 v[70:71], v[64:65], v[64:65]
	v_pk_mul_f32 v[74:75], v[66:67], v[66:67]
	v_max_f32_e32 v56, v56, v56
	v_max_f32_e32 v57, v57, v57
	v_cvt_pk_bf16_f32 v64, v68, v69
	v_cvt_pk_bf16_f32 v65, v70, v71
	v_cvt_pk_bf16_f32 v66, v72, v73
	v_cvt_pk_bf16_f32 v67, v74, v75
	v_max_f32_e32 v56, 0, v56
	v_max_f32_e32 v57, 0, v57
	global_store_dwordx4 v[76:77], v[64:67], off offset:256
	v_max_f32_e32 v60, v60, v60
	v_max_f32_e32 v61, v61, v61
	v_pk_mul_f32 v[64:65], v[56:57], v[56:57]
	v_max_f32_e32 v57, v58, v58
	v_max_f32_e32 v56, v62, v62
	v_max_f32_e32 v58, 0, v57
	v_max_f32_e32 v57, v63, v63
	v_max_f32_e32 v56, 0, v56
	v_max_f32_e32 v57, 0, v57
	v_max_f32_e32 v59, v59, v59
	v_max_f32_e32 v60, 0, v60
	v_max_f32_e32 v61, 0, v61
	v_max_f32_e32 v59, 0, v59
	v_pk_mul_f32 v[62:63], v[56:57], v[56:57]
	v_pk_mul_f32 v[60:61], v[60:61], v[60:61]
	v_pk_mul_f32 v[66:67], v[58:59], v[58:59]
	v_cvt_pk_bf16_f32 v57, v62, v63
	v_add_co_u32_e32 v62, vcc, s70, v120
	v_max_f32_e32 v48, v48, v48
	v_max_f32_e32 v49, v49, v49
	v_cvt_pk_bf16_f32 v56, v60, v61
	v_cvt_pk_bf16_f32 v58, v64, v65
	v_cvt_pk_bf16_f32 v59, v66, v67
	v_addc_co_u32_e32 v63, vcc, 0, v121, vcc
	v_max_f32_e32 v48, 0, v48
	v_max_f32_e32 v49, 0, v49
	global_store_dwordx4 v[62:63], v[56:59], off
	v_max_f32_e32 v52, v52, v52
	v_max_f32_e32 v53, v53, v53
	v_pk_mul_f32 v[56:57], v[48:49], v[48:49]
	v_max_f32_e32 v49, v50, v50
	v_max_f32_e32 v48, v54, v54
	v_max_f32_e32 v50, 0, v49
	v_max_f32_e32 v49, v55, v55
	v_max_f32_e32 v51, v51, v51
	v_max_f32_e32 v52, 0, v52
	v_max_f32_e32 v53, 0, v53
	v_max_f32_e32 v48, 0, v48
	v_max_f32_e32 v49, 0, v49
	v_max_f32_e32 v51, 0, v51
	v_pk_mul_f32 v[52:53], v[52:53], v[52:53]
	v_pk_mul_f32 v[54:55], v[48:49], v[48:49]
	v_pk_mul_f32 v[58:59], v[50:51], v[50:51]
	v_max_f32_e32 v40, v40, v40
	v_max_f32_e32 v41, v41, v41
	v_lshl_add_u64 v[60:61], v[120:121], 0, s[10:11]
	v_cvt_pk_bf16_f32 v48, v52, v53
	v_cvt_pk_bf16_f32 v49, v54, v55
	v_cvt_pk_bf16_f32 v50, v56, v57
	v_cvt_pk_bf16_f32 v51, v58, v59
	v_max_f32_e32 v40, 0, v40
	v_max_f32_e32 v41, 0, v41
	global_store_dwordx4 v[60:61], v[48:51], off offset:256
	v_max_f32_e32 v44, v44, v44
	v_max_f32_e32 v45, v45, v45
	v_pk_mul_f32 v[48:49], v[40:41], v[40:41]
	v_max_f32_e32 v41, v42, v42
	v_max_f32_e32 v40, v46, v46
	v_max_f32_e32 v42, 0, v41
	v_max_f32_e32 v41, v47, v47
	v_max_f32_e32 v40, 0, v40
	v_max_f32_e32 v41, 0, v41
	v_max_f32_e32 v43, v43, v43
	v_max_f32_e32 v44, 0, v44
	v_max_f32_e32 v45, 0, v45
	v_max_f32_e32 v43, 0, v43
	v_pk_mul_f32 v[46:47], v[40:41], v[40:41]
	v_pk_mul_f32 v[44:45], v[44:45], v[44:45]
	v_pk_mul_f32 v[50:51], v[42:43], v[42:43]
	v_cvt_pk_bf16_f32 v41, v46, v47
	v_add_co_u32_e32 v46, vcc, s71, v120
	v_max_f32_e32 v32, v32, v32
	v_max_f32_e32 v33, v33, v33
	v_cvt_pk_bf16_f32 v40, v44, v45
	v_cvt_pk_bf16_f32 v42, v48, v49
	v_cvt_pk_bf16_f32 v43, v50, v51
	v_addc_co_u32_e32 v47, vcc, 0, v121, vcc
	v_max_f32_e32 v32, 0, v32
	v_max_f32_e32 v33, 0, v33
	global_store_dwordx4 v[46:47], v[40:43], off
	v_max_f32_e32 v36, v36, v36
	v_max_f32_e32 v37, v37, v37
	v_pk_mul_f32 v[40:41], v[32:33], v[32:33]
	v_max_f32_e32 v33, v34, v34
	v_max_f32_e32 v32, v38, v38
	v_max_f32_e32 v34, 0, v33
	v_max_f32_e32 v33, v39, v39
	v_max_f32_e32 v35, v35, v35
	v_max_f32_e32 v36, 0, v36
	v_max_f32_e32 v37, 0, v37
	v_max_f32_e32 v32, 0, v32
	v_max_f32_e32 v33, 0, v33
	v_max_f32_e32 v35, 0, v35
	v_pk_mul_f32 v[36:37], v[36:37], v[36:37]
	v_pk_mul_f32 v[38:39], v[32:33], v[32:33]
	v_pk_mul_f32 v[42:43], v[34:35], v[34:35]
	v_max_f32_e32 v24, v24, v24
	v_max_f32_e32 v25, v25, v25
	v_lshl_add_u64 v[44:45], v[120:121], 0, s[12:13]
	v_cvt_pk_bf16_f32 v32, v36, v37
	v_cvt_pk_bf16_f32 v33, v38, v39
	v_cvt_pk_bf16_f32 v34, v40, v41
	v_cvt_pk_bf16_f32 v35, v42, v43
	v_max_f32_e32 v24, 0, v24
	v_max_f32_e32 v25, 0, v25
	global_store_dwordx4 v[44:45], v[32:35], off offset:256
	v_max_f32_e32 v28, v28, v28
	v_max_f32_e32 v29, v29, v29
	v_pk_mul_f32 v[32:33], v[24:25], v[24:25]
	v_max_f32_e32 v25, v26, v26
	v_max_f32_e32 v24, v30, v30
	v_max_f32_e32 v26, 0, v25
	v_max_f32_e32 v25, v31, v31
	v_max_f32_e32 v24, 0, v24
	v_max_f32_e32 v25, 0, v25
	v_max_f32_e32 v27, v27, v27
	v_max_f32_e32 v28, 0, v28
	v_max_f32_e32 v29, 0, v29
	v_max_f32_e32 v27, 0, v27
	v_pk_mul_f32 v[30:31], v[24:25], v[24:25]
	v_pk_mul_f32 v[28:29], v[28:29], v[28:29]
	v_pk_mul_f32 v[34:35], v[26:27], v[26:27]
	v_cvt_pk_bf16_f32 v25, v30, v31
	v_add_co_u32_e32 v30, vcc, s72, v120
	v_max_f32_e32 v16, v16, v16
	v_max_f32_e32 v17, v17, v17
	v_cvt_pk_bf16_f32 v24, v28, v29
	v_cvt_pk_bf16_f32 v26, v32, v33
	v_cvt_pk_bf16_f32 v27, v34, v35
	v_addc_co_u32_e32 v31, vcc, 0, v121, vcc
	v_max_f32_e32 v16, 0, v16
	v_max_f32_e32 v17, 0, v17
	global_store_dwordx4 v[30:31], v[24:27], off
	v_max_f32_e32 v20, v20, v20
	v_max_f32_e32 v21, v21, v21
	v_pk_mul_f32 v[24:25], v[16:17], v[16:17]
	v_max_f32_e32 v17, v18, v18
	v_max_f32_e32 v16, v22, v22
	v_max_f32_e32 v18, 0, v17
	v_max_f32_e32 v17, v23, v23
	v_max_f32_e32 v19, v19, v19
	v_max_f32_e32 v20, 0, v20
	v_max_f32_e32 v21, 0, v21
	v_max_f32_e32 v16, 0, v16
	v_max_f32_e32 v17, 0, v17
	v_max_f32_e32 v19, 0, v19
	v_pk_mul_f32 v[20:21], v[20:21], v[20:21]
	v_pk_mul_f32 v[22:23], v[16:17], v[16:17]
	v_pk_mul_f32 v[26:27], v[18:19], v[18:19]
	v_max_f32_e32 v8, v8, v8
	v_max_f32_e32 v9, v9, v9
	v_lshl_add_u64 v[28:29], v[120:121], 0, s[14:15]
	v_cvt_pk_bf16_f32 v16, v20, v21
	v_cvt_pk_bf16_f32 v17, v22, v23
	v_cvt_pk_bf16_f32 v18, v24, v25
	v_cvt_pk_bf16_f32 v19, v26, v27
	v_max_f32_e32 v8, 0, v8
	v_max_f32_e32 v9, 0, v9
	global_store_dwordx4 v[28:29], v[16:19], off offset:256
	v_max_f32_e32 v12, v12, v12
	v_max_f32_e32 v13, v13, v13
	v_pk_mul_f32 v[16:17], v[8:9], v[8:9]
	v_max_f32_e32 v9, v10, v10
	v_max_f32_e32 v8, v14, v14
	v_max_f32_e32 v10, 0, v9
	v_max_f32_e32 v9, v15, v15
	v_max_f32_e32 v8, 0, v8
	v_max_f32_e32 v9, 0, v9
	v_max_f32_e32 v11, v11, v11
	v_max_f32_e32 v12, 0, v12
	v_max_f32_e32 v13, 0, v13
	v_max_f32_e32 v11, 0, v11
	v_pk_mul_f32 v[14:15], v[8:9], v[8:9]
	v_pk_mul_f32 v[12:13], v[12:13], v[12:13]
	v_pk_mul_f32 v[18:19], v[10:11], v[10:11]
	v_cvt_pk_bf16_f32 v9, v14, v15
	v_add_co_u32_e32 v14, vcc, s73, v120
	v_max_f32_e32 v0, v0, v0
	v_max_f32_e32 v1, v1, v1
	v_cvt_pk_bf16_f32 v8, v12, v13
	v_cvt_pk_bf16_f32 v10, v16, v17
	v_cvt_pk_bf16_f32 v11, v18, v19
	v_addc_co_u32_e32 v15, vcc, 0, v121, vcc
	v_max_f32_e32 v0, 0, v0
	v_max_f32_e32 v1, 0, v1
	global_store_dwordx4 v[14:15], v[8:11], off
	v_max_f32_e32 v4, v4, v4
	v_max_f32_e32 v5, v5, v5
	v_pk_mul_f32 v[8:9], v[0:1], v[0:1]
	v_max_f32_e32 v1, v2, v2
	v_max_f32_e32 v0, v6, v6
	v_max_f32_e32 v2, 0, v1
	v_max_f32_e32 v1, v7, v7
	v_max_f32_e32 v3, v3, v3
	v_max_f32_e32 v4, 0, v4
	v_max_f32_e32 v5, 0, v5
	v_max_f32_e32 v0, 0, v0
	v_max_f32_e32 v1, 0, v1
	v_max_f32_e32 v3, 0, v3
	v_pk_mul_f32 v[4:5], v[4:5], v[4:5]
	v_pk_mul_f32 v[6:7], v[0:1], v[0:1]
	v_pk_mul_f32 v[10:11], v[2:3], v[2:3]
	v_lshl_add_u64 v[12:13], v[120:121], 0, s[16:17]
	v_cvt_pk_bf16_f32 v0, v4, v5
	v_cvt_pk_bf16_f32 v1, v6, v7
	v_cvt_pk_bf16_f32 v2, v8, v9
	v_cvt_pk_bf16_f32 v3, v10, v11
	s_and_b64 vcc, exec, s[4:5]
	s_mov_b32 s74, s18
	s_mov_b32 s30, s20
	s_mov_b64 s[36:37], s[28:29]
	s_mov_b64 s[34:35], s[26:27]
	global_store_dwordx4 v[12:13], v[0:3], off offset:256
	s_mov_b32 s94, 1
	s_cbranch_vccz .LBB0_1284
	s_mov_b32 s94, 0
	s_waitcnt vmcnt(16)
	s_cmpk_gt_u32 s40, 0xff
	s_cbranch_scc1 .LBB0_1295
	s_barrier

.LBB0_1310:
	ds_read_b128 v[154:157], v151
	ds_read_b128 v[158:161], v151 offset:1024
	ds_read_b128 v[162:165], v151 offset:2048
	ds_read_b128 v[166:169], v151 offset:3072
	s_add_u32 s38, s36, 0xfffc0080
	s_addc_u32 s39, s37, -1
	s_cmp_eq_u32 s77, 12
	s_cselect_b32 s41, s27, s39
	s_cselect_b32 s40, s73, s38
	s_cselect_b32 s39, s21, s76
	s_cselect_b32 s38, s74, s75
	v_lshl_add_u64 v[202:203], s[36:37], 0, v[138:139]
	s_add_i32 m0, s35, 0xc000
	ds_read_b128 v[170:173], v152
	ds_read_b128 v[174:177], v152 offset:1024
	ds_read_b128 v[178:181], v152 offset:2048
	ds_read_b128 v[182:185], v152 offset:3072
	ds_read_b128 v[186:189], v152 offset:4096
	ds_read_b128 v[190:193], v152 offset:5120
	ds_read_b128 v[194:197], v152 offset:6144
	ds_read_b128 v[198:201], v152 offset:7168
	global_load_lds_dwordx4 v[202:203], off
	v_lshl_add_u64 v[202:203], s[36:37], 0, v[140:141]
	s_add_i32 m0, s35, 0xe000
	s_nop 0
	global_load_lds_dwordx4 v[202:203], off
	s_waitcnt lgkmcnt(8)
	s_barrier
	s_waitcnt lgkmcnt(0)
	s_waitcnt lgkmcnt(0)
	v_mfma_f32_16x16x32_bf16 v[124:127], v[154:157], v[170:173], v[124:127]
	v_mfma_f32_16x16x32_bf16 v[120:123], v[162:165], v[170:173], v[120:123]
	v_mfma_f32_16x16x32_bf16 v[108:111], v[154:157], v[178:181], v[108:111]
	v_mfma_f32_16x16x32_bf16 v[104:107], v[162:165], v[178:181], v[104:107]
	v_mfma_f32_16x16x32_bf16 v[92:95], v[154:157], v[186:189], v[92:95]
	v_mfma_f32_16x16x32_bf16 v[88:91], v[162:165], v[186:189], v[88:91]
	v_mfma_f32_16x16x32_bf16 v[76:79], v[154:157], v[194:197], v[76:79]
	v_mfma_f32_16x16x32_bf16 v[72:75], v[162:165], v[194:197], v[72:75]
	v_mfma_f32_16x16x32_bf16 v[124:127], v[158:161], v[174:177], v[124:127]
	v_mfma_f32_16x16x32_bf16 v[120:123], v[166:169], v[174:177], v[120:123]
	v_mfma_f32_16x16x32_bf16 v[108:111], v[158:161], v[182:185], v[108:111]
	v_mfma_f32_16x16x32_bf16 v[104:107], v[166:169], v[182:185], v[104:107]
	v_mfma_f32_16x16x32_bf16 v[92:95], v[158:161], v[190:193], v[92:95]
	v_mfma_f32_16x16x32_bf16 v[88:91], v[166:169], v[190:193], v[88:91]
	v_mfma_f32_16x16x32_bf16 v[76:79], v[158:161], v[198:201], v[76:79]
	v_mfma_f32_16x16x32_bf16 v[72:75], v[166:169], v[198:201], v[72:75]
	s_barrier
	s_add_i32 s78, s62, s52
	v_lshl_add_u64 v[218:219], s[38:39], 0, v[132:133]
	s_mov_b32 m0, s78
	ds_read_b128 v[202:205], v153
	ds_read_b128 v[206:209], v153 offset:1024
	ds_read_b128 v[210:213], v153 offset:2048
	ds_read_b128 v[214:217], v153 offset:3072
	global_load_lds_dwordx4 v[218:219], off
	v_lshl_add_u64 v[220:221], s[38:39], 0, v[136:137]
	s_add_i32 m0, s78, 0x2000
	s_nop 0
	global_load_lds_dwordx4 v[220:221], off
	s_barrier
	s_waitcnt lgkmcnt(0)
	s_waitcnt lgkmcnt(0)
	v_mfma_f32_16x16x32_bf16 v[116:119], v[202:205], v[170:173], v[116:119]
	v_mfma_f32_16x16x32_bf16 v[112:115], v[210:213], v[170:173], v[112:115]
	v_mfma_f32_16x16x32_bf16 v[100:103], v[202:205], v[178:181], v[100:103]
	v_mfma_f32_16x16x32_bf16 v[96:99], v[210:213], v[178:181], v[96:99]
	v_mfma_f32_16x16x32_bf16 v[84:87], v[202:205], v[186:189], v[84:87]
	v_mfma_f32_16x16x32_bf16 v[80:83], v[210:213], v[186:189], v[80:83]
	v_mfma_f32_16x16x32_bf16 v[68:71], v[202:205], v[194:197], v[68:71]
	v_mfma_f32_16x16x32_bf16 v[64:67], v[210:213], v[194:197], v[64:67]
	v_mfma_f32_16x16x32_bf16 v[116:119], v[206:209], v[174:177], v[116:119]
	v_mfma_f32_16x16x32_bf16 v[112:115], v[214:217], v[174:177], v[112:115]
	v_mfma_f32_16x16x32_bf16 v[100:103], v[206:209], v[182:185], v[100:103]
	v_mfma_f32_16x16x32_bf16 v[96:99], v[214:217], v[182:185], v[96:99]
	v_mfma_f32_16x16x32_bf16 v[84:87], v[206:209], v[190:193], v[84:87]
	v_mfma_f32_16x16x32_bf16 v[80:83], v[214:217], v[190:193], v[80:83]
	v_mfma_f32_16x16x32_bf16 v[68:71], v[206:209], v[198:201], v[68:71]
	v_mfma_f32_16x16x32_bf16 v[64:67], v[214:217], v[198:201], v[64:67]
	s_mov_b32 m0, s35
	v_lshl_add_u64 v[222:223], s[40:41], 0, v[130:131]
	s_barrier
	ds_read_b128 v[170:173], v152 offset:16384
	ds_read_b128 v[174:177], v152 offset:17408
	ds_read_b128 v[178:181], v152 offset:18432
	ds_read_b128 v[182:185], v152 offset:19456
	ds_read_b128 v[186:189], v152 offset:20480
	ds_read_b128 v[190:193], v152 offset:21504
	ds_read_b128 v[194:197], v152 offset:22528
	ds_read_b128 v[198:201], v152 offset:23552
	global_load_lds_dwordx4 v[222:223], off
	v_lshl_add_u64 v[224:225], s[40:41], 0, v[134:135]
	s_mov_b32 m0, s53
	s_nop 0
	global_load_lds_dwordx4 v[224:225], off
	s_barrier
	s_waitcnt lgkmcnt(0)
	s_waitcnt lgkmcnt(0)
	v_mfma_f32_16x16x32_bf16 v[60:63], v[154:157], v[170:173], v[60:63]
	v_mfma_f32_16x16x32_bf16 v[56:59], v[162:165], v[170:173], v[56:59]
	v_mfma_f32_16x16x32_bf16 v[44:47], v[154:157], v[178:181], v[44:47]
	v_mfma_f32_16x16x32_bf16 v[40:43], v[162:165], v[178:181], v[40:43]
	v_mfma_f32_16x16x32_bf16 v[28:31], v[154:157], v[186:189], v[28:31]
	v_mfma_f32_16x16x32_bf16 v[24:27], v[162:165], v[186:189], v[24:27]
	v_mfma_f32_16x16x32_bf16 v[12:15], v[154:157], v[194:197], v[12:15]
	v_mfma_f32_16x16x32_bf16 v[8:11], v[162:165], v[194:197], v[8:11]
	v_mfma_f32_16x16x32_bf16 v[60:63], v[158:161], v[174:177], v[60:63]
	v_mfma_f32_16x16x32_bf16 v[56:59], v[166:169], v[174:177], v[56:59]
	v_mfma_f32_16x16x32_bf16 v[44:47], v[158:161], v[182:185], v[44:47]
	v_mfma_f32_16x16x32_bf16 v[40:43], v[166:169], v[182:185], v[40:43]
	v_mfma_f32_16x16x32_bf16 v[28:31], v[158:161], v[190:193], v[28:31]
	v_mfma_f32_16x16x32_bf16 v[24:27], v[166:169], v[190:193], v[24:27]
	v_mfma_f32_16x16x32_bf16 v[12:15], v[158:161], v[198:201], v[12:15]
	v_mfma_f32_16x16x32_bf16 v[8:11], v[166:169], v[198:201], v[8:11]
	s_barrier
	s_add_u32 s78, s38, 0x40000
	s_addc_u32 s79, s39, 0
	s_add_i32 s80, s63, s52
	v_lshl_add_u64 v[154:155], s[78:79], 0, v[132:133]
	s_mov_b32 m0, s80
	s_nop 0
	global_load_lds_dwordx4 v[154:155], off
	v_lshl_add_u64 v[154:155], s[78:79], 0, v[136:137]
	s_add_i32 m0, s80, 0x2000
	s_nop 0
	global_load_lds_dwordx4 v[154:155], off
	s_cmp_lg_u32 s94, 0
	s_cbranch_scc1 .Lrx10a
	s_waitcnt vmcnt(6)
.Lrx10a:
	s_waitcnt vmcnt(24)
	s_barrier
	v_mfma_f32_16x16x32_bf16 v[52:55], v[202:205], v[170:173], v[52:55]
	v_mfma_f32_16x16x32_bf16 v[48:51], v[210:213], v[170:173], v[48:51]
	v_mfma_f32_16x16x32_bf16 v[36:39], v[202:205], v[178:181], v[36:39]
	v_mfma_f32_16x16x32_bf16 v[32:35], v[210:213], v[178:181], v[32:35]
	v_mfma_f32_16x16x32_bf16 v[20:23], v[202:205], v[186:189], v[20:23]
	v_mfma_f32_16x16x32_bf16 v[16:19], v[210:213], v[186:189], v[16:19]
	v_mfma_f32_16x16x32_bf16 v[4:7], v[202:205], v[194:197], v[4:7]
	v_mfma_f32_16x16x32_bf16 v[0:3], v[210:213], v[194:197], v[0:3]
	v_mfma_f32_16x16x32_bf16 v[52:55], v[206:209], v[174:177], v[52:55]
	v_mfma_f32_16x16x32_bf16 v[48:51], v[214:217], v[174:177], v[48:51]
	v_mfma_f32_16x16x32_bf16 v[36:39], v[206:209], v[182:185], v[36:39]
	v_mfma_f32_16x16x32_bf16 v[32:35], v[214:217], v[182:185], v[32:35]
	v_mfma_f32_16x16x32_bf16 v[20:23], v[206:209], v[190:193], v[20:23]
	v_mfma_f32_16x16x32_bf16 v[16:19], v[214:217], v[190:193], v[16:19]
	v_mfma_f32_16x16x32_bf16 v[4:7], v[206:209], v[198:201], v[4:7]
	v_mfma_f32_16x16x32_bf16 v[0:3], v[214:217], v[198:201], v[0:3]
	s_add_i32 s78, 0, 0x18000
	v_add_u32_e32 v166, s78, v149
	s_barrier
	ds_read_b128 v[154:157], v166
	ds_read_b128 v[158:161], v166 offset:1024
	ds_read_b128 v[162:165], v166 offset:2048
	ds_read_b128 v[166:169], v166 offset:3072
	s_add_u32 s40, s40, 0x40000
	s_addc_u32 s41, s41, 0
	s_mov_b32 m0, s54
	v_lshl_add_u64 v[202:203], s[40:41], 0, v[130:131]
	ds_read_b128 v[170:173], v152 offset:32768
	ds_read_b128 v[174:177], v152 offset:33792
	ds_read_b128 v[178:181], v152 offset:34816
	ds_read_b128 v[182:185], v152 offset:35840
	ds_read_b128 v[186:189], v152 offset:36864
	ds_read_b128 v[190:193], v152 offset:37888
	ds_read_b128 v[194:197], v152 offset:38912
	ds_read_b128 v[198:201], v152 offset:39936
	global_load_lds_dwordx4 v[202:203], off
	v_lshl_add_u64 v[202:203], s[40:41], 0, v[134:135]
	s_mov_b32 m0, s55
	s_nop 0
	global_load_lds_dwordx4 v[202:203], off
	s_waitcnt lgkmcnt(8)
	s_barrier
	s_waitcnt lgkmcnt(0)
	s_waitcnt lgkmcnt(0)
	v_mfma_f32_16x16x32_bf16 v[124:127], v[154:157], v[170:173], v[124:127]
	v_mfma_f32_16x16x32_bf16 v[120:123], v[162:165], v[170:173], v[120:123]
	v_mfma_f32_16x16x32_bf16 v[108:111], v[154:157], v[178:181], v[108:111]
	v_mfma_f32_16x16x32_bf16 v[104:107], v[162:165], v[178:181], v[104:107]
	v_mfma_f32_16x16x32_bf16 v[92:95], v[154:157], v[186:189], v[92:95]
	v_mfma_f32_16x16x32_bf16 v[88:91], v[162:165], v[186:189], v[88:91]
	v_mfma_f32_16x16x32_bf16 v[76:79], v[154:157], v[194:197], v[76:79]
	v_mfma_f32_16x16x32_bf16 v[72:75], v[162:165], v[194:197], v[72:75]
	v_mfma_f32_16x16x32_bf16 v[124:127], v[158:161], v[174:177], v[124:127]
	v_mfma_f32_16x16x32_bf16 v[120:123], v[166:169], v[174:177], v[120:123]
	v_mfma_f32_16x16x32_bf16 v[108:111], v[158:161], v[182:185], v[108:111]
	v_mfma_f32_16x16x32_bf16 v[104:107], v[166:169], v[182:185], v[104:107]
	v_mfma_f32_16x16x32_bf16 v[92:95], v[158:161], v[190:193], v[92:95]
	v_mfma_f32_16x16x32_bf16 v[88:91], v[166:169], v[190:193], v[88:91]
	v_mfma_f32_16x16x32_bf16 v[76:79], v[158:161], v[198:201], v[76:79]
	v_mfma_f32_16x16x32_bf16 v[72:75], v[166:169], v[198:201], v[72:75]
	s_barrier
	s_add_i32 s40, 0, 0x1c000
	s_add_i32 s41, s78, s52
	v_add_u32_e32 v214, s40, v149
	v_lshl_add_u64 v[218:219], v[218:219], 0, s[10:11]
	s_mov_b32 m0, s41
	ds_read_b128 v[202:205], v214
	ds_read_b128 v[206:209], v214 offset:1024
	ds_read_b128 v[210:213], v214 offset:2048
	ds_read_b128 v[214:217], v214 offset:3072
	global_load_lds_dwordx4 v[218:219], off
	v_lshl_add_u64 v[218:219], v[220:221], 0, s[10:11]
	s_add_i32 m0, s41, 0x2000
	s_nop 0
	global_load_lds_dwordx4 v[218:219], off
	s_cmp_lg_u32 s94, 0
	s_cbranch_scc0 .Lrx10c
	s_waitcnt vmcnt(10)
	s_mov_b32 s94, 0
.Lrx10c:
	s_barrier
	s_waitcnt lgkmcnt(0)
	s_waitcnt lgkmcnt(0)
	v_mfma_f32_16x16x32_bf16 v[116:119], v[202:205], v[170:173], v[116:119]
	v_mfma_f32_16x16x32_bf16 v[112:115], v[210:213], v[170:173], v[112:115]
	v_mfma_f32_16x16x32_bf16 v[100:103], v[202:205], v[178:181], v[100:103]
	v_mfma_f32_16x16x32_bf16 v[96:99], v[210:213], v[178:181], v[96:99]
	v_mfma_f32_16x16x32_bf16 v[84:87], v[202:205], v[186:189], v[84:87]
	v_mfma_f32_16x16x32_bf16 v[80:83], v[210:213], v[186:189], v[80:83]
	v_mfma_f32_16x16x32_bf16 v[68:71], v[202:205], v[194:197], v[68:71]
	v_mfma_f32_16x16x32_bf16 v[64:67], v[210:213], v[194:197], v[64:67]
	v_mfma_f32_16x16x32_bf16 v[116:119], v[206:209], v[174:177], v[116:119]
	v_mfma_f32_16x16x32_bf16 v[112:115], v[214:217], v[174:177], v[112:115]
	v_mfma_f32_16x16x32_bf16 v[100:103], v[206:209], v[182:185], v[100:103]
	v_mfma_f32_16x16x32_bf16 v[96:99], v[214:217], v[182:185], v[96:99]
	v_mfma_f32_16x16x32_bf16 v[84:87], v[206:209], v[190:193], v[84:87]
	v_mfma_f32_16x16x32_bf16 v[80:83], v[214:217], v[190:193], v[80:83]
	v_mfma_f32_16x16x32_bf16 v[68:71], v[206:209], v[198:201], v[68:71]
	v_mfma_f32_16x16x32_bf16 v[64:67], v[214:217], v[198:201], v[64:67]
	s_mov_b32 m0, s57
	v_lshl_add_u64 v[218:219], v[222:223], 0, s[10:11]
	s_barrier
	ds_read_b128 v[170:173], v152 offset:49152
	ds_read_b128 v[174:177], v152 offset:50176
	ds_read_b128 v[178:181], v152 offset:51200
	ds_read_b128 v[182:185], v152 offset:52224
	ds_read_b128 v[186:189], v152 offset:53248
	ds_read_b128 v[190:193], v152 offset:54272
	ds_read_b128 v[194:197], v152 offset:55296
	ds_read_b128 v[198:201], v152 offset:56320
	global_load_lds_dwordx4 v[218:219], off
	v_lshl_add_u64 v[218:219], v[224:225], 0, s[10:11]
	s_mov_b32 m0, s60
	s_nop 0
	global_load_lds_dwordx4 v[218:219], off
	s_barrier
	s_waitcnt lgkmcnt(0)
	s_waitcnt lgkmcnt(0)
	v_mfma_f32_16x16x32_bf16 v[60:63], v[154:157], v[170:173], v[60:63]
	v_mfma_f32_16x16x32_bf16 v[56:59], v[162:165], v[170:173], v[56:59]
	v_mfma_f32_16x16x32_bf16 v[44:47], v[154:157], v[178:181], v[44:47]
	v_mfma_f32_16x16x32_bf16 v[40:43], v[162:165], v[178:181], v[40:43]
	v_mfma_f32_16x16x32_bf16 v[28:31], v[154:157], v[186:189], v[28:31]
	v_mfma_f32_16x16x32_bf16 v[24:27], v[162:165], v[186:189], v[24:27]
	v_mfma_f32_16x16x32_bf16 v[12:15], v[154:157], v[194:197], v[12:15]
	v_mfma_f32_16x16x32_bf16 v[8:11], v[162:165], v[194:197], v[8:11]
	v_mfma_f32_16x16x32_bf16 v[60:63], v[158:161], v[174:177], v[60:63]
	v_mfma_f32_16x16x32_bf16 v[56:59], v[166:169], v[174:177], v[56:59]
	v_mfma_f32_16x16x32_bf16 v[44:47], v[158:161], v[182:185], v[44:47]
	v_mfma_f32_16x16x32_bf16 v[40:43], v[166:169], v[182:185], v[40:43]
	v_mfma_f32_16x16x32_bf16 v[28:31], v[158:161], v[190:193], v[28:31]
	v_mfma_f32_16x16x32_bf16 v[24:27], v[166:169], v[190:193], v[24:27]
	v_mfma_f32_16x16x32_bf16 v[12:15], v[158:161], v[198:201], v[12:15]
	v_mfma_f32_16x16x32_bf16 v[8:11], v[166:169], v[198:201], v[8:11]
	s_barrier
	s_add_u32 s38, s38, 0x40080
	s_addc_u32 s39, s39, 0
	s_add_i32 s40, s40, s52
	v_lshl_add_u64 v[154:155], s[38:39], 0, v[132:133]
	s_mov_b32 m0, s40
	s_nop 0
	global_load_lds_dwordx4 v[154:155], off
	v_lshl_add_u64 v[154:155], s[38:39], 0, v[136:137]
	s_add_i32 m0, s40, 0x2000
	s_nop 0
	global_load_lds_dwordx4 v[154:155], off
	s_waitcnt vmcnt(6)
	s_barrier
	v_mfma_f32_16x16x32_bf16 v[52:55], v[202:205], v[170:173], v[52:55]
	v_mfma_f32_16x16x32_bf16 v[48:51], v[210:213], v[170:173], v[48:51]
	v_mfma_f32_16x16x32_bf16 v[36:39], v[202:205], v[178:181], v[36:39]
	v_mfma_f32_16x16x32_bf16 v[32:35], v[210:213], v[178:181], v[32:35]
	v_mfma_f32_16x16x32_bf16 v[20:23], v[202:205], v[186:189], v[20:23]
	v_mfma_f32_16x16x32_bf16 v[16:19], v[210:213], v[186:189], v[16:19]
	v_mfma_f32_16x16x32_bf16 v[4:7], v[202:205], v[194:197], v[4:7]
	v_mfma_f32_16x16x32_bf16 v[0:3], v[210:213], v[194:197], v[0:3]
	v_mfma_f32_16x16x32_bf16 v[52:55], v[206:209], v[174:177], v[52:55]
	v_mfma_f32_16x16x32_bf16 v[48:51], v[214:217], v[174:177], v[48:51]
	v_mfma_f32_16x16x32_bf16 v[36:39], v[206:209], v[182:185], v[36:39]
	v_mfma_f32_16x16x32_bf16 v[32:35], v[214:217], v[182:185], v[32:35]
	v_mfma_f32_16x16x32_bf16 v[20:23], v[206:209], v[190:193], v[20:23]
	v_mfma_f32_16x16x32_bf16 v[16:19], v[214:217], v[190:193], v[16:19]
	v_mfma_f32_16x16x32_bf16 v[4:7], v[206:209], v[198:201], v[4:7]
	v_mfma_f32_16x16x32_bf16 v[0:3], v[214:217], v[198:201], v[0:3]
	s_add_i32 s77, s77, 2
	s_add_u32 s36, s36, 0x100
	s_addc_u32 s37, s37, 0
	s_add_u32 s75, s75, 0x100
	s_addc_u32 s76, s76, 0
	s_cmp_gt_u32 s77, 13
	s_barrier
	s_cbranch_scc0 .LBB0_1310
	v_lshl_add_u32 v154, s34, 8, v148
	v_max_f32_e32 v126, v126, v126
	v_max_f32_e32 v127, v127, v127
	v_lshl_or_b32 v156, s72, 8, v150
	v_ashrrev_i32_e32 v155, 31, v154
	v_max_f32_e32 v124, v124, v124
	v_max_f32_e32 v120, v120, v120
	v_max_f32_e32 v125, v125, v125
	v_max_f32_e32 v121, v121, v121
	v_max_f32_e32 v126, 0, v126
	v_max_f32_e32 v122, v122, v122
	v_max_f32_e32 v127, 0, v127
	v_max_f32_e32 v123, v123, v123
	v_lshlrev_b64 v[158:159], 13, v[154:155]
	v_max_f32_e32 v124, 0, v124
	v_max_f32_e32 v120, 0, v120
	v_max_f32_e32 v125, 0, v125
	v_max_f32_e32 v121, 0, v121
	v_max_f32_e32 v122, 0, v122
	v_max_f32_e32 v123, 0, v123
	v_pk_mul_f32 v[126:127], v[126:127], v[126:127]
	v_ashrrev_i32_e32 v157, 31, v156
	v_lshl_add_u64 v[158:159], s[46:47], 0, v[158:159]
	v_pk_mul_f32 v[124:125], v[124:125], v[124:125]
	v_pk_mul_f32 v[120:121], v[120:121], v[120:121]
	v_pk_mul_f32 v[160:161], v[122:123], v[122:123]
	v_cvt_pk_bf16_f32 v123, v126, v127
	v_lshlrev_b64 v[126:127], 1, v[156:157]
	v_max_f32_e32 v112, v112, v112
	v_max_f32_e32 v113, v113, v113
	v_cvt_pk_bf16_f32 v122, v124, v125
	v_cvt_pk_bf16_f32 v124, v120, v121
	v_cvt_pk_bf16_f32 v125, v160, v161
	v_lshl_add_u64 v[120:121], v[158:159], 0, v[126:127]
	v_max_f32_e32 v112, 0, v112
	v_max_f32_e32 v113, 0, v113
	global_store_dwordx4 v[120:121], v[122:125], off
	v_max_f32_e32 v116, v116, v116
	v_max_f32_e32 v117, v117, v117
	v_pk_mul_f32 v[122:123], v[112:113], v[112:113]
	v_max_f32_e32 v113, v114, v114
	v_max_f32_e32 v112, v118, v118
	v_max_f32_e32 v114, 0, v113
	v_max_f32_e32 v113, v119, v119
	v_max_f32_e32 v115, v115, v115
	v_max_f32_e32 v116, 0, v116
	v_max_f32_e32 v117, 0, v117
	v_max_f32_e32 v112, 0, v112
	v_max_f32_e32 v113, 0, v113
	v_max_f32_e32 v115, 0, v115
	v_pk_mul_f32 v[116:117], v[116:117], v[116:117]
	v_pk_mul_f32 v[118:119], v[112:113], v[112:113]
	v_pk_mul_f32 v[124:125], v[114:115], v[114:115]
	v_max_f32_e32 v104, v104, v104
	v_max_f32_e32 v105, v105, v105
	v_cvt_pk_bf16_f32 v112, v116, v117
	v_cvt_pk_bf16_f32 v113, v118, v119
	v_cvt_pk_bf16_f32 v114, v122, v123
	v_cvt_pk_bf16_f32 v115, v124, v125
	v_max_f32_e32 v104, 0, v104
	v_max_f32_e32 v105, 0, v105
	global_store_dwordx4 v[120:121], v[112:115], off offset:256
	v_max_f32_e32 v108, v108, v108
	v_max_f32_e32 v109, v109, v109
	v_or_b32_e32 v112, 16, v154
	v_pk_mul_f32 v[114:115], v[104:105], v[104:105]
	v_max_f32_e32 v105, v106, v106
	v_ashrrev_i32_e32 v113, 31, v112
	v_max_f32_e32 v104, v110, v110
	v_max_f32_e32 v106, 0, v105
	v_max_f32_e32 v105, v111, v111
	v_max_f32_e32 v107, v107, v107
	v_lshlrev_b64 v[112:113], 13, v[112:113]
	v_max_f32_e32 v108, 0, v108
	v_max_f32_e32 v109, 0, v109
	v_max_f32_e32 v104, 0, v104
	v_max_f32_e32 v105, 0, v105
	v_max_f32_e32 v107, 0, v107
	v_lshl_add_u64 v[112:113], s[46:47], 0, v[112:113]
	v_pk_mul_f32 v[108:109], v[108:109], v[108:109]
	v_pk_mul_f32 v[110:111], v[104:105], v[104:105]
	v_pk_mul_f32 v[116:117], v[106:107], v[106:107]
	v_max_f32_e32 v96, v96, v96
	v_max_f32_e32 v97, v97, v97
	v_cvt_pk_bf16_f32 v104, v108, v109
	v_cvt_pk_bf16_f32 v105, v110, v111
	v_cvt_pk_bf16_f32 v106, v114, v115
	v_cvt_pk_bf16_f32 v107, v116, v117
	v_lshl_add_u64 v[108:109], v[112:113], 0, v[126:127]
	v_max_f32_e32 v96, 0, v96
	v_max_f32_e32 v97, 0, v97
	global_store_dwordx4 v[108:109], v[104:107], off
	v_max_f32_e32 v100, v100, v100
	v_max_f32_e32 v101, v101, v101
	v_pk_mul_f32 v[104:105], v[96:97], v[96:97]
	v_max_f32_e32 v97, v98, v98
	v_max_f32_e32 v96, v102, v102
	v_max_f32_e32 v98, 0, v97
	v_max_f32_e32 v97, v103, v103
	v_max_f32_e32 v99, v99, v99
	v_max_f32_e32 v100, 0, v100
	v_max_f32_e32 v101, 0, v101
	v_max_f32_e32 v96, 0, v96
	v_max_f32_e32 v97, 0, v97
	v_max_f32_e32 v99, 0, v99
	v_pk_mul_f32 v[100:101], v[100:101], v[100:101]
	v_pk_mul_f32 v[102:103], v[96:97], v[96:97]
	v_pk_mul_f32 v[106:107], v[98:99], v[98:99]
	v_max_f32_e32 v88, v88, v88
	v_max_f32_e32 v89, v89, v89
	v_cvt_pk_bf16_f32 v96, v100, v101
	v_cvt_pk_bf16_f32 v97, v102, v103
	v_cvt_pk_bf16_f32 v98, v104, v105
	v_cvt_pk_bf16_f32 v99, v106, v107
	v_max_f32_e32 v88, 0, v88
	v_max_f32_e32 v89, 0, v89
	global_store_dwordx4 v[108:109], v[96:99], off offset:256
	v_max_f32_e32 v92, v92, v92
	v_max_f32_e32 v93, v93, v93
	v_or_b32_e32 v96, 32, v154
	v_pk_mul_f32 v[98:99], v[88:89], v[88:89]
	v_max_f32_e32 v89, v90, v90
	v_ashrrev_i32_e32 v97, 31, v96
	v_max_f32_e32 v88, v94, v94
	v_max_f32_e32 v90, 0, v89
	v_max_f32_e32 v89, v95, v95
	v_max_f32_e32 v91, v91, v91
	v_lshlrev_b64 v[96:97], 13, v[96:97]
	v_max_f32_e32 v92, 0, v92
	v_max_f32_e32 v93, 0, v93
	v_max_f32_e32 v88, 0, v88
	v_max_f32_e32 v89, 0, v89
	v_max_f32_e32 v91, 0, v91
	v_lshl_add_u64 v[96:97], s[46:47], 0, v[96:97]
	v_pk_mul_f32 v[92:93], v[92:93], v[92:93]
	v_pk_mul_f32 v[94:95], v[88:89], v[88:89]
	v_pk_mul_f32 v[100:101], v[90:91], v[90:91]
	v_max_f32_e32 v80, v80, v80
	v_max_f32_e32 v81, v81, v81
	v_cvt_pk_bf16_f32 v88, v92, v93
	v_cvt_pk_bf16_f32 v89, v94, v95
	v_cvt_pk_bf16_f32 v90, v98, v99
	v_cvt_pk_bf16_f32 v91, v100, v101
	v_lshl_add_u64 v[92:93], v[96:97], 0, v[126:127]
	v_max_f32_e32 v80, 0, v80
	v_max_f32_e32 v81, 0, v81
	global_store_dwordx4 v[92:93], v[88:91], off
	v_max_f32_e32 v84, v84, v84
	v_max_f32_e32 v85, v85, v85
	v_pk_mul_f32 v[88:89], v[80:81], v[80:81]
	v_max_f32_e32 v81, v82, v82
	v_max_f32_e32 v80, v86, v86
	v_max_f32_e32 v82, 0, v81
	v_max_f32_e32 v81, v87, v87
	v_max_f32_e32 v83, v83, v83
	v_max_f32_e32 v84, 0, v84
	v_max_f32_e32 v85, 0, v85
	v_max_f32_e32 v80, 0, v80
	v_max_f32_e32 v81, 0, v81
	v_max_f32_e32 v83, 0, v83
	v_pk_mul_f32 v[84:85], v[84:85], v[84:85]
	v_pk_mul_f32 v[86:87], v[80:81], v[80:81]
	v_pk_mul_f32 v[90:91], v[82:83], v[82:83]
	v_max_f32_e32 v72, v72, v72
	v_max_f32_e32 v73, v73, v73
	v_cvt_pk_bf16_f32 v80, v84, v85
	v_cvt_pk_bf16_f32 v81, v86, v87
	v_cvt_pk_bf16_f32 v82, v88, v89
	v_cvt_pk_bf16_f32 v83, v90, v91
	v_max_f32_e32 v72, 0, v72
	v_max_f32_e32 v73, 0, v73
	global_store_dwordx4 v[92:93], v[80:83], off offset:256
	v_max_f32_e32 v76, v76, v76
	v_max_f32_e32 v77, v77, v77
	v_or_b32_e32 v80, 48, v154
	v_pk_mul_f32 v[82:83], v[72:73], v[72:73]
	v_max_f32_e32 v73, v74, v74
	v_ashrrev_i32_e32 v81, 31, v80
	v_max_f32_e32 v72, v78, v78
	v_max_f32_e32 v74, 0, v73
	v_max_f32_e32 v73, v79, v79
	v_max_f32_e32 v75, v75, v75
	v_lshlrev_b64 v[80:81], 13, v[80:81]
	v_max_f32_e32 v76, 0, v76
	v_max_f32_e32 v77, 0, v77
	v_max_f32_e32 v72, 0, v72
	v_max_f32_e32 v73, 0, v73
	v_max_f32_e32 v75, 0, v75
	v_lshl_add_u64 v[80:81], s[46:47], 0, v[80:81]
	v_pk_mul_f32 v[76:77], v[76:77], v[76:77]
	v_pk_mul_f32 v[78:79], v[72:73], v[72:73]
	v_pk_mul_f32 v[84:85], v[74:75], v[74:75]
	v_max_f32_e32 v64, v64, v64
	v_max_f32_e32 v65, v65, v65
	v_cvt_pk_bf16_f32 v72, v76, v77
	v_cvt_pk_bf16_f32 v73, v78, v79
	v_cvt_pk_bf16_f32 v74, v82, v83
	v_cvt_pk_bf16_f32 v75, v84, v85
	v_lshl_add_u64 v[76:77], v[80:81], 0, v[126:127]
	v_max_f32_e32 v64, 0, v64
	v_max_f32_e32 v65, 0, v65
	global_store_dwordx4 v[76:77], v[72:75], off
	v_max_f32_e32 v68, v68, v68
	v_max_f32_e32 v69, v69, v69
	v_pk_mul_f32 v[72:73], v[64:65], v[64:65]
	v_max_f32_e32 v65, v66, v66
	v_max_f32_e32 v64, v70, v70
	v_max_f32_e32 v66, 0, v65
	v_max_f32_e32 v65, v71, v71
	v_max_f32_e32 v67, v67, v67
	v_max_f32_e32 v68, 0, v68
	v_max_f32_e32 v69, 0, v69
	v_max_f32_e32 v64, 0, v64
	v_max_f32_e32 v65, 0, v65
	v_max_f32_e32 v67, 0, v67
	v_pk_mul_f32 v[68:69], v[68:69], v[68:69]
	v_pk_mul_f32 v[70:71], v[64:65], v[64:65]
	v_pk_mul_f32 v[74:75], v[66:67], v[66:67]
	v_max_f32_e32 v56, v56, v56
	v_max_f32_e32 v57, v57, v57
	v_cvt_pk_bf16_f32 v64, v68, v69
	v_cvt_pk_bf16_f32 v65, v70, v71
	v_cvt_pk_bf16_f32 v66, v72, v73
	v_cvt_pk_bf16_f32 v67, v74, v75
	v_max_f32_e32 v56, 0, v56
	v_max_f32_e32 v57, 0, v57
	global_store_dwordx4 v[76:77], v[64:67], off offset:256
	v_max_f32_e32 v60, v60, v60
	v_max_f32_e32 v61, v61, v61
	v_pk_mul_f32 v[64:65], v[56:57], v[56:57]
	v_max_f32_e32 v57, v58, v58
	v_max_f32_e32 v56, v62, v62
	v_max_f32_e32 v58, 0, v57
	v_max_f32_e32 v57, v63, v63
	v_max_f32_e32 v56, 0, v56
	v_max_f32_e32 v57, 0, v57
	v_max_f32_e32 v59, v59, v59
	v_max_f32_e32 v60, 0, v60
	v_max_f32_e32 v61, 0, v61
	v_max_f32_e32 v59, 0, v59
	v_pk_mul_f32 v[62:63], v[56:57], v[56:57]
	v_pk_mul_f32 v[60:61], v[60:61], v[60:61]
	v_pk_mul_f32 v[66:67], v[58:59], v[58:59]
	v_cvt_pk_bf16_f32 v57, v62, v63
	v_add_co_u32_e32 v62, vcc, s64, v120
	v_max_f32_e32 v48, v48, v48
	v_max_f32_e32 v49, v49, v49
	v_cvt_pk_bf16_f32 v56, v60, v61
	v_cvt_pk_bf16_f32 v58, v64, v65
	v_cvt_pk_bf16_f32 v59, v66, v67
	v_addc_co_u32_e32 v63, vcc, 0, v121, vcc
	v_max_f32_e32 v48, 0, v48
	v_max_f32_e32 v49, 0, v49
	global_store_dwordx4 v[62:63], v[56:59], off
	v_max_f32_e32 v52, v52, v52
	v_max_f32_e32 v53, v53, v53
	v_pk_mul_f32 v[56:57], v[48:49], v[48:49]
	v_max_f32_e32 v49, v50, v50
	v_max_f32_e32 v48, v54, v54
	v_max_f32_e32 v50, 0, v49
	v_max_f32_e32 v49, v55, v55
	v_max_f32_e32 v51, v51, v51
	v_max_f32_e32 v52, 0, v52
	v_max_f32_e32 v53, 0, v53
	v_max_f32_e32 v48, 0, v48
	v_max_f32_e32 v49, 0, v49
	v_max_f32_e32 v51, 0, v51
	v_pk_mul_f32 v[52:53], v[52:53], v[52:53]
	v_pk_mul_f32 v[54:55], v[48:49], v[48:49]
	v_pk_mul_f32 v[58:59], v[50:51], v[50:51]
	v_max_f32_e32 v40, v40, v40
	v_max_f32_e32 v41, v41, v41
	v_lshl_add_u64 v[60:61], v[120:121], 0, s[12:13]
	v_cvt_pk_bf16_f32 v48, v52, v53
	v_cvt_pk_bf16_f32 v49, v54, v55
	v_cvt_pk_bf16_f32 v50, v56, v57
	v_cvt_pk_bf16_f32 v51, v58, v59
	v_max_f32_e32 v40, 0, v40
	v_max_f32_e32 v41, 0, v41
	global_store_dwordx4 v[60:61], v[48:51], off offset:256
	v_max_f32_e32 v44, v44, v44
	v_max_f32_e32 v45, v45, v45
	v_pk_mul_f32 v[48:49], v[40:41], v[40:41]
	v_max_f32_e32 v41, v42, v42
	v_max_f32_e32 v40, v46, v46
	v_max_f32_e32 v42, 0, v41
	v_max_f32_e32 v41, v47, v47
	v_max_f32_e32 v40, 0, v40
	v_max_f32_e32 v41, 0, v41
	v_max_f32_e32 v43, v43, v43
	v_max_f32_e32 v44, 0, v44
	v_max_f32_e32 v45, 0, v45
	v_max_f32_e32 v43, 0, v43
	v_pk_mul_f32 v[46:47], v[40:41], v[40:41]
	v_pk_mul_f32 v[44:45], v[44:45], v[44:45]
	v_pk_mul_f32 v[50:51], v[42:43], v[42:43]
	v_cvt_pk_bf16_f32 v41, v46, v47
	v_add_co_u32_e32 v46, vcc, s65, v120
	v_max_f32_e32 v32, v32, v32
	v_max_f32_e32 v33, v33, v33
	v_cvt_pk_bf16_f32 v40, v44, v45
	v_cvt_pk_bf16_f32 v42, v48, v49
	v_cvt_pk_bf16_f32 v43, v50, v51
	v_addc_co_u32_e32 v47, vcc, 0, v121, vcc
	v_max_f32_e32 v32, 0, v32
	v_max_f32_e32 v33, 0, v33
	global_store_dwordx4 v[46:47], v[40:43], off
	v_max_f32_e32 v36, v36, v36
	v_max_f32_e32 v37, v37, v37
	v_pk_mul_f32 v[40:41], v[32:33], v[32:33]
	v_max_f32_e32 v33, v34, v34
	v_max_f32_e32 v32, v38, v38
	v_max_f32_e32 v34, 0, v33
	v_max_f32_e32 v33, v39, v39
	v_max_f32_e32 v35, v35, v35
	v_max_f32_e32 v36, 0, v36
	v_max_f32_e32 v37, 0, v37
	v_max_f32_e32 v32, 0, v32
	v_max_f32_e32 v33, 0, v33
	v_max_f32_e32 v35, 0, v35
	v_pk_mul_f32 v[36:37], v[36:37], v[36:37]
	v_pk_mul_f32 v[38:39], v[32:33], v[32:33]
	v_pk_mul_f32 v[42:43], v[34:35], v[34:35]
	v_max_f32_e32 v24, v24, v24
	v_max_f32_e32 v25, v25, v25
	v_lshl_add_u64 v[44:45], v[120:121], 0, s[14:15]
	v_cvt_pk_bf16_f32 v32, v36, v37
	v_cvt_pk_bf16_f32 v33, v38, v39
	v_cvt_pk_bf16_f32 v34, v40, v41
	v_cvt_pk_bf16_f32 v35, v42, v43
	v_max_f32_e32 v24, 0, v24
	v_max_f32_e32 v25, 0, v25
	global_store_dwordx4 v[44:45], v[32:35], off offset:256
	v_max_f32_e32 v28, v28, v28
	v_max_f32_e32 v29, v29, v29
	v_pk_mul_f32 v[32:33], v[24:25], v[24:25]
	v_max_f32_e32 v25, v26, v26
	v_max_f32_e32 v24, v30, v30
	v_max_f32_e32 v26, 0, v25
	v_max_f32_e32 v25, v31, v31
	v_max_f32_e32 v24, 0, v24
	v_max_f32_e32 v25, 0, v25
	v_max_f32_e32 v27, v27, v27
	v_max_f32_e32 v28, 0, v28
	v_max_f32_e32 v29, 0, v29
	v_max_f32_e32 v27, 0, v27
	v_pk_mul_f32 v[30:31], v[24:25], v[24:25]
	v_pk_mul_f32 v[28:29], v[28:29], v[28:29]
	v_pk_mul_f32 v[34:35], v[26:27], v[26:27]
	v_cvt_pk_bf16_f32 v25, v30, v31
	v_add_co_u32_e32 v30, vcc, s70, v120
	v_max_f32_e32 v16, v16, v16
	v_max_f32_e32 v17, v17, v17
	v_cvt_pk_bf16_f32 v24, v28, v29
	v_cvt_pk_bf16_f32 v26, v32, v33
	v_cvt_pk_bf16_f32 v27, v34, v35
	v_addc_co_u32_e32 v31, vcc, 0, v121, vcc
	v_max_f32_e32 v16, 0, v16
	v_max_f32_e32 v17, 0, v17
	global_store_dwordx4 v[30:31], v[24:27], off
	v_max_f32_e32 v20, v20, v20
	v_max_f32_e32 v21, v21, v21
	v_pk_mul_f32 v[24:25], v[16:17], v[16:17]
	v_max_f32_e32 v17, v18, v18
	v_max_f32_e32 v16, v22, v22
	v_max_f32_e32 v18, 0, v17
	v_max_f32_e32 v17, v23, v23
	v_max_f32_e32 v19, v19, v19
	v_max_f32_e32 v20, 0, v20
	v_max_f32_e32 v21, 0, v21
	v_max_f32_e32 v16, 0, v16
	v_max_f32_e32 v17, 0, v17
	v_max_f32_e32 v19, 0, v19
	v_pk_mul_f32 v[20:21], v[20:21], v[20:21]
	v_pk_mul_f32 v[22:23], v[16:17], v[16:17]
	v_pk_mul_f32 v[26:27], v[18:19], v[18:19]
	v_max_f32_e32 v8, v8, v8
	v_max_f32_e32 v9, v9, v9
	v_lshl_add_u64 v[28:29], v[120:121], 0, s[16:17]
	v_cvt_pk_bf16_f32 v16, v20, v21
	v_cvt_pk_bf16_f32 v17, v22, v23
	v_cvt_pk_bf16_f32 v18, v24, v25
	v_cvt_pk_bf16_f32 v19, v26, v27
	v_max_f32_e32 v8, 0, v8
	v_max_f32_e32 v9, 0, v9
	global_store_dwordx4 v[28:29], v[16:19], off offset:256
	v_max_f32_e32 v12, v12, v12
	v_max_f32_e32 v13, v13, v13
	v_pk_mul_f32 v[16:17], v[8:9], v[8:9]
	v_max_f32_e32 v9, v10, v10
	v_max_f32_e32 v8, v14, v14
	v_max_f32_e32 v10, 0, v9
	v_max_f32_e32 v9, v15, v15
	v_max_f32_e32 v8, 0, v8
	v_max_f32_e32 v9, 0, v9
	v_max_f32_e32 v11, v11, v11
	v_max_f32_e32 v12, 0, v12
	v_max_f32_e32 v13, 0, v13
	v_max_f32_e32 v11, 0, v11
	v_pk_mul_f32 v[14:15], v[8:9], v[8:9]
	v_pk_mul_f32 v[12:13], v[12:13], v[12:13]
	v_pk_mul_f32 v[18:19], v[10:11], v[10:11]
	v_cvt_pk_bf16_f32 v9, v14, v15
	v_add_co_u32_e32 v14, vcc, s71, v120
	v_max_f32_e32 v0, v0, v0
	v_max_f32_e32 v1, v1, v1
	v_cvt_pk_bf16_f32 v8, v12, v13
	v_cvt_pk_bf16_f32 v10, v16, v17
	v_cvt_pk_bf16_f32 v11, v18, v19
	v_addc_co_u32_e32 v15, vcc, 0, v121, vcc
	v_max_f32_e32 v0, 0, v0
	v_max_f32_e32 v1, 0, v1
	global_store_dwordx4 v[14:15], v[8:11], off
	v_max_f32_e32 v4, v4, v4
	v_max_f32_e32 v5, v5, v5
	v_pk_mul_f32 v[8:9], v[0:1], v[0:1]
	v_max_f32_e32 v1, v2, v2
	v_max_f32_e32 v0, v6, v6
	v_max_f32_e32 v2, 0, v1
	v_max_f32_e32 v1, v7, v7
	v_max_f32_e32 v3, v3, v3
	v_max_f32_e32 v4, 0, v4
	v_max_f32_e32 v5, 0, v5
	v_max_f32_e32 v0, 0, v0
	v_max_f32_e32 v1, 0, v1
	v_max_f32_e32 v3, 0, v3
	v_pk_mul_f32 v[4:5], v[4:5], v[4:5]
	v_pk_mul_f32 v[6:7], v[0:1], v[0:1]
	v_pk_mul_f32 v[10:11], v[2:3], v[2:3]
	v_lshl_add_u64 v[12:13], v[120:121], 0, s[18:19]
	v_cvt_pk_bf16_f32 v0, v4, v5
	v_cvt_pk_bf16_f32 v1, v6, v7
	v_cvt_pk_bf16_f32 v2, v8, v9
	v_cvt_pk_bf16_f32 v3, v10, v11
	s_and_b64 vcc, exec, s[4:5]
	s_mov_b32 s72, s20
	s_mov_b32 s34, s26
	s_mov_b64 s[38:39], s[30:31]
	s_mov_b64 s[36:37], s[28:29]
	global_store_dwordx4 v[12:13], v[0:3], off offset:256
	s_mov_b32 s94, 1
	s_cbranch_vccz .LBB0_1303
	s_mov_b32 s94, 0
	s_waitcnt vmcnt(16)
	s_cmpk_gt_u32 s42, 0xff
	s_cbranch_scc1 .LBB0_1314
	s_barrier

.LBB0_1384:
	ds_read_b128 v[156:159], v153
	ds_read_b128 v[160:163], v153 offset:1024
	ds_read_b128 v[164:167], v153 offset:2048
	ds_read_b128 v[168:171], v153 offset:3072
	s_add_u32 s36, s34, 0xfff00080
	s_addc_u32 s37, s35, -1
	s_cmp_eq_u32 s77, 60
	s_cselect_b32 s39, s27, s37
	s_cselect_b32 s38, s73, s36
	s_cselect_b32 s37, s21, s76
	s_cselect_b32 s36, s74, s75
	v_lshl_add_u64 v[204:205], s[34:35], 0, v[138:139]
	s_add_i32 m0, s19, 0xc000
	ds_read_b128 v[172:175], v154
	ds_read_b128 v[176:179], v154 offset:1024
	ds_read_b128 v[180:183], v154 offset:2048
	ds_read_b128 v[184:187], v154 offset:3072
	ds_read_b128 v[188:191], v154 offset:4096
	ds_read_b128 v[192:195], v154 offset:5120
	ds_read_b128 v[196:199], v154 offset:6144
	ds_read_b128 v[200:203], v154 offset:7168
	global_load_lds_dwordx4 v[204:205], off
	v_lshl_add_u64 v[204:205], s[34:35], 0, v[140:141]
	s_add_i32 m0, s19, 0xe000
	s_nop 0
	global_load_lds_dwordx4 v[204:205], off
	s_waitcnt lgkmcnt(8)
	s_barrier
	s_waitcnt lgkmcnt(0)
	s_waitcnt lgkmcnt(0)
	v_mfma_f32_16x16x32_bf16 v[124:127], v[156:159], v[172:175], v[124:127]
	v_mfma_f32_16x16x32_bf16 v[120:123], v[164:167], v[172:175], v[120:123]
	v_mfma_f32_16x16x32_bf16 v[116:119], v[156:159], v[180:183], v[116:119]
	v_mfma_f32_16x16x32_bf16 v[112:115], v[164:167], v[180:183], v[112:115]
	v_mfma_f32_16x16x32_bf16 v[100:103], v[156:159], v[188:191], v[100:103]
	v_mfma_f32_16x16x32_bf16 v[96:99], v[164:167], v[188:191], v[96:99]
	v_mfma_f32_16x16x32_bf16 v[84:87], v[156:159], v[196:199], v[84:87]
	v_mfma_f32_16x16x32_bf16 v[80:83], v[164:167], v[196:199], v[80:83]
	v_mfma_f32_16x16x32_bf16 v[124:127], v[160:163], v[176:179], v[124:127]
	v_mfma_f32_16x16x32_bf16 v[120:123], v[168:171], v[176:179], v[120:123]
	v_mfma_f32_16x16x32_bf16 v[116:119], v[160:163], v[184:187], v[116:119]
	v_mfma_f32_16x16x32_bf16 v[112:115], v[168:171], v[184:187], v[112:115]
	v_mfma_f32_16x16x32_bf16 v[100:103], v[160:163], v[192:195], v[100:103]
	v_mfma_f32_16x16x32_bf16 v[96:99], v[168:171], v[192:195], v[96:99]
	v_mfma_f32_16x16x32_bf16 v[84:87], v[160:163], v[200:203], v[84:87]
	v_mfma_f32_16x16x32_bf16 v[80:83], v[168:171], v[200:203], v[80:83]
	s_barrier
	s_add_i32 s78, s62, s43
	v_lshl_add_u64 v[220:221], s[36:37], 0, v[134:135]
	s_mov_b32 m0, s78
	ds_read_b128 v[204:207], v155
	ds_read_b128 v[208:211], v155 offset:1024
	ds_read_b128 v[212:215], v155 offset:2048
	ds_read_b128 v[216:219], v155 offset:3072
	global_load_lds_dwordx4 v[220:221], off
	v_lshl_add_u64 v[222:223], s[36:37], 0, v[130:131]
	s_add_i32 m0, s78, 0x2000
	s_nop 0
	global_load_lds_dwordx4 v[222:223], off
	s_barrier
	s_waitcnt lgkmcnt(0)
	s_waitcnt lgkmcnt(0)
	v_mfma_f32_16x16x32_bf16 v[108:111], v[204:207], v[172:175], v[108:111]
	v_mfma_f32_16x16x32_bf16 v[104:107], v[212:215], v[172:175], v[104:107]
	v_mfma_f32_16x16x32_bf16 v[92:95], v[204:207], v[180:183], v[92:95]
	v_mfma_f32_16x16x32_bf16 v[88:91], v[212:215], v[180:183], v[88:91]
	v_mfma_f32_16x16x32_bf16 v[76:79], v[204:207], v[188:191], v[76:79]
	v_mfma_f32_16x16x32_bf16 v[72:75], v[212:215], v[188:191], v[72:75]
	v_mfma_f32_16x16x32_bf16 v[68:71], v[204:207], v[196:199], v[68:71]
	v_mfma_f32_16x16x32_bf16 v[64:67], v[212:215], v[196:199], v[64:67]
	v_mfma_f32_16x16x32_bf16 v[108:111], v[208:211], v[176:179], v[108:111]
	v_mfma_f32_16x16x32_bf16 v[104:107], v[216:219], v[176:179], v[104:107]
	v_mfma_f32_16x16x32_bf16 v[92:95], v[208:211], v[184:187], v[92:95]
	v_mfma_f32_16x16x32_bf16 v[88:91], v[216:219], v[184:187], v[88:91]
	v_mfma_f32_16x16x32_bf16 v[76:79], v[208:211], v[192:195], v[76:79]
	v_mfma_f32_16x16x32_bf16 v[72:75], v[216:219], v[192:195], v[72:75]
	v_mfma_f32_16x16x32_bf16 v[68:71], v[208:211], v[200:203], v[68:71]
	v_mfma_f32_16x16x32_bf16 v[64:67], v[216:219], v[200:203], v[64:67]
	s_mov_b32 m0, s19
	v_lshl_add_u64 v[224:225], s[38:39], 0, v[136:137]
	s_barrier
	ds_read_b128 v[172:175], v154 offset:16384
	ds_read_b128 v[176:179], v154 offset:17408
	ds_read_b128 v[180:183], v154 offset:18432
	ds_read_b128 v[184:187], v154 offset:19456
	ds_read_b128 v[188:191], v154 offset:20480
	ds_read_b128 v[192:195], v154 offset:21504
	ds_read_b128 v[196:199], v154 offset:22528
	ds_read_b128 v[200:203], v154 offset:23552
	global_load_lds_dwordx4 v[224:225], off
	v_lshl_add_u64 v[226:227], s[38:39], 0, v[132:133]
	s_mov_b32 m0, s53
	s_nop 0
	global_load_lds_dwordx4 v[226:227], off
	s_barrier
	s_waitcnt lgkmcnt(0)
	s_waitcnt lgkmcnt(0)
	v_mfma_f32_16x16x32_bf16 v[60:63], v[156:159], v[172:175], v[60:63]
	v_mfma_f32_16x16x32_bf16 v[56:59], v[164:167], v[172:175], v[56:59]
	v_mfma_f32_16x16x32_bf16 v[52:55], v[156:159], v[180:183], v[52:55]
	v_mfma_f32_16x16x32_bf16 v[48:51], v[164:167], v[180:183], v[48:51]
	v_mfma_f32_16x16x32_bf16 v[36:39], v[156:159], v[188:191], v[36:39]
	v_mfma_f32_16x16x32_bf16 v[32:35], v[164:167], v[188:191], v[32:35]
	v_mfma_f32_16x16x32_bf16 v[20:23], v[156:159], v[196:199], v[20:23]
	v_mfma_f32_16x16x32_bf16 v[16:19], v[164:167], v[196:199], v[16:19]
	v_mfma_f32_16x16x32_bf16 v[60:63], v[160:163], v[176:179], v[60:63]
	v_mfma_f32_16x16x32_bf16 v[56:59], v[168:171], v[176:179], v[56:59]
	v_mfma_f32_16x16x32_bf16 v[52:55], v[160:163], v[184:187], v[52:55]
	v_mfma_f32_16x16x32_bf16 v[48:51], v[168:171], v[184:187], v[48:51]
	v_mfma_f32_16x16x32_bf16 v[36:39], v[160:163], v[192:195], v[36:39]
	v_mfma_f32_16x16x32_bf16 v[32:35], v[168:171], v[192:195], v[32:35]
	v_mfma_f32_16x16x32_bf16 v[20:23], v[160:163], v[200:203], v[20:23]
	v_mfma_f32_16x16x32_bf16 v[16:19], v[168:171], v[200:203], v[16:19]
	s_barrier
	s_add_u32 s78, s36, 0x100000
	s_addc_u32 s79, s37, 0
	s_add_i32 s80, s63, s43
	v_lshl_add_u64 v[156:157], s[78:79], 0, v[134:135]
	s_mov_b32 m0, s80
	s_nop 0
	global_load_lds_dwordx4 v[156:157], off
	v_lshl_add_u64 v[156:157], s[78:79], 0, v[130:131]
	s_add_i32 m0, s80, 0x2000
	s_nop 0
	global_load_lds_dwordx4 v[156:157], off
	s_cmp_lg_u32 s94, 0
	s_cbranch_scc1 .Lrx11a
	s_waitcnt vmcnt(6)
.Lrx11a:
	s_waitcnt vmcnt(24)
	s_barrier
	v_mfma_f32_16x16x32_bf16 v[44:47], v[204:207], v[172:175], v[44:47]
	v_mfma_f32_16x16x32_bf16 v[40:43], v[212:215], v[172:175], v[40:43]
	v_mfma_f32_16x16x32_bf16 v[28:31], v[204:207], v[180:183], v[28:31]
	v_mfma_f32_16x16x32_bf16 v[24:27], v[212:215], v[180:183], v[24:27]
	v_mfma_f32_16x16x32_bf16 v[12:15], v[204:207], v[188:191], v[12:15]
	v_mfma_f32_16x16x32_bf16 v[8:11], v[212:215], v[188:191], v[8:11]
	v_mfma_f32_16x16x32_bf16 v[4:7], v[204:207], v[196:199], v[4:7]
	v_mfma_f32_16x16x32_bf16 v[0:3], v[212:215], v[196:199], v[0:3]
	v_mfma_f32_16x16x32_bf16 v[44:47], v[208:211], v[176:179], v[44:47]
	v_mfma_f32_16x16x32_bf16 v[40:43], v[216:219], v[176:179], v[40:43]
	v_mfma_f32_16x16x32_bf16 v[28:31], v[208:211], v[184:187], v[28:31]
	v_mfma_f32_16x16x32_bf16 v[24:27], v[216:219], v[184:187], v[24:27]
	v_mfma_f32_16x16x32_bf16 v[12:15], v[208:211], v[192:195], v[12:15]
	v_mfma_f32_16x16x32_bf16 v[8:11], v[216:219], v[192:195], v[8:11]
	v_mfma_f32_16x16x32_bf16 v[4:7], v[208:211], v[200:203], v[4:7]
	v_mfma_f32_16x16x32_bf16 v[0:3], v[216:219], v[200:203], v[0:3]
	s_add_i32 s78, 0, 0x18000
	v_add_u32_e32 v168, s78, v151
	s_barrier
	ds_read_b128 v[156:159], v168
	ds_read_b128 v[160:163], v168 offset:1024
	ds_read_b128 v[164:167], v168 offset:2048
	ds_read_b128 v[168:171], v168 offset:3072
	s_add_u32 s38, s38, 0x100000
	s_addc_u32 s39, s39, 0
	s_mov_b32 m0, s54
	v_lshl_add_u64 v[204:205], s[38:39], 0, v[136:137]
	ds_read_b128 v[172:175], v154 offset:32768
	ds_read_b128 v[176:179], v154 offset:33792
	ds_read_b128 v[180:183], v154 offset:34816
	ds_read_b128 v[184:187], v154 offset:35840
	ds_read_b128 v[188:191], v154 offset:36864
	ds_read_b128 v[192:195], v154 offset:37888
	ds_read_b128 v[196:199], v154 offset:38912
	ds_read_b128 v[200:203], v154 offset:39936
	global_load_lds_dwordx4 v[204:205], off
	v_lshl_add_u64 v[204:205], s[38:39], 0, v[132:133]
	s_mov_b32 m0, s55
	s_nop 0
	global_load_lds_dwordx4 v[204:205], off
	s_waitcnt lgkmcnt(8)
	s_barrier
	s_waitcnt lgkmcnt(0)
	s_waitcnt lgkmcnt(0)
	v_mfma_f32_16x16x32_bf16 v[124:127], v[156:159], v[172:175], v[124:127]
	v_mfma_f32_16x16x32_bf16 v[120:123], v[164:167], v[172:175], v[120:123]
	v_mfma_f32_16x16x32_bf16 v[116:119], v[156:159], v[180:183], v[116:119]
	v_mfma_f32_16x16x32_bf16 v[112:115], v[164:167], v[180:183], v[112:115]
	v_mfma_f32_16x16x32_bf16 v[100:103], v[156:159], v[188:191], v[100:103]
	v_mfma_f32_16x16x32_bf16 v[96:99], v[164:167], v[188:191], v[96:99]
	v_mfma_f32_16x16x32_bf16 v[84:87], v[156:159], v[196:199], v[84:87]
	v_mfma_f32_16x16x32_bf16 v[80:83], v[164:167], v[196:199], v[80:83]
	v_mfma_f32_16x16x32_bf16 v[124:127], v[160:163], v[176:179], v[124:127]
	v_mfma_f32_16x16x32_bf16 v[120:123], v[168:171], v[176:179], v[120:123]
	v_mfma_f32_16x16x32_bf16 v[116:119], v[160:163], v[184:187], v[116:119]
	v_mfma_f32_16x16x32_bf16 v[112:115], v[168:171], v[184:187], v[112:115]
	v_mfma_f32_16x16x32_bf16 v[100:103], v[160:163], v[192:195], v[100:103]
	v_mfma_f32_16x16x32_bf16 v[96:99], v[168:171], v[192:195], v[96:99]
	v_mfma_f32_16x16x32_bf16 v[84:87], v[160:163], v[200:203], v[84:87]
	v_mfma_f32_16x16x32_bf16 v[80:83], v[168:171], v[200:203], v[80:83]
	s_barrier
	s_add_i32 s38, 0, 0x1c000
	s_add_i32 s39, s78, s43
	v_add_u32_e32 v216, s38, v151
	v_lshl_add_u64 v[220:221], v[220:221], 0, s[8:9]
	s_mov_b32 m0, s39
	ds_read_b128 v[204:207], v216
	ds_read_b128 v[208:211], v216 offset:1024
	ds_read_b128 v[212:215], v216 offset:2048
	ds_read_b128 v[216:219], v216 offset:3072
	global_load_lds_dwordx4 v[220:221], off
	v_lshl_add_u64 v[220:221], v[222:223], 0, s[8:9]
	s_add_i32 m0, s39, 0x2000
	s_nop 0
	global_load_lds_dwordx4 v[220:221], off
	s_cmp_lg_u32 s94, 0
	s_cbranch_scc0 .Lrx11c
	s_waitcnt vmcnt(10)
	s_mov_b32 s94, 0
.Lrx11c:
	s_barrier
	s_waitcnt lgkmcnt(0)
	s_waitcnt lgkmcnt(0)
	v_mfma_f32_16x16x32_bf16 v[108:111], v[204:207], v[172:175], v[108:111]
	v_mfma_f32_16x16x32_bf16 v[104:107], v[212:215], v[172:175], v[104:107]
	v_mfma_f32_16x16x32_bf16 v[92:95], v[204:207], v[180:183], v[92:95]
	v_mfma_f32_16x16x32_bf16 v[88:91], v[212:215], v[180:183], v[88:91]
	v_mfma_f32_16x16x32_bf16 v[76:79], v[204:207], v[188:191], v[76:79]
	v_mfma_f32_16x16x32_bf16 v[72:75], v[212:215], v[188:191], v[72:75]
	v_mfma_f32_16x16x32_bf16 v[68:71], v[204:207], v[196:199], v[68:71]
	v_mfma_f32_16x16x32_bf16 v[64:67], v[212:215], v[196:199], v[64:67]
	v_mfma_f32_16x16x32_bf16 v[108:111], v[208:211], v[176:179], v[108:111]
	v_mfma_f32_16x16x32_bf16 v[104:107], v[216:219], v[176:179], v[104:107]
	v_mfma_f32_16x16x32_bf16 v[92:95], v[208:211], v[184:187], v[92:95]
	v_mfma_f32_16x16x32_bf16 v[88:91], v[216:219], v[184:187], v[88:91]
	v_mfma_f32_16x16x32_bf16 v[76:79], v[208:211], v[192:195], v[76:79]
	v_mfma_f32_16x16x32_bf16 v[72:75], v[216:219], v[192:195], v[72:75]
	v_mfma_f32_16x16x32_bf16 v[68:71], v[208:211], v[200:203], v[68:71]
	v_mfma_f32_16x16x32_bf16 v[64:67], v[216:219], v[200:203], v[64:67]
	s_mov_b32 m0, s57
	v_lshl_add_u64 v[220:221], v[224:225], 0, s[8:9]
	s_barrier
	ds_read_b128 v[172:175], v154 offset:49152
	ds_read_b128 v[176:179], v154 offset:50176
	ds_read_b128 v[180:183], v154 offset:51200
	ds_read_b128 v[184:187], v154 offset:52224
	ds_read_b128 v[188:191], v154 offset:53248
	ds_read_b128 v[192:195], v154 offset:54272
	ds_read_b128 v[196:199], v154 offset:55296
	ds_read_b128 v[200:203], v154 offset:56320
	global_load_lds_dwordx4 v[220:221], off
	v_lshl_add_u64 v[220:221], v[226:227], 0, s[8:9]
	s_mov_b32 m0, s60
	s_nop 0
	global_load_lds_dwordx4 v[220:221], off
	s_barrier
	s_waitcnt lgkmcnt(0)
	s_waitcnt lgkmcnt(0)
	v_mfma_f32_16x16x32_bf16 v[60:63], v[156:159], v[172:175], v[60:63]
	v_mfma_f32_16x16x32_bf16 v[56:59], v[164:167], v[172:175], v[56:59]
	v_mfma_f32_16x16x32_bf16 v[52:55], v[156:159], v[180:183], v[52:55]
	v_mfma_f32_16x16x32_bf16 v[48:51], v[164:167], v[180:183], v[48:51]
	v_mfma_f32_16x16x32_bf16 v[36:39], v[156:159], v[188:191], v[36:39]
	v_mfma_f32_16x16x32_bf16 v[32:35], v[164:167], v[188:191], v[32:35]
	v_mfma_f32_16x16x32_bf16 v[20:23], v[156:159], v[196:199], v[20:23]
	v_mfma_f32_16x16x32_bf16 v[16:19], v[164:167], v[196:199], v[16:19]
	v_mfma_f32_16x16x32_bf16 v[60:63], v[160:163], v[176:179], v[60:63]
	v_mfma_f32_16x16x32_bf16 v[56:59], v[168:171], v[176:179], v[56:59]
	v_mfma_f32_16x16x32_bf16 v[52:55], v[160:163], v[184:187], v[52:55]
	v_mfma_f32_16x16x32_bf16 v[48:51], v[168:171], v[184:187], v[48:51]
	v_mfma_f32_16x16x32_bf16 v[36:39], v[160:163], v[192:195], v[36:39]
	v_mfma_f32_16x16x32_bf16 v[32:35], v[168:171], v[192:195], v[32:35]
	v_mfma_f32_16x16x32_bf16 v[20:23], v[160:163], v[200:203], v[20:23]
	v_mfma_f32_16x16x32_bf16 v[16:19], v[168:171], v[200:203], v[16:19]
	s_barrier
	s_add_u32 s36, s36, 0x100080
	s_addc_u32 s37, s37, 0
	s_add_i32 s38, s38, s43
	v_lshl_add_u64 v[156:157], s[36:37], 0, v[134:135]
	s_mov_b32 m0, s38
	s_nop 0
	global_load_lds_dwordx4 v[156:157], off
	v_lshl_add_u64 v[156:157], s[36:37], 0, v[130:131]
	s_add_i32 m0, s38, 0x2000
	s_nop 0
	global_load_lds_dwordx4 v[156:157], off
	s_waitcnt vmcnt(6)
	s_barrier
	v_mfma_f32_16x16x32_bf16 v[44:47], v[204:207], v[172:175], v[44:47]
	v_mfma_f32_16x16x32_bf16 v[40:43], v[212:215], v[172:175], v[40:43]
	v_mfma_f32_16x16x32_bf16 v[28:31], v[204:207], v[180:183], v[28:31]
	v_mfma_f32_16x16x32_bf16 v[24:27], v[212:215], v[180:183], v[24:27]
	v_mfma_f32_16x16x32_bf16 v[12:15], v[204:207], v[188:191], v[12:15]
	v_mfma_f32_16x16x32_bf16 v[8:11], v[212:215], v[188:191], v[8:11]
	v_mfma_f32_16x16x32_bf16 v[4:7], v[204:207], v[196:199], v[4:7]
	v_mfma_f32_16x16x32_bf16 v[0:3], v[212:215], v[196:199], v[0:3]
	v_mfma_f32_16x16x32_bf16 v[44:47], v[208:211], v[176:179], v[44:47]
	v_mfma_f32_16x16x32_bf16 v[40:43], v[216:219], v[176:179], v[40:43]
	v_mfma_f32_16x16x32_bf16 v[28:31], v[208:211], v[184:187], v[28:31]
	v_mfma_f32_16x16x32_bf16 v[24:27], v[216:219], v[184:187], v[24:27]
	v_mfma_f32_16x16x32_bf16 v[12:15], v[208:211], v[192:195], v[12:15]
	v_mfma_f32_16x16x32_bf16 v[8:11], v[216:219], v[192:195], v[8:11]
	v_mfma_f32_16x16x32_bf16 v[4:7], v[208:211], v[200:203], v[4:7]
	v_mfma_f32_16x16x32_bf16 v[0:3], v[216:219], v[200:203], v[0:3]
	s_add_i32 s77, s77, 2
	s_add_u32 s34, s34, 0x100
	s_addc_u32 s35, s35, 0
	s_add_u32 s75, s75, 0x100
	s_addc_u32 s76, s76, 0
	s_cmp_gt_u32 s77, 61
	s_barrier
	s_cbranch_scc0 .LBB0_1384
	v_lshl_add_u32 v156, s18, 8, v150
	v_lshl_or_b32 v158, s72, 8, v152
	v_ashrrev_i32_e32 v157, 31, v156
	v_lshlrev_b64 v[160:161], 11, v[156:157]
	v_ashrrev_i32_e32 v159, 31, v158
	v_lshl_add_u64 v[160:161], s[44:45], 0, v[160:161]
	v_cvt_pk_bf16_f32 v124, v124, v125
	v_cvt_pk_bf16_f32 v125, v126, v127
	v_cvt_pk_bf16_f32 v126, v120, v121
	v_lshlrev_b64 v[120:121], 1, v[158:159]
	v_cvt_pk_bf16_f32 v127, v122, v123
	v_lshl_add_u64 v[122:123], v[160:161], 0, v[120:121]
	v_cvt_pk_bf16_f32 v108, v108, v109
	v_cvt_pk_bf16_f32 v109, v110, v111
	v_cvt_pk_bf16_f32 v110, v104, v105
	v_or_b32_e32 v104, 16, v156
	v_cvt_pk_bf16_f32 v60, v60, v61
	v_cvt_pk_bf16_f32 v61, v62, v63
	v_cvt_pk_bf16_f32 v63, v58, v59
	v_add_co_u32_e32 v58, vcc, s64, v122
	v_ashrrev_i32_e32 v105, 31, v104
	v_cvt_pk_bf16_f32 v62, v56, v57
	v_lshl_add_u64 v[56:57], v[122:123], 0, s[10:11]
	v_addc_co_u32_e32 v59, vcc, 0, v123, vcc
	v_cvt_pk_bf16_f32 v44, v44, v45
	v_cvt_pk_bf16_f32 v45, v46, v47
	v_cvt_pk_bf16_f32 v46, v40, v41
	v_cvt_pk_bf16_f32 v47, v42, v43
	v_cvt_pk_bf16_f32 v111, v106, v107
	v_lshlrev_b64 v[104:105], 11, v[104:105]
	v_cvt_pk_bf16_f32 v92, v92, v93
	v_cvt_pk_bf16_f32 v93, v94, v95
	v_cvt_pk_bf16_f32 v94, v88, v89
	v_or_b32_e32 v88, 32, v156
	global_store_dwordx4 v[56:57], v[44:47], off offset:256
	global_store_dwordx4 v[122:123], v[108:111], off offset:256
	v_ashrrev_i32_e32 v89, 31, v88
	v_add_co_u32_e32 v46, vcc, s65, v122
	v_lshl_add_u64 v[108:109], s[44:45], 0, v[104:105]
	v_lshl_add_u64 v[44:45], v[122:123], 0, s[12:13]
	v_addc_co_u32_e32 v47, vcc, 0, v123, vcc
	v_cvt_pk_bf16_f32 v28, v28, v29
	v_cvt_pk_bf16_f32 v29, v30, v31
	v_cvt_pk_bf16_f32 v30, v24, v25
	v_cvt_pk_bf16_f32 v31, v26, v27
	v_lshl_add_u64 v[108:109], v[108:109], 0, v[120:121]
	v_cvt_pk_bf16_f32 v95, v90, v91
	v_lshlrev_b64 v[88:89], 11, v[88:89]
	v_cvt_pk_bf16_f32 v76, v76, v77
	v_cvt_pk_bf16_f32 v77, v78, v79
	v_cvt_pk_bf16_f32 v78, v72, v73
	v_or_b32_e32 v72, 48, v156
	global_store_dwordx4 v[44:45], v[28:31], off offset:256
	global_store_dwordx4 v[108:109], v[92:95], off offset:256
	v_ashrrev_i32_e32 v73, 31, v72
	v_add_co_u32_e32 v30, vcc, s70, v122
	v_lshl_add_u64 v[92:93], s[44:45], 0, v[88:89]
	v_lshl_add_u64 v[28:29], v[122:123], 0, s[14:15]
	v_addc_co_u32_e32 v31, vcc, 0, v123, vcc
	v_cvt_pk_bf16_f32 v12, v12, v13
	v_cvt_pk_bf16_f32 v13, v14, v15
	v_cvt_pk_bf16_f32 v14, v8, v9
	v_cvt_pk_bf16_f32 v15, v10, v11
	v_lshl_add_u64 v[92:93], v[92:93], 0, v[120:121]
	v_cvt_pk_bf16_f32 v79, v74, v75
	v_lshlrev_b64 v[72:73], 11, v[72:73]
	global_store_dwordx4 v[28:29], v[12:15], off offset:256
	global_store_dwordx4 v[92:93], v[76:79], off offset:256
	v_cvt_pk_bf16_f32 v104, v116, v117
	v_add_co_u32_e32 v14, vcc, s71, v122
	v_lshl_add_u64 v[76:77], s[44:45], 0, v[72:73]
	s_nop 0
	v_addc_co_u32_e32 v15, vcc, 0, v123, vcc
	v_cvt_pk_bf16_f32 v105, v118, v119
	v_cvt_pk_bf16_f32 v106, v112, v113
	v_cvt_pk_bf16_f32 v107, v114, v115
	v_cvt_pk_bf16_f32 v88, v100, v101
	v_cvt_pk_bf16_f32 v89, v102, v103
	v_cvt_pk_bf16_f32 v90, v96, v97
	v_cvt_pk_bf16_f32 v91, v98, v99
	v_cvt_pk_bf16_f32 v72, v84, v85
	v_cvt_pk_bf16_f32 v73, v86, v87
	v_cvt_pk_bf16_f32 v74, v80, v81
	v_cvt_pk_bf16_f32 v75, v82, v83
	v_lshl_add_u64 v[76:77], v[76:77], 0, v[120:121]
	v_cvt_pk_bf16_f32 v68, v68, v69
	v_cvt_pk_bf16_f32 v69, v70, v71
	v_cvt_pk_bf16_f32 v70, v64, v65
	v_cvt_pk_bf16_f32 v71, v66, v67
	v_cvt_pk_bf16_f32 v40, v52, v53
	v_cvt_pk_bf16_f32 v41, v54, v55
	v_cvt_pk_bf16_f32 v42, v48, v49
	v_cvt_pk_bf16_f32 v43, v50, v51
	v_cvt_pk_bf16_f32 v24, v36, v37
	v_cvt_pk_bf16_f32 v25, v38, v39
	v_cvt_pk_bf16_f32 v26, v32, v33
	v_cvt_pk_bf16_f32 v27, v34, v35
	v_cvt_pk_bf16_f32 v8, v20, v21
	v_cvt_pk_bf16_f32 v9, v22, v23
	v_cvt_pk_bf16_f32 v10, v16, v17
	v_cvt_pk_bf16_f32 v11, v18, v19
	v_lshl_add_u64 v[12:13], v[122:123], 0, s[16:17]
	v_cvt_pk_bf16_f32 v4, v4, v5
	v_cvt_pk_bf16_f32 v5, v6, v7
	v_cvt_pk_bf16_f32 v6, v0, v1
	v_cvt_pk_bf16_f32 v7, v2, v3
	s_and_b64 vcc, exec, s[4:5]
	s_mov_b32 s72, s20
	s_mov_b32 s18, s26
	s_mov_b64 s[36:37], s[30:31]
	s_mov_b64 s[34:35], s[28:29]
	global_store_dwordx4 v[122:123], v[124:127], off
	global_store_dwordx4 v[108:109], v[104:107], off
	global_store_dwordx4 v[92:93], v[88:91], off
	global_store_dwordx4 v[76:77], v[72:75], off
	global_store_dwordx4 v[76:77], v[68:71], off offset:256
	global_store_dwordx4 v[58:59], v[60:63], off
	global_store_dwordx4 v[46:47], v[40:43], off
	global_store_dwordx4 v[30:31], v[24:27], off
	global_store_dwordx4 v[14:15], v[8:11], off
	global_store_dwordx4 v[12:13], v[4:7], off offset:256
	s_mov_b32 s94, 1
	s_cbranch_vccz .LBB0_1381
	s_mov_b32 s94, 0
	s_waitcnt vmcnt(16)
	s_cmpk_gt_u32 s40, 0xff
	s_cbranch_scc1 .LBB0_1388
	s_barrier
